# K-loops: last 2 LDS-DMA pieces of 2nd/4th load segment moved into the following MFMA segment; 4th-segment DMAs reuse addresses via offset:128 with M0-128
# speedup vs baseline: 1.0091x; 1.0091x over previous
; #define PG8_STAGE(bufoff, gbase, voff) do { _Pragma("unroll") for (int _i = 0; _i < 2; ++_i) \
;         __builtin_amdgcn_global_load_lds((const unsigned*)((const char*)(gbase) + (voff)[_i]), (PG8_LAS unsigned*)(lds + (bufoff) + ldsw + _i * 8192), 16, 0, 0); } while (0)
; #define PG8_LDA(dst, b, h) do { _Pragma("unroll") for (int m = 0; m < 4; ++m) _Pragma("unroll") for (int k = 0; k < 2; ++k) dst[m][k] = *(const PG8_LAS bf16x8*)(lds + PG8_SA(b, h) + aoff + m * 2048 + k * 1024); } while (0)
; #define PG8_LDB(dst, b, h) do { _Pragma("unroll") for (int n = 0; n < 2; ++n) _Pragma("unroll") for (int k = 0; k < 2; ++k) dst[n][k] = *(const PG8_LAS bf16x8*)(lds + PG8_SB(b, h) + boff + n * 2048 + k * 1024); } while (0)
; #define PG8_MMA(ai, bj, At, Bt) do { __builtin_amdgcn_s_setprio(1); _Pragma("unroll") for (int m = 0; m < 4; ++m) _Pragma("unroll") for (int n = 0; n < 2; ++n) _Pragma("unroll") for (int k = 0; k < 2; ++k) \
;         acc[ai][bj][m][n] = __builtin_amdgcn_mfma_f32_16x16x32_bf16(Bt[n][k], At[m][k], acc[ai][bj][m][n], 0, 0, 0); __builtin_amdgcn_s_setprio(0); } while (0)
; #define PG8_WAIT_V(n) asm volatile("s_waitcnt vmcnt(" #n ")" ::: "memory")
; #define PG8_BAR __builtin_amdgcn_s_barrier()
; template <class Epi, class Sched, bool ALIGN_EPI = false, bool SP2 = false>
; __device__ __forceinline__ void gemm_phase(PG8_LAS unsigned char* lds, const Gemm g, const Sched& S, const Epi& E) {
;     ...
;         for (int t = 0; t < nt; t += 2) {
;             const bool last = (t == nt - 2);
;             const char* a1 = cA + (size_t)(t + 1) * kstep;
;             const char* a2 = last ? nA : cA + (size_t)(t + 2) * kstep; const char* b2 = last ? nB : cB + (size_t)(t + 2) * kstep;
;             const char* a3 = a2 + kstep; const char* b3 = b2 + kstep;
;             if (last && has_next) S.a_ready(nxt);
;             if constexpr (SP2) {
;             PG8_LDB(B0, 0, 0); PG8_LDB(B1, 0, 1); PG8_SCHED; PG8_LDA(At, 0, 0); PG8_STAGE(PG8_SA(1, 1), a1 + hstep, voffA);
;             PG8_WAIT_V(8); PG8_WAIT_L(0); PG8_BAR; PG8_MMA(0, 0, At, B0); PG8_MMA(0, 1, At, B1); PG8_BAR; PG8_SCHED;
;             PG8_LDA(At, 0, 1); PG8_STAGE(PG8_SB(0, 0), b2, voffB); PG8_STAGE(PG8_SB(0, 1), b2 + hstep, voffB); PG8_STAGE(PG8_SA(0, 0), a2, voffA);
;             PG8_WAIT_V(8); PG8_WAIT_L(0); PG8_BAR; PG8_MMA(1, 0, At, B0); PG8_MMA(1, 1, At, B1); PG8_BAR; PG8_SCHED;
.LBB0_304:
	v_add_u32_e32 v166, s54, v169
	v_add_u32_e32 v168, s55, v169
	ds_read_b128 v[162:165], v166
	ds_read_b128 v[182:185], v166 offset:1024
	ds_read_b128 v[186:189], v166 offset:2048
	ds_read_b128 v[190:193], v166 offset:3072
	ds_read_b128 v[194:197], v168
	ds_read_b128 v[198:201], v168 offset:1024
	ds_read_b128 v[202:205], v168 offset:2048
	ds_read_b128 v[206:209], v168 offset:3072
	s_cmp_eq_u32 s53, s10
	v_lshl_add_u64 v[172:173], v[160:161], 0, s[22:23]
	s_cselect_b64 vcc, -1, 0
	s_add_i32 s10, s10, 2
	v_cndmask_b32_e32 v173, v173, v153, vcc
	v_cndmask_b32_e32 v172, v172, v152, vcc
	v_cndmask_b32_e32 v245, v159, v155, vcc
	v_cndmask_b32_e32 v244, v158, v154, vcc
	s_mov_b32 m0, s56
	v_lshl_add_u64 v[246:247], v[160:161], 0, v[148:149]
	ds_read_b128 v[210:213], v179
	ds_read_b128 v[216:219], v179 offset:1024
	ds_read_b128 v[220:223], v179 offset:2048
	ds_read_b128 v[224:227], v179 offset:3072
	ds_read_b128 v[228:231], v179 offset:4096
	ds_read_b128 v[232:235], v179 offset:5120
	ds_read_b128 v[236:239], v179 offset:6144
	ds_read_b128 v[240:243], v179 offset:7168
	global_load_lds_dwordx4 v[246:247], off
	s_mov_b32 m0, s57
	v_lshl_add_u64 v[246:247], v[160:161], 0, v[146:147]
	global_load_lds_dwordx4 v[246:247], off
	s_waitcnt vmcnt(8) lgkmcnt(0)
	s_setprio 1
	s_barrier
	v_mfma_f32_16x16x32_bf16 v[124:127], v[162:165], v[210:213], v[124:127]
	v_mfma_f32_16x16x32_bf16 v[116:119], v[186:189], v[210:213], v[116:119]
	v_mfma_f32_16x16x32_bf16 v[108:111], v[162:165], v[220:223], v[108:111]
	v_mfma_f32_16x16x32_bf16 v[100:103], v[186:189], v[220:223], v[100:103]
	v_mfma_f32_16x16x32_bf16 v[92:95], v[162:165], v[228:231], v[92:95]
	v_mfma_f32_16x16x32_bf16 v[84:87], v[186:189], v[228:231], v[84:87]
	v_mfma_f32_16x16x32_bf16 v[76:79], v[162:165], v[236:239], v[76:79]
	v_mfma_f32_16x16x32_bf16 v[68:71], v[186:189], v[236:239], v[68:71]
	v_mfma_f32_16x16x32_bf16 v[124:127], v[182:185], v[216:219], v[124:127]
	v_mfma_f32_16x16x32_bf16 v[116:119], v[190:193], v[216:219], v[116:119]
	v_mfma_f32_16x16x32_bf16 v[108:111], v[182:185], v[224:227], v[108:111]
	v_mfma_f32_16x16x32_bf16 v[100:103], v[190:193], v[224:227], v[100:103]
	v_mfma_f32_16x16x32_bf16 v[92:95], v[182:185], v[232:235], v[92:95]
	v_mfma_f32_16x16x32_bf16 v[84:87], v[190:193], v[232:235], v[84:87]
	v_mfma_f32_16x16x32_bf16 v[76:79], v[182:185], v[240:243], v[76:79]
	v_mfma_f32_16x16x32_bf16 v[68:71], v[190:193], v[240:243], v[68:71]
	v_mfma_f32_16x16x32_bf16 v[120:123], v[194:197], v[210:213], v[120:123]
	v_mfma_f32_16x16x32_bf16 v[112:115], v[202:205], v[210:213], v[112:115]
	v_mfma_f32_16x16x32_bf16 v[104:107], v[194:197], v[220:223], v[104:107]
	v_mfma_f32_16x16x32_bf16 v[96:99], v[202:205], v[220:223], v[96:99]
	v_mfma_f32_16x16x32_bf16 v[88:91], v[194:197], v[228:231], v[88:91]
	v_mfma_f32_16x16x32_bf16 v[80:83], v[202:205], v[228:231], v[80:83]
	v_mfma_f32_16x16x32_bf16 v[72:75], v[194:197], v[236:239], v[72:75]
	v_mfma_f32_16x16x32_bf16 v[64:67], v[202:205], v[236:239], v[64:67]
	v_mfma_f32_16x16x32_bf16 v[120:123], v[198:201], v[216:219], v[120:123]
	v_mfma_f32_16x16x32_bf16 v[112:115], v[206:209], v[216:219], v[112:115]
	v_mfma_f32_16x16x32_bf16 v[104:107], v[198:201], v[224:227], v[104:107]
	v_mfma_f32_16x16x32_bf16 v[96:99], v[206:209], v[224:227], v[96:99]
	v_mfma_f32_16x16x32_bf16 v[88:91], v[198:201], v[232:235], v[88:91]
	v_mfma_f32_16x16x32_bf16 v[80:83], v[206:209], v[232:235], v[80:83]
	v_mfma_f32_16x16x32_bf16 v[72:75], v[198:201], v[240:243], v[72:75]
	v_mfma_f32_16x16x32_bf16 v[64:67], v[206:209], v[240:243], v[64:67]
	s_setprio 0
	s_barrier
	s_mov_b32 m0, s60
	v_lshl_add_u64 v[246:247], v[244:245], 0, v[138:139]
	ds_read_b128 v[210:213], v179 offset:16384
	ds_read_b128 v[216:219], v179 offset:17408
	ds_read_b128 v[220:223], v179 offset:18432
	ds_read_b128 v[224:227], v179 offset:19456
	ds_read_b128 v[228:231], v179 offset:20480
	ds_read_b128 v[232:235], v179 offset:21504
	ds_read_b128 v[236:239], v179 offset:22528
	global_load_lds_dwordx4 v[246:247], off
	v_lshl_add_u64 v[248:249], v[244:245], 0, v[134:135]
	s_mov_b32 m0, s61
	v_lshl_add_u64 v[244:245], v[244:245], 0, s[14:15]
	global_load_lds_dwordx4 v[248:249], off
	v_lshl_add_u64 v[250:251], v[244:245], 0, v[138:139]
	s_mov_b32 m0, s62
	v_lshl_add_u64 v[244:245], v[244:245], 0, v[134:135]
	global_load_lds_dwordx4 v[250:251], off
	s_add_i32 m0, s62, 0x2000
	ds_read_b128 v[240:243], v179 offset:23552
	global_load_lds_dwordx4 v[244:245], off
	s_waitcnt vmcnt(6) lgkmcnt(0)
	s_setprio 1
	s_barrier
; #define PG8_STAGE(bufoff, gbase, voff) do { _Pragma("unroll") for (int _i = 0; _i < 2; ++_i) \
;         __builtin_amdgcn_global_load_lds((const unsigned*)((const char*)(gbase) + (voff)[_i]), (PG8_LAS unsigned*)(lds + (bufoff) + ldsw + _i * 8192), 16, 0, 0); } while (0)
; #define PG8_LDA(dst, b, h) do { _Pragma("unroll") for (int m = 0; m < 4; ++m) _Pragma("unroll") for (int k = 0; k < 2; ++k) dst[m][k] = *(const PG8_LAS bf16x8*)(lds + PG8_SA(b, h) + aoff + m * 2048 + k * 1024); } while (0)
; #define PG8_LDB(dst, b, h) do { _Pragma("unroll") for (int n = 0; n < 2; ++n) _Pragma("unroll") for (int k = 0; k < 2; ++k) dst[n][k] = *(const PG8_LAS bf16x8*)(lds + PG8_SB(b, h) + boff + n * 2048 + k * 1024); } while (0)
; #define PG8_MMA(ai, bj, At, Bt) do { __builtin_amdgcn_s_setprio(1); _Pragma("unroll") for (int m = 0; m < 4; ++m) _Pragma("unroll") for (int n = 0; n < 2; ++n) _Pragma("unroll") for (int k = 0; k < 2; ++k) \
;         acc[ai][bj][m][n] = __builtin_amdgcn_mfma_f32_16x16x32_bf16(Bt[n][k], At[m][k], acc[ai][bj][m][n], 0, 0, 0); __builtin_amdgcn_s_setprio(0); } while (0)
; #define PG8_WAIT_V(n) asm volatile("s_waitcnt vmcnt(" #n ")" ::: "memory")
; #define PG8_WAIT_L(n) asm volatile("s_waitcnt lgkmcnt(" #n ")" ::: "memory")
; #define PG8_BAR __builtin_amdgcn_s_barrier()
; #define PG8_SCHED __builtin_amdgcn_sched_barrier(0)
; template <class Epi, class Sched, bool ALIGN_EPI = false, bool SP2 = false>
; __device__ __forceinline__ void gemm_phase(PG8_LAS unsigned char* lds, const Gemm g, const Sched& S, const Epi& E) {
;     ...
;             PG8_WAIT_V(8); PG8_WAIT_L(0); PG8_BAR; PG8_MMA(1, 0, At, B0); PG8_MMA(1, 1, At, B1); PG8_BAR; PG8_SCHED;
;             PG8_LDB(B0, 1, 0); PG8_LDB(B1, 1, 1); PG8_SCHED; PG8_LDA(At, 1, 0); PG8_STAGE(PG8_SA(0, 1), a2 + hstep, voffA);
;             PG8_WAIT_V(8); PG8_WAIT_L(0); PG8_BAR; PG8_MMA(0, 0, At, B0); PG8_MMA(0, 1, At, B1); PG8_BAR; PG8_SCHED;
	v_mfma_f32_16x16x32_bf16 v[60:63], v[162:165], v[210:213], v[60:63]
	v_mfma_f32_16x16x32_bf16 v[52:55], v[186:189], v[210:213], v[52:55]
	v_mfma_f32_16x16x32_bf16 v[44:47], v[162:165], v[220:223], v[44:47]
	v_mfma_f32_16x16x32_bf16 v[36:39], v[186:189], v[220:223], v[36:39]
	s_mov_b32 m0, s46
	v_lshl_add_u64 v[252:253], v[172:173], 0, v[140:141]
	v_mfma_f32_16x16x32_bf16 v[28:31], v[162:165], v[228:231], v[28:31]
	global_load_lds_dwordx4 v[252:253], off
	v_mfma_f32_16x16x32_bf16 v[20:23], v[186:189], v[228:231], v[20:23]
	v_mfma_f32_16x16x32_bf16 v[12:15], v[162:165], v[236:239], v[12:15]
	v_mfma_f32_16x16x32_bf16 v[4:7], v[186:189], v[236:239], v[4:7]
	v_mfma_f32_16x16x32_bf16 v[60:63], v[182:185], v[216:219], v[60:63]
	v_mfma_f32_16x16x32_bf16 v[52:55], v[190:193], v[216:219], v[52:55]
	s_mov_b32 m0, s47
	v_lshl_add_u64 v[214:215], v[172:173], 0, v[136:137]
	v_mfma_f32_16x16x32_bf16 v[44:47], v[182:185], v[224:227], v[44:47]
	global_load_lds_dwordx4 v[214:215], off
	v_mfma_f32_16x16x32_bf16 v[36:39], v[190:193], v[224:227], v[36:39]
	v_mfma_f32_16x16x32_bf16 v[28:31], v[182:185], v[232:235], v[28:31]
	v_mfma_f32_16x16x32_bf16 v[20:23], v[190:193], v[232:235], v[20:23]
	v_mfma_f32_16x16x32_bf16 v[12:15], v[182:185], v[240:243], v[12:15]
	v_mfma_f32_16x16x32_bf16 v[4:7], v[190:193], v[240:243], v[4:7]
	v_mfma_f32_16x16x32_bf16 v[56:59], v[194:197], v[210:213], v[56:59]
	v_mfma_f32_16x16x32_bf16 v[48:51], v[202:205], v[210:213], v[48:51]
	v_mfma_f32_16x16x32_bf16 v[40:43], v[194:197], v[220:223], v[40:43]
	v_mfma_f32_16x16x32_bf16 v[32:35], v[202:205], v[220:223], v[32:35]
	v_mfma_f32_16x16x32_bf16 v[24:27], v[194:197], v[228:231], v[24:27]
	v_mfma_f32_16x16x32_bf16 v[16:19], v[202:205], v[228:231], v[16:19]
	v_mfma_f32_16x16x32_bf16 v[8:11], v[194:197], v[236:239], v[8:11]
	v_mfma_f32_16x16x32_bf16 v[0:3], v[202:205], v[236:239], v[0:3]
	v_mfma_f32_16x16x32_bf16 v[56:59], v[198:201], v[216:219], v[56:59]
	v_mfma_f32_16x16x32_bf16 v[48:51], v[206:209], v[216:219], v[48:51]
	v_mfma_f32_16x16x32_bf16 v[40:43], v[198:201], v[224:227], v[40:43]
	v_mfma_f32_16x16x32_bf16 v[32:35], v[206:209], v[224:227], v[32:35]
	v_mfma_f32_16x16x32_bf16 v[24:27], v[198:201], v[232:235], v[24:27]
	v_mfma_f32_16x16x32_bf16 v[16:19], v[206:209], v[232:235], v[16:19]
	v_mfma_f32_16x16x32_bf16 v[8:11], v[198:201], v[240:243], v[8:11]
	v_mfma_f32_16x16x32_bf16 v[0:3], v[206:209], v[240:243], v[0:3]
	s_setprio 0
	s_barrier
	s_add_i32 s11, 0, 0x18000
	v_add_u32_e32 v166, s11, v169
	s_add_i32 s13, 0, 0x1c000
	ds_read_b128 v[162:165], v166
	ds_read_b128 v[182:185], v166 offset:1024
	ds_read_b128 v[186:189], v166 offset:2048
	ds_read_b128 v[190:193], v166 offset:3072
	v_add_u32_e32 v166, s13, v169
	ds_read_b128 v[194:197], v166
	ds_read_b128 v[198:201], v166 offset:1024
	ds_read_b128 v[202:205], v166 offset:2048
	ds_read_b128 v[206:209], v166 offset:3072
	v_lshl_add_u64 v[172:173], v[172:173], 0, s[14:15]
	s_mov_b32 m0, s48
	v_lshl_add_u64 v[170:171], v[172:173], 0, v[140:141]
	ds_read_b128 v[210:213], v179 offset:32768
	ds_read_b128 v[216:219], v179 offset:33792
	ds_read_b128 v[220:223], v179 offset:34816
	ds_read_b128 v[224:227], v179 offset:35840
	ds_read_b128 v[228:231], v179 offset:36864
	ds_read_b128 v[232:235], v179 offset:37888
	ds_read_b128 v[236:239], v179 offset:38912
	ds_read_b128 v[240:243], v179 offset:39936
	global_load_lds_dwordx4 v[170:171], off
	s_mov_b32 m0, s49
	v_lshl_add_u64 v[170:171], v[172:173], 0, v[136:137]
	global_load_lds_dwordx4 v[170:171], off
	s_waitcnt vmcnt(8) lgkmcnt(0)
	s_setprio 1
	s_barrier
; #define PG8_STAGE(bufoff, gbase, voff) do { _Pragma("unroll") for (int _i = 0; _i < 2; ++_i) \
;         __builtin_amdgcn_global_load_lds((const unsigned*)((const char*)(gbase) + (voff)[_i]), (PG8_LAS unsigned*)(lds + (bufoff) + ldsw + _i * 8192), 16, 0, 0); } while (0)
; #define PG8_LDA(dst, b, h) do { _Pragma("unroll") for (int m = 0; m < 4; ++m) _Pragma("unroll") for (int k = 0; k < 2; ++k) dst[m][k] = *(const PG8_LAS bf16x8*)(lds + PG8_SA(b, h) + aoff + m * 2048 + k * 1024); } while (0)
; #define PG8_MMA(ai, bj, At, Bt) do { __builtin_amdgcn_s_setprio(1); _Pragma("unroll") for (int m = 0; m < 4; ++m) _Pragma("unroll") for (int n = 0; n < 2; ++n) _Pragma("unroll") for (int k = 0; k < 2; ++k) \
;         acc[ai][bj][m][n] = __builtin_amdgcn_mfma_f32_16x16x32_bf16(Bt[n][k], At[m][k], acc[ai][bj][m][n], 0, 0, 0); __builtin_amdgcn_s_setprio(0); } while (0)
; #define PG8_WAIT_V(n) asm volatile("s_waitcnt vmcnt(" #n ")" ::: "memory")
; #define PG8_WAIT_L(n) asm volatile("s_waitcnt lgkmcnt(" #n ")" ::: "memory")
; #define PG8_BAR __builtin_amdgcn_s_barrier()
; #define PG8_SCHED __builtin_amdgcn_sched_barrier(0)
; template <class Epi, class Sched, bool ALIGN_EPI = false, bool SP2 = false>
; __device__ __forceinline__ void gemm_phase(PG8_LAS unsigned char* lds, const Gemm g, const Sched& S, const Epi& E) {
;     ...
;             PG8_WAIT_V(8); PG8_WAIT_L(0); PG8_BAR; PG8_MMA(0, 0, At, B0); PG8_MMA(0, 1, At, B1); PG8_BAR; PG8_SCHED;
;             PG8_LDA(At, 1, 1); PG8_STAGE(PG8_SB(1, 0), b3, voffB); PG8_STAGE(PG8_SB(1, 1), b3 + hstep, voffB); PG8_STAGE(PG8_SA(1, 0), a3, voffA);
;             PG8_WAIT_V(8); PG8_WAIT_L(0); PG8_BAR; PG8_MMA(1, 0, At, B0); PG8_MMA(1, 1, At, B1); PG8_BAR; PG8_SCHED;
	v_mfma_f32_16x16x32_bf16 v[124:127], v[162:165], v[210:213], v[124:127]
	v_mfma_f32_16x16x32_bf16 v[116:119], v[186:189], v[210:213], v[116:119]
	v_mfma_f32_16x16x32_bf16 v[108:111], v[162:165], v[220:223], v[108:111]
	v_mfma_f32_16x16x32_bf16 v[100:103], v[186:189], v[220:223], v[100:103]
	v_mfma_f32_16x16x32_bf16 v[92:95], v[162:165], v[228:231], v[92:95]
	v_mfma_f32_16x16x32_bf16 v[84:87], v[186:189], v[228:231], v[84:87]
	v_mfma_f32_16x16x32_bf16 v[76:79], v[162:165], v[236:239], v[76:79]
	v_mfma_f32_16x16x32_bf16 v[68:71], v[186:189], v[236:239], v[68:71]
	v_mfma_f32_16x16x32_bf16 v[124:127], v[182:185], v[216:219], v[124:127]
	v_mfma_f32_16x16x32_bf16 v[116:119], v[190:193], v[216:219], v[116:119]
	v_mfma_f32_16x16x32_bf16 v[108:111], v[182:185], v[224:227], v[108:111]
	v_mfma_f32_16x16x32_bf16 v[100:103], v[190:193], v[224:227], v[100:103]
	v_mfma_f32_16x16x32_bf16 v[92:95], v[182:185], v[232:235], v[92:95]
	v_mfma_f32_16x16x32_bf16 v[84:87], v[190:193], v[232:235], v[84:87]
	v_mfma_f32_16x16x32_bf16 v[76:79], v[182:185], v[240:243], v[76:79]
	v_mfma_f32_16x16x32_bf16 v[68:71], v[190:193], v[240:243], v[68:71]
	v_mfma_f32_16x16x32_bf16 v[120:123], v[194:197], v[210:213], v[120:123]
	v_mfma_f32_16x16x32_bf16 v[112:115], v[202:205], v[210:213], v[112:115]
	v_mfma_f32_16x16x32_bf16 v[104:107], v[194:197], v[220:223], v[104:107]
	v_mfma_f32_16x16x32_bf16 v[96:99], v[202:205], v[220:223], v[96:99]
	v_mfma_f32_16x16x32_bf16 v[88:91], v[194:197], v[228:231], v[88:91]
	v_mfma_f32_16x16x32_bf16 v[80:83], v[202:205], v[228:231], v[80:83]
	v_mfma_f32_16x16x32_bf16 v[72:75], v[194:197], v[236:239], v[72:75]
	v_mfma_f32_16x16x32_bf16 v[64:67], v[202:205], v[236:239], v[64:67]
	v_mfma_f32_16x16x32_bf16 v[120:123], v[198:201], v[216:219], v[120:123]
	v_mfma_f32_16x16x32_bf16 v[112:115], v[206:209], v[216:219], v[112:115]
	v_mfma_f32_16x16x32_bf16 v[104:107], v[198:201], v[224:227], v[104:107]
	v_mfma_f32_16x16x32_bf16 v[96:99], v[206:209], v[224:227], v[96:99]
	v_mfma_f32_16x16x32_bf16 v[88:91], v[198:201], v[232:235], v[88:91]
	v_mfma_f32_16x16x32_bf16 v[80:83], v[206:209], v[232:235], v[80:83]
	v_mfma_f32_16x16x32_bf16 v[72:75], v[198:201], v[240:243], v[72:75]
	v_mfma_f32_16x16x32_bf16 v[64:67], v[206:209], v[240:243], v[64:67]
	s_setprio 0
	s_barrier
	s_add_i32 s11, s11, s29
	s_add_i32 m0, s11, 0xffffff80
	ds_read_b128 v[210:213], v179 offset:49152
	ds_read_b128 v[216:219], v179 offset:50176
	ds_read_b128 v[220:223], v179 offset:51200
	ds_read_b128 v[224:227], v179 offset:52224
	ds_read_b128 v[228:231], v179 offset:53248
	ds_read_b128 v[232:235], v179 offset:54272
	global_load_lds_dwordx4 v[246:247], off offset:128
	s_add_i32 m0, s11, 0x1f80
	s_add_i32 s11, s13, s29
	global_load_lds_dwordx4 v[248:249], off offset:128
	s_add_i32 m0, s11, 0xffffff80
	ds_read_b128 v[240:243], v179 offset:56320
	global_load_lds_dwordx4 v[250:251], off offset:128
	s_add_i32 m0, s11, 0x1f80
	ds_read_b128 v[236:239], v179 offset:55296
	global_load_lds_dwordx4 v[244:245], off offset:128
	s_waitcnt vmcnt(6) lgkmcnt(0)
	s_setprio 1
	s_barrier
	v_mfma_f32_16x16x32_bf16 v[60:63], v[162:165], v[210:213], v[60:63]
	v_mfma_f32_16x16x32_bf16 v[52:55], v[186:189], v[210:213], v[52:55]
	v_mfma_f32_16x16x32_bf16 v[44:47], v[162:165], v[220:223], v[44:47]
	v_mfma_f32_16x16x32_bf16 v[36:39], v[186:189], v[220:223], v[36:39]
	s_add_i32 m0, s50, 0xffffff80
	v_mfma_f32_16x16x32_bf16 v[28:31], v[162:165], v[228:231], v[28:31]
	global_load_lds_dwordx4 v[252:253], off offset:128
	v_mfma_f32_16x16x32_bf16 v[20:23], v[186:189], v[228:231], v[20:23]
	v_mfma_f32_16x16x32_bf16 v[12:15], v[162:165], v[236:239], v[12:15]
	v_mfma_f32_16x16x32_bf16 v[4:7], v[186:189], v[236:239], v[4:7]
	v_mfma_f32_16x16x32_bf16 v[60:63], v[182:185], v[216:219], v[60:63]
	v_mfma_f32_16x16x32_bf16 v[52:55], v[190:193], v[216:219], v[52:55]
	s_add_i32 m0, s51, 0xffffff80
	v_mfma_f32_16x16x32_bf16 v[44:47], v[182:185], v[224:227], v[44:47]
	global_load_lds_dwordx4 v[214:215], off offset:128
	v_mfma_f32_16x16x32_bf16 v[36:39], v[190:193], v[224:227], v[36:39]
	v_mfma_f32_16x16x32_bf16 v[28:31], v[182:185], v[232:235], v[28:31]
	v_mfma_f32_16x16x32_bf16 v[20:23], v[190:193], v[232:235], v[20:23]
	v_mfma_f32_16x16x32_bf16 v[12:15], v[182:185], v[240:243], v[12:15]
	v_mfma_f32_16x16x32_bf16 v[4:7], v[190:193], v[240:243], v[4:7]
	v_mfma_f32_16x16x32_bf16 v[56:59], v[194:197], v[210:213], v[56:59]
	v_mfma_f32_16x16x32_bf16 v[48:51], v[202:205], v[210:213], v[48:51]
	v_mfma_f32_16x16x32_bf16 v[40:43], v[194:197], v[220:223], v[40:43]
	v_mfma_f32_16x16x32_bf16 v[32:35], v[202:205], v[220:223], v[32:35]
	v_mfma_f32_16x16x32_bf16 v[24:27], v[194:197], v[228:231], v[24:27]
	v_mfma_f32_16x16x32_bf16 v[16:19], v[202:205], v[228:231], v[16:19]
	v_mfma_f32_16x16x32_bf16 v[8:11], v[194:197], v[236:239], v[8:11]
	v_mfma_f32_16x16x32_bf16 v[0:3], v[202:205], v[236:239], v[0:3]
	v_mfma_f32_16x16x32_bf16 v[56:59], v[198:201], v[216:219], v[56:59]
	v_mfma_f32_16x16x32_bf16 v[48:51], v[206:209], v[216:219], v[48:51]
	v_mfma_f32_16x16x32_bf16 v[40:43], v[198:201], v[224:227], v[40:43]
	v_mfma_f32_16x16x32_bf16 v[32:35], v[206:209], v[224:227], v[32:35]
	v_mfma_f32_16x16x32_bf16 v[24:27], v[198:201], v[232:235], v[24:27]
	v_mfma_f32_16x16x32_bf16 v[16:19], v[206:209], v[232:235], v[16:19]
	v_mfma_f32_16x16x32_bf16 v[8:11], v[198:201], v[240:243], v[8:11]
	v_mfma_f32_16x16x32_bf16 v[0:3], v[206:209], v[240:243], v[0:3]
	s_setprio 0
	s_barrier
	v_lshl_add_u64 v[158:159], v[158:159], 0, s[26:27]
	s_cmp_ge_i32 s10, s52
	v_lshl_add_u64 v[160:161], v[160:161], 0, s[26:27]
	s_cbranch_scc0 .LBB0_304

; #define PG8_STAGE(bufoff, gbase, voff) do { _Pragma("unroll") for (int _i = 0; _i < 2; ++_i) \
;         __builtin_amdgcn_global_load_lds((const unsigned*)((const char*)(gbase) + (voff)[_i]), (PG8_LAS unsigned*)(lds + (bufoff) + ldsw + _i * 8192), 16, 0, 0); } while (0)
; #define PG8_LDA(dst, b, h) do { _Pragma("unroll") for (int m = 0; m < 4; ++m) _Pragma("unroll") for (int k = 0; k < 2; ++k) dst[m][k] = *(const PG8_LAS bf16x8*)(lds + PG8_SA(b, h) + aoff + m * 2048 + k * 1024); } while (0)
; #define PG8_LDB(dst, b, h) do { _Pragma("unroll") for (int n = 0; n < 2; ++n) _Pragma("unroll") for (int k = 0; k < 2; ++k) dst[n][k] = *(const PG8_LAS bf16x8*)(lds + PG8_SB(b, h) + boff + n * 2048 + k * 1024); } while (0)
; #define PG8_MMA(ai, bj, At, Bt) do { __builtin_amdgcn_s_setprio(1); _Pragma("unroll") for (int m = 0; m < 4; ++m) _Pragma("unroll") for (int n = 0; n < 2; ++n) _Pragma("unroll") for (int k = 0; k < 2; ++k) \
;         acc[ai][bj][m][n] = __builtin_amdgcn_mfma_f32_16x16x32_bf16(Bt[n][k], At[m][k], acc[ai][bj][m][n], 0, 0, 0); __builtin_amdgcn_s_setprio(0); } while (0)
; #define PG8_WAIT_V(n) asm volatile("s_waitcnt vmcnt(" #n ")" ::: "memory")
; #define PG8_BAR __builtin_amdgcn_s_barrier()
; template <class Epi, class Sched, bool ALIGN_EPI = false, bool SP2 = false>
; __device__ __forceinline__ void gemm_phase(PG8_LAS unsigned char* lds, const Gemm g, const Sched& S, const Epi& E) {
;     ...
;         for (int t = 0; t < nt; t += 2) {
;             const bool last = (t == nt - 2);
;             const char* a1 = cA + (size_t)(t + 1) * kstep;
;             const char* a2 = last ? nA : cA + (size_t)(t + 2) * kstep; const char* b2 = last ? nB : cB + (size_t)(t + 2) * kstep;
;             const char* a3 = a2 + kstep; const char* b3 = b2 + kstep;
;             if (last && has_next) S.a_ready(nxt);
;             if constexpr (SP2) {
;             PG8_LDB(B0, 0, 0); PG8_LDB(B1, 0, 1); PG8_SCHED; PG8_LDA(At, 0, 0); PG8_STAGE(PG8_SA(1, 1), a1 + hstep, voffA);
;             PG8_WAIT_V(8); PG8_WAIT_L(0); PG8_BAR; PG8_MMA(0, 0, At, B0); PG8_MMA(0, 1, At, B1); PG8_BAR; PG8_SCHED;
;             PG8_LDA(At, 0, 1); PG8_STAGE(PG8_SB(0, 0), b2, voffB); PG8_STAGE(PG8_SB(0, 1), b2 + hstep, voffB); PG8_STAGE(PG8_SA(0, 0), a2, voffA);
;             PG8_WAIT_V(8); PG8_WAIT_L(0); PG8_BAR; PG8_MMA(1, 0, At, B0); PG8_MMA(1, 1, At, B1); PG8_BAR; PG8_SCHED;
.LBB0_371:
	v_add_u32_e32 v148, s54, v201
	v_add_u32_e32 v190, s55, v201
	ds_read_b128 v[136:139], v148
	ds_read_b128 v[140:143], v148 offset:1024
	ds_read_b128 v[144:147], v148 offset:2048
	ds_read_b128 v[148:151], v148 offset:3072
	ds_read_b128 v[152:155], v190
	ds_read_b128 v[182:185], v190 offset:1024
	ds_read_b128 v[186:189], v190 offset:2048
	ds_read_b128 v[190:193], v190 offset:3072
	s_cmp_eq_u32 s48, s12
	v_lshl_add_u64 v[194:195], v[134:135], 0, s[22:23]
	s_cselect_b64 vcc, -1, 0
	s_add_i32 s12, s12, 2
	v_cndmask_b32_e32 v199, v195, v179, vcc
	v_cndmask_b32_e32 v198, v194, v178, vcc
	v_cndmask_b32_e32 v215, v133, v181, vcc
	v_cndmask_b32_e32 v214, v132, v180, vcc
	s_mov_b32 m0, s56
	v_lshl_add_u64 v[236:237], v[134:135], 0, v[174:175]
	ds_read_b128 v[194:197], v203
	ds_read_b128 v[206:209], v203 offset:1024
	ds_read_b128 v[210:213], v203 offset:2048
	ds_read_b128 v[216:219], v203 offset:3072
	ds_read_b128 v[220:223], v203 offset:4096
	ds_read_b128 v[224:227], v203 offset:5120
	ds_read_b128 v[228:231], v203 offset:6144
	ds_read_b128 v[232:235], v203 offset:7168
	global_load_lds_dwordx4 v[236:237], off
	s_mov_b32 m0, s57
	v_lshl_add_u64 v[236:237], v[134:135], 0, v[172:173]
	global_load_lds_dwordx4 v[236:237], off
	s_waitcnt vmcnt(8) lgkmcnt(0)
	s_setprio 1
	s_barrier
	v_mfma_f32_16x16x32_bf16 v[124:127], v[136:139], v[194:197], v[124:127]
	v_mfma_f32_16x16x32_bf16 v[128:131], v[144:147], v[194:197], v[128:131]
	v_mfma_f32_16x16x32_bf16 v[112:115], v[136:139], v[210:213], v[112:115]
	v_mfma_f32_16x16x32_bf16 v[108:111], v[144:147], v[210:213], v[108:111]
	v_mfma_f32_16x16x32_bf16 v[96:99], v[136:139], v[220:223], v[96:99]
	v_mfma_f32_16x16x32_bf16 v[92:95], v[144:147], v[220:223], v[92:95]
	v_mfma_f32_16x16x32_bf16 v[80:83], v[136:139], v[228:231], v[80:83]
	v_mfma_f32_16x16x32_bf16 v[76:79], v[144:147], v[228:231], v[76:79]
	v_mfma_f32_16x16x32_bf16 v[124:127], v[140:143], v[206:209], v[124:127]
	v_mfma_f32_16x16x32_bf16 v[128:131], v[148:151], v[206:209], v[128:131]
	v_mfma_f32_16x16x32_bf16 v[112:115], v[140:143], v[216:219], v[112:115]
	v_mfma_f32_16x16x32_bf16 v[108:111], v[148:151], v[216:219], v[108:111]
	v_mfma_f32_16x16x32_bf16 v[96:99], v[140:143], v[224:227], v[96:99]
	v_mfma_f32_16x16x32_bf16 v[92:95], v[148:151], v[224:227], v[92:95]
	v_mfma_f32_16x16x32_bf16 v[80:83], v[140:143], v[232:235], v[80:83]
	v_mfma_f32_16x16x32_bf16 v[76:79], v[148:151], v[232:235], v[76:79]
	v_mfma_f32_16x16x32_bf16 v[120:123], v[152:155], v[194:197], v[120:123]
	v_mfma_f32_16x16x32_bf16 v[116:119], v[186:189], v[194:197], v[116:119]
	v_mfma_f32_16x16x32_bf16 v[104:107], v[152:155], v[210:213], v[104:107]
	v_mfma_f32_16x16x32_bf16 v[100:103], v[186:189], v[210:213], v[100:103]
	v_mfma_f32_16x16x32_bf16 v[88:91], v[152:155], v[220:223], v[88:91]
	v_mfma_f32_16x16x32_bf16 v[84:87], v[186:189], v[220:223], v[84:87]
	v_mfma_f32_16x16x32_bf16 v[72:75], v[152:155], v[228:231], v[72:75]
	v_mfma_f32_16x16x32_bf16 v[68:71], v[186:189], v[228:231], v[68:71]
	v_mfma_f32_16x16x32_bf16 v[120:123], v[182:185], v[206:209], v[120:123]
	v_mfma_f32_16x16x32_bf16 v[116:119], v[190:193], v[206:209], v[116:119]
	v_mfma_f32_16x16x32_bf16 v[104:107], v[182:185], v[216:219], v[104:107]
	v_mfma_f32_16x16x32_bf16 v[100:103], v[190:193], v[216:219], v[100:103]
	v_mfma_f32_16x16x32_bf16 v[88:91], v[182:185], v[224:227], v[88:91]
	v_mfma_f32_16x16x32_bf16 v[84:87], v[190:193], v[224:227], v[84:87]
	v_mfma_f32_16x16x32_bf16 v[72:75], v[182:185], v[232:235], v[72:75]
	v_mfma_f32_16x16x32_bf16 v[68:71], v[190:193], v[232:235], v[68:71]
	s_setprio 0
	s_barrier
	s_mov_b32 m0, s58
	v_lshl_add_u64 v[236:237], v[214:215], 0, v[166:167]
	ds_read_b128 v[194:197], v203 offset:16384
	ds_read_b128 v[206:209], v203 offset:17408
	ds_read_b128 v[210:213], v203 offset:18432
	ds_read_b128 v[216:219], v203 offset:19456
	ds_read_b128 v[220:223], v203 offset:20480
	ds_read_b128 v[224:227], v203 offset:21504
	ds_read_b128 v[228:231], v203 offset:22528
	global_load_lds_dwordx4 v[236:237], off
	v_lshl_add_u64 v[238:239], v[214:215], 0, v[170:171]
	s_mov_b32 m0, s59
	v_lshl_add_u64 v[214:215], v[214:215], 0, s[14:15]
	s_add_i32 s13, s55, s30
	global_load_lds_dwordx4 v[238:239], off
	v_lshl_add_u64 v[240:241], v[214:215], 0, v[166:167]
	s_mov_b32 m0, s13
	v_lshl_add_u64 v[214:215], v[214:215], 0, v[170:171]
	global_load_lds_dwordx4 v[240:241], off
	s_add_i32 m0, s13, 0x2000
	ds_read_b128 v[232:235], v203 offset:23552
	global_load_lds_dwordx4 v[214:215], off
	s_waitcnt vmcnt(6) lgkmcnt(0)
	s_setprio 1
	s_barrier
; #define PG8_STAGE(bufoff, gbase, voff) do { _Pragma("unroll") for (int _i = 0; _i < 2; ++_i) \
;         __builtin_amdgcn_global_load_lds((const unsigned*)((const char*)(gbase) + (voff)[_i]), (PG8_LAS unsigned*)(lds + (bufoff) + ldsw + _i * 8192), 16, 0, 0); } while (0)
; #define PG8_LDA(dst, b, h) do { _Pragma("unroll") for (int m = 0; m < 4; ++m) _Pragma("unroll") for (int k = 0; k < 2; ++k) dst[m][k] = *(const PG8_LAS bf16x8*)(lds + PG8_SA(b, h) + aoff + m * 2048 + k * 1024); } while (0)
; #define PG8_LDB(dst, b, h) do { _Pragma("unroll") for (int n = 0; n < 2; ++n) _Pragma("unroll") for (int k = 0; k < 2; ++k) dst[n][k] = *(const PG8_LAS bf16x8*)(lds + PG8_SB(b, h) + boff + n * 2048 + k * 1024); } while (0)
; #define PG8_MMA(ai, bj, At, Bt) do { __builtin_amdgcn_s_setprio(1); _Pragma("unroll") for (int m = 0; m < 4; ++m) _Pragma("unroll") for (int n = 0; n < 2; ++n) _Pragma("unroll") for (int k = 0; k < 2; ++k) \
;         acc[ai][bj][m][n] = __builtin_amdgcn_mfma_f32_16x16x32_bf16(Bt[n][k], At[m][k], acc[ai][bj][m][n], 0, 0, 0); __builtin_amdgcn_s_setprio(0); } while (0)
; #define PG8_WAIT_V(n) asm volatile("s_waitcnt vmcnt(" #n ")" ::: "memory")
; #define PG8_WAIT_L(n) asm volatile("s_waitcnt lgkmcnt(" #n ")" ::: "memory")
; #define PG8_BAR __builtin_amdgcn_s_barrier()
; #define PG8_SCHED __builtin_amdgcn_sched_barrier(0)
; template <class Epi, class Sched, bool ALIGN_EPI = false, bool SP2 = false>
; __device__ __forceinline__ void gemm_phase(PG8_LAS unsigned char* lds, const Gemm g, const Sched& S, const Epi& E) {
;     ...
;             PG8_WAIT_V(8); PG8_WAIT_L(0); PG8_BAR; PG8_MMA(1, 0, At, B0); PG8_MMA(1, 1, At, B1); PG8_BAR; PG8_SCHED;
;             PG8_LDB(B0, 1, 0); PG8_LDB(B1, 1, 1); PG8_SCHED; PG8_LDA(At, 1, 0); PG8_STAGE(PG8_SA(0, 1), a2 + hstep, voffA);
;             PG8_WAIT_V(8); PG8_WAIT_L(0); PG8_BAR; PG8_MMA(0, 0, At, B0); PG8_MMA(0, 1, At, B1); PG8_BAR; PG8_SCHED;
	v_mfma_f32_16x16x32_bf16 v[64:67], v[136:139], v[194:197], v[64:67]
	v_mfma_f32_16x16x32_bf16 v[60:63], v[144:147], v[194:197], v[60:63]
	v_mfma_f32_16x16x32_bf16 v[48:51], v[136:139], v[210:213], v[48:51]
	v_mfma_f32_16x16x32_bf16 v[44:47], v[144:147], v[210:213], v[44:47]
	s_mov_b32 m0, s31
	v_lshl_add_u64 v[242:243], v[198:199], 0, v[164:165]
	v_mfma_f32_16x16x32_bf16 v[32:35], v[136:139], v[220:223], v[32:35]
	global_load_lds_dwordx4 v[242:243], off
	v_mfma_f32_16x16x32_bf16 v[28:31], v[144:147], v[220:223], v[28:31]
	v_mfma_f32_16x16x32_bf16 v[16:19], v[136:139], v[228:231], v[16:19]
	v_mfma_f32_16x16x32_bf16 v[12:15], v[144:147], v[228:231], v[12:15]
	v_mfma_f32_16x16x32_bf16 v[64:67], v[140:143], v[206:209], v[64:67]
	v_mfma_f32_16x16x32_bf16 v[60:63], v[148:151], v[206:209], v[60:63]
	s_mov_b32 m0, s34
	v_lshl_add_u64 v[244:245], v[198:199], 0, v[168:169]
	v_mfma_f32_16x16x32_bf16 v[48:51], v[140:143], v[216:219], v[48:51]
	global_load_lds_dwordx4 v[244:245], off
	v_mfma_f32_16x16x32_bf16 v[44:47], v[148:151], v[216:219], v[44:47]
	v_mfma_f32_16x16x32_bf16 v[32:35], v[140:143], v[224:227], v[32:35]
	v_mfma_f32_16x16x32_bf16 v[28:31], v[148:151], v[224:227], v[28:31]
	v_mfma_f32_16x16x32_bf16 v[16:19], v[140:143], v[232:235], v[16:19]
	v_mfma_f32_16x16x32_bf16 v[12:15], v[148:151], v[232:235], v[12:15]
	v_mfma_f32_16x16x32_bf16 v[56:59], v[152:155], v[194:197], v[56:59]
	v_mfma_f32_16x16x32_bf16 v[52:55], v[186:189], v[194:197], v[52:55]
	v_mfma_f32_16x16x32_bf16 v[40:43], v[152:155], v[210:213], v[40:43]
	v_mfma_f32_16x16x32_bf16 v[36:39], v[186:189], v[210:213], v[36:39]
	v_mfma_f32_16x16x32_bf16 v[24:27], v[152:155], v[220:223], v[24:27]
	v_mfma_f32_16x16x32_bf16 v[20:23], v[186:189], v[220:223], v[20:23]
	v_mfma_f32_16x16x32_bf16 v[8:11], v[152:155], v[228:231], v[8:11]
	v_mfma_f32_16x16x32_bf16 v[4:7], v[186:189], v[228:231], v[4:7]
	v_mfma_f32_16x16x32_bf16 v[56:59], v[182:185], v[206:209], v[56:59]
	v_mfma_f32_16x16x32_bf16 v[52:55], v[190:193], v[206:209], v[52:55]
	v_mfma_f32_16x16x32_bf16 v[40:43], v[182:185], v[216:219], v[40:43]
	v_mfma_f32_16x16x32_bf16 v[36:39], v[190:193], v[216:219], v[36:39]
	v_mfma_f32_16x16x32_bf16 v[24:27], v[182:185], v[224:227], v[24:27]
	v_mfma_f32_16x16x32_bf16 v[20:23], v[190:193], v[224:227], v[20:23]
	v_mfma_f32_16x16x32_bf16 v[8:11], v[182:185], v[232:235], v[8:11]
	v_mfma_f32_16x16x32_bf16 v[4:7], v[190:193], v[232:235], v[4:7]
	s_setprio 0
	s_barrier
	s_add_i32 s13, 0, 0x18000
	s_add_i32 s29, 0, 0x1c000
	v_add_u32_e32 v148, s13, v201
	v_add_u32_e32 v190, s29, v201
	ds_read_b128 v[136:139], v148
	ds_read_b128 v[140:143], v148 offset:1024
	ds_read_b128 v[144:147], v148 offset:2048
	ds_read_b128 v[148:151], v148 offset:3072
	ds_read_b128 v[152:155], v190
	ds_read_b128 v[182:185], v190 offset:1024
	ds_read_b128 v[186:189], v190 offset:2048
	ds_read_b128 v[190:193], v190 offset:3072
	v_lshl_add_u64 v[198:199], v[198:199], 0, s[14:15]
	s_mov_b32 m0, s35
	v_lshl_add_u64 v[246:247], v[198:199], 0, v[164:165]
	ds_read_b128 v[194:197], v203 offset:32768
	ds_read_b128 v[206:209], v203 offset:33792
	ds_read_b128 v[210:213], v203 offset:34816
	ds_read_b128 v[216:219], v203 offset:35840
	ds_read_b128 v[220:223], v203 offset:36864
	ds_read_b128 v[224:227], v203 offset:37888
	ds_read_b128 v[228:231], v203 offset:38912
	ds_read_b128 v[232:235], v203 offset:39936
	global_load_lds_dwordx4 v[246:247], off
	s_mov_b32 m0, s36
	v_lshl_add_u64 v[198:199], v[198:199], 0, v[168:169]
	global_load_lds_dwordx4 v[198:199], off
	s_waitcnt vmcnt(8) lgkmcnt(0)
	s_setprio 1
	s_barrier
; #define PG8_STAGE(bufoff, gbase, voff) do { _Pragma("unroll") for (int _i = 0; _i < 2; ++_i) \
;         __builtin_amdgcn_global_load_lds((const unsigned*)((const char*)(gbase) + (voff)[_i]), (PG8_LAS unsigned*)(lds + (bufoff) + ldsw + _i * 8192), 16, 0, 0); } while (0)
; #define PG8_LDA(dst, b, h) do { _Pragma("unroll") for (int m = 0; m < 4; ++m) _Pragma("unroll") for (int k = 0; k < 2; ++k) dst[m][k] = *(const PG8_LAS bf16x8*)(lds + PG8_SA(b, h) + aoff + m * 2048 + k * 1024); } while (0)
; #define PG8_MMA(ai, bj, At, Bt) do { __builtin_amdgcn_s_setprio(1); _Pragma("unroll") for (int m = 0; m < 4; ++m) _Pragma("unroll") for (int n = 0; n < 2; ++n) _Pragma("unroll") for (int k = 0; k < 2; ++k) \
;         acc[ai][bj][m][n] = __builtin_amdgcn_mfma_f32_16x16x32_bf16(Bt[n][k], At[m][k], acc[ai][bj][m][n], 0, 0, 0); __builtin_amdgcn_s_setprio(0); } while (0)
; #define PG8_WAIT_V(n) asm volatile("s_waitcnt vmcnt(" #n ")" ::: "memory")
; #define PG8_WAIT_L(n) asm volatile("s_waitcnt lgkmcnt(" #n ")" ::: "memory")
; #define PG8_BAR __builtin_amdgcn_s_barrier()
; #define PG8_SCHED __builtin_amdgcn_sched_barrier(0)
; template <class Epi, class Sched, bool ALIGN_EPI = false, bool SP2 = false>
; __device__ __forceinline__ void gemm_phase(PG8_LAS unsigned char* lds, const Gemm g, const Sched& S, const Epi& E) {
;     ...
;             PG8_WAIT_V(8); PG8_WAIT_L(0); PG8_BAR; PG8_MMA(0, 0, At, B0); PG8_MMA(0, 1, At, B1); PG8_BAR; PG8_SCHED;
;             PG8_LDA(At, 1, 1); PG8_STAGE(PG8_SB(1, 0), b3, voffB); PG8_STAGE(PG8_SB(1, 1), b3 + hstep, voffB); PG8_STAGE(PG8_SA(1, 0), a3, voffA);
;             PG8_WAIT_V(8); PG8_WAIT_L(0); PG8_BAR; PG8_MMA(1, 0, At, B0); PG8_MMA(1, 1, At, B1); PG8_BAR; PG8_SCHED;
	v_mfma_f32_16x16x32_bf16 v[124:127], v[136:139], v[194:197], v[124:127]
	v_mfma_f32_16x16x32_bf16 v[128:131], v[144:147], v[194:197], v[128:131]
	v_mfma_f32_16x16x32_bf16 v[112:115], v[136:139], v[210:213], v[112:115]
	v_mfma_f32_16x16x32_bf16 v[108:111], v[144:147], v[210:213], v[108:111]
	v_mfma_f32_16x16x32_bf16 v[96:99], v[136:139], v[220:223], v[96:99]
	v_mfma_f32_16x16x32_bf16 v[92:95], v[144:147], v[220:223], v[92:95]
	v_mfma_f32_16x16x32_bf16 v[80:83], v[136:139], v[228:231], v[80:83]
	v_mfma_f32_16x16x32_bf16 v[76:79], v[144:147], v[228:231], v[76:79]
	v_mfma_f32_16x16x32_bf16 v[124:127], v[140:143], v[206:209], v[124:127]
	v_mfma_f32_16x16x32_bf16 v[128:131], v[148:151], v[206:209], v[128:131]
	v_mfma_f32_16x16x32_bf16 v[112:115], v[140:143], v[216:219], v[112:115]
	v_mfma_f32_16x16x32_bf16 v[108:111], v[148:151], v[216:219], v[108:111]
	v_mfma_f32_16x16x32_bf16 v[96:99], v[140:143], v[224:227], v[96:99]
	v_mfma_f32_16x16x32_bf16 v[92:95], v[148:151], v[224:227], v[92:95]
	v_mfma_f32_16x16x32_bf16 v[80:83], v[140:143], v[232:235], v[80:83]
	v_mfma_f32_16x16x32_bf16 v[76:79], v[148:151], v[232:235], v[76:79]
	v_mfma_f32_16x16x32_bf16 v[120:123], v[152:155], v[194:197], v[120:123]
	v_mfma_f32_16x16x32_bf16 v[116:119], v[186:189], v[194:197], v[116:119]
	v_mfma_f32_16x16x32_bf16 v[104:107], v[152:155], v[210:213], v[104:107]
	v_mfma_f32_16x16x32_bf16 v[100:103], v[186:189], v[210:213], v[100:103]
	v_mfma_f32_16x16x32_bf16 v[88:91], v[152:155], v[220:223], v[88:91]
	v_mfma_f32_16x16x32_bf16 v[84:87], v[186:189], v[220:223], v[84:87]
	v_mfma_f32_16x16x32_bf16 v[72:75], v[152:155], v[228:231], v[72:75]
	v_mfma_f32_16x16x32_bf16 v[68:71], v[186:189], v[228:231], v[68:71]
	v_mfma_f32_16x16x32_bf16 v[120:123], v[182:185], v[206:209], v[120:123]
	v_mfma_f32_16x16x32_bf16 v[116:119], v[190:193], v[206:209], v[116:119]
	v_mfma_f32_16x16x32_bf16 v[104:107], v[182:185], v[216:219], v[104:107]
	v_mfma_f32_16x16x32_bf16 v[100:103], v[190:193], v[216:219], v[100:103]
	v_mfma_f32_16x16x32_bf16 v[88:91], v[182:185], v[224:227], v[88:91]
	v_mfma_f32_16x16x32_bf16 v[84:87], v[190:193], v[224:227], v[84:87]
	v_mfma_f32_16x16x32_bf16 v[72:75], v[182:185], v[232:235], v[72:75]
	v_mfma_f32_16x16x32_bf16 v[68:71], v[190:193], v[232:235], v[68:71]
	s_setprio 0
	s_barrier
	s_add_i32 s13, s13, s30
	s_add_i32 m0, s13, 0xffffff80
	ds_read_b128 v[194:197], v203 offset:49152
	ds_read_b128 v[206:209], v203 offset:50176
	ds_read_b128 v[210:213], v203 offset:51200
	ds_read_b128 v[216:219], v203 offset:52224
	ds_read_b128 v[220:223], v203 offset:53248
	ds_read_b128 v[224:227], v203 offset:54272
	global_load_lds_dwordx4 v[236:237], off offset:128
	s_add_i32 m0, s13, 0x1f80
	s_add_i32 s13, s29, s30
	global_load_lds_dwordx4 v[238:239], off offset:128
	s_add_i32 m0, s13, 0xffffff80
	ds_read_b128 v[232:235], v203 offset:56320
	global_load_lds_dwordx4 v[240:241], off offset:128
	s_add_i32 m0, s13, 0x1f80
	ds_read_b128 v[228:231], v203 offset:55296
	global_load_lds_dwordx4 v[214:215], off offset:128
	s_waitcnt vmcnt(6) lgkmcnt(0)
	s_setprio 1
	s_barrier
	v_mfma_f32_16x16x32_bf16 v[64:67], v[136:139], v[194:197], v[64:67]
	v_mfma_f32_16x16x32_bf16 v[60:63], v[144:147], v[194:197], v[60:63]
	v_mfma_f32_16x16x32_bf16 v[48:51], v[136:139], v[210:213], v[48:51]
	v_mfma_f32_16x16x32_bf16 v[44:47], v[144:147], v[210:213], v[44:47]
	s_add_i32 m0, s37, 0xffffff80
	v_mfma_f32_16x16x32_bf16 v[32:35], v[136:139], v[220:223], v[32:35]
	global_load_lds_dwordx4 v[242:243], off offset:128
	v_mfma_f32_16x16x32_bf16 v[28:31], v[144:147], v[220:223], v[28:31]
	v_mfma_f32_16x16x32_bf16 v[16:19], v[136:139], v[228:231], v[16:19]
	v_mfma_f32_16x16x32_bf16 v[12:15], v[144:147], v[228:231], v[12:15]
	v_mfma_f32_16x16x32_bf16 v[64:67], v[140:143], v[206:209], v[64:67]
	v_mfma_f32_16x16x32_bf16 v[60:63], v[148:151], v[206:209], v[60:63]
	s_add_i32 m0, s41, 0xffffff80
	v_mfma_f32_16x16x32_bf16 v[48:51], v[140:143], v[216:219], v[48:51]
	global_load_lds_dwordx4 v[244:245], off offset:128
	v_mfma_f32_16x16x32_bf16 v[44:47], v[148:151], v[216:219], v[44:47]
	v_mfma_f32_16x16x32_bf16 v[32:35], v[140:143], v[224:227], v[32:35]
	v_mfma_f32_16x16x32_bf16 v[28:31], v[148:151], v[224:227], v[28:31]
	v_mfma_f32_16x16x32_bf16 v[16:19], v[140:143], v[232:235], v[16:19]
	v_mfma_f32_16x16x32_bf16 v[12:15], v[148:151], v[232:235], v[12:15]
	v_mfma_f32_16x16x32_bf16 v[56:59], v[152:155], v[194:197], v[56:59]
	v_mfma_f32_16x16x32_bf16 v[52:55], v[186:189], v[194:197], v[52:55]
	v_mfma_f32_16x16x32_bf16 v[40:43], v[152:155], v[210:213], v[40:43]
	v_mfma_f32_16x16x32_bf16 v[36:39], v[186:189], v[210:213], v[36:39]
	v_mfma_f32_16x16x32_bf16 v[24:27], v[152:155], v[220:223], v[24:27]
	v_mfma_f32_16x16x32_bf16 v[20:23], v[186:189], v[220:223], v[20:23]
	v_mfma_f32_16x16x32_bf16 v[8:11], v[152:155], v[228:231], v[8:11]
	v_mfma_f32_16x16x32_bf16 v[4:7], v[186:189], v[228:231], v[4:7]
	v_mfma_f32_16x16x32_bf16 v[56:59], v[182:185], v[206:209], v[56:59]
	v_mfma_f32_16x16x32_bf16 v[52:55], v[190:193], v[206:209], v[52:55]
	v_mfma_f32_16x16x32_bf16 v[40:43], v[182:185], v[216:219], v[40:43]
	v_mfma_f32_16x16x32_bf16 v[36:39], v[190:193], v[216:219], v[36:39]
	v_mfma_f32_16x16x32_bf16 v[24:27], v[182:185], v[224:227], v[24:27]
	v_mfma_f32_16x16x32_bf16 v[20:23], v[190:193], v[224:227], v[20:23]
	v_mfma_f32_16x16x32_bf16 v[8:11], v[182:185], v[232:235], v[8:11]
	v_mfma_f32_16x16x32_bf16 v[4:7], v[190:193], v[232:235], v[4:7]
	s_setprio 0
	s_barrier
	v_lshl_add_u64 v[132:133], v[132:133], 0, s[26:27]
	s_cmp_ge_i32 s12, s47
	v_lshl_add_u64 v[134:135], v[134:135], 0, s[26:27]
	s_cbranch_scc0 .LBB0_371

; #define PG8_STAGE(bufoff, gbase, voff) do { _Pragma("unroll") for (int _i = 0; _i < 2; ++_i) \
;         __builtin_amdgcn_global_load_lds((const unsigned*)((const char*)(gbase) + (voff)[_i]), (PG8_LAS unsigned*)(lds + (bufoff) + ldsw + _i * 8192), 16, 0, 0); } while (0)
; #define PG8_LDA(dst, b, h) do { _Pragma("unroll") for (int m = 0; m < 4; ++m) _Pragma("unroll") for (int k = 0; k < 2; ++k) dst[m][k] = *(const PG8_LAS bf16x8*)(lds + PG8_SA(b, h) + aoff + m * 2048 + k * 1024); } while (0)
; #define PG8_MMA(ai, bj, At, Bt) do { __builtin_amdgcn_s_setprio(1); _Pragma("unroll") for (int m = 0; m < 4; ++m) _Pragma("unroll") for (int n = 0; n < 2; ++n) _Pragma("unroll") for (int k = 0; k < 2; ++k) \
;         acc[ai][bj][m][n] = __builtin_amdgcn_mfma_f32_16x16x32_bf16(Bt[n][k], At[m][k], acc[ai][bj][m][n], 0, 0, 0); __builtin_amdgcn_s_setprio(0); } while (0)
; #define PG8_WAIT_V(n) asm volatile("s_waitcnt vmcnt(" #n ")" ::: "memory")
; #define PG8_WAIT_L(n) asm volatile("s_waitcnt lgkmcnt(" #n ")" ::: "memory")
; #define PG8_BAR __builtin_amdgcn_s_barrier()
; #define PG8_SCHED __builtin_amdgcn_sched_barrier(0)
; template <class Epi, class Sched, bool ALIGN_EPI = false, bool SP2 = false>
; __device__ __forceinline__ void gemm_phase(PG8_LAS unsigned char* lds, const Gemm g, const Sched& S, const Epi& E) {
;     ...
;             PG8_WAIT_V(8); PG8_WAIT_L(0); PG8_BAR; PG8_MMA(0, 0, At, B0); PG8_MMA(0, 1, At, B1); PG8_BAR; PG8_SCHED;
;             PG8_LDA(At, 0, 1); PG8_STAGE(PG8_SB(0, 0), b2, voffB); PG8_STAGE(PG8_SB(0, 1), b2 + hstep, voffB); PG8_STAGE(PG8_SA(0, 0), a2, voffA);
;             PG8_WAIT_V(8); PG8_WAIT_L(0); PG8_BAR; PG8_MMA(1, 0, At, B0); PG8_MMA(1, 1, At, B1); PG8_BAR; PG8_SCHED;
.Lie_skipk0:
	s_setprio 0
	s_barrier
	s_add_i32 s13, s69, s37
	v_lshl_add_u64 v[214:215], v[212:213], 0, v[146:147]
	s_mov_b32 m0, s13
	ds_read_b128 v[200:203], v216 offset:16384
	ds_read_b128 v[204:207], v216 offset:17408
	ds_read_b128 v[218:221], v216 offset:18432
	ds_read_b128 v[222:225], v216 offset:19456
	ds_read_b128 v[226:229], v216 offset:20480
	ds_read_b128 v[230:233], v216 offset:21504
	ds_read_b128 v[234:237], v216 offset:22528
	global_load_lds_dwordx4 v[214:215], off
	v_lshl_add_u64 v[242:243], v[212:213], 0, v[150:151]
	s_add_i32 m0, s13, 0x2000
	v_lshl_add_u64 v[212:213], v[212:213], 0, s[16:17]
	s_add_i32 s13, s70, s37
	global_load_lds_dwordx4 v[242:243], off
	v_lshl_add_u64 v[244:245], v[212:213], 0, v[146:147]
	s_mov_b32 m0, s13
	v_lshl_add_u64 v[212:213], v[212:213], 0, v[150:151]
	global_load_lds_dwordx4 v[244:245], off
	s_add_i32 m0, s13, 0x2000
	ds_read_b128 v[238:241], v216 offset:23552
	global_load_lds_dwordx4 v[212:213], off
	s_waitcnt vmcnt(6) lgkmcnt(0)
	s_setprio 1
	s_barrier
	v_mfma_f32_16x16x32_bf16 v[60:63], v[132:135], v[200:203], v[60:63]
	v_mfma_f32_16x16x32_bf16 v[56:59], v[176:179], v[200:203], v[56:59]
	v_mfma_f32_16x16x32_bf16 v[44:47], v[132:135], v[218:221], v[44:47]
	v_mfma_f32_16x16x32_bf16 v[40:43], v[176:179], v[218:221], v[40:43]
	s_mov_b32 m0, s41
	v_lshl_add_u64 v[246:247], v[208:209], 0, v[144:145]
	v_mfma_f32_16x16x32_bf16 v[28:31], v[132:135], v[226:229], v[28:31]
	global_load_lds_dwordx4 v[246:247], off
	v_mfma_f32_16x16x32_bf16 v[24:27], v[176:179], v[226:229], v[24:27]
	v_mfma_f32_16x16x32_bf16 v[12:15], v[132:135], v[234:237], v[12:15]
	v_mfma_f32_16x16x32_bf16 v[8:11], v[176:179], v[234:237], v[8:11]
	v_mfma_f32_16x16x32_bf16 v[60:63], v[136:139], v[204:207], v[60:63]
	v_mfma_f32_16x16x32_bf16 v[56:59], v[180:183], v[204:207], v[56:59]
	s_mov_b32 m0, s50
	v_lshl_add_u64 v[248:249], v[208:209], 0, v[148:149]
	v_mfma_f32_16x16x32_bf16 v[44:47], v[136:139], v[222:225], v[44:47]
	global_load_lds_dwordx4 v[248:249], off
	v_mfma_f32_16x16x32_bf16 v[40:43], v[180:183], v[222:225], v[40:43]
	v_mfma_f32_16x16x32_bf16 v[28:31], v[136:139], v[230:233], v[28:31]
	v_mfma_f32_16x16x32_bf16 v[24:27], v[180:183], v[230:233], v[24:27]
	v_mfma_f32_16x16x32_bf16 v[12:15], v[136:139], v[238:241], v[12:15]
	v_mfma_f32_16x16x32_bf16 v[8:11], v[180:183], v[238:241], v[8:11]
	s_cmp_gt_u32 s75, 3
	s_cbranch_scc1 .Lie_skipk1
	v_mfma_f32_16x16x32_bf16 v[52:55], v[184:187], v[200:203], v[52:55]
	v_mfma_f32_16x16x32_bf16 v[48:51], v[192:195], v[200:203], v[48:51]
	v_mfma_f32_16x16x32_bf16 v[36:39], v[184:187], v[218:221], v[36:39]
	v_mfma_f32_16x16x32_bf16 v[32:35], v[192:195], v[218:221], v[32:35]
	v_mfma_f32_16x16x32_bf16 v[20:23], v[184:187], v[226:229], v[20:23]
	v_mfma_f32_16x16x32_bf16 v[16:19], v[192:195], v[226:229], v[16:19]
	v_mfma_f32_16x16x32_bf16 v[4:7], v[184:187], v[234:237], v[4:7]
	v_mfma_f32_16x16x32_bf16 v[0:3], v[192:195], v[234:237], v[0:3]
	v_mfma_f32_16x16x32_bf16 v[52:55], v[188:191], v[204:207], v[52:55]
	v_mfma_f32_16x16x32_bf16 v[48:51], v[196:199], v[204:207], v[48:51]
	v_mfma_f32_16x16x32_bf16 v[36:39], v[188:191], v[222:225], v[36:39]
	v_mfma_f32_16x16x32_bf16 v[32:35], v[196:199], v[222:225], v[32:35]
	v_mfma_f32_16x16x32_bf16 v[20:23], v[188:191], v[230:233], v[20:23]
	v_mfma_f32_16x16x32_bf16 v[16:19], v[196:199], v[230:233], v[16:19]
	v_mfma_f32_16x16x32_bf16 v[4:7], v[188:191], v[238:241], v[4:7]
	v_mfma_f32_16x16x32_bf16 v[0:3], v[196:199], v[238:241], v[0:3]

; #define PG8_STAGE(bufoff, gbase, voff) do { _Pragma("unroll") for (int _i = 0; _i < 2; ++_i) \
;         __builtin_amdgcn_global_load_lds((const unsigned*)((const char*)(gbase) + (voff)[_i]), (PG8_LAS unsigned*)(lds + (bufoff) + ldsw + _i * 8192), 16, 0, 0); } while (0)
; #define PG8_LDA(dst, b, h) do { _Pragma("unroll") for (int m = 0; m < 4; ++m) _Pragma("unroll") for (int k = 0; k < 2; ++k) dst[m][k] = *(const PG8_LAS bf16x8*)(lds + PG8_SA(b, h) + aoff + m * 2048 + k * 1024); } while (0)
; #define PG8_MMA(ai, bj, At, Bt) do { __builtin_amdgcn_s_setprio(1); _Pragma("unroll") for (int m = 0; m < 4; ++m) _Pragma("unroll") for (int n = 0; n < 2; ++n) _Pragma("unroll") for (int k = 0; k < 2; ++k) \
;         acc[ai][bj][m][n] = __builtin_amdgcn_mfma_f32_16x16x32_bf16(Bt[n][k], At[m][k], acc[ai][bj][m][n], 0, 0, 0); __builtin_amdgcn_s_setprio(0); } while (0)
; #define PG8_WAIT_V(n) asm volatile("s_waitcnt vmcnt(" #n ")" ::: "memory")
; #define PG8_WAIT_L(n) asm volatile("s_waitcnt lgkmcnt(" #n ")" ::: "memory")
; #define PG8_BAR __builtin_amdgcn_s_barrier()
; #define PG8_SCHED __builtin_amdgcn_sched_barrier(0)
; template <class Epi, class Sched, bool ALIGN_EPI = false, bool SP2 = false>
; __device__ __forceinline__ void gemm_phase(PG8_LAS unsigned char* lds, const Gemm g, const Sched& S, const Epi& E) {
;     ...
;             PG8_LDA(At, 1, 1); PG8_STAGE(PG8_SB(1, 0), b3, voffB); PG8_STAGE(PG8_SB(1, 1), b3 + hstep, voffB); PG8_STAGE(PG8_SA(1, 0), a3, voffA);
;             PG8_WAIT_V(8); PG8_WAIT_L(0); PG8_BAR; PG8_MMA(1, 0, At, B0); PG8_MMA(1, 1, At, B1); PG8_BAR; PG8_SCHED;
.Lie_skipk2:
	s_setprio 0
	s_barrier
	s_add_i32 s13, s13, s37
	s_add_i32 m0, s13, 0xffffff80
	ds_read_b128 v[200:203], v216 offset:49152
	ds_read_b128 v[204:207], v216 offset:50176
	ds_read_b128 v[218:221], v216 offset:51200
	ds_read_b128 v[222:225], v216 offset:52224
	ds_read_b128 v[226:229], v216 offset:53248
	ds_read_b128 v[230:233], v216 offset:54272
	global_load_lds_dwordx4 v[214:215], off offset:128
	s_add_i32 m0, s13, 0x1f80
	s_add_i32 s13, s15, s37
	global_load_lds_dwordx4 v[242:243], off offset:128
	s_add_i32 m0, s13, 0xffffff80
	ds_read_b128 v[238:241], v216 offset:56320
	global_load_lds_dwordx4 v[244:245], off offset:128
	s_add_i32 m0, s13, 0x1f80
	ds_read_b128 v[234:237], v216 offset:55296
	global_load_lds_dwordx4 v[212:213], off offset:128
	s_waitcnt vmcnt(6) lgkmcnt(0)
	s_setprio 1
	s_barrier
	v_mfma_f32_16x16x32_bf16 v[60:63], v[132:135], v[200:203], v[60:63]
	v_mfma_f32_16x16x32_bf16 v[56:59], v[176:179], v[200:203], v[56:59]
	v_mfma_f32_16x16x32_bf16 v[44:47], v[132:135], v[218:221], v[44:47]
	v_mfma_f32_16x16x32_bf16 v[40:43], v[176:179], v[218:221], v[40:43]
	s_add_i32 m0, s56, 0xffffff80
	v_mfma_f32_16x16x32_bf16 v[28:31], v[132:135], v[226:229], v[28:31]
	global_load_lds_dwordx4 v[246:247], off offset:128
	v_mfma_f32_16x16x32_bf16 v[24:27], v[176:179], v[226:229], v[24:27]
	v_mfma_f32_16x16x32_bf16 v[12:15], v[132:135], v[234:237], v[12:15]
	v_mfma_f32_16x16x32_bf16 v[8:11], v[176:179], v[234:237], v[8:11]
	v_mfma_f32_16x16x32_bf16 v[60:63], v[136:139], v[204:207], v[60:63]
	v_mfma_f32_16x16x32_bf16 v[56:59], v[180:183], v[204:207], v[56:59]
	s_add_i32 m0, s57, 0xffffff80
	v_mfma_f32_16x16x32_bf16 v[44:47], v[136:139], v[222:225], v[44:47]
	global_load_lds_dwordx4 v[248:249], off offset:128
	v_mfma_f32_16x16x32_bf16 v[40:43], v[180:183], v[222:225], v[40:43]
	v_mfma_f32_16x16x32_bf16 v[28:31], v[136:139], v[230:233], v[28:31]
	v_mfma_f32_16x16x32_bf16 v[24:27], v[180:183], v[230:233], v[24:27]
	v_mfma_f32_16x16x32_bf16 v[12:15], v[136:139], v[238:241], v[12:15]
	v_mfma_f32_16x16x32_bf16 v[8:11], v[180:183], v[238:241], v[8:11]
	s_cmp_gt_u32 s75, 3
	s_cbranch_scc1 .Lie_skipk3
	v_mfma_f32_16x16x32_bf16 v[52:55], v[184:187], v[200:203], v[52:55]
	v_mfma_f32_16x16x32_bf16 v[48:51], v[192:195], v[200:203], v[48:51]
	v_mfma_f32_16x16x32_bf16 v[36:39], v[184:187], v[218:221], v[36:39]
	v_mfma_f32_16x16x32_bf16 v[32:35], v[192:195], v[218:221], v[32:35]
	v_mfma_f32_16x16x32_bf16 v[20:23], v[184:187], v[226:229], v[20:23]
	v_mfma_f32_16x16x32_bf16 v[16:19], v[192:195], v[226:229], v[16:19]
	v_mfma_f32_16x16x32_bf16 v[4:7], v[184:187], v[234:237], v[4:7]
	v_mfma_f32_16x16x32_bf16 v[0:3], v[192:195], v[234:237], v[0:3]
	v_mfma_f32_16x16x32_bf16 v[52:55], v[188:191], v[204:207], v[52:55]
	v_mfma_f32_16x16x32_bf16 v[48:51], v[196:199], v[204:207], v[48:51]
	v_mfma_f32_16x16x32_bf16 v[36:39], v[188:191], v[222:225], v[36:39]
	v_mfma_f32_16x16x32_bf16 v[32:35], v[196:199], v[222:225], v[32:35]
	v_mfma_f32_16x16x32_bf16 v[20:23], v[188:191], v[230:233], v[20:23]
	v_mfma_f32_16x16x32_bf16 v[16:19], v[196:199], v[230:233], v[16:19]
	v_mfma_f32_16x16x32_bf16 v[4:7], v[188:191], v[238:241], v[4:7]
	v_mfma_f32_16x16x32_bf16 v[0:3], v[196:199], v[238:241], v[0:3]

; #define PG8_STAGE(bufoff, gbase, voff) do { _Pragma("unroll") for (int _i = 0; _i < 2; ++_i) \
;         __builtin_amdgcn_global_load_lds((const unsigned*)((const char*)(gbase) + (voff)[_i]), (PG8_LAS unsigned*)(lds + (bufoff) + ldsw + _i * 8192), 16, 0, 0); } while (0)
; #define PG8_LDA(dst, b, h) do { _Pragma("unroll") for (int m = 0; m < 4; ++m) _Pragma("unroll") for (int k = 0; k < 2; ++k) dst[m][k] = *(const PG8_LAS bf16x8*)(lds + PG8_SA(b, h) + aoff + m * 2048 + k * 1024); } while (0)
; #define PG8_LDB(dst, b, h) do { _Pragma("unroll") for (int n = 0; n < 2; ++n) _Pragma("unroll") for (int k = 0; k < 2; ++k) dst[n][k] = *(const PG8_LAS bf16x8*)(lds + PG8_SB(b, h) + boff + n * 2048 + k * 1024); } while (0)
; #define PG8_MMA(ai, bj, At, Bt) do { __builtin_amdgcn_s_setprio(1); _Pragma("unroll") for (int m = 0; m < 4; ++m) _Pragma("unroll") for (int n = 0; n < 2; ++n) _Pragma("unroll") for (int k = 0; k < 2; ++k) \
;         acc[ai][bj][m][n] = __builtin_amdgcn_mfma_f32_16x16x32_bf16(Bt[n][k], At[m][k], acc[ai][bj][m][n], 0, 0, 0); __builtin_amdgcn_s_setprio(0); } while (0)
; #define PG8_BAR __builtin_amdgcn_s_barrier()
; template <class Epi, class Sched, bool ALIGN_EPI = false, bool SP2 = false>
; __device__ __forceinline__ void gemm_phase(PG8_LAS unsigned char* lds, const Gemm g, const Sched& S, const Epi& E) {
;     ...
;         const bool has_next = S.next(ui + 1, nxt);
;         const char* nA = has_next ? (const char*)g.A + (size_t)nxt.pm * tstep : cA; const char* nB = has_next ? (const char*)g.Bt + (size_t)nxt.pn * tstep : cB;
;         for (int t = 0; t < nt; t += 2) {
;             const bool last = (t == nt - 2);
;             const char* a1 = cA + (size_t)(t + 1) * kstep;
;             const char* a2 = last ? nA : cA + (size_t)(t + 2) * kstep; const char* b2 = last ? nB : cB + (size_t)(t + 2) * kstep;
;             const char* a3 = a2 + kstep; const char* b3 = b2 + kstep;
;             if (last && has_next) S.a_ready(nxt);
;             if constexpr (SP2) {
;             PG8_LDB(B0, 0, 0); PG8_LDB(B1, 0, 1); PG8_SCHED; PG8_LDA(At, 0, 0); PG8_STAGE(PG8_SA(1, 1), a1 + hstep, voffA);
;             PG8_WAIT_V(8); PG8_WAIT_L(0); PG8_BAR; PG8_MMA(0, 0, At, B0); PG8_MMA(0, 1, At, B1); PG8_BAR; PG8_SCHED;
;             PG8_LDA(At, 0, 1); PG8_STAGE(PG8_SB(0, 0), b2, voffB); PG8_STAGE(PG8_SB(0, 1), b2 + hstep, voffB); PG8_STAGE(PG8_SA(0, 0), a2, voffA);
.LBB0_635:
	v_add_u32_e32 v144, s64, v209
	v_add_u32_e32 v194, s65, v209
	ds_read_b128 v[92:95], v144
	ds_read_b128 v[128:131], v144 offset:1024
	ds_read_b128 v[132:135], v144 offset:2048
	ds_read_b128 v[144:147], v144 offset:3072
	ds_read_b128 v[148:151], v194
	ds_read_b128 v[152:155], v194 offset:1024
	ds_read_b128 v[190:193], v194 offset:2048
	ds_read_b128 v[194:197], v194 offset:3072
	s_cmp_eq_u32 s58, s10
	v_lshl_add_u64 v[198:199], v[90:91], 0, s[24:25]
	s_cselect_b64 vcc, -1, 0
	s_add_i32 s10, s10, 2
	v_cndmask_b32_e32 v207, v199, v187, vcc
	v_cndmask_b32_e32 v206, v198, v186, vcc
	v_cndmask_b32_e32 v215, v89, v189, vcc
	v_cndmask_b32_e32 v214, v88, v188, vcc
	v_lshl_add_u64 v[238:239], v[90:91], 0, v[180:181]
	s_add_i32 m0, s41, 0xc000
	ds_read_b128 v[198:201], v216
	ds_read_b128 v[202:205], v216 offset:1024
	ds_read_b128 v[210:213], v216 offset:2048
	ds_read_b128 v[218:221], v216 offset:3072
	ds_read_b128 v[222:225], v216 offset:4096
	ds_read_b128 v[226:229], v216 offset:5120
	ds_read_b128 v[230:233], v216 offset:6144
	ds_read_b128 v[234:237], v216 offset:7168
	global_load_lds_dwordx4 v[238:239], off
	s_add_i32 m0, s41, 0xe000
	v_lshl_add_u64 v[238:239], v[90:91], 0, v[178:179]
	global_load_lds_dwordx4 v[238:239], off
	s_waitcnt vmcnt(8) lgkmcnt(0)
	s_setprio 1
	s_barrier
	v_mfma_f32_16x16x32_bf16 v[140:143], v[92:95], v[198:201], v[140:143]
	v_mfma_f32_16x16x32_bf16 v[136:139], v[132:135], v[198:201], v[136:139]
	v_mfma_f32_16x16x32_bf16 v[116:119], v[92:95], v[210:213], v[116:119]
	v_mfma_f32_16x16x32_bf16 v[112:115], v[132:135], v[210:213], v[112:115]
	v_mfma_f32_16x16x32_bf16 v[100:103], v[92:95], v[222:225], v[100:103]
	v_mfma_f32_16x16x32_bf16 v[96:99], v[132:135], v[222:225], v[96:99]
	v_mfma_f32_16x16x32_bf16 v[76:79], v[92:95], v[230:233], v[76:79]
	v_mfma_f32_16x16x32_bf16 v[72:75], v[132:135], v[230:233], v[72:75]
	v_mfma_f32_16x16x32_bf16 v[140:143], v[128:131], v[202:205], v[140:143]
	v_mfma_f32_16x16x32_bf16 v[136:139], v[144:147], v[202:205], v[136:139]
	v_mfma_f32_16x16x32_bf16 v[116:119], v[128:131], v[218:221], v[116:119]
	v_mfma_f32_16x16x32_bf16 v[112:115], v[144:147], v[218:221], v[112:115]
	v_mfma_f32_16x16x32_bf16 v[100:103], v[128:131], v[226:229], v[100:103]
	v_mfma_f32_16x16x32_bf16 v[96:99], v[144:147], v[226:229], v[96:99]
	v_mfma_f32_16x16x32_bf16 v[76:79], v[128:131], v[234:237], v[76:79]
	v_mfma_f32_16x16x32_bf16 v[72:75], v[144:147], v[234:237], v[72:75]
	v_mfma_f32_16x16x32_bf16 v[124:127], v[148:151], v[198:201], v[124:127]
	v_mfma_f32_16x16x32_bf16 v[120:123], v[190:193], v[198:201], v[120:123]
	v_mfma_f32_16x16x32_bf16 v[108:111], v[148:151], v[210:213], v[108:111]
	v_mfma_f32_16x16x32_bf16 v[104:107], v[190:193], v[210:213], v[104:107]
	v_mfma_f32_16x16x32_bf16 v[84:87], v[148:151], v[222:225], v[84:87]
	v_mfma_f32_16x16x32_bf16 v[80:83], v[190:193], v[222:225], v[80:83]
	v_mfma_f32_16x16x32_bf16 v[68:71], v[148:151], v[230:233], v[68:71]
	v_mfma_f32_16x16x32_bf16 v[64:67], v[190:193], v[230:233], v[64:67]
	v_mfma_f32_16x16x32_bf16 v[124:127], v[152:155], v[202:205], v[124:127]
	v_mfma_f32_16x16x32_bf16 v[120:123], v[194:197], v[202:205], v[120:123]
	v_mfma_f32_16x16x32_bf16 v[108:111], v[152:155], v[218:221], v[108:111]
	v_mfma_f32_16x16x32_bf16 v[104:107], v[194:197], v[218:221], v[104:107]
	v_mfma_f32_16x16x32_bf16 v[84:87], v[152:155], v[226:229], v[84:87]
	v_mfma_f32_16x16x32_bf16 v[80:83], v[194:197], v[226:229], v[80:83]
	v_mfma_f32_16x16x32_bf16 v[68:71], v[152:155], v[234:237], v[68:71]
	v_mfma_f32_16x16x32_bf16 v[64:67], v[194:197], v[234:237], v[64:67]
	s_setprio 0
	s_barrier
	s_add_i32 s11, s64, s35
	v_lshl_add_u64 v[238:239], v[214:215], 0, v[168:169]
	s_mov_b32 m0, s11
	ds_read_b128 v[198:201], v216 offset:16384
	ds_read_b128 v[202:205], v216 offset:17408
	ds_read_b128 v[210:213], v216 offset:18432
	ds_read_b128 v[218:221], v216 offset:19456
	ds_read_b128 v[222:225], v216 offset:20480
	ds_read_b128 v[226:229], v216 offset:21504
	ds_read_b128 v[230:233], v216 offset:22528
	global_load_lds_dwordx4 v[238:239], off
	v_lshl_add_u64 v[240:241], v[214:215], 0, v[172:173]
	s_add_i32 m0, s11, 0x2000
	v_lshl_add_u64 v[214:215], v[214:215], 0, s[18:19]
	s_add_i32 s11, s65, s35
	global_load_lds_dwordx4 v[240:241], off
	v_lshl_add_u64 v[242:243], v[214:215], 0, v[168:169]
	s_mov_b32 m0, s11
	v_lshl_add_u64 v[214:215], v[214:215], 0, v[172:173]
	global_load_lds_dwordx4 v[242:243], off
	s_add_i32 m0, s11, 0x2000
	ds_read_b128 v[234:237], v216 offset:23552
	global_load_lds_dwordx4 v[214:215], off
	s_waitcnt vmcnt(6) lgkmcnt(0)
	s_setprio 1
	s_barrier
; #define PG8_STAGE(bufoff, gbase, voff) do { _Pragma("unroll") for (int _i = 0; _i < 2; ++_i) \
;         __builtin_amdgcn_global_load_lds((const unsigned*)((const char*)(gbase) + (voff)[_i]), (PG8_LAS unsigned*)(lds + (bufoff) + ldsw + _i * 8192), 16, 0, 0); } while (0)
; #define PG8_LDA(dst, b, h) do { _Pragma("unroll") for (int m = 0; m < 4; ++m) _Pragma("unroll") for (int k = 0; k < 2; ++k) dst[m][k] = *(const PG8_LAS bf16x8*)(lds + PG8_SA(b, h) + aoff + m * 2048 + k * 1024); } while (0)
; #define PG8_LDB(dst, b, h) do { _Pragma("unroll") for (int n = 0; n < 2; ++n) _Pragma("unroll") for (int k = 0; k < 2; ++k) dst[n][k] = *(const PG8_LAS bf16x8*)(lds + PG8_SB(b, h) + boff + n * 2048 + k * 1024); } while (0)
; #define PG8_MMA(ai, bj, At, Bt) do { __builtin_amdgcn_s_setprio(1); _Pragma("unroll") for (int m = 0; m < 4; ++m) _Pragma("unroll") for (int n = 0; n < 2; ++n) _Pragma("unroll") for (int k = 0; k < 2; ++k) \
;         acc[ai][bj][m][n] = __builtin_amdgcn_mfma_f32_16x16x32_bf16(Bt[n][k], At[m][k], acc[ai][bj][m][n], 0, 0, 0); __builtin_amdgcn_s_setprio(0); } while (0)
; #define PG8_WAIT_V(n) asm volatile("s_waitcnt vmcnt(" #n ")" ::: "memory")
; #define PG8_WAIT_L(n) asm volatile("s_waitcnt lgkmcnt(" #n ")" ::: "memory")
; #define PG8_BAR __builtin_amdgcn_s_barrier()
; #define PG8_SCHED __builtin_amdgcn_sched_barrier(0)
; template <class Epi, class Sched, bool ALIGN_EPI = false, bool SP2 = false>
; __device__ __forceinline__ void gemm_phase(PG8_LAS unsigned char* lds, const Gemm g, const Sched& S, const Epi& E) {
;     ...
;             PG8_WAIT_V(8); PG8_WAIT_L(0); PG8_BAR; PG8_MMA(1, 0, At, B0); PG8_MMA(1, 1, At, B1); PG8_BAR; PG8_SCHED;
;             PG8_LDB(B0, 1, 0); PG8_LDB(B1, 1, 1); PG8_SCHED; PG8_LDA(At, 1, 0); PG8_STAGE(PG8_SA(0, 1), a2 + hstep, voffA);
;             PG8_WAIT_V(8); PG8_WAIT_L(0); PG8_BAR; PG8_MMA(0, 0, At, B0); PG8_MMA(0, 1, At, B1); PG8_BAR; PG8_SCHED;
	v_mfma_f32_16x16x32_bf16 v[60:63], v[92:95], v[198:201], v[60:63]
	v_mfma_f32_16x16x32_bf16 v[56:59], v[132:135], v[198:201], v[56:59]
	v_mfma_f32_16x16x32_bf16 v[44:47], v[92:95], v[210:213], v[44:47]
	v_mfma_f32_16x16x32_bf16 v[40:43], v[132:135], v[210:213], v[40:43]
	s_mov_b32 m0, s41
	v_lshl_add_u64 v[244:245], v[206:207], 0, v[166:167]
	v_mfma_f32_16x16x32_bf16 v[28:31], v[92:95], v[222:225], v[28:31]
	global_load_lds_dwordx4 v[244:245], off
	v_mfma_f32_16x16x32_bf16 v[24:27], v[132:135], v[222:225], v[24:27]
	v_mfma_f32_16x16x32_bf16 v[12:15], v[92:95], v[230:233], v[12:15]
	v_mfma_f32_16x16x32_bf16 v[8:11], v[132:135], v[230:233], v[8:11]
	v_mfma_f32_16x16x32_bf16 v[60:63], v[128:131], v[202:205], v[60:63]
	v_mfma_f32_16x16x32_bf16 v[56:59], v[144:147], v[202:205], v[56:59]
	s_mov_b32 m0, s50
	v_lshl_add_u64 v[246:247], v[206:207], 0, v[170:171]
	v_mfma_f32_16x16x32_bf16 v[44:47], v[128:131], v[218:221], v[44:47]
	global_load_lds_dwordx4 v[246:247], off
	v_mfma_f32_16x16x32_bf16 v[40:43], v[144:147], v[218:221], v[40:43]
	v_mfma_f32_16x16x32_bf16 v[28:31], v[128:131], v[226:229], v[28:31]
	v_mfma_f32_16x16x32_bf16 v[24:27], v[144:147], v[226:229], v[24:27]
	v_mfma_f32_16x16x32_bf16 v[12:15], v[128:131], v[234:237], v[12:15]
	v_mfma_f32_16x16x32_bf16 v[8:11], v[144:147], v[234:237], v[8:11]
	v_mfma_f32_16x16x32_bf16 v[52:55], v[148:151], v[198:201], v[52:55]
	v_mfma_f32_16x16x32_bf16 v[48:51], v[190:193], v[198:201], v[48:51]
	v_mfma_f32_16x16x32_bf16 v[36:39], v[148:151], v[210:213], v[36:39]
	v_mfma_f32_16x16x32_bf16 v[32:35], v[190:193], v[210:213], v[32:35]
	v_mfma_f32_16x16x32_bf16 v[20:23], v[148:151], v[222:225], v[20:23]
	v_mfma_f32_16x16x32_bf16 v[16:19], v[190:193], v[222:225], v[16:19]
	v_mfma_f32_16x16x32_bf16 v[4:7], v[148:151], v[230:233], v[4:7]
	v_mfma_f32_16x16x32_bf16 v[0:3], v[190:193], v[230:233], v[0:3]
	v_mfma_f32_16x16x32_bf16 v[52:55], v[152:155], v[202:205], v[52:55]
	v_mfma_f32_16x16x32_bf16 v[48:51], v[194:197], v[202:205], v[48:51]
	v_mfma_f32_16x16x32_bf16 v[36:39], v[152:155], v[218:221], v[36:39]
	v_mfma_f32_16x16x32_bf16 v[32:35], v[194:197], v[218:221], v[32:35]
	v_mfma_f32_16x16x32_bf16 v[20:23], v[152:155], v[226:229], v[20:23]
	v_mfma_f32_16x16x32_bf16 v[16:19], v[194:197], v[226:229], v[16:19]
	v_mfma_f32_16x16x32_bf16 v[4:7], v[152:155], v[234:237], v[4:7]
	v_mfma_f32_16x16x32_bf16 v[0:3], v[194:197], v[234:237], v[0:3]
	s_setprio 0
	s_barrier
	s_add_i32 s11, 0, 0x18000
	s_add_i32 s14, 0, 0x1c000
	v_add_u32_e32 v144, s11, v209
	v_add_u32_e32 v194, s14, v209
	ds_read_b128 v[92:95], v144
	ds_read_b128 v[128:131], v144 offset:1024
	ds_read_b128 v[132:135], v144 offset:2048
	ds_read_b128 v[144:147], v144 offset:3072
	ds_read_b128 v[148:151], v194
	ds_read_b128 v[152:155], v194 offset:1024
	ds_read_b128 v[190:193], v194 offset:2048
	ds_read_b128 v[194:197], v194 offset:3072
	v_lshl_add_u64 v[206:207], v[206:207], 0, s[18:19]
	s_mov_b32 m0, s51
	v_lshl_add_u64 v[248:249], v[206:207], 0, v[166:167]
	ds_read_b128 v[198:201], v216 offset:32768
	ds_read_b128 v[202:205], v216 offset:33792
	ds_read_b128 v[210:213], v216 offset:34816
	ds_read_b128 v[218:221], v216 offset:35840
	ds_read_b128 v[222:225], v216 offset:36864
	ds_read_b128 v[226:229], v216 offset:37888
	ds_read_b128 v[230:233], v216 offset:38912
	ds_read_b128 v[234:237], v216 offset:39936
	global_load_lds_dwordx4 v[248:249], off
	s_mov_b32 m0, s52
	v_lshl_add_u64 v[206:207], v[206:207], 0, v[170:171]
	global_load_lds_dwordx4 v[206:207], off
	s_waitcnt vmcnt(8) lgkmcnt(0)
	s_setprio 1
	s_barrier
; #define PG8_STAGE(bufoff, gbase, voff) do { _Pragma("unroll") for (int _i = 0; _i < 2; ++_i) \
;         __builtin_amdgcn_global_load_lds((const unsigned*)((const char*)(gbase) + (voff)[_i]), (PG8_LAS unsigned*)(lds + (bufoff) + ldsw + _i * 8192), 16, 0, 0); } while (0)
; #define PG8_LDA(dst, b, h) do { _Pragma("unroll") for (int m = 0; m < 4; ++m) _Pragma("unroll") for (int k = 0; k < 2; ++k) dst[m][k] = *(const PG8_LAS bf16x8*)(lds + PG8_SA(b, h) + aoff + m * 2048 + k * 1024); } while (0)
; #define PG8_MMA(ai, bj, At, Bt) do { __builtin_amdgcn_s_setprio(1); _Pragma("unroll") for (int m = 0; m < 4; ++m) _Pragma("unroll") for (int n = 0; n < 2; ++n) _Pragma("unroll") for (int k = 0; k < 2; ++k) \
;         acc[ai][bj][m][n] = __builtin_amdgcn_mfma_f32_16x16x32_bf16(Bt[n][k], At[m][k], acc[ai][bj][m][n], 0, 0, 0); __builtin_amdgcn_s_setprio(0); } while (0)
; #define PG8_WAIT_V(n) asm volatile("s_waitcnt vmcnt(" #n ")" ::: "memory")
; #define PG8_WAIT_L(n) asm volatile("s_waitcnt lgkmcnt(" #n ")" ::: "memory")
; #define PG8_BAR __builtin_amdgcn_s_barrier()
; #define PG8_SCHED __builtin_amdgcn_sched_barrier(0)
; template <class Epi, class Sched, bool ALIGN_EPI = false, bool SP2 = false>
; __device__ __forceinline__ void gemm_phase(PG8_LAS unsigned char* lds, const Gemm g, const Sched& S, const Epi& E) {
;     ...
;             PG8_WAIT_V(8); PG8_WAIT_L(0); PG8_BAR; PG8_MMA(0, 0, At, B0); PG8_MMA(0, 1, At, B1); PG8_BAR; PG8_SCHED;
;             PG8_LDA(At, 1, 1); PG8_STAGE(PG8_SB(1, 0), b3, voffB); PG8_STAGE(PG8_SB(1, 1), b3 + hstep, voffB); PG8_STAGE(PG8_SA(1, 0), a3, voffA);
;             PG8_WAIT_V(8); PG8_WAIT_L(0); PG8_BAR; PG8_MMA(1, 0, At, B0); PG8_MMA(1, 1, At, B1); PG8_BAR; PG8_SCHED;
	v_mfma_f32_16x16x32_bf16 v[140:143], v[92:95], v[198:201], v[140:143]
	v_mfma_f32_16x16x32_bf16 v[136:139], v[132:135], v[198:201], v[136:139]
	v_mfma_f32_16x16x32_bf16 v[116:119], v[92:95], v[210:213], v[116:119]
	v_mfma_f32_16x16x32_bf16 v[112:115], v[132:135], v[210:213], v[112:115]
	v_mfma_f32_16x16x32_bf16 v[100:103], v[92:95], v[222:225], v[100:103]
	v_mfma_f32_16x16x32_bf16 v[96:99], v[132:135], v[222:225], v[96:99]
	v_mfma_f32_16x16x32_bf16 v[76:79], v[92:95], v[230:233], v[76:79]
	v_mfma_f32_16x16x32_bf16 v[72:75], v[132:135], v[230:233], v[72:75]
	v_mfma_f32_16x16x32_bf16 v[140:143], v[128:131], v[202:205], v[140:143]
	v_mfma_f32_16x16x32_bf16 v[136:139], v[144:147], v[202:205], v[136:139]
	v_mfma_f32_16x16x32_bf16 v[116:119], v[128:131], v[218:221], v[116:119]
	v_mfma_f32_16x16x32_bf16 v[112:115], v[144:147], v[218:221], v[112:115]
	v_mfma_f32_16x16x32_bf16 v[100:103], v[128:131], v[226:229], v[100:103]
	v_mfma_f32_16x16x32_bf16 v[96:99], v[144:147], v[226:229], v[96:99]
	v_mfma_f32_16x16x32_bf16 v[76:79], v[128:131], v[234:237], v[76:79]
	v_mfma_f32_16x16x32_bf16 v[72:75], v[144:147], v[234:237], v[72:75]
	v_mfma_f32_16x16x32_bf16 v[124:127], v[148:151], v[198:201], v[124:127]
	v_mfma_f32_16x16x32_bf16 v[120:123], v[190:193], v[198:201], v[120:123]
	v_mfma_f32_16x16x32_bf16 v[108:111], v[148:151], v[210:213], v[108:111]
	v_mfma_f32_16x16x32_bf16 v[104:107], v[190:193], v[210:213], v[104:107]
	v_mfma_f32_16x16x32_bf16 v[84:87], v[148:151], v[222:225], v[84:87]
	v_mfma_f32_16x16x32_bf16 v[80:83], v[190:193], v[222:225], v[80:83]
	v_mfma_f32_16x16x32_bf16 v[68:71], v[148:151], v[230:233], v[68:71]
	v_mfma_f32_16x16x32_bf16 v[64:67], v[190:193], v[230:233], v[64:67]
	v_mfma_f32_16x16x32_bf16 v[124:127], v[152:155], v[202:205], v[124:127]
	v_mfma_f32_16x16x32_bf16 v[120:123], v[194:197], v[202:205], v[120:123]
	v_mfma_f32_16x16x32_bf16 v[108:111], v[152:155], v[218:221], v[108:111]
	v_mfma_f32_16x16x32_bf16 v[104:107], v[194:197], v[218:221], v[104:107]
	v_mfma_f32_16x16x32_bf16 v[84:87], v[152:155], v[226:229], v[84:87]
	v_mfma_f32_16x16x32_bf16 v[80:83], v[194:197], v[226:229], v[80:83]
	v_mfma_f32_16x16x32_bf16 v[68:71], v[152:155], v[234:237], v[68:71]
	v_mfma_f32_16x16x32_bf16 v[64:67], v[194:197], v[234:237], v[64:67]
	s_setprio 0
	s_barrier
	s_add_i32 s11, s11, s35
	s_add_i32 m0, s11, 0xffffff80
	ds_read_b128 v[198:201], v216 offset:49152
	ds_read_b128 v[202:205], v216 offset:50176
	ds_read_b128 v[210:213], v216 offset:51200
	ds_read_b128 v[218:221], v216 offset:52224
	ds_read_b128 v[222:225], v216 offset:53248
	ds_read_b128 v[226:229], v216 offset:54272
	global_load_lds_dwordx4 v[238:239], off offset:128
	s_add_i32 m0, s11, 0x1f80
	s_add_i32 s11, s14, s35
	global_load_lds_dwordx4 v[240:241], off offset:128
	s_add_i32 m0, s11, 0xffffff80
	ds_read_b128 v[234:237], v216 offset:56320
	global_load_lds_dwordx4 v[242:243], off offset:128
	s_add_i32 m0, s11, 0x1f80
	ds_read_b128 v[230:233], v216 offset:55296
	global_load_lds_dwordx4 v[214:215], off offset:128
	s_waitcnt vmcnt(6) lgkmcnt(0)
	s_setprio 1
	s_barrier
	v_mfma_f32_16x16x32_bf16 v[60:63], v[92:95], v[198:201], v[60:63]
	v_mfma_f32_16x16x32_bf16 v[56:59], v[132:135], v[198:201], v[56:59]
	v_mfma_f32_16x16x32_bf16 v[44:47], v[92:95], v[210:213], v[44:47]
	v_mfma_f32_16x16x32_bf16 v[40:43], v[132:135], v[210:213], v[40:43]
	s_add_i32 m0, s54, 0xffffff80
	v_mfma_f32_16x16x32_bf16 v[28:31], v[92:95], v[222:225], v[28:31]
	global_load_lds_dwordx4 v[244:245], off offset:128
	v_mfma_f32_16x16x32_bf16 v[24:27], v[132:135], v[222:225], v[24:27]
	v_mfma_f32_16x16x32_bf16 v[12:15], v[92:95], v[230:233], v[12:15]
	v_mfma_f32_16x16x32_bf16 v[8:11], v[132:135], v[230:233], v[8:11]
	v_mfma_f32_16x16x32_bf16 v[60:63], v[128:131], v[202:205], v[60:63]
	v_mfma_f32_16x16x32_bf16 v[56:59], v[144:147], v[202:205], v[56:59]
	s_add_i32 m0, s55, 0xffffff80
	v_mfma_f32_16x16x32_bf16 v[44:47], v[128:131], v[218:221], v[44:47]
	global_load_lds_dwordx4 v[246:247], off offset:128
	v_mfma_f32_16x16x32_bf16 v[40:43], v[144:147], v[218:221], v[40:43]
	v_mfma_f32_16x16x32_bf16 v[28:31], v[128:131], v[226:229], v[28:31]
	v_mfma_f32_16x16x32_bf16 v[24:27], v[144:147], v[226:229], v[24:27]
	v_mfma_f32_16x16x32_bf16 v[12:15], v[128:131], v[234:237], v[12:15]
	v_mfma_f32_16x16x32_bf16 v[8:11], v[144:147], v[234:237], v[8:11]
	v_mfma_f32_16x16x32_bf16 v[52:55], v[148:151], v[198:201], v[52:55]
	v_mfma_f32_16x16x32_bf16 v[48:51], v[190:193], v[198:201], v[48:51]
	v_mfma_f32_16x16x32_bf16 v[36:39], v[148:151], v[210:213], v[36:39]
	v_mfma_f32_16x16x32_bf16 v[32:35], v[190:193], v[210:213], v[32:35]
	v_mfma_f32_16x16x32_bf16 v[20:23], v[148:151], v[222:225], v[20:23]
	v_mfma_f32_16x16x32_bf16 v[16:19], v[190:193], v[222:225], v[16:19]
	v_mfma_f32_16x16x32_bf16 v[4:7], v[148:151], v[230:233], v[4:7]
	v_mfma_f32_16x16x32_bf16 v[0:3], v[190:193], v[230:233], v[0:3]
	v_mfma_f32_16x16x32_bf16 v[52:55], v[152:155], v[202:205], v[52:55]
	v_mfma_f32_16x16x32_bf16 v[48:51], v[194:197], v[202:205], v[48:51]
	v_mfma_f32_16x16x32_bf16 v[36:39], v[152:155], v[218:221], v[36:39]
	v_mfma_f32_16x16x32_bf16 v[32:35], v[194:197], v[218:221], v[32:35]
	v_mfma_f32_16x16x32_bf16 v[20:23], v[152:155], v[226:229], v[20:23]
	v_mfma_f32_16x16x32_bf16 v[16:19], v[194:197], v[226:229], v[16:19]
	v_mfma_f32_16x16x32_bf16 v[4:7], v[152:155], v[234:237], v[4:7]
	v_mfma_f32_16x16x32_bf16 v[0:3], v[194:197], v[234:237], v[0:3]
	s_setprio 0
	s_barrier
	v_lshl_add_u64 v[88:89], v[88:89], 0, s[30:31]
	s_cmp_ge_i32 s10, s57
	v_lshl_add_u64 v[90:91], v[90:91], 0, s[30:31]
	s_cbranch_scc0 .LBB0_635

; #define PG8_STAGE(bufoff, gbase, voff) do { _Pragma("unroll") for (int _i = 0; _i < 2; ++_i) \
;         __builtin_amdgcn_global_load_lds((const unsigned*)((const char*)(gbase) + (voff)[_i]), (PG8_LAS unsigned*)(lds + (bufoff) + ldsw + _i * 8192), 16, 0, 0); } while (0)
; #define PG8_LDA(dst, b, h) do { _Pragma("unroll") for (int m = 0; m < 4; ++m) _Pragma("unroll") for (int k = 0; k < 2; ++k) dst[m][k] = *(const PG8_LAS bf16x8*)(lds + PG8_SA(b, h) + aoff + m * 2048 + k * 1024); } while (0)
; #define PG8_LDB(dst, b, h) do { _Pragma("unroll") for (int n = 0; n < 2; ++n) _Pragma("unroll") for (int k = 0; k < 2; ++k) dst[n][k] = *(const PG8_LAS bf16x8*)(lds + PG8_SB(b, h) + boff + n * 2048 + k * 1024); } while (0)
; #define PG8_MMA(ai, bj, At, Bt) do { __builtin_amdgcn_s_setprio(1); _Pragma("unroll") for (int m = 0; m < 4; ++m) _Pragma("unroll") for (int n = 0; n < 2; ++n) _Pragma("unroll") for (int k = 0; k < 2; ++k) \
;         acc[ai][bj][m][n] = __builtin_amdgcn_mfma_f32_16x16x32_bf16(Bt[n][k], At[m][k], acc[ai][bj][m][n], 0, 0, 0); __builtin_amdgcn_s_setprio(0); } while (0)
; #define PG8_BAR __builtin_amdgcn_s_barrier()
; template <class Epi, class Sched, bool ALIGN_EPI = false, bool SP2 = false>
; __device__ __forceinline__ void gemm_phase(PG8_LAS unsigned char* lds, const Gemm g, const Sched& S, const Epi& E) {
;     ...
;         const bool has_next = S.next(ui + 1, nxt);
;         const char* nA = has_next ? (const char*)g.A + (size_t)nxt.pm * tstep : cA; const char* nB = has_next ? (const char*)g.Bt + (size_t)nxt.pn * tstep : cB;
;         for (int t = 0; t < nt; t += 2) {
;             const bool last = (t == nt - 2);
;             const char* a1 = cA + (size_t)(t + 1) * kstep;
;             const char* a2 = last ? nA : cA + (size_t)(t + 2) * kstep; const char* b2 = last ? nB : cB + (size_t)(t + 2) * kstep;
;             const char* a3 = a2 + kstep; const char* b3 = b2 + kstep;
;             if (last && has_next) S.a_ready(nxt);
;             if constexpr (SP2) {
;             PG8_LDB(B0, 0, 0); PG8_LDB(B1, 0, 1); PG8_SCHED; PG8_LDA(At, 0, 0); PG8_STAGE(PG8_SA(1, 1), a1 + hstep, voffA);
;             PG8_WAIT_V(8); PG8_WAIT_L(0); PG8_BAR; PG8_MMA(0, 0, At, B0); PG8_MMA(0, 1, At, B1); PG8_BAR; PG8_SCHED;
;             PG8_LDA(At, 0, 1); PG8_STAGE(PG8_SB(0, 0), b2, voffB); PG8_STAGE(PG8_SB(0, 1), b2 + hstep, voffB); PG8_STAGE(PG8_SA(0, 0), a2, voffA);
.LBB0_722:
	v_add_u32_e32 v144, s59, v183
	v_add_u32_e32 v170, s60, v183
	ds_read_b128 v[116:119], v144
	ds_read_b128 v[136:139], v144 offset:1024
	ds_read_b128 v[140:143], v144 offset:2048
	ds_read_b128 v[144:147], v144 offset:3072
	ds_read_b128 v[148:151], v170
	ds_read_b128 v[188:191], v170 offset:1024
	ds_read_b128 v[192:195], v170 offset:2048
	ds_read_b128 v[198:201], v170 offset:3072
	s_cmp_eq_u32 s53, s8
	v_lshl_add_u64 v[204:205], v[114:115], 0, s[18:19]
	s_cselect_b64 vcc, -1, 0
	s_add_i32 s8, s8, 2
	v_cndmask_b32_e32 v213, v205, v185, vcc
	v_cndmask_b32_e32 v212, v204, v184, vcc
	v_cndmask_b32_e32 v215, v113, v187, vcc
	v_cndmask_b32_e32 v214, v112, v186, vcc
	v_lshl_add_u64 v[240:241], v[114:115], 0, v[178:179]
	s_add_i32 m0, s34, 0xc000
	ds_read_b128 v[204:207], v202
	ds_read_b128 v[208:211], v202 offset:1024
	ds_read_b128 v[216:219], v202 offset:2048
	ds_read_b128 v[220:223], v202 offset:3072
	ds_read_b128 v[224:227], v202 offset:4096
	ds_read_b128 v[228:231], v202 offset:5120
	ds_read_b128 v[232:235], v202 offset:6144
	ds_read_b128 v[236:239], v202 offset:7168
	global_load_lds_dwordx4 v[240:241], off
	s_add_i32 m0, s34, 0xe000
	v_lshl_add_u64 v[240:241], v[114:115], 0, v[176:177]
	global_load_lds_dwordx4 v[240:241], off
	s_waitcnt vmcnt(8) lgkmcnt(0)
	s_setprio 1
	s_barrier
	v_mfma_f32_16x16x32_bf16 v[132:135], v[116:119], v[204:207], v[132:135]
	v_mfma_f32_16x16x32_bf16 v[128:131], v[140:143], v[204:207], v[128:131]
	v_mfma_f32_16x16x32_bf16 v[108:111], v[116:119], v[216:219], v[108:111]
	v_mfma_f32_16x16x32_bf16 v[104:107], v[140:143], v[216:219], v[104:107]
	v_mfma_f32_16x16x32_bf16 v[92:95], v[116:119], v[224:227], v[92:95]
	v_mfma_f32_16x16x32_bf16 v[88:91], v[140:143], v[224:227], v[88:91]
	v_mfma_f32_16x16x32_bf16 v[76:79], v[116:119], v[232:235], v[76:79]
	v_mfma_f32_16x16x32_bf16 v[72:75], v[140:143], v[232:235], v[72:75]
	v_mfma_f32_16x16x32_bf16 v[132:135], v[136:139], v[208:211], v[132:135]
	v_mfma_f32_16x16x32_bf16 v[128:131], v[144:147], v[208:211], v[128:131]
	v_mfma_f32_16x16x32_bf16 v[108:111], v[136:139], v[220:223], v[108:111]
	v_mfma_f32_16x16x32_bf16 v[104:107], v[144:147], v[220:223], v[104:107]
	v_mfma_f32_16x16x32_bf16 v[92:95], v[136:139], v[228:231], v[92:95]
	v_mfma_f32_16x16x32_bf16 v[88:91], v[144:147], v[228:231], v[88:91]
	v_mfma_f32_16x16x32_bf16 v[76:79], v[136:139], v[236:239], v[76:79]
	v_mfma_f32_16x16x32_bf16 v[72:75], v[144:147], v[236:239], v[72:75]
	v_mfma_f32_16x16x32_bf16 v[124:127], v[148:151], v[204:207], v[124:127]
	v_mfma_f32_16x16x32_bf16 v[120:123], v[192:195], v[204:207], v[120:123]
	v_mfma_f32_16x16x32_bf16 v[100:103], v[148:151], v[216:219], v[100:103]
	v_mfma_f32_16x16x32_bf16 v[96:99], v[192:195], v[216:219], v[96:99]
	v_mfma_f32_16x16x32_bf16 v[84:87], v[148:151], v[224:227], v[84:87]
	v_mfma_f32_16x16x32_bf16 v[80:83], v[192:195], v[224:227], v[80:83]
	v_mfma_f32_16x16x32_bf16 v[68:71], v[148:151], v[232:235], v[68:71]
	v_mfma_f32_16x16x32_bf16 v[64:67], v[192:195], v[232:235], v[64:67]
	v_mfma_f32_16x16x32_bf16 v[124:127], v[188:191], v[208:211], v[124:127]
	v_mfma_f32_16x16x32_bf16 v[120:123], v[198:201], v[208:211], v[120:123]
	v_mfma_f32_16x16x32_bf16 v[100:103], v[188:191], v[220:223], v[100:103]
	v_mfma_f32_16x16x32_bf16 v[96:99], v[198:201], v[220:223], v[96:99]
	v_mfma_f32_16x16x32_bf16 v[84:87], v[188:191], v[228:231], v[84:87]
	v_mfma_f32_16x16x32_bf16 v[80:83], v[198:201], v[228:231], v[80:83]
	v_mfma_f32_16x16x32_bf16 v[68:71], v[188:191], v[236:239], v[68:71]
	v_mfma_f32_16x16x32_bf16 v[64:67], v[198:201], v[236:239], v[64:67]
	s_setprio 0
	s_barrier
	s_add_i32 s9, s59, s29
	v_lshl_add_u64 v[240:241], v[214:215], 0, v[164:165]
	s_mov_b32 m0, s9
	ds_read_b128 v[204:207], v202 offset:16384
	ds_read_b128 v[208:211], v202 offset:17408
	ds_read_b128 v[216:219], v202 offset:18432
	ds_read_b128 v[220:223], v202 offset:19456
	ds_read_b128 v[224:227], v202 offset:20480
	ds_read_b128 v[228:231], v202 offset:21504
	ds_read_b128 v[232:235], v202 offset:22528
	global_load_lds_dwordx4 v[240:241], off
	v_lshl_add_u64 v[242:243], v[214:215], 0, v[168:169]
	s_add_i32 m0, s9, 0x2000
	v_lshl_add_u64 v[214:215], v[214:215], 0, s[12:13]
	s_add_i32 s9, s60, s29
	global_load_lds_dwordx4 v[242:243], off
	v_lshl_add_u64 v[244:245], v[214:215], 0, v[164:165]
	s_mov_b32 m0, s9
	v_lshl_add_u64 v[214:215], v[214:215], 0, v[168:169]
	global_load_lds_dwordx4 v[244:245], off
	s_add_i32 m0, s9, 0x2000
	ds_read_b128 v[236:239], v202 offset:23552
	global_load_lds_dwordx4 v[214:215], off
	s_waitcnt vmcnt(6) lgkmcnt(0)
	s_setprio 1
	s_barrier
; #define PG8_STAGE(bufoff, gbase, voff) do { _Pragma("unroll") for (int _i = 0; _i < 2; ++_i) \
;         __builtin_amdgcn_global_load_lds((const unsigned*)((const char*)(gbase) + (voff)[_i]), (PG8_LAS unsigned*)(lds + (bufoff) + ldsw + _i * 8192), 16, 0, 0); } while (0)
; #define PG8_LDA(dst, b, h) do { _Pragma("unroll") for (int m = 0; m < 4; ++m) _Pragma("unroll") for (int k = 0; k < 2; ++k) dst[m][k] = *(const PG8_LAS bf16x8*)(lds + PG8_SA(b, h) + aoff + m * 2048 + k * 1024); } while (0)
; #define PG8_LDB(dst, b, h) do { _Pragma("unroll") for (int n = 0; n < 2; ++n) _Pragma("unroll") for (int k = 0; k < 2; ++k) dst[n][k] = *(const PG8_LAS bf16x8*)(lds + PG8_SB(b, h) + boff + n * 2048 + k * 1024); } while (0)
; #define PG8_MMA(ai, bj, At, Bt) do { __builtin_amdgcn_s_setprio(1); _Pragma("unroll") for (int m = 0; m < 4; ++m) _Pragma("unroll") for (int n = 0; n < 2; ++n) _Pragma("unroll") for (int k = 0; k < 2; ++k) \
;         acc[ai][bj][m][n] = __builtin_amdgcn_mfma_f32_16x16x32_bf16(Bt[n][k], At[m][k], acc[ai][bj][m][n], 0, 0, 0); __builtin_amdgcn_s_setprio(0); } while (0)
; #define PG8_WAIT_V(n) asm volatile("s_waitcnt vmcnt(" #n ")" ::: "memory")
; #define PG8_WAIT_L(n) asm volatile("s_waitcnt lgkmcnt(" #n ")" ::: "memory")
; #define PG8_BAR __builtin_amdgcn_s_barrier()
; #define PG8_SCHED __builtin_amdgcn_sched_barrier(0)
; template <class Epi, class Sched, bool ALIGN_EPI = false, bool SP2 = false>
; __device__ __forceinline__ void gemm_phase(PG8_LAS unsigned char* lds, const Gemm g, const Sched& S, const Epi& E) {
;     ...
;             PG8_WAIT_V(8); PG8_WAIT_L(0); PG8_BAR; PG8_MMA(1, 0, At, B0); PG8_MMA(1, 1, At, B1); PG8_BAR; PG8_SCHED;
;             PG8_LDB(B0, 1, 0); PG8_LDB(B1, 1, 1); PG8_SCHED; PG8_LDA(At, 1, 0); PG8_STAGE(PG8_SA(0, 1), a2 + hstep, voffA);
;             PG8_WAIT_V(8); PG8_WAIT_L(0); PG8_BAR; PG8_MMA(0, 0, At, B0); PG8_MMA(0, 1, At, B1); PG8_BAR; PG8_SCHED;
	v_mfma_f32_16x16x32_bf16 v[60:63], v[116:119], v[204:207], v[60:63]
	v_mfma_f32_16x16x32_bf16 v[56:59], v[140:143], v[204:207], v[56:59]
	v_mfma_f32_16x16x32_bf16 v[44:47], v[116:119], v[216:219], v[44:47]
	v_mfma_f32_16x16x32_bf16 v[40:43], v[140:143], v[216:219], v[40:43]
	s_mov_b32 m0, s34
	v_lshl_add_u64 v[246:247], v[212:213], 0, v[162:163]
	v_mfma_f32_16x16x32_bf16 v[28:31], v[116:119], v[224:227], v[28:31]
	global_load_lds_dwordx4 v[246:247], off
	v_mfma_f32_16x16x32_bf16 v[24:27], v[140:143], v[224:227], v[24:27]
	v_mfma_f32_16x16x32_bf16 v[12:15], v[116:119], v[232:235], v[12:15]
	v_mfma_f32_16x16x32_bf16 v[8:11], v[140:143], v[232:235], v[8:11]
	v_mfma_f32_16x16x32_bf16 v[60:63], v[136:139], v[208:211], v[60:63]
	v_mfma_f32_16x16x32_bf16 v[56:59], v[144:147], v[208:211], v[56:59]
	s_mov_b32 m0, s36
	v_lshl_add_u64 v[248:249], v[212:213], 0, v[166:167]
	v_mfma_f32_16x16x32_bf16 v[44:47], v[136:139], v[220:223], v[44:47]
	global_load_lds_dwordx4 v[248:249], off
	v_mfma_f32_16x16x32_bf16 v[40:43], v[144:147], v[220:223], v[40:43]
	v_mfma_f32_16x16x32_bf16 v[28:31], v[136:139], v[228:231], v[28:31]
	v_mfma_f32_16x16x32_bf16 v[24:27], v[144:147], v[228:231], v[24:27]
	v_mfma_f32_16x16x32_bf16 v[12:15], v[136:139], v[236:239], v[12:15]
	v_mfma_f32_16x16x32_bf16 v[8:11], v[144:147], v[236:239], v[8:11]
	v_mfma_f32_16x16x32_bf16 v[52:55], v[148:151], v[204:207], v[52:55]
	v_mfma_f32_16x16x32_bf16 v[48:51], v[192:195], v[204:207], v[48:51]
	v_mfma_f32_16x16x32_bf16 v[36:39], v[148:151], v[216:219], v[36:39]
	v_mfma_f32_16x16x32_bf16 v[32:35], v[192:195], v[216:219], v[32:35]
	v_mfma_f32_16x16x32_bf16 v[20:23], v[148:151], v[224:227], v[20:23]
	v_mfma_f32_16x16x32_bf16 v[16:19], v[192:195], v[224:227], v[16:19]
	v_mfma_f32_16x16x32_bf16 v[4:7], v[148:151], v[232:235], v[4:7]
	v_mfma_f32_16x16x32_bf16 v[0:3], v[192:195], v[232:235], v[0:3]
	v_mfma_f32_16x16x32_bf16 v[52:55], v[188:191], v[208:211], v[52:55]
	v_mfma_f32_16x16x32_bf16 v[48:51], v[198:201], v[208:211], v[48:51]
	v_mfma_f32_16x16x32_bf16 v[36:39], v[188:191], v[220:223], v[36:39]
	v_mfma_f32_16x16x32_bf16 v[32:35], v[198:201], v[220:223], v[32:35]
	v_mfma_f32_16x16x32_bf16 v[20:23], v[188:191], v[228:231], v[20:23]
	v_mfma_f32_16x16x32_bf16 v[16:19], v[198:201], v[228:231], v[16:19]
	v_mfma_f32_16x16x32_bf16 v[4:7], v[188:191], v[236:239], v[4:7]
	v_mfma_f32_16x16x32_bf16 v[0:3], v[198:201], v[236:239], v[0:3]
	s_setprio 0
	s_barrier
	s_add_i32 s9, 0, 0x18000
	s_add_i32 s10, 0, 0x1c000
	v_add_u32_e32 v144, s9, v183
	v_add_u32_e32 v170, s10, v183
	ds_read_b128 v[116:119], v144
	ds_read_b128 v[136:139], v144 offset:1024
	ds_read_b128 v[140:143], v144 offset:2048
	ds_read_b128 v[144:147], v144 offset:3072
	ds_read_b128 v[148:151], v170
	ds_read_b128 v[188:191], v170 offset:1024
	ds_read_b128 v[192:195], v170 offset:2048
	ds_read_b128 v[198:201], v170 offset:3072
	v_lshl_add_u64 v[212:213], v[212:213], 0, s[12:13]
	s_mov_b32 m0, s37
	v_lshl_add_u64 v[250:251], v[212:213], 0, v[162:163]
	ds_read_b128 v[204:207], v202 offset:32768
	ds_read_b128 v[208:211], v202 offset:33792
	ds_read_b128 v[216:219], v202 offset:34816
	ds_read_b128 v[220:223], v202 offset:35840
	ds_read_b128 v[224:227], v202 offset:36864
	ds_read_b128 v[228:231], v202 offset:37888
	ds_read_b128 v[232:235], v202 offset:38912
	ds_read_b128 v[236:239], v202 offset:39936
	global_load_lds_dwordx4 v[250:251], off
	s_mov_b32 m0, s41
	v_lshl_add_u64 v[212:213], v[212:213], 0, v[166:167]
	global_load_lds_dwordx4 v[212:213], off
	s_waitcnt vmcnt(8) lgkmcnt(0)
	s_setprio 1
	s_barrier
; #define PG8_STAGE(bufoff, gbase, voff) do { _Pragma("unroll") for (int _i = 0; _i < 2; ++_i) \
;         __builtin_amdgcn_global_load_lds((const unsigned*)((const char*)(gbase) + (voff)[_i]), (PG8_LAS unsigned*)(lds + (bufoff) + ldsw + _i * 8192), 16, 0, 0); } while (0)
; #define PG8_LDA(dst, b, h) do { _Pragma("unroll") for (int m = 0; m < 4; ++m) _Pragma("unroll") for (int k = 0; k < 2; ++k) dst[m][k] = *(const PG8_LAS bf16x8*)(lds + PG8_SA(b, h) + aoff + m * 2048 + k * 1024); } while (0)
; #define PG8_MMA(ai, bj, At, Bt) do { __builtin_amdgcn_s_setprio(1); _Pragma("unroll") for (int m = 0; m < 4; ++m) _Pragma("unroll") for (int n = 0; n < 2; ++n) _Pragma("unroll") for (int k = 0; k < 2; ++k) \
;         acc[ai][bj][m][n] = __builtin_amdgcn_mfma_f32_16x16x32_bf16(Bt[n][k], At[m][k], acc[ai][bj][m][n], 0, 0, 0); __builtin_amdgcn_s_setprio(0); } while (0)
; #define PG8_WAIT_V(n) asm volatile("s_waitcnt vmcnt(" #n ")" ::: "memory")
; #define PG8_WAIT_L(n) asm volatile("s_waitcnt lgkmcnt(" #n ")" ::: "memory")
; #define PG8_BAR __builtin_amdgcn_s_barrier()
; #define PG8_SCHED __builtin_amdgcn_sched_barrier(0)
; template <class Epi, class Sched, bool ALIGN_EPI = false, bool SP2 = false>
; __device__ __forceinline__ void gemm_phase(PG8_LAS unsigned char* lds, const Gemm g, const Sched& S, const Epi& E) {
;     ...
;             PG8_WAIT_V(8); PG8_WAIT_L(0); PG8_BAR; PG8_MMA(0, 0, At, B0); PG8_MMA(0, 1, At, B1); PG8_BAR; PG8_SCHED;
;             PG8_LDA(At, 1, 1); PG8_STAGE(PG8_SB(1, 0), b3, voffB); PG8_STAGE(PG8_SB(1, 1), b3 + hstep, voffB); PG8_STAGE(PG8_SA(1, 0), a3, voffA);
;             PG8_WAIT_V(8); PG8_WAIT_L(0); PG8_BAR; PG8_MMA(1, 0, At, B0); PG8_MMA(1, 1, At, B1); PG8_BAR; PG8_SCHED;
	v_mfma_f32_16x16x32_bf16 v[132:135], v[116:119], v[204:207], v[132:135]
	v_mfma_f32_16x16x32_bf16 v[128:131], v[140:143], v[204:207], v[128:131]
	v_mfma_f32_16x16x32_bf16 v[108:111], v[116:119], v[216:219], v[108:111]
	v_mfma_f32_16x16x32_bf16 v[104:107], v[140:143], v[216:219], v[104:107]
	v_mfma_f32_16x16x32_bf16 v[92:95], v[116:119], v[224:227], v[92:95]
	v_mfma_f32_16x16x32_bf16 v[88:91], v[140:143], v[224:227], v[88:91]
	v_mfma_f32_16x16x32_bf16 v[76:79], v[116:119], v[232:235], v[76:79]
	v_mfma_f32_16x16x32_bf16 v[72:75], v[140:143], v[232:235], v[72:75]
	v_mfma_f32_16x16x32_bf16 v[132:135], v[136:139], v[208:211], v[132:135]
	v_mfma_f32_16x16x32_bf16 v[128:131], v[144:147], v[208:211], v[128:131]
	v_mfma_f32_16x16x32_bf16 v[108:111], v[136:139], v[220:223], v[108:111]
	v_mfma_f32_16x16x32_bf16 v[104:107], v[144:147], v[220:223], v[104:107]
	v_mfma_f32_16x16x32_bf16 v[92:95], v[136:139], v[228:231], v[92:95]
	v_mfma_f32_16x16x32_bf16 v[88:91], v[144:147], v[228:231], v[88:91]
	v_mfma_f32_16x16x32_bf16 v[76:79], v[136:139], v[236:239], v[76:79]
	v_mfma_f32_16x16x32_bf16 v[72:75], v[144:147], v[236:239], v[72:75]
	v_mfma_f32_16x16x32_bf16 v[124:127], v[148:151], v[204:207], v[124:127]
	v_mfma_f32_16x16x32_bf16 v[120:123], v[192:195], v[204:207], v[120:123]
	v_mfma_f32_16x16x32_bf16 v[100:103], v[148:151], v[216:219], v[100:103]
	v_mfma_f32_16x16x32_bf16 v[96:99], v[192:195], v[216:219], v[96:99]
	v_mfma_f32_16x16x32_bf16 v[84:87], v[148:151], v[224:227], v[84:87]
	v_mfma_f32_16x16x32_bf16 v[80:83], v[192:195], v[224:227], v[80:83]
	v_mfma_f32_16x16x32_bf16 v[68:71], v[148:151], v[232:235], v[68:71]
	v_mfma_f32_16x16x32_bf16 v[64:67], v[192:195], v[232:235], v[64:67]
	v_mfma_f32_16x16x32_bf16 v[124:127], v[188:191], v[208:211], v[124:127]
	v_mfma_f32_16x16x32_bf16 v[120:123], v[198:201], v[208:211], v[120:123]
	v_mfma_f32_16x16x32_bf16 v[100:103], v[188:191], v[220:223], v[100:103]
	v_mfma_f32_16x16x32_bf16 v[96:99], v[198:201], v[220:223], v[96:99]
	v_mfma_f32_16x16x32_bf16 v[84:87], v[188:191], v[228:231], v[84:87]
	v_mfma_f32_16x16x32_bf16 v[80:83], v[198:201], v[228:231], v[80:83]
	v_mfma_f32_16x16x32_bf16 v[68:71], v[188:191], v[236:239], v[68:71]
	v_mfma_f32_16x16x32_bf16 v[64:67], v[198:201], v[236:239], v[64:67]
	s_setprio 0
	s_barrier
	s_add_i32 s9, s9, s29
	s_add_i32 m0, s9, 0xffffff80
	ds_read_b128 v[204:207], v202 offset:49152
	ds_read_b128 v[208:211], v202 offset:50176
	ds_read_b128 v[216:219], v202 offset:51200
	ds_read_b128 v[220:223], v202 offset:52224
	ds_read_b128 v[224:227], v202 offset:53248
	ds_read_b128 v[228:231], v202 offset:54272
	global_load_lds_dwordx4 v[240:241], off offset:128
	s_add_i32 m0, s9, 0x1f80
	s_add_i32 s9, s10, s29
	global_load_lds_dwordx4 v[242:243], off offset:128
	s_add_i32 m0, s9, 0xffffff80
	ds_read_b128 v[236:239], v202 offset:56320
	global_load_lds_dwordx4 v[244:245], off offset:128
	s_add_i32 m0, s9, 0x1f80
	ds_read_b128 v[232:235], v202 offset:55296
	global_load_lds_dwordx4 v[214:215], off offset:128
	s_waitcnt vmcnt(6) lgkmcnt(0)
	s_setprio 1
	s_barrier
	v_mfma_f32_16x16x32_bf16 v[60:63], v[116:119], v[204:207], v[60:63]
	v_mfma_f32_16x16x32_bf16 v[56:59], v[140:143], v[204:207], v[56:59]
	v_mfma_f32_16x16x32_bf16 v[44:47], v[116:119], v[216:219], v[44:47]
	v_mfma_f32_16x16x32_bf16 v[40:43], v[140:143], v[216:219], v[40:43]
	s_add_i32 m0, s49, 0xffffff80
	v_mfma_f32_16x16x32_bf16 v[28:31], v[116:119], v[224:227], v[28:31]
	global_load_lds_dwordx4 v[246:247], off offset:128
	v_mfma_f32_16x16x32_bf16 v[24:27], v[140:143], v[224:227], v[24:27]
	v_mfma_f32_16x16x32_bf16 v[12:15], v[116:119], v[232:235], v[12:15]
	v_mfma_f32_16x16x32_bf16 v[8:11], v[140:143], v[232:235], v[8:11]
	v_mfma_f32_16x16x32_bf16 v[60:63], v[136:139], v[208:211], v[60:63]
	v_mfma_f32_16x16x32_bf16 v[56:59], v[144:147], v[208:211], v[56:59]
	s_add_i32 m0, s50, 0xffffff80
	v_mfma_f32_16x16x32_bf16 v[44:47], v[136:139], v[220:223], v[44:47]
	global_load_lds_dwordx4 v[248:249], off offset:128
	v_mfma_f32_16x16x32_bf16 v[40:43], v[144:147], v[220:223], v[40:43]
	v_mfma_f32_16x16x32_bf16 v[28:31], v[136:139], v[228:231], v[28:31]
	v_mfma_f32_16x16x32_bf16 v[24:27], v[144:147], v[228:231], v[24:27]
	v_mfma_f32_16x16x32_bf16 v[12:15], v[136:139], v[236:239], v[12:15]
	v_mfma_f32_16x16x32_bf16 v[8:11], v[144:147], v[236:239], v[8:11]
	v_mfma_f32_16x16x32_bf16 v[52:55], v[148:151], v[204:207], v[52:55]
	v_mfma_f32_16x16x32_bf16 v[48:51], v[192:195], v[204:207], v[48:51]
	v_mfma_f32_16x16x32_bf16 v[36:39], v[148:151], v[216:219], v[36:39]
	v_mfma_f32_16x16x32_bf16 v[32:35], v[192:195], v[216:219], v[32:35]
	v_mfma_f32_16x16x32_bf16 v[20:23], v[148:151], v[224:227], v[20:23]
	v_mfma_f32_16x16x32_bf16 v[16:19], v[192:195], v[224:227], v[16:19]
	v_mfma_f32_16x16x32_bf16 v[4:7], v[148:151], v[232:235], v[4:7]
	v_mfma_f32_16x16x32_bf16 v[0:3], v[192:195], v[232:235], v[0:3]
	v_mfma_f32_16x16x32_bf16 v[52:55], v[188:191], v[208:211], v[52:55]
	v_mfma_f32_16x16x32_bf16 v[48:51], v[198:201], v[208:211], v[48:51]
	v_mfma_f32_16x16x32_bf16 v[36:39], v[188:191], v[220:223], v[36:39]
	v_mfma_f32_16x16x32_bf16 v[32:35], v[198:201], v[220:223], v[32:35]
	v_mfma_f32_16x16x32_bf16 v[20:23], v[188:191], v[228:231], v[20:23]
	v_mfma_f32_16x16x32_bf16 v[16:19], v[198:201], v[228:231], v[16:19]
	v_mfma_f32_16x16x32_bf16 v[4:7], v[188:191], v[236:239], v[4:7]
	v_mfma_f32_16x16x32_bf16 v[0:3], v[198:201], v[236:239], v[0:3]
	s_setprio 0
	s_barrier
	v_lshl_add_u64 v[112:113], v[112:113], 0, s[26:27]
	s_cmp_ge_i32 s8, s51
	v_lshl_add_u64 v[114:115], v[114:115], 0, s[26:27]
	s_cbranch_scc0 .LBB0_722

; #define PG8_STAGE(bufoff, gbase, voff) do { _Pragma("unroll") for (int _i = 0; _i < 2; ++_i) \
;         __builtin_amdgcn_global_load_lds((const unsigned*)((const char*)(gbase) + (voff)[_i]), (PG8_LAS unsigned*)(lds + (bufoff) + ldsw + _i * 8192), 16, 0, 0); } while (0)
; #define PG8_LDA(dst, b, h) do { _Pragma("unroll") for (int m = 0; m < 4; ++m) _Pragma("unroll") for (int k = 0; k < 2; ++k) dst[m][k] = *(const PG8_LAS bf16x8*)(lds + PG8_SA(b, h) + aoff + m * 2048 + k * 1024); } while (0)
; #define PG8_LDB(dst, b, h) do { _Pragma("unroll") for (int n = 0; n < 2; ++n) _Pragma("unroll") for (int k = 0; k < 2; ++k) dst[n][k] = *(const PG8_LAS bf16x8*)(lds + PG8_SB(b, h) + boff + n * 2048 + k * 1024); } while (0)
; #define PG8_MMA(ai, bj, At, Bt) do { __builtin_amdgcn_s_setprio(1); _Pragma("unroll") for (int m = 0; m < 4; ++m) _Pragma("unroll") for (int n = 0; n < 2; ++n) _Pragma("unroll") for (int k = 0; k < 2; ++k) \
;         acc[ai][bj][m][n] = __builtin_amdgcn_mfma_f32_16x16x32_bf16(Bt[n][k], At[m][k], acc[ai][bj][m][n], 0, 0, 0); __builtin_amdgcn_s_setprio(0); } while (0)
; #define PG8_BAR __builtin_amdgcn_s_barrier()
; template <class Epi, class Sched, bool ALIGN_EPI = false, bool SP2 = false>
; __device__ __forceinline__ void gemm_phase(PG8_LAS unsigned char* lds, const Gemm g, const Sched& S, const Epi& E) {
;     ...
;         const bool has_next = S.next(ui + 1, nxt);
;         const char* nA = has_next ? (const char*)g.A + (size_t)nxt.pm * tstep : cA; const char* nB = has_next ? (const char*)g.Bt + (size_t)nxt.pn * tstep : cB;
;         for (int t = 0; t < nt; t += 2) {
;             const bool last = (t == nt - 2);
;             const char* a1 = cA + (size_t)(t + 1) * kstep;
;             const char* a2 = last ? nA : cA + (size_t)(t + 2) * kstep; const char* b2 = last ? nB : cB + (size_t)(t + 2) * kstep;
;             const char* a3 = a2 + kstep; const char* b3 = b2 + kstep;
;             if (last && has_next) S.a_ready(nxt);
;             if constexpr (SP2) {
;             PG8_LDB(B0, 0, 0); PG8_LDB(B1, 0, 1); PG8_SCHED; PG8_LDA(At, 0, 0); PG8_STAGE(PG8_SA(1, 1), a1 + hstep, voffA);
;             PG8_WAIT_V(8); PG8_WAIT_L(0); PG8_BAR; PG8_MMA(0, 0, At, B0); PG8_MMA(0, 1, At, B1); PG8_BAR; PG8_SCHED;
;             PG8_LDA(At, 0, 1); PG8_STAGE(PG8_SB(0, 0), b2, voffB); PG8_STAGE(PG8_SB(0, 1), b2 + hstep, voffB); PG8_STAGE(PG8_SA(0, 0), a2, voffA);
.LBB0_940:
	v_add_u32_e32 v188, s55, v199
	ds_read_b128 v[132:135], v201
	ds_read_b128 v[136:139], v201 offset:1024
	ds_read_b128 v[140:143], v201 offset:2048
	ds_read_b128 v[144:147], v201 offset:3072
	ds_read_b128 v[148:151], v188
	ds_read_b128 v[180:183], v188 offset:1024
	ds_read_b128 v[184:187], v188 offset:2048
	ds_read_b128 v[188:191], v188 offset:3072
	s_cmp_eq_u32 s48, s12
	v_lshl_add_u64 v[192:193], v[130:131], 0, s[22:23]
	s_cselect_b64 vcc, -1, 0
	s_add_i32 s12, s12, 2
	v_cndmask_b32_e32 v197, v193, v177, vcc
	v_cndmask_b32_e32 v196, v192, v176, vcc
	v_cndmask_b32_e32 v213, v129, v179, vcc
	v_cndmask_b32_e32 v212, v128, v178, vcc
	s_mov_b32 m0, s56
	v_lshl_add_u64 v[214:215], v[130:131], 0, v[172:173]
	ds_read_b128 v[192:195], v202
	ds_read_b128 v[204:207], v202 offset:1024
	ds_read_b128 v[208:211], v202 offset:2048
	ds_read_b128 v[216:219], v202 offset:3072
	ds_read_b128 v[220:223], v202 offset:4096
	ds_read_b128 v[224:227], v202 offset:5120
	ds_read_b128 v[228:231], v202 offset:6144
	ds_read_b128 v[232:235], v202 offset:7168
	global_load_lds_dwordx4 v[214:215], off
	s_mov_b32 m0, s57
	v_lshl_add_u64 v[214:215], v[130:131], 0, v[170:171]
	global_load_lds_dwordx4 v[214:215], off
	s_waitcnt vmcnt(8) lgkmcnt(0)
	s_setprio 1
	s_barrier
	v_mfma_f32_16x16x32_bf16 v[120:123], v[132:135], v[192:195], v[120:123]
	v_mfma_f32_16x16x32_bf16 v[124:127], v[140:143], v[192:195], v[124:127]
	v_mfma_f32_16x16x32_bf16 v[108:111], v[132:135], v[208:211], v[108:111]
	v_mfma_f32_16x16x32_bf16 v[104:107], v[140:143], v[208:211], v[104:107]
	v_mfma_f32_16x16x32_bf16 v[92:95], v[132:135], v[220:223], v[92:95]
	v_mfma_f32_16x16x32_bf16 v[88:91], v[140:143], v[220:223], v[88:91]
	v_mfma_f32_16x16x32_bf16 v[76:79], v[132:135], v[228:231], v[76:79]
	v_mfma_f32_16x16x32_bf16 v[72:75], v[140:143], v[228:231], v[72:75]
	v_mfma_f32_16x16x32_bf16 v[120:123], v[136:139], v[204:207], v[120:123]
	v_mfma_f32_16x16x32_bf16 v[124:127], v[144:147], v[204:207], v[124:127]
	v_mfma_f32_16x16x32_bf16 v[108:111], v[136:139], v[216:219], v[108:111]
	v_mfma_f32_16x16x32_bf16 v[104:107], v[144:147], v[216:219], v[104:107]
	v_mfma_f32_16x16x32_bf16 v[92:95], v[136:139], v[224:227], v[92:95]
	v_mfma_f32_16x16x32_bf16 v[88:91], v[144:147], v[224:227], v[88:91]
	v_mfma_f32_16x16x32_bf16 v[76:79], v[136:139], v[232:235], v[76:79]
	v_mfma_f32_16x16x32_bf16 v[72:75], v[144:147], v[232:235], v[72:75]
	v_mfma_f32_16x16x32_bf16 v[116:119], v[148:151], v[192:195], v[116:119]
	v_mfma_f32_16x16x32_bf16 v[112:115], v[184:187], v[192:195], v[112:115]
	v_mfma_f32_16x16x32_bf16 v[100:103], v[148:151], v[208:211], v[100:103]
	v_mfma_f32_16x16x32_bf16 v[96:99], v[184:187], v[208:211], v[96:99]
	v_mfma_f32_16x16x32_bf16 v[84:87], v[148:151], v[220:223], v[84:87]
	v_mfma_f32_16x16x32_bf16 v[80:83], v[184:187], v[220:223], v[80:83]
	v_mfma_f32_16x16x32_bf16 v[68:71], v[148:151], v[228:231], v[68:71]
	v_mfma_f32_16x16x32_bf16 v[64:67], v[184:187], v[228:231], v[64:67]
	v_mfma_f32_16x16x32_bf16 v[116:119], v[180:183], v[204:207], v[116:119]
	v_mfma_f32_16x16x32_bf16 v[112:115], v[188:191], v[204:207], v[112:115]
	v_mfma_f32_16x16x32_bf16 v[100:103], v[180:183], v[216:219], v[100:103]
	v_mfma_f32_16x16x32_bf16 v[96:99], v[188:191], v[216:219], v[96:99]
	v_mfma_f32_16x16x32_bf16 v[84:87], v[180:183], v[224:227], v[84:87]
	v_mfma_f32_16x16x32_bf16 v[80:83], v[188:191], v[224:227], v[80:83]
	v_mfma_f32_16x16x32_bf16 v[68:71], v[180:183], v[232:235], v[68:71]
	v_mfma_f32_16x16x32_bf16 v[64:67], v[188:191], v[232:235], v[64:67]
	s_setprio 0
	s_barrier
	s_mov_b32 m0, s58
	v_lshl_add_u64 v[214:215], v[212:213], 0, v[164:165]
	ds_read_b128 v[192:195], v202 offset:16384
	ds_read_b128 v[204:207], v202 offset:17408
	ds_read_b128 v[208:211], v202 offset:18432
	ds_read_b128 v[216:219], v202 offset:19456
	ds_read_b128 v[220:223], v202 offset:20480
	ds_read_b128 v[224:227], v202 offset:21504
	ds_read_b128 v[228:231], v202 offset:22528
	global_load_lds_dwordx4 v[214:215], off
	v_lshl_add_u64 v[236:237], v[212:213], 0, v[168:169]
	s_mov_b32 m0, s59
	v_lshl_add_u64 v[212:213], v[212:213], 0, s[14:15]
	s_add_i32 s13, s55, s30
	global_load_lds_dwordx4 v[236:237], off
	v_lshl_add_u64 v[238:239], v[212:213], 0, v[164:165]
	s_mov_b32 m0, s13
	v_lshl_add_u64 v[212:213], v[212:213], 0, v[168:169]
	global_load_lds_dwordx4 v[238:239], off
	s_add_i32 m0, s13, 0x2000
	ds_read_b128 v[232:235], v202 offset:23552
	global_load_lds_dwordx4 v[212:213], off
	s_waitcnt vmcnt(6) lgkmcnt(0)
	s_setprio 1
	s_barrier
; #define PG8_STAGE(bufoff, gbase, voff) do { _Pragma("unroll") for (int _i = 0; _i < 2; ++_i) \
;         __builtin_amdgcn_global_load_lds((const unsigned*)((const char*)(gbase) + (voff)[_i]), (PG8_LAS unsigned*)(lds + (bufoff) + ldsw + _i * 8192), 16, 0, 0); } while (0)
; #define PG8_LDA(dst, b, h) do { _Pragma("unroll") for (int m = 0; m < 4; ++m) _Pragma("unroll") for (int k = 0; k < 2; ++k) dst[m][k] = *(const PG8_LAS bf16x8*)(lds + PG8_SA(b, h) + aoff + m * 2048 + k * 1024); } while (0)
; #define PG8_LDB(dst, b, h) do { _Pragma("unroll") for (int n = 0; n < 2; ++n) _Pragma("unroll") for (int k = 0; k < 2; ++k) dst[n][k] = *(const PG8_LAS bf16x8*)(lds + PG8_SB(b, h) + boff + n * 2048 + k * 1024); } while (0)
; #define PG8_MMA(ai, bj, At, Bt) do { __builtin_amdgcn_s_setprio(1); _Pragma("unroll") for (int m = 0; m < 4; ++m) _Pragma("unroll") for (int n = 0; n < 2; ++n) _Pragma("unroll") for (int k = 0; k < 2; ++k) \
;         acc[ai][bj][m][n] = __builtin_amdgcn_mfma_f32_16x16x32_bf16(Bt[n][k], At[m][k], acc[ai][bj][m][n], 0, 0, 0); __builtin_amdgcn_s_setprio(0); } while (0)
; #define PG8_WAIT_V(n) asm volatile("s_waitcnt vmcnt(" #n ")" ::: "memory")
; #define PG8_WAIT_L(n) asm volatile("s_waitcnt lgkmcnt(" #n ")" ::: "memory")
; #define PG8_BAR __builtin_amdgcn_s_barrier()
; #define PG8_SCHED __builtin_amdgcn_sched_barrier(0)
; template <class Epi, class Sched, bool ALIGN_EPI = false, bool SP2 = false>
; __device__ __forceinline__ void gemm_phase(PG8_LAS unsigned char* lds, const Gemm g, const Sched& S, const Epi& E) {
;     ...
;             PG8_WAIT_V(8); PG8_WAIT_L(0); PG8_BAR; PG8_MMA(1, 0, At, B0); PG8_MMA(1, 1, At, B1); PG8_BAR; PG8_SCHED;
;             PG8_LDB(B0, 1, 0); PG8_LDB(B1, 1, 1); PG8_SCHED; PG8_LDA(At, 1, 0); PG8_STAGE(PG8_SA(0, 1), a2 + hstep, voffA);
;             PG8_WAIT_V(8); PG8_WAIT_L(0); PG8_BAR; PG8_MMA(0, 0, At, B0); PG8_MMA(0, 1, At, B1); PG8_BAR; PG8_SCHED;
	v_mfma_f32_16x16x32_bf16 v[60:63], v[132:135], v[192:195], v[60:63]
	v_mfma_f32_16x16x32_bf16 v[56:59], v[140:143], v[192:195], v[56:59]
	v_mfma_f32_16x16x32_bf16 v[44:47], v[132:135], v[208:211], v[44:47]
	v_mfma_f32_16x16x32_bf16 v[40:43], v[140:143], v[208:211], v[40:43]
	s_mov_b32 m0, s31
	v_lshl_add_u64 v[240:241], v[196:197], 0, v[162:163]
	v_mfma_f32_16x16x32_bf16 v[28:31], v[132:135], v[220:223], v[28:31]
	global_load_lds_dwordx4 v[240:241], off
	v_mfma_f32_16x16x32_bf16 v[24:27], v[140:143], v[220:223], v[24:27]
	v_mfma_f32_16x16x32_bf16 v[12:15], v[132:135], v[228:231], v[12:15]
	v_mfma_f32_16x16x32_bf16 v[8:11], v[140:143], v[228:231], v[8:11]
	v_mfma_f32_16x16x32_bf16 v[60:63], v[136:139], v[204:207], v[60:63]
	v_mfma_f32_16x16x32_bf16 v[56:59], v[144:147], v[204:207], v[56:59]
	s_mov_b32 m0, s34
	v_lshl_add_u64 v[242:243], v[196:197], 0, v[166:167]
	v_mfma_f32_16x16x32_bf16 v[44:47], v[136:139], v[216:219], v[44:47]
	global_load_lds_dwordx4 v[242:243], off
	v_mfma_f32_16x16x32_bf16 v[40:43], v[144:147], v[216:219], v[40:43]
	v_mfma_f32_16x16x32_bf16 v[28:31], v[136:139], v[224:227], v[28:31]
	v_mfma_f32_16x16x32_bf16 v[24:27], v[144:147], v[224:227], v[24:27]
	v_mfma_f32_16x16x32_bf16 v[12:15], v[136:139], v[232:235], v[12:15]
	v_mfma_f32_16x16x32_bf16 v[8:11], v[144:147], v[232:235], v[8:11]
	v_mfma_f32_16x16x32_bf16 v[52:55], v[148:151], v[192:195], v[52:55]
	v_mfma_f32_16x16x32_bf16 v[48:51], v[184:187], v[192:195], v[48:51]
	v_mfma_f32_16x16x32_bf16 v[36:39], v[148:151], v[208:211], v[36:39]
	v_mfma_f32_16x16x32_bf16 v[32:35], v[184:187], v[208:211], v[32:35]
	v_mfma_f32_16x16x32_bf16 v[20:23], v[148:151], v[220:223], v[20:23]
	v_mfma_f32_16x16x32_bf16 v[16:19], v[184:187], v[220:223], v[16:19]
	v_mfma_f32_16x16x32_bf16 v[4:7], v[148:151], v[228:231], v[4:7]
	v_mfma_f32_16x16x32_bf16 v[0:3], v[184:187], v[228:231], v[0:3]
	v_mfma_f32_16x16x32_bf16 v[52:55], v[180:183], v[204:207], v[52:55]
	v_mfma_f32_16x16x32_bf16 v[48:51], v[188:191], v[204:207], v[48:51]
	v_mfma_f32_16x16x32_bf16 v[36:39], v[180:183], v[216:219], v[36:39]
	v_mfma_f32_16x16x32_bf16 v[32:35], v[188:191], v[216:219], v[32:35]
	v_mfma_f32_16x16x32_bf16 v[20:23], v[180:183], v[224:227], v[20:23]
	v_mfma_f32_16x16x32_bf16 v[16:19], v[188:191], v[224:227], v[16:19]
	v_mfma_f32_16x16x32_bf16 v[4:7], v[180:183], v[232:235], v[4:7]
	v_mfma_f32_16x16x32_bf16 v[0:3], v[188:191], v[232:235], v[0:3]
	s_setprio 0
	s_barrier
	s_add_i32 s13, 0, 0x18000
	s_add_i32 s29, 0, 0x1c000
	v_add_u32_e32 v144, s13, v199
	v_add_u32_e32 v188, s29, v199
	ds_read_b128 v[132:135], v144
	ds_read_b128 v[136:139], v144 offset:1024
	ds_read_b128 v[140:143], v144 offset:2048
	ds_read_b128 v[144:147], v144 offset:3072
	ds_read_b128 v[148:151], v188
	ds_read_b128 v[180:183], v188 offset:1024
	ds_read_b128 v[184:187], v188 offset:2048
	ds_read_b128 v[188:191], v188 offset:3072
	v_lshl_add_u64 v[196:197], v[196:197], 0, s[14:15]
	s_mov_b32 m0, s35
	v_lshl_add_u64 v[244:245], v[196:197], 0, v[162:163]
	ds_read_b128 v[192:195], v202 offset:32768
	ds_read_b128 v[204:207], v202 offset:33792
	ds_read_b128 v[208:211], v202 offset:34816
	ds_read_b128 v[216:219], v202 offset:35840
	ds_read_b128 v[220:223], v202 offset:36864
	ds_read_b128 v[224:227], v202 offset:37888
	ds_read_b128 v[228:231], v202 offset:38912
	ds_read_b128 v[232:235], v202 offset:39936
	global_load_lds_dwordx4 v[244:245], off
	s_mov_b32 m0, s36
	v_lshl_add_u64 v[196:197], v[196:197], 0, v[166:167]
	global_load_lds_dwordx4 v[196:197], off
	s_waitcnt vmcnt(8) lgkmcnt(0)
	s_setprio 1
	s_barrier
; #define PG8_STAGE(bufoff, gbase, voff) do { _Pragma("unroll") for (int _i = 0; _i < 2; ++_i) \
;         __builtin_amdgcn_global_load_lds((const unsigned*)((const char*)(gbase) + (voff)[_i]), (PG8_LAS unsigned*)(lds + (bufoff) + ldsw + _i * 8192), 16, 0, 0); } while (0)
; #define PG8_LDA(dst, b, h) do { _Pragma("unroll") for (int m = 0; m < 4; ++m) _Pragma("unroll") for (int k = 0; k < 2; ++k) dst[m][k] = *(const PG8_LAS bf16x8*)(lds + PG8_SA(b, h) + aoff + m * 2048 + k * 1024); } while (0)
; #define PG8_MMA(ai, bj, At, Bt) do { __builtin_amdgcn_s_setprio(1); _Pragma("unroll") for (int m = 0; m < 4; ++m) _Pragma("unroll") for (int n = 0; n < 2; ++n) _Pragma("unroll") for (int k = 0; k < 2; ++k) \
;         acc[ai][bj][m][n] = __builtin_amdgcn_mfma_f32_16x16x32_bf16(Bt[n][k], At[m][k], acc[ai][bj][m][n], 0, 0, 0); __builtin_amdgcn_s_setprio(0); } while (0)
; #define PG8_WAIT_V(n) asm volatile("s_waitcnt vmcnt(" #n ")" ::: "memory")
; #define PG8_WAIT_L(n) asm volatile("s_waitcnt lgkmcnt(" #n ")" ::: "memory")
; #define PG8_BAR __builtin_amdgcn_s_barrier()
; #define PG8_SCHED __builtin_amdgcn_sched_barrier(0)
; template <class Epi, class Sched, bool ALIGN_EPI = false, bool SP2 = false>
; __device__ __forceinline__ void gemm_phase(PG8_LAS unsigned char* lds, const Gemm g, const Sched& S, const Epi& E) {
;     ...
;             PG8_WAIT_V(8); PG8_WAIT_L(0); PG8_BAR; PG8_MMA(0, 0, At, B0); PG8_MMA(0, 1, At, B1); PG8_BAR; PG8_SCHED;
;             PG8_LDA(At, 1, 1); PG8_STAGE(PG8_SB(1, 0), b3, voffB); PG8_STAGE(PG8_SB(1, 1), b3 + hstep, voffB); PG8_STAGE(PG8_SA(1, 0), a3, voffA);
;             PG8_WAIT_V(8); PG8_WAIT_L(0); PG8_BAR; PG8_MMA(1, 0, At, B0); PG8_MMA(1, 1, At, B1); PG8_BAR; PG8_SCHED;
	v_mfma_f32_16x16x32_bf16 v[120:123], v[132:135], v[192:195], v[120:123]
	v_mfma_f32_16x16x32_bf16 v[124:127], v[140:143], v[192:195], v[124:127]
	v_mfma_f32_16x16x32_bf16 v[108:111], v[132:135], v[208:211], v[108:111]
	v_mfma_f32_16x16x32_bf16 v[104:107], v[140:143], v[208:211], v[104:107]
	v_mfma_f32_16x16x32_bf16 v[92:95], v[132:135], v[220:223], v[92:95]
	v_mfma_f32_16x16x32_bf16 v[88:91], v[140:143], v[220:223], v[88:91]
	v_mfma_f32_16x16x32_bf16 v[76:79], v[132:135], v[228:231], v[76:79]
	v_mfma_f32_16x16x32_bf16 v[72:75], v[140:143], v[228:231], v[72:75]
	v_mfma_f32_16x16x32_bf16 v[120:123], v[136:139], v[204:207], v[120:123]
	v_mfma_f32_16x16x32_bf16 v[124:127], v[144:147], v[204:207], v[124:127]
	v_mfma_f32_16x16x32_bf16 v[108:111], v[136:139], v[216:219], v[108:111]
	v_mfma_f32_16x16x32_bf16 v[104:107], v[144:147], v[216:219], v[104:107]
	v_mfma_f32_16x16x32_bf16 v[92:95], v[136:139], v[224:227], v[92:95]
	v_mfma_f32_16x16x32_bf16 v[88:91], v[144:147], v[224:227], v[88:91]
	v_mfma_f32_16x16x32_bf16 v[76:79], v[136:139], v[232:235], v[76:79]
	v_mfma_f32_16x16x32_bf16 v[72:75], v[144:147], v[232:235], v[72:75]
	v_mfma_f32_16x16x32_bf16 v[116:119], v[148:151], v[192:195], v[116:119]
	v_mfma_f32_16x16x32_bf16 v[112:115], v[184:187], v[192:195], v[112:115]
	v_mfma_f32_16x16x32_bf16 v[100:103], v[148:151], v[208:211], v[100:103]
	v_mfma_f32_16x16x32_bf16 v[96:99], v[184:187], v[208:211], v[96:99]
	v_mfma_f32_16x16x32_bf16 v[84:87], v[148:151], v[220:223], v[84:87]
	v_mfma_f32_16x16x32_bf16 v[80:83], v[184:187], v[220:223], v[80:83]
	v_mfma_f32_16x16x32_bf16 v[68:71], v[148:151], v[228:231], v[68:71]
	v_mfma_f32_16x16x32_bf16 v[64:67], v[184:187], v[228:231], v[64:67]
	v_mfma_f32_16x16x32_bf16 v[116:119], v[180:183], v[204:207], v[116:119]
	v_mfma_f32_16x16x32_bf16 v[112:115], v[188:191], v[204:207], v[112:115]
	v_mfma_f32_16x16x32_bf16 v[100:103], v[180:183], v[216:219], v[100:103]
	v_mfma_f32_16x16x32_bf16 v[96:99], v[188:191], v[216:219], v[96:99]
	v_mfma_f32_16x16x32_bf16 v[84:87], v[180:183], v[224:227], v[84:87]
	v_mfma_f32_16x16x32_bf16 v[80:83], v[188:191], v[224:227], v[80:83]
	v_mfma_f32_16x16x32_bf16 v[68:71], v[180:183], v[232:235], v[68:71]
	v_mfma_f32_16x16x32_bf16 v[64:67], v[188:191], v[232:235], v[64:67]
	s_setprio 0
	s_barrier
	s_add_i32 s13, s13, s30
	s_add_i32 m0, s13, 0xffffff80
	ds_read_b128 v[192:195], v202 offset:49152
	ds_read_b128 v[204:207], v202 offset:50176
	ds_read_b128 v[208:211], v202 offset:51200
	ds_read_b128 v[216:219], v202 offset:52224
	ds_read_b128 v[220:223], v202 offset:53248
	ds_read_b128 v[224:227], v202 offset:54272
	global_load_lds_dwordx4 v[214:215], off offset:128
	s_add_i32 m0, s13, 0x1f80
	s_add_i32 s13, s29, s30
	global_load_lds_dwordx4 v[236:237], off offset:128
	s_add_i32 m0, s13, 0xffffff80
	ds_read_b128 v[232:235], v202 offset:56320
	global_load_lds_dwordx4 v[238:239], off offset:128
	s_add_i32 m0, s13, 0x1f80
	ds_read_b128 v[228:231], v202 offset:55296
	global_load_lds_dwordx4 v[212:213], off offset:128
	s_waitcnt vmcnt(6) lgkmcnt(0)
	s_setprio 1
	s_barrier
	v_mfma_f32_16x16x32_bf16 v[60:63], v[132:135], v[192:195], v[60:63]
	v_mfma_f32_16x16x32_bf16 v[56:59], v[140:143], v[192:195], v[56:59]
	v_mfma_f32_16x16x32_bf16 v[44:47], v[132:135], v[208:211], v[44:47]
	v_mfma_f32_16x16x32_bf16 v[40:43], v[140:143], v[208:211], v[40:43]
	s_add_i32 m0, s37, 0xffffff80
	v_mfma_f32_16x16x32_bf16 v[28:31], v[132:135], v[220:223], v[28:31]
	global_load_lds_dwordx4 v[240:241], off offset:128
	v_mfma_f32_16x16x32_bf16 v[24:27], v[140:143], v[220:223], v[24:27]
	v_mfma_f32_16x16x32_bf16 v[12:15], v[132:135], v[228:231], v[12:15]
	v_mfma_f32_16x16x32_bf16 v[8:11], v[140:143], v[228:231], v[8:11]
	v_mfma_f32_16x16x32_bf16 v[60:63], v[136:139], v[204:207], v[60:63]
	v_mfma_f32_16x16x32_bf16 v[56:59], v[144:147], v[204:207], v[56:59]
	s_add_i32 m0, s41, 0xffffff80
	v_mfma_f32_16x16x32_bf16 v[44:47], v[136:139], v[216:219], v[44:47]
	global_load_lds_dwordx4 v[242:243], off offset:128
	v_mfma_f32_16x16x32_bf16 v[40:43], v[144:147], v[216:219], v[40:43]
	v_mfma_f32_16x16x32_bf16 v[28:31], v[136:139], v[224:227], v[28:31]
	v_mfma_f32_16x16x32_bf16 v[24:27], v[144:147], v[224:227], v[24:27]
	v_mfma_f32_16x16x32_bf16 v[12:15], v[136:139], v[232:235], v[12:15]
	v_mfma_f32_16x16x32_bf16 v[8:11], v[144:147], v[232:235], v[8:11]
	v_mfma_f32_16x16x32_bf16 v[52:55], v[148:151], v[192:195], v[52:55]
	v_mfma_f32_16x16x32_bf16 v[48:51], v[184:187], v[192:195], v[48:51]
	v_mfma_f32_16x16x32_bf16 v[36:39], v[148:151], v[208:211], v[36:39]
	v_mfma_f32_16x16x32_bf16 v[32:35], v[184:187], v[208:211], v[32:35]
	v_mfma_f32_16x16x32_bf16 v[20:23], v[148:151], v[220:223], v[20:23]
	v_mfma_f32_16x16x32_bf16 v[16:19], v[184:187], v[220:223], v[16:19]
	v_mfma_f32_16x16x32_bf16 v[4:7], v[148:151], v[228:231], v[4:7]
	v_mfma_f32_16x16x32_bf16 v[0:3], v[184:187], v[228:231], v[0:3]
	v_mfma_f32_16x16x32_bf16 v[52:55], v[180:183], v[204:207], v[52:55]
	v_mfma_f32_16x16x32_bf16 v[48:51], v[188:191], v[204:207], v[48:51]
	v_mfma_f32_16x16x32_bf16 v[36:39], v[180:183], v[216:219], v[36:39]
	v_mfma_f32_16x16x32_bf16 v[32:35], v[188:191], v[216:219], v[32:35]
	v_mfma_f32_16x16x32_bf16 v[20:23], v[180:183], v[224:227], v[20:23]
	v_mfma_f32_16x16x32_bf16 v[16:19], v[188:191], v[224:227], v[16:19]
	v_mfma_f32_16x16x32_bf16 v[4:7], v[180:183], v[232:235], v[4:7]
	v_mfma_f32_16x16x32_bf16 v[0:3], v[188:191], v[232:235], v[0:3]
	s_setprio 0
	s_barrier
	v_lshl_add_u64 v[128:129], v[128:129], 0, s[26:27]
	s_cmp_ge_i32 s12, s47
	v_lshl_add_u64 v[130:131], v[130:131], 0, s[26:27]
	s_cbranch_scc0 .LBB0_940

; #define PG8_STAGE(bufoff, gbase, voff) do { _Pragma("unroll") for (int _i = 0; _i < 2; ++_i) \
;         __builtin_amdgcn_global_load_lds((const unsigned*)((const char*)(gbase) + (voff)[_i]), (PG8_LAS unsigned*)(lds + (bufoff) + ldsw + _i * 8192), 16, 0, 0); } while (0)
; #define PG8_LDA(dst, b, h) do { _Pragma("unroll") for (int m = 0; m < 4; ++m) _Pragma("unroll") for (int k = 0; k < 2; ++k) dst[m][k] = *(const PG8_LAS bf16x8*)(lds + PG8_SA(b, h) + aoff + m * 2048 + k * 1024); } while (0)
; #define PG8_LDB(dst, b, h) do { _Pragma("unroll") for (int n = 0; n < 2; ++n) _Pragma("unroll") for (int k = 0; k < 2; ++k) dst[n][k] = *(const PG8_LAS bf16x8*)(lds + PG8_SB(b, h) + boff + n * 2048 + k * 1024); } while (0)
; #define PG8_MMA(ai, bj, At, Bt) do { __builtin_amdgcn_s_setprio(1); _Pragma("unroll") for (int m = 0; m < 4; ++m) _Pragma("unroll") for (int n = 0; n < 2; ++n) _Pragma("unroll") for (int k = 0; k < 2; ++k) \
;         acc[ai][bj][m][n] = __builtin_amdgcn_mfma_f32_16x16x32_bf16(Bt[n][k], At[m][k], acc[ai][bj][m][n], 0, 0, 0); __builtin_amdgcn_s_setprio(0); } while (0)
; #define PG8_BAR __builtin_amdgcn_s_barrier()
; template <class Epi, class Sched, bool ALIGN_EPI = false, bool SP2 = false>
; __device__ __forceinline__ void gemm_phase(PG8_LAS unsigned char* lds, const Gemm g, const Sched& S, const Epi& E) {
;     ...
;         const bool has_next = S.next(ui + 1, nxt);
;         const char* nA = has_next ? (const char*)g.A + (size_t)nxt.pm * tstep : cA; const char* nB = has_next ? (const char*)g.Bt + (size_t)nxt.pn * tstep : cB;
;         for (int t = 0; t < nt; t += 2) {
;             const bool last = (t == nt - 2);
;             const char* a1 = cA + (size_t)(t + 1) * kstep;
;             const char* a2 = last ? nA : cA + (size_t)(t + 2) * kstep; const char* b2 = last ? nB : cB + (size_t)(t + 2) * kstep;
;             const char* a3 = a2 + kstep; const char* b3 = b2 + kstep;
;             if (last && has_next) S.a_ready(nxt);
;             if constexpr (SP2) {
;             PG8_LDB(B0, 0, 0); PG8_LDB(B1, 0, 1); PG8_SCHED; PG8_LDA(At, 0, 0); PG8_STAGE(PG8_SA(1, 1), a1 + hstep, voffA);
;             PG8_WAIT_V(8); PG8_WAIT_L(0); PG8_BAR; PG8_MMA(0, 0, At, B0); PG8_MMA(0, 1, At, B1); PG8_BAR; PG8_SCHED;
;             PG8_LDA(At, 0, 1); PG8_STAGE(PG8_SB(0, 0), b2, voffB); PG8_STAGE(PG8_SB(0, 1), b2 + hstep, voffB); PG8_STAGE(PG8_SA(0, 0), a2, voffA);
.LBB0_1021:
	v_add_u32_e32 v166, s55, v169
	v_add_u32_e32 v168, s56, v169
	ds_read_b128 v[162:165], v166
	ds_read_b128 v[182:185], v166 offset:1024
	ds_read_b128 v[186:189], v166 offset:2048
	ds_read_b128 v[190:193], v166 offset:3072
	ds_read_b128 v[194:197], v168
	ds_read_b128 v[198:201], v168 offset:1024
	ds_read_b128 v[202:205], v168 offset:2048
	ds_read_b128 v[206:209], v168 offset:3072
	s_cmp_eq_u32 s54, s10
	v_lshl_add_u64 v[172:173], v[160:161], 0, s[22:23]
	s_cselect_b64 vcc, -1, 0
	s_add_i32 s10, s10, 2
	v_cndmask_b32_e32 v173, v173, v153, vcc
	v_cndmask_b32_e32 v172, v172, v152, vcc
	v_cndmask_b32_e32 v215, v159, v155, vcc
	v_cndmask_b32_e32 v214, v158, v154, vcc
	s_mov_b32 m0, s57
	v_lshl_add_u64 v[244:245], v[160:161], 0, v[148:149]
	ds_read_b128 v[210:213], v179
	ds_read_b128 v[216:219], v179 offset:1024
	ds_read_b128 v[220:223], v179 offset:2048
	ds_read_b128 v[224:227], v179 offset:3072
	ds_read_b128 v[228:231], v179 offset:4096
	ds_read_b128 v[232:235], v179 offset:5120
	ds_read_b128 v[236:239], v179 offset:6144
	ds_read_b128 v[240:243], v179 offset:7168
	global_load_lds_dwordx4 v[244:245], off
	s_mov_b32 m0, s58
	v_lshl_add_u64 v[244:245], v[160:161], 0, v[146:147]
	global_load_lds_dwordx4 v[244:245], off
	s_waitcnt vmcnt(8) lgkmcnt(0)
	s_setprio 1
	s_barrier
	v_mfma_f32_16x16x32_bf16 v[124:127], v[162:165], v[210:213], v[124:127]
	v_mfma_f32_16x16x32_bf16 v[116:119], v[186:189], v[210:213], v[116:119]
	v_mfma_f32_16x16x32_bf16 v[108:111], v[162:165], v[220:223], v[108:111]
	v_mfma_f32_16x16x32_bf16 v[100:103], v[186:189], v[220:223], v[100:103]
	v_mfma_f32_16x16x32_bf16 v[92:95], v[162:165], v[228:231], v[92:95]
	v_mfma_f32_16x16x32_bf16 v[84:87], v[186:189], v[228:231], v[84:87]
	v_mfma_f32_16x16x32_bf16 v[76:79], v[162:165], v[236:239], v[76:79]
	v_mfma_f32_16x16x32_bf16 v[68:71], v[186:189], v[236:239], v[68:71]
	v_mfma_f32_16x16x32_bf16 v[124:127], v[182:185], v[216:219], v[124:127]
	v_mfma_f32_16x16x32_bf16 v[116:119], v[190:193], v[216:219], v[116:119]
	v_mfma_f32_16x16x32_bf16 v[108:111], v[182:185], v[224:227], v[108:111]
	v_mfma_f32_16x16x32_bf16 v[100:103], v[190:193], v[224:227], v[100:103]
	v_mfma_f32_16x16x32_bf16 v[92:95], v[182:185], v[232:235], v[92:95]
	v_mfma_f32_16x16x32_bf16 v[84:87], v[190:193], v[232:235], v[84:87]
	v_mfma_f32_16x16x32_bf16 v[76:79], v[182:185], v[240:243], v[76:79]
	v_mfma_f32_16x16x32_bf16 v[68:71], v[190:193], v[240:243], v[68:71]
	v_mfma_f32_16x16x32_bf16 v[120:123], v[194:197], v[210:213], v[120:123]
	v_mfma_f32_16x16x32_bf16 v[112:115], v[202:205], v[210:213], v[112:115]
	v_mfma_f32_16x16x32_bf16 v[104:107], v[194:197], v[220:223], v[104:107]
	v_mfma_f32_16x16x32_bf16 v[96:99], v[202:205], v[220:223], v[96:99]
	v_mfma_f32_16x16x32_bf16 v[88:91], v[194:197], v[228:231], v[88:91]
	v_mfma_f32_16x16x32_bf16 v[80:83], v[202:205], v[228:231], v[80:83]
	v_mfma_f32_16x16x32_bf16 v[72:75], v[194:197], v[236:239], v[72:75]
	v_mfma_f32_16x16x32_bf16 v[64:67], v[202:205], v[236:239], v[64:67]
	v_mfma_f32_16x16x32_bf16 v[120:123], v[198:201], v[216:219], v[120:123]
	v_mfma_f32_16x16x32_bf16 v[112:115], v[206:209], v[216:219], v[112:115]
	v_mfma_f32_16x16x32_bf16 v[104:107], v[198:201], v[224:227], v[104:107]
	v_mfma_f32_16x16x32_bf16 v[96:99], v[206:209], v[224:227], v[96:99]
	v_mfma_f32_16x16x32_bf16 v[88:91], v[198:201], v[232:235], v[88:91]
	v_mfma_f32_16x16x32_bf16 v[80:83], v[206:209], v[232:235], v[80:83]
	v_mfma_f32_16x16x32_bf16 v[72:75], v[198:201], v[240:243], v[72:75]
	v_mfma_f32_16x16x32_bf16 v[64:67], v[206:209], v[240:243], v[64:67]
	s_setprio 0
	s_barrier
	s_mov_b32 m0, s61
	v_lshl_add_u64 v[244:245], v[214:215], 0, v[138:139]
	ds_read_b128 v[210:213], v179 offset:16384
	ds_read_b128 v[216:219], v179 offset:17408
	ds_read_b128 v[220:223], v179 offset:18432
	ds_read_b128 v[224:227], v179 offset:19456
	ds_read_b128 v[228:231], v179 offset:20480
	ds_read_b128 v[232:235], v179 offset:21504
	ds_read_b128 v[236:239], v179 offset:22528
	global_load_lds_dwordx4 v[244:245], off
	v_lshl_add_u64 v[246:247], v[214:215], 0, v[134:135]
	s_mov_b32 m0, s62
	v_lshl_add_u64 v[214:215], v[214:215], 0, s[14:15]
	global_load_lds_dwordx4 v[246:247], off
	v_lshl_add_u64 v[248:249], v[214:215], 0, v[138:139]
	s_mov_b32 m0, s63
	v_lshl_add_u64 v[214:215], v[214:215], 0, v[134:135]
	global_load_lds_dwordx4 v[248:249], off
	s_add_i32 m0, s63, 0x2000
	ds_read_b128 v[240:243], v179 offset:23552
	global_load_lds_dwordx4 v[214:215], off
	s_waitcnt vmcnt(6) lgkmcnt(0)
	s_setprio 1
	s_barrier
; #define PG8_STAGE(bufoff, gbase, voff) do { _Pragma("unroll") for (int _i = 0; _i < 2; ++_i) \
;         __builtin_amdgcn_global_load_lds((const unsigned*)((const char*)(gbase) + (voff)[_i]), (PG8_LAS unsigned*)(lds + (bufoff) + ldsw + _i * 8192), 16, 0, 0); } while (0)
; #define PG8_LDA(dst, b, h) do { _Pragma("unroll") for (int m = 0; m < 4; ++m) _Pragma("unroll") for (int k = 0; k < 2; ++k) dst[m][k] = *(const PG8_LAS bf16x8*)(lds + PG8_SA(b, h) + aoff + m * 2048 + k * 1024); } while (0)
; #define PG8_LDB(dst, b, h) do { _Pragma("unroll") for (int n = 0; n < 2; ++n) _Pragma("unroll") for (int k = 0; k < 2; ++k) dst[n][k] = *(const PG8_LAS bf16x8*)(lds + PG8_SB(b, h) + boff + n * 2048 + k * 1024); } while (0)
; #define PG8_MMA(ai, bj, At, Bt) do { __builtin_amdgcn_s_setprio(1); _Pragma("unroll") for (int m = 0; m < 4; ++m) _Pragma("unroll") for (int n = 0; n < 2; ++n) _Pragma("unroll") for (int k = 0; k < 2; ++k) \
;         acc[ai][bj][m][n] = __builtin_amdgcn_mfma_f32_16x16x32_bf16(Bt[n][k], At[m][k], acc[ai][bj][m][n], 0, 0, 0); __builtin_amdgcn_s_setprio(0); } while (0)
; #define PG8_WAIT_V(n) asm volatile("s_waitcnt vmcnt(" #n ")" ::: "memory")
; #define PG8_WAIT_L(n) asm volatile("s_waitcnt lgkmcnt(" #n ")" ::: "memory")
; #define PG8_BAR __builtin_amdgcn_s_barrier()
; #define PG8_SCHED __builtin_amdgcn_sched_barrier(0)
; template <class Epi, class Sched, bool ALIGN_EPI = false, bool SP2 = false>
; __device__ __forceinline__ void gemm_phase(PG8_LAS unsigned char* lds, const Gemm g, const Sched& S, const Epi& E) {
;     ...
;             PG8_WAIT_V(8); PG8_WAIT_L(0); PG8_BAR; PG8_MMA(1, 0, At, B0); PG8_MMA(1, 1, At, B1); PG8_BAR; PG8_SCHED;
;             PG8_LDB(B0, 1, 0); PG8_LDB(B1, 1, 1); PG8_SCHED; PG8_LDA(At, 1, 0); PG8_STAGE(PG8_SA(0, 1), a2 + hstep, voffA);
;             PG8_WAIT_V(8); PG8_WAIT_L(0); PG8_BAR; PG8_MMA(0, 0, At, B0); PG8_MMA(0, 1, At, B1); PG8_BAR; PG8_SCHED;
	v_mfma_f32_16x16x32_bf16 v[60:63], v[162:165], v[210:213], v[60:63]
	v_mfma_f32_16x16x32_bf16 v[52:55], v[186:189], v[210:213], v[52:55]
	v_mfma_f32_16x16x32_bf16 v[44:47], v[162:165], v[220:223], v[44:47]
	v_mfma_f32_16x16x32_bf16 v[36:39], v[186:189], v[220:223], v[36:39]
	s_mov_b32 m0, s46
	v_lshl_add_u64 v[250:251], v[172:173], 0, v[140:141]
	v_mfma_f32_16x16x32_bf16 v[28:31], v[162:165], v[228:231], v[28:31]
	global_load_lds_dwordx4 v[250:251], off
	v_mfma_f32_16x16x32_bf16 v[20:23], v[186:189], v[228:231], v[20:23]
	v_mfma_f32_16x16x32_bf16 v[12:15], v[162:165], v[236:239], v[12:15]
	v_mfma_f32_16x16x32_bf16 v[4:7], v[186:189], v[236:239], v[4:7]
	v_mfma_f32_16x16x32_bf16 v[60:63], v[182:185], v[216:219], v[60:63]
	v_mfma_f32_16x16x32_bf16 v[52:55], v[190:193], v[216:219], v[52:55]
	s_mov_b32 m0, s47
	v_lshl_add_u64 v[252:253], v[172:173], 0, v[136:137]
	v_mfma_f32_16x16x32_bf16 v[44:47], v[182:185], v[224:227], v[44:47]
	global_load_lds_dwordx4 v[252:253], off
	v_mfma_f32_16x16x32_bf16 v[36:39], v[190:193], v[224:227], v[36:39]
	v_mfma_f32_16x16x32_bf16 v[28:31], v[182:185], v[232:235], v[28:31]
	v_mfma_f32_16x16x32_bf16 v[20:23], v[190:193], v[232:235], v[20:23]
	v_mfma_f32_16x16x32_bf16 v[12:15], v[182:185], v[240:243], v[12:15]
	v_mfma_f32_16x16x32_bf16 v[4:7], v[190:193], v[240:243], v[4:7]
	v_mfma_f32_16x16x32_bf16 v[56:59], v[194:197], v[210:213], v[56:59]
	v_mfma_f32_16x16x32_bf16 v[48:51], v[202:205], v[210:213], v[48:51]
	v_mfma_f32_16x16x32_bf16 v[40:43], v[194:197], v[220:223], v[40:43]
	v_mfma_f32_16x16x32_bf16 v[32:35], v[202:205], v[220:223], v[32:35]
	v_mfma_f32_16x16x32_bf16 v[24:27], v[194:197], v[228:231], v[24:27]
	v_mfma_f32_16x16x32_bf16 v[16:19], v[202:205], v[228:231], v[16:19]
	v_mfma_f32_16x16x32_bf16 v[8:11], v[194:197], v[236:239], v[8:11]
	v_mfma_f32_16x16x32_bf16 v[0:3], v[202:205], v[236:239], v[0:3]
	v_mfma_f32_16x16x32_bf16 v[56:59], v[198:201], v[216:219], v[56:59]
	v_mfma_f32_16x16x32_bf16 v[48:51], v[206:209], v[216:219], v[48:51]
	v_mfma_f32_16x16x32_bf16 v[40:43], v[198:201], v[224:227], v[40:43]
	v_mfma_f32_16x16x32_bf16 v[32:35], v[206:209], v[224:227], v[32:35]
	v_mfma_f32_16x16x32_bf16 v[24:27], v[198:201], v[232:235], v[24:27]
	v_mfma_f32_16x16x32_bf16 v[16:19], v[206:209], v[232:235], v[16:19]
	v_mfma_f32_16x16x32_bf16 v[8:11], v[198:201], v[240:243], v[8:11]
	v_mfma_f32_16x16x32_bf16 v[0:3], v[206:209], v[240:243], v[0:3]
	s_setprio 0
	s_barrier
	s_add_i32 s11, 0, 0x18000
	v_add_u32_e32 v166, s11, v169
	s_add_i32 s13, 0, 0x1c000
	ds_read_b128 v[162:165], v166
	ds_read_b128 v[182:185], v166 offset:1024
	ds_read_b128 v[186:189], v166 offset:2048
	ds_read_b128 v[190:193], v166 offset:3072
	v_add_u32_e32 v166, s13, v169
	ds_read_b128 v[194:197], v166
	ds_read_b128 v[198:201], v166 offset:1024
	ds_read_b128 v[202:205], v166 offset:2048
	ds_read_b128 v[206:209], v166 offset:3072
	v_lshl_add_u64 v[172:173], v[172:173], 0, s[14:15]
	s_mov_b32 m0, s48
	v_lshl_add_u64 v[170:171], v[172:173], 0, v[140:141]
	ds_read_b128 v[210:213], v179 offset:32768
	ds_read_b128 v[216:219], v179 offset:33792
	ds_read_b128 v[220:223], v179 offset:34816
	ds_read_b128 v[224:227], v179 offset:35840
	ds_read_b128 v[228:231], v179 offset:36864
	ds_read_b128 v[232:235], v179 offset:37888
	ds_read_b128 v[236:239], v179 offset:38912
	ds_read_b128 v[240:243], v179 offset:39936
	global_load_lds_dwordx4 v[170:171], off
	s_mov_b32 m0, s49
	v_lshl_add_u64 v[170:171], v[172:173], 0, v[136:137]
	global_load_lds_dwordx4 v[170:171], off
	s_waitcnt vmcnt(8) lgkmcnt(0)
	s_setprio 1
	s_barrier
; #define PG8_STAGE(bufoff, gbase, voff) do { _Pragma("unroll") for (int _i = 0; _i < 2; ++_i) \
;         __builtin_amdgcn_global_load_lds((const unsigned*)((const char*)(gbase) + (voff)[_i]), (PG8_LAS unsigned*)(lds + (bufoff) + ldsw + _i * 8192), 16, 0, 0); } while (0)
; #define PG8_LDA(dst, b, h) do { _Pragma("unroll") for (int m = 0; m < 4; ++m) _Pragma("unroll") for (int k = 0; k < 2; ++k) dst[m][k] = *(const PG8_LAS bf16x8*)(lds + PG8_SA(b, h) + aoff + m * 2048 + k * 1024); } while (0)
; #define PG8_MMA(ai, bj, At, Bt) do { __builtin_amdgcn_s_setprio(1); _Pragma("unroll") for (int m = 0; m < 4; ++m) _Pragma("unroll") for (int n = 0; n < 2; ++n) _Pragma("unroll") for (int k = 0; k < 2; ++k) \
;         acc[ai][bj][m][n] = __builtin_amdgcn_mfma_f32_16x16x32_bf16(Bt[n][k], At[m][k], acc[ai][bj][m][n], 0, 0, 0); __builtin_amdgcn_s_setprio(0); } while (0)
; #define PG8_WAIT_V(n) asm volatile("s_waitcnt vmcnt(" #n ")" ::: "memory")
; #define PG8_WAIT_L(n) asm volatile("s_waitcnt lgkmcnt(" #n ")" ::: "memory")
; #define PG8_BAR __builtin_amdgcn_s_barrier()
; #define PG8_SCHED __builtin_amdgcn_sched_barrier(0)
; template <class Epi, class Sched, bool ALIGN_EPI = false, bool SP2 = false>
; __device__ __forceinline__ void gemm_phase(PG8_LAS unsigned char* lds, const Gemm g, const Sched& S, const Epi& E) {
;     ...
;             PG8_WAIT_V(8); PG8_WAIT_L(0); PG8_BAR; PG8_MMA(0, 0, At, B0); PG8_MMA(0, 1, At, B1); PG8_BAR; PG8_SCHED;
;             PG8_LDA(At, 1, 1); PG8_STAGE(PG8_SB(1, 0), b3, voffB); PG8_STAGE(PG8_SB(1, 1), b3 + hstep, voffB); PG8_STAGE(PG8_SA(1, 0), a3, voffA);
;             PG8_WAIT_V(8); PG8_WAIT_L(0); PG8_BAR; PG8_MMA(1, 0, At, B0); PG8_MMA(1, 1, At, B1); PG8_BAR; PG8_SCHED;
	v_mfma_f32_16x16x32_bf16 v[124:127], v[162:165], v[210:213], v[124:127]
	v_mfma_f32_16x16x32_bf16 v[116:119], v[186:189], v[210:213], v[116:119]
	v_mfma_f32_16x16x32_bf16 v[108:111], v[162:165], v[220:223], v[108:111]
	v_mfma_f32_16x16x32_bf16 v[100:103], v[186:189], v[220:223], v[100:103]
	v_mfma_f32_16x16x32_bf16 v[92:95], v[162:165], v[228:231], v[92:95]
	v_mfma_f32_16x16x32_bf16 v[84:87], v[186:189], v[228:231], v[84:87]
	v_mfma_f32_16x16x32_bf16 v[76:79], v[162:165], v[236:239], v[76:79]
	v_mfma_f32_16x16x32_bf16 v[68:71], v[186:189], v[236:239], v[68:71]
	v_mfma_f32_16x16x32_bf16 v[124:127], v[182:185], v[216:219], v[124:127]
	v_mfma_f32_16x16x32_bf16 v[116:119], v[190:193], v[216:219], v[116:119]
	v_mfma_f32_16x16x32_bf16 v[108:111], v[182:185], v[224:227], v[108:111]
	v_mfma_f32_16x16x32_bf16 v[100:103], v[190:193], v[224:227], v[100:103]
	v_mfma_f32_16x16x32_bf16 v[92:95], v[182:185], v[232:235], v[92:95]
	v_mfma_f32_16x16x32_bf16 v[84:87], v[190:193], v[232:235], v[84:87]
	v_mfma_f32_16x16x32_bf16 v[76:79], v[182:185], v[240:243], v[76:79]
	v_mfma_f32_16x16x32_bf16 v[68:71], v[190:193], v[240:243], v[68:71]
	v_mfma_f32_16x16x32_bf16 v[120:123], v[194:197], v[210:213], v[120:123]
	v_mfma_f32_16x16x32_bf16 v[112:115], v[202:205], v[210:213], v[112:115]
	v_mfma_f32_16x16x32_bf16 v[104:107], v[194:197], v[220:223], v[104:107]
	v_mfma_f32_16x16x32_bf16 v[96:99], v[202:205], v[220:223], v[96:99]
	v_mfma_f32_16x16x32_bf16 v[88:91], v[194:197], v[228:231], v[88:91]
	v_mfma_f32_16x16x32_bf16 v[80:83], v[202:205], v[228:231], v[80:83]
	v_mfma_f32_16x16x32_bf16 v[72:75], v[194:197], v[236:239], v[72:75]
	v_mfma_f32_16x16x32_bf16 v[64:67], v[202:205], v[236:239], v[64:67]
	v_mfma_f32_16x16x32_bf16 v[120:123], v[198:201], v[216:219], v[120:123]
	v_mfma_f32_16x16x32_bf16 v[112:115], v[206:209], v[216:219], v[112:115]
	v_mfma_f32_16x16x32_bf16 v[104:107], v[198:201], v[224:227], v[104:107]
	v_mfma_f32_16x16x32_bf16 v[96:99], v[206:209], v[224:227], v[96:99]
	v_mfma_f32_16x16x32_bf16 v[88:91], v[198:201], v[232:235], v[88:91]
	v_mfma_f32_16x16x32_bf16 v[80:83], v[206:209], v[232:235], v[80:83]
	v_mfma_f32_16x16x32_bf16 v[72:75], v[198:201], v[240:243], v[72:75]
	v_mfma_f32_16x16x32_bf16 v[64:67], v[206:209], v[240:243], v[64:67]
	s_setprio 0
	s_barrier
	s_add_i32 s11, s11, s29
	s_add_i32 m0, s11, 0xffffff80
	ds_read_b128 v[210:213], v179 offset:49152
	ds_read_b128 v[216:219], v179 offset:50176
	ds_read_b128 v[220:223], v179 offset:51200
	ds_read_b128 v[224:227], v179 offset:52224
	ds_read_b128 v[228:231], v179 offset:53248
	ds_read_b128 v[232:235], v179 offset:54272
	global_load_lds_dwordx4 v[244:245], off offset:128
	s_add_i32 m0, s11, 0x1f80
	s_add_i32 s11, s13, s29
	global_load_lds_dwordx4 v[246:247], off offset:128
	s_add_i32 m0, s11, 0xffffff80
	ds_read_b128 v[240:243], v179 offset:56320
	global_load_lds_dwordx4 v[248:249], off offset:128
	s_add_i32 m0, s11, 0x1f80
	ds_read_b128 v[236:239], v179 offset:55296
	global_load_lds_dwordx4 v[214:215], off offset:128
	s_waitcnt vmcnt(6) lgkmcnt(0)
	s_setprio 1
	s_barrier
	v_mfma_f32_16x16x32_bf16 v[60:63], v[162:165], v[210:213], v[60:63]
	v_mfma_f32_16x16x32_bf16 v[52:55], v[186:189], v[210:213], v[52:55]
	v_mfma_f32_16x16x32_bf16 v[44:47], v[162:165], v[220:223], v[44:47]
	v_mfma_f32_16x16x32_bf16 v[36:39], v[186:189], v[220:223], v[36:39]
	s_add_i32 m0, s50, 0xffffff80
	v_mfma_f32_16x16x32_bf16 v[28:31], v[162:165], v[228:231], v[28:31]
	global_load_lds_dwordx4 v[250:251], off offset:128
	v_mfma_f32_16x16x32_bf16 v[20:23], v[186:189], v[228:231], v[20:23]
	v_mfma_f32_16x16x32_bf16 v[12:15], v[162:165], v[236:239], v[12:15]
	v_mfma_f32_16x16x32_bf16 v[4:7], v[186:189], v[236:239], v[4:7]
	v_mfma_f32_16x16x32_bf16 v[60:63], v[182:185], v[216:219], v[60:63]
	v_mfma_f32_16x16x32_bf16 v[52:55], v[190:193], v[216:219], v[52:55]
	s_add_i32 m0, s51, 0xffffff80
	v_mfma_f32_16x16x32_bf16 v[44:47], v[182:185], v[224:227], v[44:47]
	global_load_lds_dwordx4 v[252:253], off offset:128
	v_mfma_f32_16x16x32_bf16 v[36:39], v[190:193], v[224:227], v[36:39]
	v_mfma_f32_16x16x32_bf16 v[28:31], v[182:185], v[232:235], v[28:31]
	v_mfma_f32_16x16x32_bf16 v[20:23], v[190:193], v[232:235], v[20:23]
	v_mfma_f32_16x16x32_bf16 v[12:15], v[182:185], v[240:243], v[12:15]
	v_mfma_f32_16x16x32_bf16 v[4:7], v[190:193], v[240:243], v[4:7]
	v_mfma_f32_16x16x32_bf16 v[56:59], v[194:197], v[210:213], v[56:59]
	v_mfma_f32_16x16x32_bf16 v[48:51], v[202:205], v[210:213], v[48:51]
	v_mfma_f32_16x16x32_bf16 v[40:43], v[194:197], v[220:223], v[40:43]
	v_mfma_f32_16x16x32_bf16 v[32:35], v[202:205], v[220:223], v[32:35]
	v_mfma_f32_16x16x32_bf16 v[24:27], v[194:197], v[228:231], v[24:27]
	v_mfma_f32_16x16x32_bf16 v[16:19], v[202:205], v[228:231], v[16:19]
	v_mfma_f32_16x16x32_bf16 v[8:11], v[194:197], v[236:239], v[8:11]
	v_mfma_f32_16x16x32_bf16 v[0:3], v[202:205], v[236:239], v[0:3]
	v_mfma_f32_16x16x32_bf16 v[56:59], v[198:201], v[216:219], v[56:59]
	v_mfma_f32_16x16x32_bf16 v[48:51], v[206:209], v[216:219], v[48:51]
	v_mfma_f32_16x16x32_bf16 v[40:43], v[198:201], v[224:227], v[40:43]
	v_mfma_f32_16x16x32_bf16 v[32:35], v[206:209], v[224:227], v[32:35]
	v_mfma_f32_16x16x32_bf16 v[24:27], v[198:201], v[232:235], v[24:27]
	v_mfma_f32_16x16x32_bf16 v[16:19], v[206:209], v[232:235], v[16:19]
	v_mfma_f32_16x16x32_bf16 v[8:11], v[198:201], v[240:243], v[8:11]
	v_mfma_f32_16x16x32_bf16 v[0:3], v[206:209], v[240:243], v[0:3]
	s_setprio 0
	s_barrier
	v_lshl_add_u64 v[158:159], v[158:159], 0, s[26:27]
	s_cmp_ge_i32 s10, s52
	v_lshl_add_u64 v[160:161], v[160:161], 0, s[26:27]
	s_cbranch_scc0 .LBB0_1021

; #define PG8_STAGE(bufoff, gbase, voff) do { _Pragma("unroll") for (int _i = 0; _i < 2; ++_i) \
;         __builtin_amdgcn_global_load_lds((const unsigned*)((const char*)(gbase) + (voff)[_i]), (PG8_LAS unsigned*)(lds + (bufoff) + ldsw + _i * 8192), 16, 0, 0); } while (0)
; #define PG8_LDA(dst, b, h) do { _Pragma("unroll") for (int m = 0; m < 4; ++m) _Pragma("unroll") for (int k = 0; k < 2; ++k) dst[m][k] = *(const PG8_LAS bf16x8*)(lds + PG8_SA(b, h) + aoff + m * 2048 + k * 1024); } while (0)
; #define PG8_LDB(dst, b, h) do { _Pragma("unroll") for (int n = 0; n < 2; ++n) _Pragma("unroll") for (int k = 0; k < 2; ++k) dst[n][k] = *(const PG8_LAS bf16x8*)(lds + PG8_SB(b, h) + boff + n * 2048 + k * 1024); } while (0)
; #define PG8_MMA(ai, bj, At, Bt) do { __builtin_amdgcn_s_setprio(1); _Pragma("unroll") for (int m = 0; m < 4; ++m) _Pragma("unroll") for (int n = 0; n < 2; ++n) _Pragma("unroll") for (int k = 0; k < 2; ++k) \
;         acc[ai][bj][m][n] = __builtin_amdgcn_mfma_f32_16x16x32_bf16(Bt[n][k], At[m][k], acc[ai][bj][m][n], 0, 0, 0); __builtin_amdgcn_s_setprio(0); } while (0)
; #define PG8_BAR __builtin_amdgcn_s_barrier()
; template <class Epi, class Sched, bool ALIGN_EPI = false, bool SP2 = false>
; __device__ __forceinline__ void gemm_phase(PG8_LAS unsigned char* lds, const Gemm g, const Sched& S, const Epi& E) {
;     ...
;         const bool has_next = S.next(ui + 1, nxt);
;         const char* nA = has_next ? (const char*)g.A + (size_t)nxt.pm * tstep : cA; const char* nB = has_next ? (const char*)g.Bt + (size_t)nxt.pn * tstep : cB;
;         for (int t = 0; t < nt; t += 2) {
;             const bool last = (t == nt - 2);
;             const char* a1 = cA + (size_t)(t + 1) * kstep;
;             const char* a2 = last ? nA : cA + (size_t)(t + 2) * kstep; const char* b2 = last ? nB : cB + (size_t)(t + 2) * kstep;
;             const char* a3 = a2 + kstep; const char* b3 = b2 + kstep;
;             if (last && has_next) S.a_ready(nxt);
;             if constexpr (SP2) {
;             PG8_LDB(B0, 0, 0); PG8_LDB(B1, 0, 1); PG8_SCHED; PG8_LDA(At, 0, 0); PG8_STAGE(PG8_SA(1, 1), a1 + hstep, voffA);
;             PG8_WAIT_V(8); PG8_WAIT_L(0); PG8_BAR; PG8_MMA(0, 0, At, B0); PG8_MMA(0, 1, At, B1); PG8_BAR; PG8_SCHED;
;             PG8_LDA(At, 0, 1); PG8_STAGE(PG8_SB(0, 0), b2, voffB); PG8_STAGE(PG8_SB(0, 1), b2 + hstep, voffB); PG8_STAGE(PG8_SA(0, 0), a2, voffA);
.LBB0_1169:
	v_add_u32_e32 v192, s52, v161
	ds_read_b128 v[164:167], v162
	ds_read_b128 v[168:171], v162 offset:1024
	ds_read_b128 v[172:175], v162 offset:2048
	ds_read_b128 v[176:179], v162 offset:3072
	ds_read_b128 v[180:183], v192
	ds_read_b128 v[184:187], v192 offset:1024
	ds_read_b128 v[188:191], v192 offset:2048
	ds_read_b128 v[192:195], v192 offset:3072
	s_cmp_eq_u32 s51, s10
	v_lshl_add_u64 v[196:197], v[158:159], 0, s[24:25]
	s_cselect_b64 vcc, -1, 0
	s_add_i32 s10, s10, 2
	v_cndmask_b32_e32 v213, v197, v151, vcc
	v_cndmask_b32_e32 v212, v196, v150, vcc
	v_cndmask_b32_e32 v215, v155, v153, vcc
	v_cndmask_b32_e32 v214, v154, v152, vcc
	s_mov_b32 m0, s54
	v_lshl_add_u64 v[232:233], v[158:159], 0, v[146:147]
	ds_read_b128 v[196:199], v163
	ds_read_b128 v[200:203], v163 offset:1024
	ds_read_b128 v[204:207], v163 offset:2048
	ds_read_b128 v[208:211], v163 offset:3072
	ds_read_b128 v[216:219], v163 offset:4096
	ds_read_b128 v[220:223], v163 offset:5120
	ds_read_b128 v[224:227], v163 offset:6144
	ds_read_b128 v[228:231], v163 offset:7168
	global_load_lds_dwordx4 v[232:233], off
	s_mov_b32 m0, s55
	v_lshl_add_u64 v[232:233], v[158:159], 0, v[144:145]
	global_load_lds_dwordx4 v[232:233], off
	s_waitcnt vmcnt(8) lgkmcnt(0)
	s_setprio 1
	s_barrier
	v_mfma_f32_16x16x32_bf16 v[124:127], v[164:167], v[196:199], v[124:127]
	v_mfma_f32_16x16x32_bf16 v[120:123], v[172:175], v[196:199], v[120:123]
	v_mfma_f32_16x16x32_bf16 v[108:111], v[164:167], v[204:207], v[108:111]
	v_mfma_f32_16x16x32_bf16 v[104:107], v[172:175], v[204:207], v[104:107]
	v_mfma_f32_16x16x32_bf16 v[92:95], v[164:167], v[216:219], v[92:95]
	v_mfma_f32_16x16x32_bf16 v[88:91], v[172:175], v[216:219], v[88:91]
	v_mfma_f32_16x16x32_bf16 v[76:79], v[164:167], v[224:227], v[76:79]
	v_mfma_f32_16x16x32_bf16 v[72:75], v[172:175], v[224:227], v[72:75]
	v_mfma_f32_16x16x32_bf16 v[124:127], v[168:171], v[200:203], v[124:127]
	v_mfma_f32_16x16x32_bf16 v[120:123], v[176:179], v[200:203], v[120:123]
	v_mfma_f32_16x16x32_bf16 v[108:111], v[168:171], v[208:211], v[108:111]
	v_mfma_f32_16x16x32_bf16 v[104:107], v[176:179], v[208:211], v[104:107]
	v_mfma_f32_16x16x32_bf16 v[92:95], v[168:171], v[220:223], v[92:95]
	v_mfma_f32_16x16x32_bf16 v[88:91], v[176:179], v[220:223], v[88:91]
	v_mfma_f32_16x16x32_bf16 v[76:79], v[168:171], v[228:231], v[76:79]
	v_mfma_f32_16x16x32_bf16 v[72:75], v[176:179], v[228:231], v[72:75]
	v_mfma_f32_16x16x32_bf16 v[116:119], v[180:183], v[196:199], v[116:119]
	v_mfma_f32_16x16x32_bf16 v[112:115], v[188:191], v[196:199], v[112:115]
	v_mfma_f32_16x16x32_bf16 v[100:103], v[180:183], v[204:207], v[100:103]
	v_mfma_f32_16x16x32_bf16 v[96:99], v[188:191], v[204:207], v[96:99]
	v_mfma_f32_16x16x32_bf16 v[84:87], v[180:183], v[216:219], v[84:87]
	v_mfma_f32_16x16x32_bf16 v[80:83], v[188:191], v[216:219], v[80:83]
	v_mfma_f32_16x16x32_bf16 v[68:71], v[180:183], v[224:227], v[68:71]
	v_mfma_f32_16x16x32_bf16 v[64:67], v[188:191], v[224:227], v[64:67]
	v_mfma_f32_16x16x32_bf16 v[116:119], v[184:187], v[200:203], v[116:119]
	v_mfma_f32_16x16x32_bf16 v[112:115], v[192:195], v[200:203], v[112:115]
	v_mfma_f32_16x16x32_bf16 v[100:103], v[184:187], v[208:211], v[100:103]
	v_mfma_f32_16x16x32_bf16 v[96:99], v[192:195], v[208:211], v[96:99]
	v_mfma_f32_16x16x32_bf16 v[84:87], v[184:187], v[220:223], v[84:87]
	v_mfma_f32_16x16x32_bf16 v[80:83], v[192:195], v[220:223], v[80:83]
	v_mfma_f32_16x16x32_bf16 v[68:71], v[184:187], v[228:231], v[68:71]
	v_mfma_f32_16x16x32_bf16 v[64:67], v[192:195], v[228:231], v[64:67]
	s_setprio 0
	s_barrier
	s_mov_b32 m0, s56
	v_lshl_add_u64 v[232:233], v[214:215], 0, v[138:139]
	ds_read_b128 v[196:199], v163 offset:16384
	ds_read_b128 v[200:203], v163 offset:17408
	ds_read_b128 v[204:207], v163 offset:18432
	ds_read_b128 v[208:211], v163 offset:19456
	ds_read_b128 v[216:219], v163 offset:20480
	ds_read_b128 v[220:223], v163 offset:21504
	ds_read_b128 v[224:227], v163 offset:22528
	global_load_lds_dwordx4 v[232:233], off
	v_lshl_add_u64 v[234:235], v[214:215], 0, v[134:135]
	s_mov_b32 m0, s57
	v_lshl_add_u64 v[214:215], v[214:215], 0, s[14:15]
	global_load_lds_dwordx4 v[234:235], off
	v_lshl_add_u64 v[236:237], v[214:215], 0, v[138:139]
	s_mov_b32 m0, s58
	v_lshl_add_u64 v[214:215], v[214:215], 0, v[134:135]
	global_load_lds_dwordx4 v[236:237], off
	s_mov_b32 m0, s59
	ds_read_b128 v[228:231], v163 offset:23552
	global_load_lds_dwordx4 v[214:215], off
	s_waitcnt vmcnt(6) lgkmcnt(0)
	s_setprio 1
	s_barrier
; #define PG8_STAGE(bufoff, gbase, voff) do { _Pragma("unroll") for (int _i = 0; _i < 2; ++_i) \
;         __builtin_amdgcn_global_load_lds((const unsigned*)((const char*)(gbase) + (voff)[_i]), (PG8_LAS unsigned*)(lds + (bufoff) + ldsw + _i * 8192), 16, 0, 0); } while (0)
; #define PG8_LDA(dst, b, h) do { _Pragma("unroll") for (int m = 0; m < 4; ++m) _Pragma("unroll") for (int k = 0; k < 2; ++k) dst[m][k] = *(const PG8_LAS bf16x8*)(lds + PG8_SA(b, h) + aoff + m * 2048 + k * 1024); } while (0)
; #define PG8_LDB(dst, b, h) do { _Pragma("unroll") for (int n = 0; n < 2; ++n) _Pragma("unroll") for (int k = 0; k < 2; ++k) dst[n][k] = *(const PG8_LAS bf16x8*)(lds + PG8_SB(b, h) + boff + n * 2048 + k * 1024); } while (0)
; #define PG8_MMA(ai, bj, At, Bt) do { __builtin_amdgcn_s_setprio(1); _Pragma("unroll") for (int m = 0; m < 4; ++m) _Pragma("unroll") for (int n = 0; n < 2; ++n) _Pragma("unroll") for (int k = 0; k < 2; ++k) \
;         acc[ai][bj][m][n] = __builtin_amdgcn_mfma_f32_16x16x32_bf16(Bt[n][k], At[m][k], acc[ai][bj][m][n], 0, 0, 0); __builtin_amdgcn_s_setprio(0); } while (0)
; #define PG8_WAIT_V(n) asm volatile("s_waitcnt vmcnt(" #n ")" ::: "memory")
; #define PG8_WAIT_L(n) asm volatile("s_waitcnt lgkmcnt(" #n ")" ::: "memory")
; #define PG8_BAR __builtin_amdgcn_s_barrier()
; #define PG8_SCHED __builtin_amdgcn_sched_barrier(0)
; template <class Epi, class Sched, bool ALIGN_EPI = false, bool SP2 = false>
; __device__ __forceinline__ void gemm_phase(PG8_LAS unsigned char* lds, const Gemm g, const Sched& S, const Epi& E) {
;     ...
;             PG8_WAIT_V(8); PG8_WAIT_L(0); PG8_BAR; PG8_MMA(1, 0, At, B0); PG8_MMA(1, 1, At, B1); PG8_BAR; PG8_SCHED;
;             PG8_LDB(B0, 1, 0); PG8_LDB(B1, 1, 1); PG8_SCHED; PG8_LDA(At, 1, 0); PG8_STAGE(PG8_SA(0, 1), a2 + hstep, voffA);
;             PG8_WAIT_V(8); PG8_WAIT_L(0); PG8_BAR; PG8_MMA(0, 0, At, B0); PG8_MMA(0, 1, At, B1); PG8_BAR; PG8_SCHED;
	v_mfma_f32_16x16x32_bf16 v[60:63], v[164:167], v[196:199], v[60:63]
	v_mfma_f32_16x16x32_bf16 v[56:59], v[172:175], v[196:199], v[56:59]
	v_mfma_f32_16x16x32_bf16 v[44:47], v[164:167], v[204:207], v[44:47]
	v_mfma_f32_16x16x32_bf16 v[40:43], v[172:175], v[204:207], v[40:43]
	s_mov_b32 m0, s37
	v_lshl_add_u64 v[238:239], v[212:213], 0, v[140:141]
	v_mfma_f32_16x16x32_bf16 v[28:31], v[164:167], v[216:219], v[28:31]
	global_load_lds_dwordx4 v[238:239], off
	v_mfma_f32_16x16x32_bf16 v[24:27], v[172:175], v[216:219], v[24:27]
	v_mfma_f32_16x16x32_bf16 v[12:15], v[164:167], v[224:227], v[12:15]
	v_mfma_f32_16x16x32_bf16 v[8:11], v[172:175], v[224:227], v[8:11]
	v_mfma_f32_16x16x32_bf16 v[60:63], v[168:171], v[200:203], v[60:63]
	v_mfma_f32_16x16x32_bf16 v[56:59], v[176:179], v[200:203], v[56:59]
	s_mov_b32 m0, s41
	v_lshl_add_u64 v[240:241], v[212:213], 0, v[136:137]
	v_mfma_f32_16x16x32_bf16 v[44:47], v[168:171], v[208:211], v[44:47]
	global_load_lds_dwordx4 v[240:241], off
	v_mfma_f32_16x16x32_bf16 v[40:43], v[176:179], v[208:211], v[40:43]
	v_mfma_f32_16x16x32_bf16 v[28:31], v[168:171], v[220:223], v[28:31]
	v_mfma_f32_16x16x32_bf16 v[24:27], v[176:179], v[220:223], v[24:27]
	v_mfma_f32_16x16x32_bf16 v[12:15], v[168:171], v[228:231], v[12:15]
	v_mfma_f32_16x16x32_bf16 v[8:11], v[176:179], v[228:231], v[8:11]
	v_mfma_f32_16x16x32_bf16 v[52:55], v[180:183], v[196:199], v[52:55]
	v_mfma_f32_16x16x32_bf16 v[48:51], v[188:191], v[196:199], v[48:51]
	v_mfma_f32_16x16x32_bf16 v[36:39], v[180:183], v[204:207], v[36:39]
	v_mfma_f32_16x16x32_bf16 v[32:35], v[188:191], v[204:207], v[32:35]
	v_mfma_f32_16x16x32_bf16 v[20:23], v[180:183], v[216:219], v[20:23]
	v_mfma_f32_16x16x32_bf16 v[16:19], v[188:191], v[216:219], v[16:19]
	v_mfma_f32_16x16x32_bf16 v[4:7], v[180:183], v[224:227], v[4:7]
	v_mfma_f32_16x16x32_bf16 v[0:3], v[188:191], v[224:227], v[0:3]
	v_mfma_f32_16x16x32_bf16 v[52:55], v[184:187], v[200:203], v[52:55]
	v_mfma_f32_16x16x32_bf16 v[48:51], v[192:195], v[200:203], v[48:51]
	v_mfma_f32_16x16x32_bf16 v[36:39], v[184:187], v[208:211], v[36:39]
	v_mfma_f32_16x16x32_bf16 v[32:35], v[192:195], v[208:211], v[32:35]
	v_mfma_f32_16x16x32_bf16 v[20:23], v[184:187], v[220:223], v[20:23]
	v_mfma_f32_16x16x32_bf16 v[16:19], v[192:195], v[220:223], v[16:19]
	v_mfma_f32_16x16x32_bf16 v[4:7], v[184:187], v[228:231], v[4:7]
	v_mfma_f32_16x16x32_bf16 v[0:3], v[192:195], v[228:231], v[0:3]
	s_setprio 0
	s_barrier
	v_add_u32_e32 v176, s60, v161
	v_add_u32_e32 v192, s61, v161
	ds_read_b128 v[164:167], v176
	ds_read_b128 v[168:171], v176 offset:1024
	ds_read_b128 v[172:175], v176 offset:2048
	ds_read_b128 v[176:179], v176 offset:3072
	ds_read_b128 v[180:183], v192
	ds_read_b128 v[184:187], v192 offset:1024
	ds_read_b128 v[188:191], v192 offset:2048
	ds_read_b128 v[192:195], v192 offset:3072
	v_lshl_add_u64 v[212:213], v[212:213], 0, s[14:15]
	s_mov_b32 m0, s46
	v_lshl_add_u64 v[242:243], v[212:213], 0, v[140:141]
	ds_read_b128 v[196:199], v163 offset:32768
	ds_read_b128 v[200:203], v163 offset:33792
	ds_read_b128 v[204:207], v163 offset:34816
	ds_read_b128 v[208:211], v163 offset:35840
	ds_read_b128 v[216:219], v163 offset:36864
	ds_read_b128 v[220:223], v163 offset:37888
	ds_read_b128 v[224:227], v163 offset:38912
	ds_read_b128 v[228:231], v163 offset:39936
	global_load_lds_dwordx4 v[242:243], off
	s_mov_b32 m0, s47
	v_lshl_add_u64 v[212:213], v[212:213], 0, v[136:137]
	global_load_lds_dwordx4 v[212:213], off
	s_waitcnt vmcnt(8) lgkmcnt(0)
	s_setprio 1
	s_barrier
; #define PG8_STAGE(bufoff, gbase, voff) do { _Pragma("unroll") for (int _i = 0; _i < 2; ++_i) \
;         __builtin_amdgcn_global_load_lds((const unsigned*)((const char*)(gbase) + (voff)[_i]), (PG8_LAS unsigned*)(lds + (bufoff) + ldsw + _i * 8192), 16, 0, 0); } while (0)
; #define PG8_LDA(dst, b, h) do { _Pragma("unroll") for (int m = 0; m < 4; ++m) _Pragma("unroll") for (int k = 0; k < 2; ++k) dst[m][k] = *(const PG8_LAS bf16x8*)(lds + PG8_SA(b, h) + aoff + m * 2048 + k * 1024); } while (0)
; #define PG8_MMA(ai, bj, At, Bt) do { __builtin_amdgcn_s_setprio(1); _Pragma("unroll") for (int m = 0; m < 4; ++m) _Pragma("unroll") for (int n = 0; n < 2; ++n) _Pragma("unroll") for (int k = 0; k < 2; ++k) \
;         acc[ai][bj][m][n] = __builtin_amdgcn_mfma_f32_16x16x32_bf16(Bt[n][k], At[m][k], acc[ai][bj][m][n], 0, 0, 0); __builtin_amdgcn_s_setprio(0); } while (0)
; #define PG8_WAIT_V(n) asm volatile("s_waitcnt vmcnt(" #n ")" ::: "memory")
; #define PG8_WAIT_L(n) asm volatile("s_waitcnt lgkmcnt(" #n ")" ::: "memory")
; #define PG8_BAR __builtin_amdgcn_s_barrier()
; #define PG8_SCHED __builtin_amdgcn_sched_barrier(0)
; template <class Epi, class Sched, bool ALIGN_EPI = false, bool SP2 = false>
; __device__ __forceinline__ void gemm_phase(PG8_LAS unsigned char* lds, const Gemm g, const Sched& S, const Epi& E) {
;     ...
;             PG8_WAIT_V(8); PG8_WAIT_L(0); PG8_BAR; PG8_MMA(0, 0, At, B0); PG8_MMA(0, 1, At, B1); PG8_BAR; PG8_SCHED;
;             PG8_LDA(At, 1, 1); PG8_STAGE(PG8_SB(1, 0), b3, voffB); PG8_STAGE(PG8_SB(1, 1), b3 + hstep, voffB); PG8_STAGE(PG8_SA(1, 0), a3, voffA);
;             PG8_WAIT_V(8); PG8_WAIT_L(0); PG8_BAR; PG8_MMA(1, 0, At, B0); PG8_MMA(1, 1, At, B1); PG8_BAR; PG8_SCHED;
	v_mfma_f32_16x16x32_bf16 v[124:127], v[164:167], v[196:199], v[124:127]
	v_mfma_f32_16x16x32_bf16 v[120:123], v[172:175], v[196:199], v[120:123]
	v_mfma_f32_16x16x32_bf16 v[108:111], v[164:167], v[204:207], v[108:111]
	v_mfma_f32_16x16x32_bf16 v[104:107], v[172:175], v[204:207], v[104:107]
	v_mfma_f32_16x16x32_bf16 v[92:95], v[164:167], v[216:219], v[92:95]
	v_mfma_f32_16x16x32_bf16 v[88:91], v[172:175], v[216:219], v[88:91]
	v_mfma_f32_16x16x32_bf16 v[76:79], v[164:167], v[224:227], v[76:79]
	v_mfma_f32_16x16x32_bf16 v[72:75], v[172:175], v[224:227], v[72:75]
	v_mfma_f32_16x16x32_bf16 v[124:127], v[168:171], v[200:203], v[124:127]
	v_mfma_f32_16x16x32_bf16 v[120:123], v[176:179], v[200:203], v[120:123]
	v_mfma_f32_16x16x32_bf16 v[108:111], v[168:171], v[208:211], v[108:111]
	v_mfma_f32_16x16x32_bf16 v[104:107], v[176:179], v[208:211], v[104:107]
	v_mfma_f32_16x16x32_bf16 v[92:95], v[168:171], v[220:223], v[92:95]
	v_mfma_f32_16x16x32_bf16 v[88:91], v[176:179], v[220:223], v[88:91]
	v_mfma_f32_16x16x32_bf16 v[76:79], v[168:171], v[228:231], v[76:79]
	v_mfma_f32_16x16x32_bf16 v[72:75], v[176:179], v[228:231], v[72:75]
	v_mfma_f32_16x16x32_bf16 v[116:119], v[180:183], v[196:199], v[116:119]
	v_mfma_f32_16x16x32_bf16 v[112:115], v[188:191], v[196:199], v[112:115]
	v_mfma_f32_16x16x32_bf16 v[100:103], v[180:183], v[204:207], v[100:103]
	v_mfma_f32_16x16x32_bf16 v[96:99], v[188:191], v[204:207], v[96:99]
	v_mfma_f32_16x16x32_bf16 v[84:87], v[180:183], v[216:219], v[84:87]
	v_mfma_f32_16x16x32_bf16 v[80:83], v[188:191], v[216:219], v[80:83]
	v_mfma_f32_16x16x32_bf16 v[68:71], v[180:183], v[224:227], v[68:71]
	v_mfma_f32_16x16x32_bf16 v[64:67], v[188:191], v[224:227], v[64:67]
	v_mfma_f32_16x16x32_bf16 v[116:119], v[184:187], v[200:203], v[116:119]
	v_mfma_f32_16x16x32_bf16 v[112:115], v[192:195], v[200:203], v[112:115]
	v_mfma_f32_16x16x32_bf16 v[100:103], v[184:187], v[208:211], v[100:103]
	v_mfma_f32_16x16x32_bf16 v[96:99], v[192:195], v[208:211], v[96:99]
	v_mfma_f32_16x16x32_bf16 v[84:87], v[184:187], v[220:223], v[84:87]
	v_mfma_f32_16x16x32_bf16 v[80:83], v[192:195], v[220:223], v[80:83]
	v_mfma_f32_16x16x32_bf16 v[68:71], v[184:187], v[228:231], v[68:71]
	v_mfma_f32_16x16x32_bf16 v[64:67], v[192:195], v[228:231], v[64:67]
	s_setprio 0
	s_barrier
	s_add_i32 m0, s62, 0xffffff80
	ds_read_b128 v[196:199], v163 offset:49152
	ds_read_b128 v[200:203], v163 offset:50176
	ds_read_b128 v[204:207], v163 offset:51200
	ds_read_b128 v[208:211], v163 offset:52224
	ds_read_b128 v[216:219], v163 offset:53248
	global_load_lds_dwordx4 v[232:233], off offset:128
	s_add_i32 m0, s63, 0xffffff80
	ds_read_b128 v[228:231], v163 offset:56320
	global_load_lds_dwordx4 v[234:235], off offset:128
	s_add_i32 m0, s64, 0xffffff80
	ds_read_b128 v[224:227], v163 offset:55296
	global_load_lds_dwordx4 v[236:237], off offset:128
	s_add_i32 m0, s65, 0xffffff80
	ds_read_b128 v[220:223], v163 offset:54272
	global_load_lds_dwordx4 v[214:215], off offset:128
	s_waitcnt vmcnt(6) lgkmcnt(0)
	s_setprio 1
	s_barrier
	v_mfma_f32_16x16x32_bf16 v[60:63], v[164:167], v[196:199], v[60:63]
	v_mfma_f32_16x16x32_bf16 v[56:59], v[172:175], v[196:199], v[56:59]
	v_mfma_f32_16x16x32_bf16 v[44:47], v[164:167], v[204:207], v[44:47]
	v_mfma_f32_16x16x32_bf16 v[40:43], v[172:175], v[204:207], v[40:43]
	s_add_i32 m0, s48, 0xffffff80
	v_mfma_f32_16x16x32_bf16 v[28:31], v[164:167], v[216:219], v[28:31]
	global_load_lds_dwordx4 v[238:239], off offset:128
	v_mfma_f32_16x16x32_bf16 v[24:27], v[172:175], v[216:219], v[24:27]
	v_mfma_f32_16x16x32_bf16 v[12:15], v[164:167], v[224:227], v[12:15]
	v_mfma_f32_16x16x32_bf16 v[8:11], v[172:175], v[224:227], v[8:11]
	v_mfma_f32_16x16x32_bf16 v[60:63], v[168:171], v[200:203], v[60:63]
	v_mfma_f32_16x16x32_bf16 v[56:59], v[176:179], v[200:203], v[56:59]
	s_add_i32 m0, s49, 0xffffff80
	v_mfma_f32_16x16x32_bf16 v[44:47], v[168:171], v[208:211], v[44:47]
	global_load_lds_dwordx4 v[240:241], off offset:128
	v_mfma_f32_16x16x32_bf16 v[40:43], v[176:179], v[208:211], v[40:43]
	v_mfma_f32_16x16x32_bf16 v[28:31], v[168:171], v[220:223], v[28:31]
	v_mfma_f32_16x16x32_bf16 v[24:27], v[176:179], v[220:223], v[24:27]
	v_mfma_f32_16x16x32_bf16 v[12:15], v[168:171], v[228:231], v[12:15]
	v_mfma_f32_16x16x32_bf16 v[8:11], v[176:179], v[228:231], v[8:11]
	v_mfma_f32_16x16x32_bf16 v[52:55], v[180:183], v[196:199], v[52:55]
	v_mfma_f32_16x16x32_bf16 v[48:51], v[188:191], v[196:199], v[48:51]
	v_mfma_f32_16x16x32_bf16 v[36:39], v[180:183], v[204:207], v[36:39]
	v_mfma_f32_16x16x32_bf16 v[32:35], v[188:191], v[204:207], v[32:35]
	v_mfma_f32_16x16x32_bf16 v[20:23], v[180:183], v[216:219], v[20:23]
	v_mfma_f32_16x16x32_bf16 v[16:19], v[188:191], v[216:219], v[16:19]
	v_mfma_f32_16x16x32_bf16 v[4:7], v[180:183], v[224:227], v[4:7]
	v_mfma_f32_16x16x32_bf16 v[0:3], v[188:191], v[224:227], v[0:3]
	v_mfma_f32_16x16x32_bf16 v[52:55], v[184:187], v[200:203], v[52:55]
	v_mfma_f32_16x16x32_bf16 v[48:51], v[192:195], v[200:203], v[48:51]
	v_mfma_f32_16x16x32_bf16 v[36:39], v[184:187], v[208:211], v[36:39]
	v_mfma_f32_16x16x32_bf16 v[32:35], v[192:195], v[208:211], v[32:35]
	v_mfma_f32_16x16x32_bf16 v[20:23], v[184:187], v[220:223], v[20:23]
	v_mfma_f32_16x16x32_bf16 v[16:19], v[192:195], v[220:223], v[16:19]
	v_mfma_f32_16x16x32_bf16 v[4:7], v[184:187], v[228:231], v[4:7]
	v_mfma_f32_16x16x32_bf16 v[0:3], v[192:195], v[228:231], v[0:3]
	s_setprio 0
	s_barrier
	v_lshl_add_u64 v[154:155], v[154:155], 0, s[28:29]
	s_cmp_ge_i32 s10, s50
	v_lshl_add_u64 v[158:159], v[158:159], 0, s[28:29]
	s_cbranch_scc0 .LBB0_1169

; #define PG8_STAGE(bufoff, gbase, voff) do { _Pragma("unroll") for (int _i = 0; _i < 2; ++_i) \
;         __builtin_amdgcn_global_load_lds((const unsigned*)((const char*)(gbase) + (voff)[_i]), (PG8_LAS unsigned*)(lds + (bufoff) + ldsw + _i * 8192), 16, 0, 0); } while (0)
; #define PG8_LDA(dst, b, h) do { _Pragma("unroll") for (int m = 0; m < 4; ++m) _Pragma("unroll") for (int k = 0; k < 2; ++k) dst[m][k] = *(const PG8_LAS bf16x8*)(lds + PG8_SA(b, h) + aoff + m * 2048 + k * 1024); } while (0)
; #define PG8_LDB(dst, b, h) do { _Pragma("unroll") for (int n = 0; n < 2; ++n) _Pragma("unroll") for (int k = 0; k < 2; ++k) dst[n][k] = *(const PG8_LAS bf16x8*)(lds + PG8_SB(b, h) + boff + n * 2048 + k * 1024); } while (0)
; #define PG8_MMA(ai, bj, At, Bt) do { __builtin_amdgcn_s_setprio(1); _Pragma("unroll") for (int m = 0; m < 4; ++m) _Pragma("unroll") for (int n = 0; n < 2; ++n) _Pragma("unroll") for (int k = 0; k < 2; ++k) \
;         acc[ai][bj][m][n] = __builtin_amdgcn_mfma_f32_16x16x32_bf16(Bt[n][k], At[m][k], acc[ai][bj][m][n], 0, 0, 0); __builtin_amdgcn_s_setprio(0); } while (0)
; #define PG8_BAR __builtin_amdgcn_s_barrier()
; template <class Epi, class Sched, bool ALIGN_EPI = false, bool SP2 = false>
; __device__ __forceinline__ void gemm_phase(PG8_LAS unsigned char* lds, const Gemm g, const Sched& S, const Epi& E) {
;     ...
;         const bool has_next = S.next(ui + 1, nxt);
;         const char* nA = has_next ? (const char*)g.A + (size_t)nxt.pm * tstep : cA; const char* nB = has_next ? (const char*)g.Bt + (size_t)nxt.pn * tstep : cB;
;         for (int t = 0; t < nt; t += 2) {
;             const bool last = (t == nt - 2);
;             const char* a1 = cA + (size_t)(t + 1) * kstep;
;             const char* a2 = last ? nA : cA + (size_t)(t + 2) * kstep; const char* b2 = last ? nB : cB + (size_t)(t + 2) * kstep;
;             const char* a3 = a2 + kstep; const char* b3 = b2 + kstep;
;             if (last && has_next) S.a_ready(nxt);
;             if constexpr (SP2) {
;             PG8_LDB(B0, 0, 0); PG8_LDB(B1, 0, 1); PG8_SCHED; PG8_LDA(At, 0, 0); PG8_STAGE(PG8_SA(1, 1), a1 + hstep, voffA);
;             PG8_WAIT_V(8); PG8_WAIT_L(0); PG8_BAR; PG8_MMA(0, 0, At, B0); PG8_MMA(0, 1, At, B1); PG8_BAR; PG8_SCHED;
;             PG8_LDA(At, 0, 1); PG8_STAGE(PG8_SB(0, 0), b2, voffB); PG8_STAGE(PG8_SB(0, 1), b2 + hstep, voffB); PG8_STAGE(PG8_SA(0, 0), a2, voffA);
.LBB0_1192:
	v_add_u32_e32 v178, s56, v216
	v_add_u32_e32 v194, s57, v216
	ds_read_b128 v[138:141], v178
	ds_read_b128 v[142:145], v178 offset:1024
	ds_read_b128 v[146:149], v178 offset:2048
	ds_read_b128 v[178:181], v178 offset:3072
	ds_read_b128 v[182:185], v194
	ds_read_b128 v[186:189], v194 offset:1024
	ds_read_b128 v[190:193], v194 offset:2048
	ds_read_b128 v[194:197], v194 offset:3072
	s_cmp_eq_u32 s49, s10
	v_lshl_add_u64 v[198:199], v[136:137], 0, s[20:21]
	s_cselect_b64 vcc, -1, 0
	s_add_i32 s10, s10, 2
	v_cndmask_b32_e32 v215, v199, v175, vcc
	v_cndmask_b32_e32 v214, v198, v174, vcc
	v_cndmask_b32_e32 v237, v135, v177, vcc
	v_cndmask_b32_e32 v236, v134, v176, vcc
	v_lshl_add_u64 v[238:239], v[136:137], 0, v[168:169]
	s_add_i32 m0, s34, 0xc000
	ds_read_b128 v[198:201], v218
	ds_read_b128 v[202:205], v218 offset:1024
	ds_read_b128 v[206:209], v218 offset:2048
	ds_read_b128 v[210:213], v218 offset:3072
	ds_read_b128 v[220:223], v218 offset:4096
	ds_read_b128 v[224:227], v218 offset:5120
	ds_read_b128 v[228:231], v218 offset:6144
	ds_read_b128 v[232:235], v218 offset:7168
	global_load_lds_dwordx4 v[238:239], off
	s_add_i32 m0, s34, 0xe000
	v_lshl_add_u64 v[238:239], v[136:137], 0, v[166:167]
	global_load_lds_dwordx4 v[238:239], off
	s_waitcnt vmcnt(8) lgkmcnt(0)
	s_setprio 1
	s_barrier
	v_mfma_f32_16x16x32_bf16 v[130:133], v[138:141], v[198:201], v[130:133]
	v_mfma_f32_16x16x32_bf16 v[126:129], v[146:149], v[198:201], v[126:129]
	v_mfma_f32_16x16x32_bf16 v[114:117], v[138:141], v[206:209], v[114:117]
	v_mfma_f32_16x16x32_bf16 v[110:113], v[146:149], v[206:209], v[110:113]
	v_mfma_f32_16x16x32_bf16 v[98:101], v[138:141], v[220:223], v[98:101]
	v_mfma_f32_16x16x32_bf16 v[94:97], v[146:149], v[220:223], v[94:97]
	v_mfma_f32_16x16x32_bf16 v[82:85], v[138:141], v[228:231], v[82:85]
	v_mfma_f32_16x16x32_bf16 v[78:81], v[146:149], v[228:231], v[78:81]
	v_mfma_f32_16x16x32_bf16 v[130:133], v[142:145], v[202:205], v[130:133]
	v_mfma_f32_16x16x32_bf16 v[126:129], v[178:181], v[202:205], v[126:129]
	v_mfma_f32_16x16x32_bf16 v[114:117], v[142:145], v[210:213], v[114:117]
	v_mfma_f32_16x16x32_bf16 v[110:113], v[178:181], v[210:213], v[110:113]
	v_mfma_f32_16x16x32_bf16 v[98:101], v[142:145], v[224:227], v[98:101]
	v_mfma_f32_16x16x32_bf16 v[94:97], v[178:181], v[224:227], v[94:97]
	v_mfma_f32_16x16x32_bf16 v[82:85], v[142:145], v[232:235], v[82:85]
	v_mfma_f32_16x16x32_bf16 v[78:81], v[178:181], v[232:235], v[78:81]
	v_mfma_f32_16x16x32_bf16 v[122:125], v[182:185], v[198:201], v[122:125]
	v_mfma_f32_16x16x32_bf16 v[118:121], v[190:193], v[198:201], v[118:121]
	v_mfma_f32_16x16x32_bf16 v[106:109], v[182:185], v[206:209], v[106:109]
	v_mfma_f32_16x16x32_bf16 v[102:105], v[190:193], v[206:209], v[102:105]
	v_mfma_f32_16x16x32_bf16 v[90:93], v[182:185], v[220:223], v[90:93]
	v_mfma_f32_16x16x32_bf16 v[86:89], v[190:193], v[220:223], v[86:89]
	v_mfma_f32_16x16x32_bf16 v[74:77], v[182:185], v[228:231], v[74:77]
	v_mfma_f32_16x16x32_bf16 v[70:73], v[190:193], v[228:231], v[70:73]
	v_mfma_f32_16x16x32_bf16 v[122:125], v[186:189], v[202:205], v[122:125]
	v_mfma_f32_16x16x32_bf16 v[118:121], v[194:197], v[202:205], v[118:121]
	v_mfma_f32_16x16x32_bf16 v[106:109], v[186:189], v[210:213], v[106:109]
	v_mfma_f32_16x16x32_bf16 v[102:105], v[194:197], v[210:213], v[102:105]
	v_mfma_f32_16x16x32_bf16 v[90:93], v[186:189], v[224:227], v[90:93]
	v_mfma_f32_16x16x32_bf16 v[86:89], v[194:197], v[224:227], v[86:89]
	v_mfma_f32_16x16x32_bf16 v[74:77], v[186:189], v[232:235], v[74:77]
	v_mfma_f32_16x16x32_bf16 v[70:73], v[194:197], v[232:235], v[70:73]
	s_setprio 0
	s_barrier
	s_add_i32 s11, s56, s29
	v_lshl_add_u64 v[238:239], v[236:237], 0, v[158:159]
	s_mov_b32 m0, s11
	ds_read_b128 v[198:201], v218 offset:16384
	ds_read_b128 v[202:205], v218 offset:17408
	ds_read_b128 v[206:209], v218 offset:18432
	ds_read_b128 v[210:213], v218 offset:19456
	ds_read_b128 v[220:223], v218 offset:20480
	ds_read_b128 v[224:227], v218 offset:21504
	ds_read_b128 v[228:231], v218 offset:22528
	global_load_lds_dwordx4 v[238:239], off
	v_lshl_add_u64 v[240:241], v[236:237], 0, v[162:163]
	s_add_i32 m0, s11, 0x2000
	v_lshl_add_u64 v[236:237], v[236:237], 0, s[12:13]
	s_add_i32 s11, s57, s29
	global_load_lds_dwordx4 v[240:241], off
	v_lshl_add_u64 v[242:243], v[236:237], 0, v[158:159]
	s_mov_b32 m0, s11
	v_lshl_add_u64 v[236:237], v[236:237], 0, v[162:163]
	global_load_lds_dwordx4 v[242:243], off
	s_add_i32 m0, s11, 0x2000
	ds_read_b128 v[232:235], v218 offset:23552
	global_load_lds_dwordx4 v[236:237], off
	s_waitcnt vmcnt(6) lgkmcnt(0)
	s_setprio 1
	s_barrier
; #define PG8_STAGE(bufoff, gbase, voff) do { _Pragma("unroll") for (int _i = 0; _i < 2; ++_i) \
;         __builtin_amdgcn_global_load_lds((const unsigned*)((const char*)(gbase) + (voff)[_i]), (PG8_LAS unsigned*)(lds + (bufoff) + ldsw + _i * 8192), 16, 0, 0); } while (0)
; #define PG8_LDA(dst, b, h) do { _Pragma("unroll") for (int m = 0; m < 4; ++m) _Pragma("unroll") for (int k = 0; k < 2; ++k) dst[m][k] = *(const PG8_LAS bf16x8*)(lds + PG8_SA(b, h) + aoff + m * 2048 + k * 1024); } while (0)
; #define PG8_LDB(dst, b, h) do { _Pragma("unroll") for (int n = 0; n < 2; ++n) _Pragma("unroll") for (int k = 0; k < 2; ++k) dst[n][k] = *(const PG8_LAS bf16x8*)(lds + PG8_SB(b, h) + boff + n * 2048 + k * 1024); } while (0)
; #define PG8_MMA(ai, bj, At, Bt) do { __builtin_amdgcn_s_setprio(1); _Pragma("unroll") for (int m = 0; m < 4; ++m) _Pragma("unroll") for (int n = 0; n < 2; ++n) _Pragma("unroll") for (int k = 0; k < 2; ++k) \
;         acc[ai][bj][m][n] = __builtin_amdgcn_mfma_f32_16x16x32_bf16(Bt[n][k], At[m][k], acc[ai][bj][m][n], 0, 0, 0); __builtin_amdgcn_s_setprio(0); } while (0)
; #define PG8_WAIT_V(n) asm volatile("s_waitcnt vmcnt(" #n ")" ::: "memory")
; #define PG8_WAIT_L(n) asm volatile("s_waitcnt lgkmcnt(" #n ")" ::: "memory")
; #define PG8_BAR __builtin_amdgcn_s_barrier()
; #define PG8_SCHED __builtin_amdgcn_sched_barrier(0)
; template <class Epi, class Sched, bool ALIGN_EPI = false, bool SP2 = false>
; __device__ __forceinline__ void gemm_phase(PG8_LAS unsigned char* lds, const Gemm g, const Sched& S, const Epi& E) {
;     ...
;             PG8_WAIT_V(8); PG8_WAIT_L(0); PG8_BAR; PG8_MMA(1, 0, At, B0); PG8_MMA(1, 1, At, B1); PG8_BAR; PG8_SCHED;
;             PG8_LDB(B0, 1, 0); PG8_LDB(B1, 1, 1); PG8_SCHED; PG8_LDA(At, 1, 0); PG8_STAGE(PG8_SA(0, 1), a2 + hstep, voffA);
;             PG8_WAIT_V(8); PG8_WAIT_L(0); PG8_BAR; PG8_MMA(0, 0, At, B0); PG8_MMA(0, 1, At, B1); PG8_BAR; PG8_SCHED;
	v_mfma_f32_16x16x32_bf16 v[66:69], v[138:141], v[198:201], v[66:69]
	v_mfma_f32_16x16x32_bf16 v[62:65], v[146:149], v[198:201], v[62:65]
	v_mfma_f32_16x16x32_bf16 v[50:53], v[138:141], v[206:209], v[50:53]
	v_mfma_f32_16x16x32_bf16 v[46:49], v[146:149], v[206:209], v[46:49]
	s_mov_b32 m0, s34
	v_lshl_add_u64 v[244:245], v[214:215], 0, v[154:155]
	v_mfma_f32_16x16x32_bf16 v[34:37], v[138:141], v[220:223], v[34:37]
	global_load_lds_dwordx4 v[244:245], off
	v_mfma_f32_16x16x32_bf16 v[30:33], v[146:149], v[220:223], v[30:33]
	v_mfma_f32_16x16x32_bf16 v[18:21], v[138:141], v[228:231], v[18:21]
	v_mfma_f32_16x16x32_bf16 v[14:17], v[146:149], v[228:231], v[14:17]
	v_mfma_f32_16x16x32_bf16 v[66:69], v[142:145], v[202:205], v[66:69]
	v_mfma_f32_16x16x32_bf16 v[62:65], v[178:181], v[202:205], v[62:65]
	s_mov_b32 m0, s35
	v_lshl_add_u64 v[246:247], v[214:215], 0, v[160:161]
	v_mfma_f32_16x16x32_bf16 v[50:53], v[142:145], v[210:213], v[50:53]
	global_load_lds_dwordx4 v[246:247], off
	v_mfma_f32_16x16x32_bf16 v[46:49], v[178:181], v[210:213], v[46:49]
	v_mfma_f32_16x16x32_bf16 v[34:37], v[142:145], v[224:227], v[34:37]
	v_mfma_f32_16x16x32_bf16 v[30:33], v[178:181], v[224:227], v[30:33]
	v_mfma_f32_16x16x32_bf16 v[18:21], v[142:145], v[232:235], v[18:21]
	v_mfma_f32_16x16x32_bf16 v[14:17], v[178:181], v[232:235], v[14:17]
	v_mfma_f32_16x16x32_bf16 v[58:61], v[182:185], v[198:201], v[58:61]
	v_mfma_f32_16x16x32_bf16 v[54:57], v[190:193], v[198:201], v[54:57]
	v_mfma_f32_16x16x32_bf16 v[42:45], v[182:185], v[206:209], v[42:45]
	v_mfma_f32_16x16x32_bf16 v[38:41], v[190:193], v[206:209], v[38:41]
	v_mfma_f32_16x16x32_bf16 v[26:29], v[182:185], v[220:223], v[26:29]
	v_mfma_f32_16x16x32_bf16 v[22:25], v[190:193], v[220:223], v[22:25]
	v_mfma_f32_16x16x32_bf16 v[10:13], v[182:185], v[228:231], v[10:13]
	v_mfma_f32_16x16x32_bf16 v[6:9], v[190:193], v[228:231], v[6:9]
	v_mfma_f32_16x16x32_bf16 v[58:61], v[186:189], v[202:205], v[58:61]
	v_mfma_f32_16x16x32_bf16 v[54:57], v[194:197], v[202:205], v[54:57]
	v_mfma_f32_16x16x32_bf16 v[42:45], v[186:189], v[210:213], v[42:45]
	v_mfma_f32_16x16x32_bf16 v[38:41], v[194:197], v[210:213], v[38:41]
	v_mfma_f32_16x16x32_bf16 v[26:29], v[186:189], v[224:227], v[26:29]
	v_mfma_f32_16x16x32_bf16 v[22:25], v[194:197], v[224:227], v[22:25]
	v_mfma_f32_16x16x32_bf16 v[10:13], v[186:189], v[232:235], v[10:13]
	v_mfma_f32_16x16x32_bf16 v[6:9], v[194:197], v[232:235], v[6:9]
	s_setprio 0
	s_barrier
	s_add_i32 s11, 0, 0x18000
	s_add_i32 s31, 0, 0x1c000
	v_add_u32_e32 v178, s11, v216
	v_add_u32_e32 v194, s31, v216
	ds_read_b128 v[138:141], v178
	ds_read_b128 v[142:145], v178 offset:1024
	ds_read_b128 v[146:149], v178 offset:2048
	ds_read_b128 v[178:181], v178 offset:3072
	ds_read_b128 v[182:185], v194
	ds_read_b128 v[186:189], v194 offset:1024
	ds_read_b128 v[190:193], v194 offset:2048
	ds_read_b128 v[194:197], v194 offset:3072
	v_lshl_add_u64 v[214:215], v[214:215], 0, s[12:13]
	s_mov_b32 m0, s36
	v_lshl_add_u64 v[248:249], v[214:215], 0, v[154:155]
	ds_read_b128 v[198:201], v218 offset:32768
	ds_read_b128 v[202:205], v218 offset:33792
	ds_read_b128 v[206:209], v218 offset:34816
	ds_read_b128 v[210:213], v218 offset:35840
	ds_read_b128 v[220:223], v218 offset:36864
	ds_read_b128 v[224:227], v218 offset:37888
	ds_read_b128 v[228:231], v218 offset:38912
	ds_read_b128 v[232:235], v218 offset:39936
	global_load_lds_dwordx4 v[248:249], off
	s_mov_b32 m0, s37
	v_lshl_add_u64 v[214:215], v[214:215], 0, v[160:161]
	global_load_lds_dwordx4 v[214:215], off
	s_waitcnt vmcnt(8) lgkmcnt(0)
	s_setprio 1
	s_barrier
; #define PG8_STAGE(bufoff, gbase, voff) do { _Pragma("unroll") for (int _i = 0; _i < 2; ++_i) \
;         __builtin_amdgcn_global_load_lds((const unsigned*)((const char*)(gbase) + (voff)[_i]), (PG8_LAS unsigned*)(lds + (bufoff) + ldsw + _i * 8192), 16, 0, 0); } while (0)
; #define PG8_LDA(dst, b, h) do { _Pragma("unroll") for (int m = 0; m < 4; ++m) _Pragma("unroll") for (int k = 0; k < 2; ++k) dst[m][k] = *(const PG8_LAS bf16x8*)(lds + PG8_SA(b, h) + aoff + m * 2048 + k * 1024); } while (0)
; #define PG8_MMA(ai, bj, At, Bt) do { __builtin_amdgcn_s_setprio(1); _Pragma("unroll") for (int m = 0; m < 4; ++m) _Pragma("unroll") for (int n = 0; n < 2; ++n) _Pragma("unroll") for (int k = 0; k < 2; ++k) \
;         acc[ai][bj][m][n] = __builtin_amdgcn_mfma_f32_16x16x32_bf16(Bt[n][k], At[m][k], acc[ai][bj][m][n], 0, 0, 0); __builtin_amdgcn_s_setprio(0); } while (0)
; #define PG8_WAIT_V(n) asm volatile("s_waitcnt vmcnt(" #n ")" ::: "memory")
; #define PG8_WAIT_L(n) asm volatile("s_waitcnt lgkmcnt(" #n ")" ::: "memory")
; #define PG8_BAR __builtin_amdgcn_s_barrier()
; #define PG8_SCHED __builtin_amdgcn_sched_barrier(0)
; template <class Epi, class Sched, bool ALIGN_EPI = false, bool SP2 = false>
; __device__ __forceinline__ void gemm_phase(PG8_LAS unsigned char* lds, const Gemm g, const Sched& S, const Epi& E) {
;     ...
;             PG8_WAIT_V(8); PG8_WAIT_L(0); PG8_BAR; PG8_MMA(0, 0, At, B0); PG8_MMA(0, 1, At, B1); PG8_BAR; PG8_SCHED;
;             PG8_LDA(At, 1, 1); PG8_STAGE(PG8_SB(1, 0), b3, voffB); PG8_STAGE(PG8_SB(1, 1), b3 + hstep, voffB); PG8_STAGE(PG8_SA(1, 0), a3, voffA);
;             PG8_WAIT_V(8); PG8_WAIT_L(0); PG8_BAR; PG8_MMA(1, 0, At, B0); PG8_MMA(1, 1, At, B1); PG8_BAR; PG8_SCHED;
	v_mfma_f32_16x16x32_bf16 v[130:133], v[138:141], v[198:201], v[130:133]
	v_mfma_f32_16x16x32_bf16 v[126:129], v[146:149], v[198:201], v[126:129]
	v_mfma_f32_16x16x32_bf16 v[114:117], v[138:141], v[206:209], v[114:117]
	v_mfma_f32_16x16x32_bf16 v[110:113], v[146:149], v[206:209], v[110:113]
	v_mfma_f32_16x16x32_bf16 v[98:101], v[138:141], v[220:223], v[98:101]
	v_mfma_f32_16x16x32_bf16 v[94:97], v[146:149], v[220:223], v[94:97]
	v_mfma_f32_16x16x32_bf16 v[82:85], v[138:141], v[228:231], v[82:85]
	v_mfma_f32_16x16x32_bf16 v[78:81], v[146:149], v[228:231], v[78:81]
	v_mfma_f32_16x16x32_bf16 v[130:133], v[142:145], v[202:205], v[130:133]
	v_mfma_f32_16x16x32_bf16 v[126:129], v[178:181], v[202:205], v[126:129]
	v_mfma_f32_16x16x32_bf16 v[114:117], v[142:145], v[210:213], v[114:117]
	v_mfma_f32_16x16x32_bf16 v[110:113], v[178:181], v[210:213], v[110:113]
	v_mfma_f32_16x16x32_bf16 v[98:101], v[142:145], v[224:227], v[98:101]
	v_mfma_f32_16x16x32_bf16 v[94:97], v[178:181], v[224:227], v[94:97]
	v_mfma_f32_16x16x32_bf16 v[82:85], v[142:145], v[232:235], v[82:85]
	v_mfma_f32_16x16x32_bf16 v[78:81], v[178:181], v[232:235], v[78:81]
	v_mfma_f32_16x16x32_bf16 v[122:125], v[182:185], v[198:201], v[122:125]
	v_mfma_f32_16x16x32_bf16 v[118:121], v[190:193], v[198:201], v[118:121]
	v_mfma_f32_16x16x32_bf16 v[106:109], v[182:185], v[206:209], v[106:109]
	v_mfma_f32_16x16x32_bf16 v[102:105], v[190:193], v[206:209], v[102:105]
	v_mfma_f32_16x16x32_bf16 v[90:93], v[182:185], v[220:223], v[90:93]
	v_mfma_f32_16x16x32_bf16 v[86:89], v[190:193], v[220:223], v[86:89]
	v_mfma_f32_16x16x32_bf16 v[74:77], v[182:185], v[228:231], v[74:77]
	v_mfma_f32_16x16x32_bf16 v[70:73], v[190:193], v[228:231], v[70:73]
	v_mfma_f32_16x16x32_bf16 v[122:125], v[186:189], v[202:205], v[122:125]
	v_mfma_f32_16x16x32_bf16 v[118:121], v[194:197], v[202:205], v[118:121]
	v_mfma_f32_16x16x32_bf16 v[106:109], v[186:189], v[210:213], v[106:109]
	v_mfma_f32_16x16x32_bf16 v[102:105], v[194:197], v[210:213], v[102:105]
	v_mfma_f32_16x16x32_bf16 v[90:93], v[186:189], v[224:227], v[90:93]
	v_mfma_f32_16x16x32_bf16 v[86:89], v[194:197], v[224:227], v[86:89]
	v_mfma_f32_16x16x32_bf16 v[74:77], v[186:189], v[232:235], v[74:77]
	v_mfma_f32_16x16x32_bf16 v[70:73], v[194:197], v[232:235], v[70:73]
	s_setprio 0
	s_barrier
	s_add_i32 s11, s11, s29
	s_add_i32 m0, s11, 0xffffff80
	ds_read_b128 v[198:201], v218 offset:49152
	ds_read_b128 v[202:205], v218 offset:50176
	ds_read_b128 v[206:209], v218 offset:51200
	ds_read_b128 v[210:213], v218 offset:52224
	ds_read_b128 v[220:223], v218 offset:53248
	ds_read_b128 v[224:227], v218 offset:54272
	global_load_lds_dwordx4 v[238:239], off offset:128
	s_add_i32 m0, s11, 0x1f80
	s_add_i32 s11, s31, s29
	global_load_lds_dwordx4 v[240:241], off offset:128
	s_add_i32 m0, s11, 0xffffff80
	ds_read_b128 v[232:235], v218 offset:56320
	global_load_lds_dwordx4 v[242:243], off offset:128
	s_add_i32 m0, s11, 0x1f80
	ds_read_b128 v[228:231], v218 offset:55296
	global_load_lds_dwordx4 v[236:237], off offset:128
	s_waitcnt vmcnt(6) lgkmcnt(0)
	s_setprio 1
	s_barrier
	v_mfma_f32_16x16x32_bf16 v[66:69], v[138:141], v[198:201], v[66:69]
	v_mfma_f32_16x16x32_bf16 v[62:65], v[146:149], v[198:201], v[62:65]
	v_mfma_f32_16x16x32_bf16 v[50:53], v[138:141], v[206:209], v[50:53]
	v_mfma_f32_16x16x32_bf16 v[46:49], v[146:149], v[206:209], v[46:49]
	s_add_i32 m0, s41, 0xffffff80
	v_mfma_f32_16x16x32_bf16 v[34:37], v[138:141], v[220:223], v[34:37]
	global_load_lds_dwordx4 v[244:245], off offset:128
	v_mfma_f32_16x16x32_bf16 v[30:33], v[146:149], v[220:223], v[30:33]
	v_mfma_f32_16x16x32_bf16 v[18:21], v[138:141], v[228:231], v[18:21]
	v_mfma_f32_16x16x32_bf16 v[14:17], v[146:149], v[228:231], v[14:17]
	v_mfma_f32_16x16x32_bf16 v[66:69], v[142:145], v[202:205], v[66:69]
	v_mfma_f32_16x16x32_bf16 v[62:65], v[178:181], v[202:205], v[62:65]
	s_add_i32 m0, s46, 0xffffff80
	v_mfma_f32_16x16x32_bf16 v[50:53], v[142:145], v[210:213], v[50:53]
	global_load_lds_dwordx4 v[246:247], off offset:128
	v_mfma_f32_16x16x32_bf16 v[46:49], v[178:181], v[210:213], v[46:49]
	v_mfma_f32_16x16x32_bf16 v[34:37], v[142:145], v[224:227], v[34:37]
	v_mfma_f32_16x16x32_bf16 v[30:33], v[178:181], v[224:227], v[30:33]
	v_mfma_f32_16x16x32_bf16 v[18:21], v[142:145], v[232:235], v[18:21]
	v_mfma_f32_16x16x32_bf16 v[14:17], v[178:181], v[232:235], v[14:17]
	v_mfma_f32_16x16x32_bf16 v[58:61], v[182:185], v[198:201], v[58:61]
	v_mfma_f32_16x16x32_bf16 v[54:57], v[190:193], v[198:201], v[54:57]
	v_mfma_f32_16x16x32_bf16 v[42:45], v[182:185], v[206:209], v[42:45]
	v_mfma_f32_16x16x32_bf16 v[38:41], v[190:193], v[206:209], v[38:41]
	v_mfma_f32_16x16x32_bf16 v[26:29], v[182:185], v[220:223], v[26:29]
	v_mfma_f32_16x16x32_bf16 v[22:25], v[190:193], v[220:223], v[22:25]
	v_mfma_f32_16x16x32_bf16 v[10:13], v[182:185], v[228:231], v[10:13]
	v_mfma_f32_16x16x32_bf16 v[6:9], v[190:193], v[228:231], v[6:9]
	v_mfma_f32_16x16x32_bf16 v[58:61], v[186:189], v[202:205], v[58:61]
	v_mfma_f32_16x16x32_bf16 v[54:57], v[194:197], v[202:205], v[54:57]
	v_mfma_f32_16x16x32_bf16 v[42:45], v[186:189], v[210:213], v[42:45]
	v_mfma_f32_16x16x32_bf16 v[38:41], v[194:197], v[210:213], v[38:41]
	v_mfma_f32_16x16x32_bf16 v[26:29], v[186:189], v[224:227], v[26:29]
	v_mfma_f32_16x16x32_bf16 v[22:25], v[194:197], v[224:227], v[22:25]
	v_mfma_f32_16x16x32_bf16 v[10:13], v[186:189], v[232:235], v[10:13]
	v_mfma_f32_16x16x32_bf16 v[6:9], v[194:197], v[232:235], v[6:9]
	s_setprio 0
	s_barrier
	v_lshl_add_u64 v[134:135], v[134:135], 0, s[26:27]
	s_cmp_ge_i32 s10, s48
	v_lshl_add_u64 v[136:137], v[136:137], 0, s[26:27]
	s_cbranch_scc0 .LBB0_1192

; #define PG8_STAGE(bufoff, gbase, voff) do { _Pragma("unroll") for (int _i = 0; _i < 2; ++_i) \
;         __builtin_amdgcn_global_load_lds((const unsigned*)((const char*)(gbase) + (voff)[_i]), (PG8_LAS unsigned*)(lds + (bufoff) + ldsw + _i * 8192), 16, 0, 0); } while (0)
; #define PG8_LDA(dst, b, h) do { _Pragma("unroll") for (int m = 0; m < 4; ++m) _Pragma("unroll") for (int k = 0; k < 2; ++k) dst[m][k] = *(const PG8_LAS bf16x8*)(lds + PG8_SA(b, h) + aoff + m * 2048 + k * 1024); } while (0)
; #define PG8_LDB(dst, b, h) do { _Pragma("unroll") for (int n = 0; n < 2; ++n) _Pragma("unroll") for (int k = 0; k < 2; ++k) dst[n][k] = *(const PG8_LAS bf16x8*)(lds + PG8_SB(b, h) + boff + n * 2048 + k * 1024); } while (0)
; #define PG8_MMA(ai, bj, At, Bt) do { __builtin_amdgcn_s_setprio(1); _Pragma("unroll") for (int m = 0; m < 4; ++m) _Pragma("unroll") for (int n = 0; n < 2; ++n) _Pragma("unroll") for (int k = 0; k < 2; ++k) \
;         acc[ai][bj][m][n] = __builtin_amdgcn_mfma_f32_16x16x32_bf16(Bt[n][k], At[m][k], acc[ai][bj][m][n], 0, 0, 0); __builtin_amdgcn_s_setprio(0); } while (0)
; #define PG8_BAR __builtin_amdgcn_s_barrier()
; template <class Epi, class Sched, bool ALIGN_EPI = false, bool SP2 = false>
; __device__ __forceinline__ void gemm_phase(PG8_LAS unsigned char* lds, const Gemm g, const Sched& S, const Epi& E) {
;     ...
;         const bool has_next = S.next(ui + 1, nxt);
;         const char* nA = has_next ? (const char*)g.A + (size_t)nxt.pm * tstep : cA; const char* nB = has_next ? (const char*)g.Bt + (size_t)nxt.pn * tstep : cB;
;         for (int t = 0; t < nt; t += 2) {
;             const bool last = (t == nt - 2);
;             const char* a1 = cA + (size_t)(t + 1) * kstep;
;             const char* a2 = last ? nA : cA + (size_t)(t + 2) * kstep; const char* b2 = last ? nB : cB + (size_t)(t + 2) * kstep;
;             const char* a3 = a2 + kstep; const char* b3 = b2 + kstep;
;             if (last && has_next) S.a_ready(nxt);
;             if constexpr (SP2) {
;             PG8_LDB(B0, 0, 0); PG8_LDB(B1, 0, 1); PG8_SCHED; PG8_LDA(At, 0, 0); PG8_STAGE(PG8_SA(1, 1), a1 + hstep, voffA);
;             PG8_WAIT_V(8); PG8_WAIT_L(0); PG8_BAR; PG8_MMA(0, 0, At, B0); PG8_MMA(0, 1, At, B1); PG8_BAR; PG8_SCHED;
;             PG8_LDA(At, 0, 1); PG8_STAGE(PG8_SB(0, 0), b2, voffB); PG8_STAGE(PG8_SB(0, 1), b2 + hstep, voffB); PG8_STAGE(PG8_SA(0, 0), a2, voffA);
.LBB0_1340:
	v_add_u32_e32 v148, s55, v201
	v_add_u32_e32 v190, s56, v201
	ds_read_b128 v[136:139], v148
	ds_read_b128 v[140:143], v148 offset:1024
	ds_read_b128 v[144:147], v148 offset:2048
	ds_read_b128 v[148:151], v148 offset:3072
	ds_read_b128 v[152:155], v190
	ds_read_b128 v[182:185], v190 offset:1024
	ds_read_b128 v[186:189], v190 offset:2048
	ds_read_b128 v[190:193], v190 offset:3072
	s_cmp_eq_u32 s48, s12
	v_lshl_add_u64 v[194:195], v[134:135], 0, s[22:23]
	s_cselect_b64 vcc, -1, 0
	s_add_i32 s12, s12, 2
	v_cndmask_b32_e32 v199, v195, v179, vcc
	v_cndmask_b32_e32 v198, v194, v178, vcc
	v_cndmask_b32_e32 v215, v133, v181, vcc
	v_cndmask_b32_e32 v214, v132, v180, vcc
	s_mov_b32 m0, s57
	v_lshl_add_u64 v[236:237], v[134:135], 0, v[174:175]
	ds_read_b128 v[194:197], v203
	ds_read_b128 v[206:209], v203 offset:1024
	ds_read_b128 v[210:213], v203 offset:2048
	ds_read_b128 v[216:219], v203 offset:3072
	ds_read_b128 v[220:223], v203 offset:4096
	ds_read_b128 v[224:227], v203 offset:5120
	ds_read_b128 v[228:231], v203 offset:6144
	ds_read_b128 v[232:235], v203 offset:7168
	global_load_lds_dwordx4 v[236:237], off
	s_mov_b32 m0, s58
	v_lshl_add_u64 v[236:237], v[134:135], 0, v[172:173]
	global_load_lds_dwordx4 v[236:237], off
	s_waitcnt vmcnt(8) lgkmcnt(0)
	s_setprio 1
	s_barrier
	v_mfma_f32_16x16x32_bf16 v[124:127], v[136:139], v[194:197], v[124:127]
	v_mfma_f32_16x16x32_bf16 v[128:131], v[144:147], v[194:197], v[128:131]
	v_mfma_f32_16x16x32_bf16 v[112:115], v[136:139], v[210:213], v[112:115]
	v_mfma_f32_16x16x32_bf16 v[108:111], v[144:147], v[210:213], v[108:111]
	v_mfma_f32_16x16x32_bf16 v[96:99], v[136:139], v[220:223], v[96:99]
	v_mfma_f32_16x16x32_bf16 v[92:95], v[144:147], v[220:223], v[92:95]
	v_mfma_f32_16x16x32_bf16 v[80:83], v[136:139], v[228:231], v[80:83]
	v_mfma_f32_16x16x32_bf16 v[76:79], v[144:147], v[228:231], v[76:79]
	v_mfma_f32_16x16x32_bf16 v[124:127], v[140:143], v[206:209], v[124:127]
	v_mfma_f32_16x16x32_bf16 v[128:131], v[148:151], v[206:209], v[128:131]
	v_mfma_f32_16x16x32_bf16 v[112:115], v[140:143], v[216:219], v[112:115]
	v_mfma_f32_16x16x32_bf16 v[108:111], v[148:151], v[216:219], v[108:111]
	v_mfma_f32_16x16x32_bf16 v[96:99], v[140:143], v[224:227], v[96:99]
	v_mfma_f32_16x16x32_bf16 v[92:95], v[148:151], v[224:227], v[92:95]
	v_mfma_f32_16x16x32_bf16 v[80:83], v[140:143], v[232:235], v[80:83]
	v_mfma_f32_16x16x32_bf16 v[76:79], v[148:151], v[232:235], v[76:79]
	v_mfma_f32_16x16x32_bf16 v[120:123], v[152:155], v[194:197], v[120:123]
	v_mfma_f32_16x16x32_bf16 v[116:119], v[186:189], v[194:197], v[116:119]
	v_mfma_f32_16x16x32_bf16 v[104:107], v[152:155], v[210:213], v[104:107]
	v_mfma_f32_16x16x32_bf16 v[100:103], v[186:189], v[210:213], v[100:103]
	v_mfma_f32_16x16x32_bf16 v[88:91], v[152:155], v[220:223], v[88:91]
	v_mfma_f32_16x16x32_bf16 v[84:87], v[186:189], v[220:223], v[84:87]
	v_mfma_f32_16x16x32_bf16 v[72:75], v[152:155], v[228:231], v[72:75]
	v_mfma_f32_16x16x32_bf16 v[68:71], v[186:189], v[228:231], v[68:71]
	v_mfma_f32_16x16x32_bf16 v[120:123], v[182:185], v[206:209], v[120:123]
	v_mfma_f32_16x16x32_bf16 v[116:119], v[190:193], v[206:209], v[116:119]
	v_mfma_f32_16x16x32_bf16 v[104:107], v[182:185], v[216:219], v[104:107]
	v_mfma_f32_16x16x32_bf16 v[100:103], v[190:193], v[216:219], v[100:103]
	v_mfma_f32_16x16x32_bf16 v[88:91], v[182:185], v[224:227], v[88:91]
	v_mfma_f32_16x16x32_bf16 v[84:87], v[190:193], v[224:227], v[84:87]
	v_mfma_f32_16x16x32_bf16 v[72:75], v[182:185], v[232:235], v[72:75]
	v_mfma_f32_16x16x32_bf16 v[68:71], v[190:193], v[232:235], v[68:71]
	s_setprio 0
	s_barrier
	s_mov_b32 m0, s59
	v_lshl_add_u64 v[236:237], v[214:215], 0, v[166:167]
	ds_read_b128 v[194:197], v203 offset:16384
	ds_read_b128 v[206:209], v203 offset:17408
	ds_read_b128 v[210:213], v203 offset:18432
	ds_read_b128 v[216:219], v203 offset:19456
	ds_read_b128 v[220:223], v203 offset:20480
	ds_read_b128 v[224:227], v203 offset:21504
	ds_read_b128 v[228:231], v203 offset:22528
	global_load_lds_dwordx4 v[236:237], off
	v_lshl_add_u64 v[238:239], v[214:215], 0, v[170:171]
	s_mov_b32 m0, s60
	v_lshl_add_u64 v[214:215], v[214:215], 0, s[14:15]
	s_add_i32 s13, s56, s30
	global_load_lds_dwordx4 v[238:239], off
	v_lshl_add_u64 v[240:241], v[214:215], 0, v[166:167]
	s_mov_b32 m0, s13
	v_lshl_add_u64 v[214:215], v[214:215], 0, v[170:171]
	global_load_lds_dwordx4 v[240:241], off
	s_add_i32 m0, s13, 0x2000
	ds_read_b128 v[232:235], v203 offset:23552
	global_load_lds_dwordx4 v[214:215], off
	s_waitcnt vmcnt(6) lgkmcnt(0)
	s_setprio 1
	s_barrier
; #define PG8_STAGE(bufoff, gbase, voff) do { _Pragma("unroll") for (int _i = 0; _i < 2; ++_i) \
;         __builtin_amdgcn_global_load_lds((const unsigned*)((const char*)(gbase) + (voff)[_i]), (PG8_LAS unsigned*)(lds + (bufoff) + ldsw + _i * 8192), 16, 0, 0); } while (0)
; #define PG8_LDA(dst, b, h) do { _Pragma("unroll") for (int m = 0; m < 4; ++m) _Pragma("unroll") for (int k = 0; k < 2; ++k) dst[m][k] = *(const PG8_LAS bf16x8*)(lds + PG8_SA(b, h) + aoff + m * 2048 + k * 1024); } while (0)
; #define PG8_LDB(dst, b, h) do { _Pragma("unroll") for (int n = 0; n < 2; ++n) _Pragma("unroll") for (int k = 0; k < 2; ++k) dst[n][k] = *(const PG8_LAS bf16x8*)(lds + PG8_SB(b, h) + boff + n * 2048 + k * 1024); } while (0)
; #define PG8_MMA(ai, bj, At, Bt) do { __builtin_amdgcn_s_setprio(1); _Pragma("unroll") for (int m = 0; m < 4; ++m) _Pragma("unroll") for (int n = 0; n < 2; ++n) _Pragma("unroll") for (int k = 0; k < 2; ++k) \
;         acc[ai][bj][m][n] = __builtin_amdgcn_mfma_f32_16x16x32_bf16(Bt[n][k], At[m][k], acc[ai][bj][m][n], 0, 0, 0); __builtin_amdgcn_s_setprio(0); } while (0)
; #define PG8_WAIT_V(n) asm volatile("s_waitcnt vmcnt(" #n ")" ::: "memory")
; #define PG8_WAIT_L(n) asm volatile("s_waitcnt lgkmcnt(" #n ")" ::: "memory")
; #define PG8_BAR __builtin_amdgcn_s_barrier()
; #define PG8_SCHED __builtin_amdgcn_sched_barrier(0)
; template <class Epi, class Sched, bool ALIGN_EPI = false, bool SP2 = false>
; __device__ __forceinline__ void gemm_phase(PG8_LAS unsigned char* lds, const Gemm g, const Sched& S, const Epi& E) {
;     ...
;             PG8_WAIT_V(8); PG8_WAIT_L(0); PG8_BAR; PG8_MMA(1, 0, At, B0); PG8_MMA(1, 1, At, B1); PG8_BAR; PG8_SCHED;
;             PG8_LDB(B0, 1, 0); PG8_LDB(B1, 1, 1); PG8_SCHED; PG8_LDA(At, 1, 0); PG8_STAGE(PG8_SA(0, 1), a2 + hstep, voffA);
;             PG8_WAIT_V(8); PG8_WAIT_L(0); PG8_BAR; PG8_MMA(0, 0, At, B0); PG8_MMA(0, 1, At, B1); PG8_BAR; PG8_SCHED;
	v_mfma_f32_16x16x32_bf16 v[64:67], v[136:139], v[194:197], v[64:67]
	v_mfma_f32_16x16x32_bf16 v[60:63], v[144:147], v[194:197], v[60:63]
	v_mfma_f32_16x16x32_bf16 v[48:51], v[136:139], v[210:213], v[48:51]
	v_mfma_f32_16x16x32_bf16 v[44:47], v[144:147], v[210:213], v[44:47]
	s_mov_b32 m0, s31
	v_lshl_add_u64 v[242:243], v[198:199], 0, v[164:165]
	v_mfma_f32_16x16x32_bf16 v[32:35], v[136:139], v[220:223], v[32:35]
	global_load_lds_dwordx4 v[242:243], off
	v_mfma_f32_16x16x32_bf16 v[28:31], v[144:147], v[220:223], v[28:31]
	v_mfma_f32_16x16x32_bf16 v[16:19], v[136:139], v[228:231], v[16:19]
	v_mfma_f32_16x16x32_bf16 v[12:15], v[144:147], v[228:231], v[12:15]
	v_mfma_f32_16x16x32_bf16 v[64:67], v[140:143], v[206:209], v[64:67]
	v_mfma_f32_16x16x32_bf16 v[60:63], v[148:151], v[206:209], v[60:63]
	s_mov_b32 m0, s34
	v_lshl_add_u64 v[244:245], v[198:199], 0, v[168:169]
	v_mfma_f32_16x16x32_bf16 v[48:51], v[140:143], v[216:219], v[48:51]
	global_load_lds_dwordx4 v[244:245], off
	v_mfma_f32_16x16x32_bf16 v[44:47], v[148:151], v[216:219], v[44:47]
	v_mfma_f32_16x16x32_bf16 v[32:35], v[140:143], v[224:227], v[32:35]
	v_mfma_f32_16x16x32_bf16 v[28:31], v[148:151], v[224:227], v[28:31]
	v_mfma_f32_16x16x32_bf16 v[16:19], v[140:143], v[232:235], v[16:19]
	v_mfma_f32_16x16x32_bf16 v[12:15], v[148:151], v[232:235], v[12:15]
	v_mfma_f32_16x16x32_bf16 v[56:59], v[152:155], v[194:197], v[56:59]
	v_mfma_f32_16x16x32_bf16 v[52:55], v[186:189], v[194:197], v[52:55]
	v_mfma_f32_16x16x32_bf16 v[40:43], v[152:155], v[210:213], v[40:43]
	v_mfma_f32_16x16x32_bf16 v[36:39], v[186:189], v[210:213], v[36:39]
	v_mfma_f32_16x16x32_bf16 v[24:27], v[152:155], v[220:223], v[24:27]
	v_mfma_f32_16x16x32_bf16 v[20:23], v[186:189], v[220:223], v[20:23]
	v_mfma_f32_16x16x32_bf16 v[8:11], v[152:155], v[228:231], v[8:11]
	v_mfma_f32_16x16x32_bf16 v[4:7], v[186:189], v[228:231], v[4:7]
	v_mfma_f32_16x16x32_bf16 v[56:59], v[182:185], v[206:209], v[56:59]
	v_mfma_f32_16x16x32_bf16 v[52:55], v[190:193], v[206:209], v[52:55]
	v_mfma_f32_16x16x32_bf16 v[40:43], v[182:185], v[216:219], v[40:43]
	v_mfma_f32_16x16x32_bf16 v[36:39], v[190:193], v[216:219], v[36:39]
	v_mfma_f32_16x16x32_bf16 v[24:27], v[182:185], v[224:227], v[24:27]
	v_mfma_f32_16x16x32_bf16 v[20:23], v[190:193], v[224:227], v[20:23]
	v_mfma_f32_16x16x32_bf16 v[8:11], v[182:185], v[232:235], v[8:11]
	v_mfma_f32_16x16x32_bf16 v[4:7], v[190:193], v[232:235], v[4:7]
	s_setprio 0
	s_barrier
	s_add_i32 s13, 0, 0x18000
	s_add_i32 s29, 0, 0x1c000
	v_add_u32_e32 v148, s13, v201
	v_add_u32_e32 v190, s29, v201
	ds_read_b128 v[136:139], v148
	ds_read_b128 v[140:143], v148 offset:1024
	ds_read_b128 v[144:147], v148 offset:2048
	ds_read_b128 v[148:151], v148 offset:3072
	ds_read_b128 v[152:155], v190
	ds_read_b128 v[182:185], v190 offset:1024
	ds_read_b128 v[186:189], v190 offset:2048
	ds_read_b128 v[190:193], v190 offset:3072
	v_lshl_add_u64 v[198:199], v[198:199], 0, s[14:15]
	s_mov_b32 m0, s35
	v_lshl_add_u64 v[246:247], v[198:199], 0, v[164:165]
	ds_read_b128 v[194:197], v203 offset:32768
	ds_read_b128 v[206:209], v203 offset:33792
	ds_read_b128 v[210:213], v203 offset:34816
	ds_read_b128 v[216:219], v203 offset:35840
	ds_read_b128 v[220:223], v203 offset:36864
	ds_read_b128 v[224:227], v203 offset:37888
	ds_read_b128 v[228:231], v203 offset:38912
	ds_read_b128 v[232:235], v203 offset:39936
	global_load_lds_dwordx4 v[246:247], off
	s_mov_b32 m0, s36
	v_lshl_add_u64 v[198:199], v[198:199], 0, v[168:169]
	global_load_lds_dwordx4 v[198:199], off
	s_waitcnt vmcnt(8) lgkmcnt(0)
	s_setprio 1
	s_barrier
; #define PG8_STAGE(bufoff, gbase, voff) do { _Pragma("unroll") for (int _i = 0; _i < 2; ++_i) \
;         __builtin_amdgcn_global_load_lds((const unsigned*)((const char*)(gbase) + (voff)[_i]), (PG8_LAS unsigned*)(lds + (bufoff) + ldsw + _i * 8192), 16, 0, 0); } while (0)
; #define PG8_LDA(dst, b, h) do { _Pragma("unroll") for (int m = 0; m < 4; ++m) _Pragma("unroll") for (int k = 0; k < 2; ++k) dst[m][k] = *(const PG8_LAS bf16x8*)(lds + PG8_SA(b, h) + aoff + m * 2048 + k * 1024); } while (0)
; #define PG8_MMA(ai, bj, At, Bt) do { __builtin_amdgcn_s_setprio(1); _Pragma("unroll") for (int m = 0; m < 4; ++m) _Pragma("unroll") for (int n = 0; n < 2; ++n) _Pragma("unroll") for (int k = 0; k < 2; ++k) \
;         acc[ai][bj][m][n] = __builtin_amdgcn_mfma_f32_16x16x32_bf16(Bt[n][k], At[m][k], acc[ai][bj][m][n], 0, 0, 0); __builtin_amdgcn_s_setprio(0); } while (0)
; #define PG8_WAIT_V(n) asm volatile("s_waitcnt vmcnt(" #n ")" ::: "memory")
; #define PG8_WAIT_L(n) asm volatile("s_waitcnt lgkmcnt(" #n ")" ::: "memory")
; #define PG8_BAR __builtin_amdgcn_s_barrier()
; #define PG8_SCHED __builtin_amdgcn_sched_barrier(0)
; template <class Epi, class Sched, bool ALIGN_EPI = false, bool SP2 = false>
; __device__ __forceinline__ void gemm_phase(PG8_LAS unsigned char* lds, const Gemm g, const Sched& S, const Epi& E) {
;     ...
;             PG8_WAIT_V(8); PG8_WAIT_L(0); PG8_BAR; PG8_MMA(0, 0, At, B0); PG8_MMA(0, 1, At, B1); PG8_BAR; PG8_SCHED;
;             PG8_LDA(At, 1, 1); PG8_STAGE(PG8_SB(1, 0), b3, voffB); PG8_STAGE(PG8_SB(1, 1), b3 + hstep, voffB); PG8_STAGE(PG8_SA(1, 0), a3, voffA);
;             PG8_WAIT_V(8); PG8_WAIT_L(0); PG8_BAR; PG8_MMA(1, 0, At, B0); PG8_MMA(1, 1, At, B1); PG8_BAR; PG8_SCHED;
	v_mfma_f32_16x16x32_bf16 v[124:127], v[136:139], v[194:197], v[124:127]
	v_mfma_f32_16x16x32_bf16 v[128:131], v[144:147], v[194:197], v[128:131]
	v_mfma_f32_16x16x32_bf16 v[112:115], v[136:139], v[210:213], v[112:115]
	v_mfma_f32_16x16x32_bf16 v[108:111], v[144:147], v[210:213], v[108:111]
	v_mfma_f32_16x16x32_bf16 v[96:99], v[136:139], v[220:223], v[96:99]
	v_mfma_f32_16x16x32_bf16 v[92:95], v[144:147], v[220:223], v[92:95]
	v_mfma_f32_16x16x32_bf16 v[80:83], v[136:139], v[228:231], v[80:83]
	v_mfma_f32_16x16x32_bf16 v[76:79], v[144:147], v[228:231], v[76:79]
	v_mfma_f32_16x16x32_bf16 v[124:127], v[140:143], v[206:209], v[124:127]
	v_mfma_f32_16x16x32_bf16 v[128:131], v[148:151], v[206:209], v[128:131]
	v_mfma_f32_16x16x32_bf16 v[112:115], v[140:143], v[216:219], v[112:115]
	v_mfma_f32_16x16x32_bf16 v[108:111], v[148:151], v[216:219], v[108:111]
	v_mfma_f32_16x16x32_bf16 v[96:99], v[140:143], v[224:227], v[96:99]
	v_mfma_f32_16x16x32_bf16 v[92:95], v[148:151], v[224:227], v[92:95]
	v_mfma_f32_16x16x32_bf16 v[80:83], v[140:143], v[232:235], v[80:83]
	v_mfma_f32_16x16x32_bf16 v[76:79], v[148:151], v[232:235], v[76:79]
	v_mfma_f32_16x16x32_bf16 v[120:123], v[152:155], v[194:197], v[120:123]
	v_mfma_f32_16x16x32_bf16 v[116:119], v[186:189], v[194:197], v[116:119]
	v_mfma_f32_16x16x32_bf16 v[104:107], v[152:155], v[210:213], v[104:107]
	v_mfma_f32_16x16x32_bf16 v[100:103], v[186:189], v[210:213], v[100:103]
	v_mfma_f32_16x16x32_bf16 v[88:91], v[152:155], v[220:223], v[88:91]
	v_mfma_f32_16x16x32_bf16 v[84:87], v[186:189], v[220:223], v[84:87]
	v_mfma_f32_16x16x32_bf16 v[72:75], v[152:155], v[228:231], v[72:75]
	v_mfma_f32_16x16x32_bf16 v[68:71], v[186:189], v[228:231], v[68:71]
	v_mfma_f32_16x16x32_bf16 v[120:123], v[182:185], v[206:209], v[120:123]
	v_mfma_f32_16x16x32_bf16 v[116:119], v[190:193], v[206:209], v[116:119]
	v_mfma_f32_16x16x32_bf16 v[104:107], v[182:185], v[216:219], v[104:107]
	v_mfma_f32_16x16x32_bf16 v[100:103], v[190:193], v[216:219], v[100:103]
	v_mfma_f32_16x16x32_bf16 v[88:91], v[182:185], v[224:227], v[88:91]
	v_mfma_f32_16x16x32_bf16 v[84:87], v[190:193], v[224:227], v[84:87]
	v_mfma_f32_16x16x32_bf16 v[72:75], v[182:185], v[232:235], v[72:75]
	v_mfma_f32_16x16x32_bf16 v[68:71], v[190:193], v[232:235], v[68:71]
	s_setprio 0
	s_barrier
	s_add_i32 s13, s13, s30
	s_add_i32 m0, s13, 0xffffff80
	ds_read_b128 v[194:197], v203 offset:49152
	ds_read_b128 v[206:209], v203 offset:50176
	ds_read_b128 v[210:213], v203 offset:51200
	ds_read_b128 v[216:219], v203 offset:52224
	ds_read_b128 v[220:223], v203 offset:53248
	ds_read_b128 v[224:227], v203 offset:54272
	global_load_lds_dwordx4 v[236:237], off offset:128
	s_add_i32 m0, s13, 0x1f80
	s_add_i32 s13, s29, s30
	global_load_lds_dwordx4 v[238:239], off offset:128
	s_add_i32 m0, s13, 0xffffff80
	ds_read_b128 v[232:235], v203 offset:56320
	global_load_lds_dwordx4 v[240:241], off offset:128
	s_add_i32 m0, s13, 0x1f80
	ds_read_b128 v[228:231], v203 offset:55296
	global_load_lds_dwordx4 v[214:215], off offset:128
	s_waitcnt vmcnt(6) lgkmcnt(0)
	s_setprio 1
	s_barrier
	v_mfma_f32_16x16x32_bf16 v[64:67], v[136:139], v[194:197], v[64:67]
	v_mfma_f32_16x16x32_bf16 v[60:63], v[144:147], v[194:197], v[60:63]
	v_mfma_f32_16x16x32_bf16 v[48:51], v[136:139], v[210:213], v[48:51]
	v_mfma_f32_16x16x32_bf16 v[44:47], v[144:147], v[210:213], v[44:47]
	s_add_i32 m0, s37, 0xffffff80
	v_mfma_f32_16x16x32_bf16 v[32:35], v[136:139], v[220:223], v[32:35]
	global_load_lds_dwordx4 v[242:243], off offset:128
	v_mfma_f32_16x16x32_bf16 v[28:31], v[144:147], v[220:223], v[28:31]
	v_mfma_f32_16x16x32_bf16 v[16:19], v[136:139], v[228:231], v[16:19]
	v_mfma_f32_16x16x32_bf16 v[12:15], v[144:147], v[228:231], v[12:15]
	v_mfma_f32_16x16x32_bf16 v[64:67], v[140:143], v[206:209], v[64:67]
	v_mfma_f32_16x16x32_bf16 v[60:63], v[148:151], v[206:209], v[60:63]
	s_add_i32 m0, s41, 0xffffff80
	v_mfma_f32_16x16x32_bf16 v[48:51], v[140:143], v[216:219], v[48:51]
	global_load_lds_dwordx4 v[244:245], off offset:128
	v_mfma_f32_16x16x32_bf16 v[44:47], v[148:151], v[216:219], v[44:47]
	v_mfma_f32_16x16x32_bf16 v[32:35], v[140:143], v[224:227], v[32:35]
	v_mfma_f32_16x16x32_bf16 v[28:31], v[148:151], v[224:227], v[28:31]
	v_mfma_f32_16x16x32_bf16 v[16:19], v[140:143], v[232:235], v[16:19]
	v_mfma_f32_16x16x32_bf16 v[12:15], v[148:151], v[232:235], v[12:15]
	v_mfma_f32_16x16x32_bf16 v[56:59], v[152:155], v[194:197], v[56:59]
	v_mfma_f32_16x16x32_bf16 v[52:55], v[186:189], v[194:197], v[52:55]
	v_mfma_f32_16x16x32_bf16 v[40:43], v[152:155], v[210:213], v[40:43]
	v_mfma_f32_16x16x32_bf16 v[36:39], v[186:189], v[210:213], v[36:39]
	v_mfma_f32_16x16x32_bf16 v[24:27], v[152:155], v[220:223], v[24:27]
	v_mfma_f32_16x16x32_bf16 v[20:23], v[186:189], v[220:223], v[20:23]
	v_mfma_f32_16x16x32_bf16 v[8:11], v[152:155], v[228:231], v[8:11]
	v_mfma_f32_16x16x32_bf16 v[4:7], v[186:189], v[228:231], v[4:7]
	v_mfma_f32_16x16x32_bf16 v[56:59], v[182:185], v[206:209], v[56:59]
	v_mfma_f32_16x16x32_bf16 v[52:55], v[190:193], v[206:209], v[52:55]
	v_mfma_f32_16x16x32_bf16 v[40:43], v[182:185], v[216:219], v[40:43]
	v_mfma_f32_16x16x32_bf16 v[36:39], v[190:193], v[216:219], v[36:39]
	v_mfma_f32_16x16x32_bf16 v[24:27], v[182:185], v[224:227], v[24:27]
	v_mfma_f32_16x16x32_bf16 v[20:23], v[190:193], v[224:227], v[20:23]
	v_mfma_f32_16x16x32_bf16 v[8:11], v[182:185], v[232:235], v[8:11]
	v_mfma_f32_16x16x32_bf16 v[4:7], v[190:193], v[232:235], v[4:7]
	s_setprio 0
	s_barrier
	v_lshl_add_u64 v[132:133], v[132:133], 0, s[26:27]
	s_cmp_ge_i32 s12, s47
	v_lshl_add_u64 v[134:135], v[134:135], 0, s[26:27]
	s_cbranch_scc0 .LBB0_1340

; #define PG8_STAGE(bufoff, gbase, voff) do { _Pragma("unroll") for (int _i = 0; _i < 2; ++_i) \
;         __builtin_amdgcn_global_load_lds((const unsigned*)((const char*)(gbase) + (voff)[_i]), (PG8_LAS unsigned*)(lds + (bufoff) + ldsw + _i * 8192), 16, 0, 0); } while (0)
; #define PG8_LDA(dst, b, h) do { _Pragma("unroll") for (int m = 0; m < 4; ++m) _Pragma("unroll") for (int k = 0; k < 2; ++k) dst[m][k] = *(const PG8_LAS bf16x8*)(lds + PG8_SA(b, h) + aoff + m * 2048 + k * 1024); } while (0)
; #define PG8_MMA(ai, bj, At, Bt) do { __builtin_amdgcn_s_setprio(1); _Pragma("unroll") for (int m = 0; m < 4; ++m) _Pragma("unroll") for (int n = 0; n < 2; ++n) _Pragma("unroll") for (int k = 0; k < 2; ++k) \
;         acc[ai][bj][m][n] = __builtin_amdgcn_mfma_f32_16x16x32_bf16(Bt[n][k], At[m][k], acc[ai][bj][m][n], 0, 0, 0); __builtin_amdgcn_s_setprio(0); } while (0)
; #define PG8_WAIT_V(n) asm volatile("s_waitcnt vmcnt(" #n ")" ::: "memory")
; #define PG8_WAIT_L(n) asm volatile("s_waitcnt lgkmcnt(" #n ")" ::: "memory")
; #define PG8_BAR __builtin_amdgcn_s_barrier()
; #define PG8_SCHED __builtin_amdgcn_sched_barrier(0)
; template <class Epi, class Sched, bool ALIGN_EPI = false, bool SP2 = false>
; __device__ __forceinline__ void gemm_phase(PG8_LAS unsigned char* lds, const Gemm g, const Sched& S, const Epi& E) {
;     ...
;             PG8_LDA(At, 0, 1); PG8_STAGE(PG8_SB(0, 0), b2, voffB); PG8_STAGE(PG8_SB(0, 1), b2 + hstep, voffB); PG8_STAGE(PG8_SA(0, 0), a2, voffA);
;             PG8_WAIT_V(8); PG8_WAIT_L(0); PG8_BAR; PG8_MMA(1, 0, At, B0); PG8_MMA(1, 1, At, B1); PG8_BAR; PG8_SCHED;
.Lio_skipk0:
	s_setprio 0
	s_barrier
	s_add_i32 s11, s81, s41
	v_lshl_add_u64 v[240:241], v[214:215], 0, v[146:147]
	s_mov_b32 m0, s11
	ds_read_b128 v[198:201], v213 offset:16384
	ds_read_b128 v[202:205], v213 offset:17408
	ds_read_b128 v[206:209], v213 offset:18432
	ds_read_b128 v[220:223], v213 offset:19456
	ds_read_b128 v[224:227], v213 offset:20480
	ds_read_b128 v[228:231], v213 offset:21504
	ds_read_b128 v[232:235], v213 offset:22528
	global_load_lds_dwordx4 v[240:241], off
	v_lshl_add_u64 v[242:243], v[214:215], 0, v[150:151]
	s_add_i32 m0, s11, 0x2000
	v_lshl_add_u64 v[214:215], v[214:215], 0, s[18:19]
	s_add_i32 s11, s82, s41
	global_load_lds_dwordx4 v[242:243], off
	v_lshl_add_u64 v[244:245], v[214:215], 0, v[146:147]
	s_mov_b32 m0, s11
	v_lshl_add_u64 v[214:215], v[214:215], 0, v[150:151]
	global_load_lds_dwordx4 v[244:245], off
	s_add_i32 m0, s11, 0x2000
	ds_read_b128 v[236:239], v213 offset:23552
	global_load_lds_dwordx4 v[214:215], off
	s_waitcnt vmcnt(6) lgkmcnt(0)
	s_setprio 1
	s_barrier
	v_mfma_f32_16x16x32_bf16 v[60:63], v[132:135], v[198:201], v[60:63]
	v_mfma_f32_16x16x32_bf16 v[56:59], v[174:177], v[198:201], v[56:59]
	v_mfma_f32_16x16x32_bf16 v[44:47], v[132:135], v[206:209], v[44:47]
	v_mfma_f32_16x16x32_bf16 v[40:43], v[174:177], v[206:209], v[40:43]
	s_mov_b32 m0, s47
	v_lshl_add_u64 v[246:247], v[210:211], 0, v[144:145]
	v_mfma_f32_16x16x32_bf16 v[28:31], v[132:135], v[224:227], v[28:31]
	global_load_lds_dwordx4 v[246:247], off
	v_mfma_f32_16x16x32_bf16 v[24:27], v[174:177], v[224:227], v[24:27]
	v_mfma_f32_16x16x32_bf16 v[12:15], v[132:135], v[232:235], v[12:15]
	v_mfma_f32_16x16x32_bf16 v[8:11], v[174:177], v[232:235], v[8:11]
	v_mfma_f32_16x16x32_bf16 v[60:63], v[136:139], v[202:205], v[60:63]
	v_mfma_f32_16x16x32_bf16 v[56:59], v[178:181], v[202:205], v[56:59]
	s_mov_b32 m0, s55
	v_lshl_add_u64 v[248:249], v[210:211], 0, v[148:149]
	v_mfma_f32_16x16x32_bf16 v[44:47], v[136:139], v[220:223], v[44:47]
	global_load_lds_dwordx4 v[248:249], off
	v_mfma_f32_16x16x32_bf16 v[40:43], v[178:181], v[220:223], v[40:43]
	v_mfma_f32_16x16x32_bf16 v[28:31], v[136:139], v[228:231], v[28:31]
	v_mfma_f32_16x16x32_bf16 v[24:27], v[178:181], v[228:231], v[24:27]
	v_mfma_f32_16x16x32_bf16 v[12:15], v[136:139], v[236:239], v[12:15]
	v_mfma_f32_16x16x32_bf16 v[8:11], v[178:181], v[236:239], v[8:11]
	s_cmp_eq_u32 s22, 12
	s_cbranch_scc1 .Lio_skipk1
	v_mfma_f32_16x16x32_bf16 v[52:55], v[182:185], v[198:201], v[52:55]
	v_mfma_f32_16x16x32_bf16 v[48:51], v[190:193], v[198:201], v[48:51]
	v_mfma_f32_16x16x32_bf16 v[36:39], v[182:185], v[206:209], v[36:39]
	v_mfma_f32_16x16x32_bf16 v[32:35], v[190:193], v[206:209], v[32:35]
	v_mfma_f32_16x16x32_bf16 v[20:23], v[182:185], v[224:227], v[20:23]
	v_mfma_f32_16x16x32_bf16 v[16:19], v[190:193], v[224:227], v[16:19]
	v_mfma_f32_16x16x32_bf16 v[4:7], v[182:185], v[232:235], v[4:7]
	v_mfma_f32_16x16x32_bf16 v[0:3], v[190:193], v[232:235], v[0:3]
	v_mfma_f32_16x16x32_bf16 v[52:55], v[186:189], v[202:205], v[52:55]
	v_mfma_f32_16x16x32_bf16 v[48:51], v[194:197], v[202:205], v[48:51]
	v_mfma_f32_16x16x32_bf16 v[36:39], v[186:189], v[220:223], v[36:39]
	v_mfma_f32_16x16x32_bf16 v[32:35], v[194:197], v[220:223], v[32:35]
	v_mfma_f32_16x16x32_bf16 v[20:23], v[186:189], v[228:231], v[20:23]
	v_mfma_f32_16x16x32_bf16 v[16:19], v[194:197], v[228:231], v[16:19]
	v_mfma_f32_16x16x32_bf16 v[4:7], v[186:189], v[236:239], v[4:7]
	v_mfma_f32_16x16x32_bf16 v[0:3], v[194:197], v[236:239], v[0:3]

; #define PG8_STAGE(bufoff, gbase, voff) do { _Pragma("unroll") for (int _i = 0; _i < 2; ++_i) \
;         __builtin_amdgcn_global_load_lds((const unsigned*)((const char*)(gbase) + (voff)[_i]), (PG8_LAS unsigned*)(lds + (bufoff) + ldsw + _i * 8192), 16, 0, 0); } while (0)
; #define PG8_LDA(dst, b, h) do { _Pragma("unroll") for (int m = 0; m < 4; ++m) _Pragma("unroll") for (int k = 0; k < 2; ++k) dst[m][k] = *(const PG8_LAS bf16x8*)(lds + PG8_SA(b, h) + aoff + m * 2048 + k * 1024); } while (0)
; #define PG8_MMA(ai, bj, At, Bt) do { __builtin_amdgcn_s_setprio(1); _Pragma("unroll") for (int m = 0; m < 4; ++m) _Pragma("unroll") for (int n = 0; n < 2; ++n) _Pragma("unroll") for (int k = 0; k < 2; ++k) \
;         acc[ai][bj][m][n] = __builtin_amdgcn_mfma_f32_16x16x32_bf16(Bt[n][k], At[m][k], acc[ai][bj][m][n], 0, 0, 0); __builtin_amdgcn_s_setprio(0); } while (0)
; #define PG8_WAIT_V(n) asm volatile("s_waitcnt vmcnt(" #n ")" ::: "memory")
; #define PG8_WAIT_L(n) asm volatile("s_waitcnt lgkmcnt(" #n ")" ::: "memory")
; #define PG8_BAR __builtin_amdgcn_s_barrier()
; #define PG8_SCHED __builtin_amdgcn_sched_barrier(0)
; template <class Epi, class Sched, bool ALIGN_EPI = false, bool SP2 = false>
; __device__ __forceinline__ void gemm_phase(PG8_LAS unsigned char* lds, const Gemm g, const Sched& S, const Epi& E) {
;     ...
;             PG8_LDA(At, 1, 1); PG8_STAGE(PG8_SB(1, 0), b3, voffB); PG8_STAGE(PG8_SB(1, 1), b3 + hstep, voffB); PG8_STAGE(PG8_SA(1, 0), a3, voffA);
;             PG8_WAIT_V(8); PG8_WAIT_L(0); PG8_BAR; PG8_MMA(1, 0, At, B0); PG8_MMA(1, 1, At, B1); PG8_BAR; PG8_SCHED;
.Lio_skipk2:
	s_setprio 0
	s_barrier
	s_add_i32 s11, s11, s41
	s_add_i32 m0, s11, 0xffffff80
	ds_read_b128 v[198:201], v213 offset:49152
	ds_read_b128 v[202:205], v213 offset:50176
	ds_read_b128 v[206:209], v213 offset:51200
	ds_read_b128 v[220:223], v213 offset:52224
	ds_read_b128 v[224:227], v213 offset:53248
	ds_read_b128 v[228:231], v213 offset:54272
	global_load_lds_dwordx4 v[240:241], off offset:128
	s_add_i32 m0, s11, 0x1f80
	s_add_i32 s11, s13, s41
	global_load_lds_dwordx4 v[242:243], off offset:128
	s_add_i32 m0, s11, 0xffffff80
	ds_read_b128 v[236:239], v213 offset:56320
	global_load_lds_dwordx4 v[244:245], off offset:128
	s_add_i32 m0, s11, 0x1f80
	ds_read_b128 v[232:235], v213 offset:55296
	global_load_lds_dwordx4 v[214:215], off offset:128
	s_waitcnt vmcnt(6) lgkmcnt(0)
	s_setprio 1
	s_barrier
	v_mfma_f32_16x16x32_bf16 v[60:63], v[132:135], v[198:201], v[60:63]
	v_mfma_f32_16x16x32_bf16 v[56:59], v[174:177], v[198:201], v[56:59]
	v_mfma_f32_16x16x32_bf16 v[44:47], v[132:135], v[206:209], v[44:47]
	v_mfma_f32_16x16x32_bf16 v[40:43], v[174:177], v[206:209], v[40:43]
	s_add_i32 m0, s69, 0xffffff80
	v_mfma_f32_16x16x32_bf16 v[28:31], v[132:135], v[224:227], v[28:31]
	global_load_lds_dwordx4 v[246:247], off offset:128
	v_mfma_f32_16x16x32_bf16 v[24:27], v[174:177], v[224:227], v[24:27]
	v_mfma_f32_16x16x32_bf16 v[12:15], v[132:135], v[232:235], v[12:15]
	v_mfma_f32_16x16x32_bf16 v[8:11], v[174:177], v[232:235], v[8:11]
	v_mfma_f32_16x16x32_bf16 v[60:63], v[136:139], v[202:205], v[60:63]
	v_mfma_f32_16x16x32_bf16 v[56:59], v[178:181], v[202:205], v[56:59]
	s_add_i32 m0, s70, 0xffffff80
	v_mfma_f32_16x16x32_bf16 v[44:47], v[136:139], v[220:223], v[44:47]
	global_load_lds_dwordx4 v[248:249], off offset:128
	v_mfma_f32_16x16x32_bf16 v[40:43], v[178:181], v[220:223], v[40:43]
	v_mfma_f32_16x16x32_bf16 v[28:31], v[136:139], v[228:231], v[28:31]
	v_mfma_f32_16x16x32_bf16 v[24:27], v[178:181], v[228:231], v[24:27]
	v_mfma_f32_16x16x32_bf16 v[12:15], v[136:139], v[236:239], v[12:15]
	v_mfma_f32_16x16x32_bf16 v[8:11], v[178:181], v[236:239], v[8:11]
	s_cmp_eq_u32 s22, 12
	s_cbranch_scc1 .Lio_skipk3
	v_mfma_f32_16x16x32_bf16 v[52:55], v[182:185], v[198:201], v[52:55]
	v_mfma_f32_16x16x32_bf16 v[48:51], v[190:193], v[198:201], v[48:51]
	v_mfma_f32_16x16x32_bf16 v[36:39], v[182:185], v[206:209], v[36:39]
	v_mfma_f32_16x16x32_bf16 v[32:35], v[190:193], v[206:209], v[32:35]
	v_mfma_f32_16x16x32_bf16 v[20:23], v[182:185], v[224:227], v[20:23]
	v_mfma_f32_16x16x32_bf16 v[16:19], v[190:193], v[224:227], v[16:19]
	v_mfma_f32_16x16x32_bf16 v[4:7], v[182:185], v[232:235], v[4:7]
	v_mfma_f32_16x16x32_bf16 v[0:3], v[190:193], v[232:235], v[0:3]
	v_mfma_f32_16x16x32_bf16 v[52:55], v[186:189], v[202:205], v[52:55]
	v_mfma_f32_16x16x32_bf16 v[48:51], v[194:197], v[202:205], v[48:51]
	v_mfma_f32_16x16x32_bf16 v[36:39], v[186:189], v[220:223], v[36:39]
	v_mfma_f32_16x16x32_bf16 v[32:35], v[194:197], v[220:223], v[32:35]
	v_mfma_f32_16x16x32_bf16 v[20:23], v[186:189], v[228:231], v[20:23]
	v_mfma_f32_16x16x32_bf16 v[16:19], v[194:197], v[228:231], v[16:19]
	v_mfma_f32_16x16x32_bf16 v[4:7], v[186:189], v[236:239], v[4:7]
	v_mfma_f32_16x16x32_bf16 v[0:3], v[194:197], v[236:239], v[0:3]

; #define PG8_STAGE(bufoff, gbase, voff) do { _Pragma("unroll") for (int _i = 0; _i < 2; ++_i) \
;         __builtin_amdgcn_global_load_lds((const unsigned*)((const char*)(gbase) + (voff)[_i]), (PG8_LAS unsigned*)(lds + (bufoff) + ldsw + _i * 8192), 16, 0, 0); } while (0)
; #define PG8_LDA(dst, b, h) do { _Pragma("unroll") for (int m = 0; m < 4; ++m) _Pragma("unroll") for (int k = 0; k < 2; ++k) dst[m][k] = *(const PG8_LAS bf16x8*)(lds + PG8_SA(b, h) + aoff + m * 2048 + k * 1024); } while (0)
; #define PG8_LDB(dst, b, h) do { _Pragma("unroll") for (int n = 0; n < 2; ++n) _Pragma("unroll") for (int k = 0; k < 2; ++k) dst[n][k] = *(const PG8_LAS bf16x8*)(lds + PG8_SB(b, h) + boff + n * 2048 + k * 1024); } while (0)
; #define PG8_MMA(ai, bj, At, Bt) do { __builtin_amdgcn_s_setprio(1); _Pragma("unroll") for (int m = 0; m < 4; ++m) _Pragma("unroll") for (int n = 0; n < 2; ++n) _Pragma("unroll") for (int k = 0; k < 2; ++k) \
;         acc[ai][bj][m][n] = __builtin_amdgcn_mfma_f32_16x16x32_bf16(Bt[n][k], At[m][k], acc[ai][bj][m][n], 0, 0, 0); __builtin_amdgcn_s_setprio(0); } while (0)
; #define PG8_WAIT_V(n) asm volatile("s_waitcnt vmcnt(" #n ")" ::: "memory")
; #define PG8_BAR __builtin_amdgcn_s_barrier()
; template <class Epi, class Sched, bool ALIGN_EPI = false, bool SP2 = false>
; __device__ __forceinline__ void gemm_phase(PG8_LAS unsigned char* lds, const Gemm g, const Sched& S, const Epi& E) {
;     ...
;         for (int t = 0; t < nt; t += 2) {
;             const bool last = (t == nt - 2);
;             const char* a1 = cA + (size_t)(t + 1) * kstep;
;             const char* a2 = last ? nA : cA + (size_t)(t + 2) * kstep; const char* b2 = last ? nB : cB + (size_t)(t + 2) * kstep;
;             const char* a3 = a2 + kstep; const char* b3 = b2 + kstep;
;             if (last && has_next) S.a_ready(nxt);
;             if constexpr (SP2) {
;             PG8_LDB(B0, 0, 0); PG8_LDB(B1, 0, 1); PG8_SCHED; PG8_LDA(At, 0, 0); PG8_STAGE(PG8_SA(1, 1), a1 + hstep, voffA);
;             PG8_WAIT_V(8); PG8_WAIT_L(0); PG8_BAR; PG8_MMA(0, 0, At, B0); PG8_MMA(0, 1, At, B1); PG8_BAR; PG8_SCHED;
;             PG8_LDA(At, 0, 1); PG8_STAGE(PG8_SB(0, 0), b2, voffB); PG8_STAGE(PG8_SB(0, 1), b2 + hstep, voffB); PG8_STAGE(PG8_SA(0, 0), a2, voffA);
;             PG8_WAIT_V(8); PG8_WAIT_L(0); PG8_BAR; PG8_MMA(1, 0, At, B0); PG8_MMA(1, 1, At, B1); PG8_BAR; PG8_SCHED;
.LBB0_1695:
	v_add_u32_e32 v188, s54, v199
	ds_read_b128 v[132:135], v201
	ds_read_b128 v[136:139], v201 offset:1024
	ds_read_b128 v[140:143], v201 offset:2048
	ds_read_b128 v[144:147], v201 offset:3072
	ds_read_b128 v[148:151], v188
	ds_read_b128 v[180:183], v188 offset:1024
	ds_read_b128 v[184:187], v188 offset:2048
	ds_read_b128 v[188:191], v188 offset:3072
	s_cmp_eq_u32 s48, s12
	v_lshl_add_u64 v[192:193], v[130:131], 0, s[22:23]
	s_cselect_b64 vcc, -1, 0
	s_add_i32 s12, s12, 2
	v_cndmask_b32_e32 v197, v193, v177, vcc
	v_cndmask_b32_e32 v196, v192, v176, vcc
	v_cndmask_b32_e32 v213, v129, v179, vcc
	v_cndmask_b32_e32 v212, v128, v178, vcc
	s_mov_b32 m0, s55
	v_lshl_add_u64 v[214:215], v[130:131], 0, v[172:173]
	ds_read_b128 v[192:195], v202
	ds_read_b128 v[204:207], v202 offset:1024
	ds_read_b128 v[208:211], v202 offset:2048
	ds_read_b128 v[216:219], v202 offset:3072
	ds_read_b128 v[220:223], v202 offset:4096
	ds_read_b128 v[224:227], v202 offset:5120
	ds_read_b128 v[228:231], v202 offset:6144
	ds_read_b128 v[232:235], v202 offset:7168
	global_load_lds_dwordx4 v[214:215], off
	s_mov_b32 m0, s56
	v_lshl_add_u64 v[214:215], v[130:131], 0, v[170:171]
	global_load_lds_dwordx4 v[214:215], off
	s_waitcnt vmcnt(8) lgkmcnt(0)
	s_setprio 1
	s_barrier
	v_mfma_f32_16x16x32_bf16 v[120:123], v[132:135], v[192:195], v[120:123]
	v_mfma_f32_16x16x32_bf16 v[124:127], v[140:143], v[192:195], v[124:127]
	v_mfma_f32_16x16x32_bf16 v[108:111], v[132:135], v[208:211], v[108:111]
	v_mfma_f32_16x16x32_bf16 v[104:107], v[140:143], v[208:211], v[104:107]
	v_mfma_f32_16x16x32_bf16 v[92:95], v[132:135], v[220:223], v[92:95]
	v_mfma_f32_16x16x32_bf16 v[88:91], v[140:143], v[220:223], v[88:91]
	v_mfma_f32_16x16x32_bf16 v[76:79], v[132:135], v[228:231], v[76:79]
	v_mfma_f32_16x16x32_bf16 v[72:75], v[140:143], v[228:231], v[72:75]
	v_mfma_f32_16x16x32_bf16 v[120:123], v[136:139], v[204:207], v[120:123]
	v_mfma_f32_16x16x32_bf16 v[124:127], v[144:147], v[204:207], v[124:127]
	v_mfma_f32_16x16x32_bf16 v[108:111], v[136:139], v[216:219], v[108:111]
	v_mfma_f32_16x16x32_bf16 v[104:107], v[144:147], v[216:219], v[104:107]
	v_mfma_f32_16x16x32_bf16 v[92:95], v[136:139], v[224:227], v[92:95]
	v_mfma_f32_16x16x32_bf16 v[88:91], v[144:147], v[224:227], v[88:91]
	v_mfma_f32_16x16x32_bf16 v[76:79], v[136:139], v[232:235], v[76:79]
	v_mfma_f32_16x16x32_bf16 v[72:75], v[144:147], v[232:235], v[72:75]
	v_mfma_f32_16x16x32_bf16 v[116:119], v[148:151], v[192:195], v[116:119]
	v_mfma_f32_16x16x32_bf16 v[112:115], v[184:187], v[192:195], v[112:115]
	v_mfma_f32_16x16x32_bf16 v[100:103], v[148:151], v[208:211], v[100:103]
	v_mfma_f32_16x16x32_bf16 v[96:99], v[184:187], v[208:211], v[96:99]
	v_mfma_f32_16x16x32_bf16 v[84:87], v[148:151], v[220:223], v[84:87]
	v_mfma_f32_16x16x32_bf16 v[80:83], v[184:187], v[220:223], v[80:83]
	v_mfma_f32_16x16x32_bf16 v[68:71], v[148:151], v[228:231], v[68:71]
	v_mfma_f32_16x16x32_bf16 v[64:67], v[184:187], v[228:231], v[64:67]
	v_mfma_f32_16x16x32_bf16 v[116:119], v[180:183], v[204:207], v[116:119]
	v_mfma_f32_16x16x32_bf16 v[112:115], v[188:191], v[204:207], v[112:115]
	v_mfma_f32_16x16x32_bf16 v[100:103], v[180:183], v[216:219], v[100:103]
	v_mfma_f32_16x16x32_bf16 v[96:99], v[188:191], v[216:219], v[96:99]
	v_mfma_f32_16x16x32_bf16 v[84:87], v[180:183], v[224:227], v[84:87]
	v_mfma_f32_16x16x32_bf16 v[80:83], v[188:191], v[224:227], v[80:83]
	v_mfma_f32_16x16x32_bf16 v[68:71], v[180:183], v[232:235], v[68:71]
	v_mfma_f32_16x16x32_bf16 v[64:67], v[188:191], v[232:235], v[64:67]
	s_setprio 0
	s_barrier
	s_mov_b32 m0, s57
	v_lshl_add_u64 v[214:215], v[212:213], 0, v[164:165]
	ds_read_b128 v[192:195], v202 offset:16384
	ds_read_b128 v[204:207], v202 offset:17408
	ds_read_b128 v[208:211], v202 offset:18432
	ds_read_b128 v[216:219], v202 offset:19456
	ds_read_b128 v[220:223], v202 offset:20480
	ds_read_b128 v[224:227], v202 offset:21504
	ds_read_b128 v[228:231], v202 offset:22528
	global_load_lds_dwordx4 v[214:215], off
	v_lshl_add_u64 v[236:237], v[212:213], 0, v[168:169]
	s_mov_b32 m0, s58
	v_lshl_add_u64 v[212:213], v[212:213], 0, s[14:15]
	s_add_i32 s13, s54, s30
	global_load_lds_dwordx4 v[236:237], off
	v_lshl_add_u64 v[238:239], v[212:213], 0, v[164:165]
	s_mov_b32 m0, s13
	v_lshl_add_u64 v[212:213], v[212:213], 0, v[168:169]
	global_load_lds_dwordx4 v[238:239], off
	s_add_i32 m0, s13, 0x2000
	ds_read_b128 v[232:235], v202 offset:23552
	global_load_lds_dwordx4 v[212:213], off
	s_waitcnt vmcnt(6) lgkmcnt(0)
	s_setprio 1
	s_barrier
; #define PG8_STAGE(bufoff, gbase, voff) do { _Pragma("unroll") for (int _i = 0; _i < 2; ++_i) \
;         __builtin_amdgcn_global_load_lds((const unsigned*)((const char*)(gbase) + (voff)[_i]), (PG8_LAS unsigned*)(lds + (bufoff) + ldsw + _i * 8192), 16, 0, 0); } while (0)
; #define PG8_LDA(dst, b, h) do { _Pragma("unroll") for (int m = 0; m < 4; ++m) _Pragma("unroll") for (int k = 0; k < 2; ++k) dst[m][k] = *(const PG8_LAS bf16x8*)(lds + PG8_SA(b, h) + aoff + m * 2048 + k * 1024); } while (0)
; #define PG8_LDB(dst, b, h) do { _Pragma("unroll") for (int n = 0; n < 2; ++n) _Pragma("unroll") for (int k = 0; k < 2; ++k) dst[n][k] = *(const PG8_LAS bf16x8*)(lds + PG8_SB(b, h) + boff + n * 2048 + k * 1024); } while (0)
; #define PG8_MMA(ai, bj, At, Bt) do { __builtin_amdgcn_s_setprio(1); _Pragma("unroll") for (int m = 0; m < 4; ++m) _Pragma("unroll") for (int n = 0; n < 2; ++n) _Pragma("unroll") for (int k = 0; k < 2; ++k) \
;         acc[ai][bj][m][n] = __builtin_amdgcn_mfma_f32_16x16x32_bf16(Bt[n][k], At[m][k], acc[ai][bj][m][n], 0, 0, 0); __builtin_amdgcn_s_setprio(0); } while (0)
; #define PG8_WAIT_V(n) asm volatile("s_waitcnt vmcnt(" #n ")" ::: "memory")
; #define PG8_WAIT_L(n) asm volatile("s_waitcnt lgkmcnt(" #n ")" ::: "memory")
; #define PG8_BAR __builtin_amdgcn_s_barrier()
; #define PG8_SCHED __builtin_amdgcn_sched_barrier(0)
; template <class Epi, class Sched, bool ALIGN_EPI = false, bool SP2 = false>
; __device__ __forceinline__ void gemm_phase(PG8_LAS unsigned char* lds, const Gemm g, const Sched& S, const Epi& E) {
;     ...
;             PG8_WAIT_V(8); PG8_WAIT_L(0); PG8_BAR; PG8_MMA(1, 0, At, B0); PG8_MMA(1, 1, At, B1); PG8_BAR; PG8_SCHED;
;             PG8_LDB(B0, 1, 0); PG8_LDB(B1, 1, 1); PG8_SCHED; PG8_LDA(At, 1, 0); PG8_STAGE(PG8_SA(0, 1), a2 + hstep, voffA);
;             PG8_WAIT_V(8); PG8_WAIT_L(0); PG8_BAR; PG8_MMA(0, 0, At, B0); PG8_MMA(0, 1, At, B1); PG8_BAR; PG8_SCHED;
	v_mfma_f32_16x16x32_bf16 v[60:63], v[132:135], v[192:195], v[60:63]
	v_mfma_f32_16x16x32_bf16 v[56:59], v[140:143], v[192:195], v[56:59]
	v_mfma_f32_16x16x32_bf16 v[44:47], v[132:135], v[208:211], v[44:47]
	v_mfma_f32_16x16x32_bf16 v[40:43], v[140:143], v[208:211], v[40:43]
	s_mov_b32 m0, s31
	v_lshl_add_u64 v[240:241], v[196:197], 0, v[162:163]
	v_mfma_f32_16x16x32_bf16 v[28:31], v[132:135], v[220:223], v[28:31]
	global_load_lds_dwordx4 v[240:241], off
	v_mfma_f32_16x16x32_bf16 v[24:27], v[140:143], v[220:223], v[24:27]
	v_mfma_f32_16x16x32_bf16 v[12:15], v[132:135], v[228:231], v[12:15]
	v_mfma_f32_16x16x32_bf16 v[8:11], v[140:143], v[228:231], v[8:11]
	v_mfma_f32_16x16x32_bf16 v[60:63], v[136:139], v[204:207], v[60:63]
	v_mfma_f32_16x16x32_bf16 v[56:59], v[144:147], v[204:207], v[56:59]
	s_mov_b32 m0, s34
	v_lshl_add_u64 v[242:243], v[196:197], 0, v[166:167]
	v_mfma_f32_16x16x32_bf16 v[44:47], v[136:139], v[216:219], v[44:47]
	global_load_lds_dwordx4 v[242:243], off
	v_mfma_f32_16x16x32_bf16 v[40:43], v[144:147], v[216:219], v[40:43]
	v_mfma_f32_16x16x32_bf16 v[28:31], v[136:139], v[224:227], v[28:31]
	v_mfma_f32_16x16x32_bf16 v[24:27], v[144:147], v[224:227], v[24:27]
	v_mfma_f32_16x16x32_bf16 v[12:15], v[136:139], v[232:235], v[12:15]
	v_mfma_f32_16x16x32_bf16 v[8:11], v[144:147], v[232:235], v[8:11]
	v_mfma_f32_16x16x32_bf16 v[52:55], v[148:151], v[192:195], v[52:55]
	v_mfma_f32_16x16x32_bf16 v[48:51], v[184:187], v[192:195], v[48:51]
	v_mfma_f32_16x16x32_bf16 v[36:39], v[148:151], v[208:211], v[36:39]
	v_mfma_f32_16x16x32_bf16 v[32:35], v[184:187], v[208:211], v[32:35]
	v_mfma_f32_16x16x32_bf16 v[20:23], v[148:151], v[220:223], v[20:23]
	v_mfma_f32_16x16x32_bf16 v[16:19], v[184:187], v[220:223], v[16:19]
	v_mfma_f32_16x16x32_bf16 v[4:7], v[148:151], v[228:231], v[4:7]
	v_mfma_f32_16x16x32_bf16 v[0:3], v[184:187], v[228:231], v[0:3]
	v_mfma_f32_16x16x32_bf16 v[52:55], v[180:183], v[204:207], v[52:55]
	v_mfma_f32_16x16x32_bf16 v[48:51], v[188:191], v[204:207], v[48:51]
	v_mfma_f32_16x16x32_bf16 v[36:39], v[180:183], v[216:219], v[36:39]
	v_mfma_f32_16x16x32_bf16 v[32:35], v[188:191], v[216:219], v[32:35]
	v_mfma_f32_16x16x32_bf16 v[20:23], v[180:183], v[224:227], v[20:23]
	v_mfma_f32_16x16x32_bf16 v[16:19], v[188:191], v[224:227], v[16:19]
	v_mfma_f32_16x16x32_bf16 v[4:7], v[180:183], v[232:235], v[4:7]
	v_mfma_f32_16x16x32_bf16 v[0:3], v[188:191], v[232:235], v[0:3]
	s_setprio 0
	s_barrier
	s_add_i32 s13, 0, 0x18000
	s_add_i32 s29, 0, 0x1c000
	v_add_u32_e32 v144, s13, v199
	v_add_u32_e32 v188, s29, v199
	ds_read_b128 v[132:135], v144
	ds_read_b128 v[136:139], v144 offset:1024
	ds_read_b128 v[140:143], v144 offset:2048
	ds_read_b128 v[144:147], v144 offset:3072
	ds_read_b128 v[148:151], v188
	ds_read_b128 v[180:183], v188 offset:1024
	ds_read_b128 v[184:187], v188 offset:2048
	ds_read_b128 v[188:191], v188 offset:3072
	v_lshl_add_u64 v[196:197], v[196:197], 0, s[14:15]
	s_mov_b32 m0, s35
	v_lshl_add_u64 v[244:245], v[196:197], 0, v[162:163]
	ds_read_b128 v[192:195], v202 offset:32768
	ds_read_b128 v[204:207], v202 offset:33792
	ds_read_b128 v[208:211], v202 offset:34816
	ds_read_b128 v[216:219], v202 offset:35840
	ds_read_b128 v[220:223], v202 offset:36864
	ds_read_b128 v[224:227], v202 offset:37888
	ds_read_b128 v[228:231], v202 offset:38912
	ds_read_b128 v[232:235], v202 offset:39936
	global_load_lds_dwordx4 v[244:245], off
	s_mov_b32 m0, s36
	v_lshl_add_u64 v[196:197], v[196:197], 0, v[166:167]
	global_load_lds_dwordx4 v[196:197], off
	s_waitcnt vmcnt(8) lgkmcnt(0)
	s_setprio 1
	s_barrier
; #define PG8_STAGE(bufoff, gbase, voff) do { _Pragma("unroll") for (int _i = 0; _i < 2; ++_i) \
;         __builtin_amdgcn_global_load_lds((const unsigned*)((const char*)(gbase) + (voff)[_i]), (PG8_LAS unsigned*)(lds + (bufoff) + ldsw + _i * 8192), 16, 0, 0); } while (0)
; #define PG8_LDA(dst, b, h) do { _Pragma("unroll") for (int m = 0; m < 4; ++m) _Pragma("unroll") for (int k = 0; k < 2; ++k) dst[m][k] = *(const PG8_LAS bf16x8*)(lds + PG8_SA(b, h) + aoff + m * 2048 + k * 1024); } while (0)
; #define PG8_MMA(ai, bj, At, Bt) do { __builtin_amdgcn_s_setprio(1); _Pragma("unroll") for (int m = 0; m < 4; ++m) _Pragma("unroll") for (int n = 0; n < 2; ++n) _Pragma("unroll") for (int k = 0; k < 2; ++k) \
;         acc[ai][bj][m][n] = __builtin_amdgcn_mfma_f32_16x16x32_bf16(Bt[n][k], At[m][k], acc[ai][bj][m][n], 0, 0, 0); __builtin_amdgcn_s_setprio(0); } while (0)
; #define PG8_WAIT_V(n) asm volatile("s_waitcnt vmcnt(" #n ")" ::: "memory")
; #define PG8_WAIT_L(n) asm volatile("s_waitcnt lgkmcnt(" #n ")" ::: "memory")
; #define PG8_BAR __builtin_amdgcn_s_barrier()
; #define PG8_SCHED __builtin_amdgcn_sched_barrier(0)
; template <class Epi, class Sched, bool ALIGN_EPI = false, bool SP2 = false>
; __device__ __forceinline__ void gemm_phase(PG8_LAS unsigned char* lds, const Gemm g, const Sched& S, const Epi& E) {
;     ...
;             PG8_WAIT_V(8); PG8_WAIT_L(0); PG8_BAR; PG8_MMA(0, 0, At, B0); PG8_MMA(0, 1, At, B1); PG8_BAR; PG8_SCHED;
;             PG8_LDA(At, 1, 1); PG8_STAGE(PG8_SB(1, 0), b3, voffB); PG8_STAGE(PG8_SB(1, 1), b3 + hstep, voffB); PG8_STAGE(PG8_SA(1, 0), a3, voffA);
;             PG8_WAIT_V(8); PG8_WAIT_L(0); PG8_BAR; PG8_MMA(1, 0, At, B0); PG8_MMA(1, 1, At, B1); PG8_BAR; PG8_SCHED;
	v_mfma_f32_16x16x32_bf16 v[120:123], v[132:135], v[192:195], v[120:123]
	v_mfma_f32_16x16x32_bf16 v[124:127], v[140:143], v[192:195], v[124:127]
	v_mfma_f32_16x16x32_bf16 v[108:111], v[132:135], v[208:211], v[108:111]
	v_mfma_f32_16x16x32_bf16 v[104:107], v[140:143], v[208:211], v[104:107]
	v_mfma_f32_16x16x32_bf16 v[92:95], v[132:135], v[220:223], v[92:95]
	v_mfma_f32_16x16x32_bf16 v[88:91], v[140:143], v[220:223], v[88:91]
	v_mfma_f32_16x16x32_bf16 v[76:79], v[132:135], v[228:231], v[76:79]
	v_mfma_f32_16x16x32_bf16 v[72:75], v[140:143], v[228:231], v[72:75]
	v_mfma_f32_16x16x32_bf16 v[120:123], v[136:139], v[204:207], v[120:123]
	v_mfma_f32_16x16x32_bf16 v[124:127], v[144:147], v[204:207], v[124:127]
	v_mfma_f32_16x16x32_bf16 v[108:111], v[136:139], v[216:219], v[108:111]
	v_mfma_f32_16x16x32_bf16 v[104:107], v[144:147], v[216:219], v[104:107]
	v_mfma_f32_16x16x32_bf16 v[92:95], v[136:139], v[224:227], v[92:95]
	v_mfma_f32_16x16x32_bf16 v[88:91], v[144:147], v[224:227], v[88:91]
	v_mfma_f32_16x16x32_bf16 v[76:79], v[136:139], v[232:235], v[76:79]
	v_mfma_f32_16x16x32_bf16 v[72:75], v[144:147], v[232:235], v[72:75]
	v_mfma_f32_16x16x32_bf16 v[116:119], v[148:151], v[192:195], v[116:119]
	v_mfma_f32_16x16x32_bf16 v[112:115], v[184:187], v[192:195], v[112:115]
	v_mfma_f32_16x16x32_bf16 v[100:103], v[148:151], v[208:211], v[100:103]
	v_mfma_f32_16x16x32_bf16 v[96:99], v[184:187], v[208:211], v[96:99]
	v_mfma_f32_16x16x32_bf16 v[84:87], v[148:151], v[220:223], v[84:87]
	v_mfma_f32_16x16x32_bf16 v[80:83], v[184:187], v[220:223], v[80:83]
	v_mfma_f32_16x16x32_bf16 v[68:71], v[148:151], v[228:231], v[68:71]
	v_mfma_f32_16x16x32_bf16 v[64:67], v[184:187], v[228:231], v[64:67]
	v_mfma_f32_16x16x32_bf16 v[116:119], v[180:183], v[204:207], v[116:119]
	v_mfma_f32_16x16x32_bf16 v[112:115], v[188:191], v[204:207], v[112:115]
	v_mfma_f32_16x16x32_bf16 v[100:103], v[180:183], v[216:219], v[100:103]
	v_mfma_f32_16x16x32_bf16 v[96:99], v[188:191], v[216:219], v[96:99]
	v_mfma_f32_16x16x32_bf16 v[84:87], v[180:183], v[224:227], v[84:87]
	v_mfma_f32_16x16x32_bf16 v[80:83], v[188:191], v[224:227], v[80:83]
	v_mfma_f32_16x16x32_bf16 v[68:71], v[180:183], v[232:235], v[68:71]
	v_mfma_f32_16x16x32_bf16 v[64:67], v[188:191], v[232:235], v[64:67]
	s_setprio 0
	s_barrier
	s_add_i32 s13, s13, s30
	s_add_i32 m0, s13, 0xffffff80
	ds_read_b128 v[192:195], v202 offset:49152
	ds_read_b128 v[204:207], v202 offset:50176
	ds_read_b128 v[208:211], v202 offset:51200
	ds_read_b128 v[216:219], v202 offset:52224
	ds_read_b128 v[220:223], v202 offset:53248
	ds_read_b128 v[224:227], v202 offset:54272
	global_load_lds_dwordx4 v[214:215], off offset:128
	s_add_i32 m0, s13, 0x1f80
	s_add_i32 s13, s29, s30
	global_load_lds_dwordx4 v[236:237], off offset:128
	s_add_i32 m0, s13, 0xffffff80
	ds_read_b128 v[232:235], v202 offset:56320
	global_load_lds_dwordx4 v[238:239], off offset:128
	s_add_i32 m0, s13, 0x1f80
	ds_read_b128 v[228:231], v202 offset:55296
	global_load_lds_dwordx4 v[212:213], off offset:128
	s_waitcnt vmcnt(6) lgkmcnt(0)
	s_setprio 1
	s_barrier
	v_mfma_f32_16x16x32_bf16 v[60:63], v[132:135], v[192:195], v[60:63]
	v_mfma_f32_16x16x32_bf16 v[56:59], v[140:143], v[192:195], v[56:59]
	v_mfma_f32_16x16x32_bf16 v[44:47], v[132:135], v[208:211], v[44:47]
	v_mfma_f32_16x16x32_bf16 v[40:43], v[140:143], v[208:211], v[40:43]
	s_add_i32 m0, s37, 0xffffff80
	v_mfma_f32_16x16x32_bf16 v[28:31], v[132:135], v[220:223], v[28:31]
	global_load_lds_dwordx4 v[240:241], off offset:128
	v_mfma_f32_16x16x32_bf16 v[24:27], v[140:143], v[220:223], v[24:27]
	v_mfma_f32_16x16x32_bf16 v[12:15], v[132:135], v[228:231], v[12:15]
	v_mfma_f32_16x16x32_bf16 v[8:11], v[140:143], v[228:231], v[8:11]
	v_mfma_f32_16x16x32_bf16 v[60:63], v[136:139], v[204:207], v[60:63]
	v_mfma_f32_16x16x32_bf16 v[56:59], v[144:147], v[204:207], v[56:59]
	s_add_i32 m0, s41, 0xffffff80
	v_mfma_f32_16x16x32_bf16 v[44:47], v[136:139], v[216:219], v[44:47]
	global_load_lds_dwordx4 v[242:243], off offset:128
	v_mfma_f32_16x16x32_bf16 v[40:43], v[144:147], v[216:219], v[40:43]
	v_mfma_f32_16x16x32_bf16 v[28:31], v[136:139], v[224:227], v[28:31]
	v_mfma_f32_16x16x32_bf16 v[24:27], v[144:147], v[224:227], v[24:27]
	v_mfma_f32_16x16x32_bf16 v[12:15], v[136:139], v[232:235], v[12:15]
	v_mfma_f32_16x16x32_bf16 v[8:11], v[144:147], v[232:235], v[8:11]
	v_mfma_f32_16x16x32_bf16 v[52:55], v[148:151], v[192:195], v[52:55]
	v_mfma_f32_16x16x32_bf16 v[48:51], v[184:187], v[192:195], v[48:51]
	v_mfma_f32_16x16x32_bf16 v[36:39], v[148:151], v[208:211], v[36:39]
	v_mfma_f32_16x16x32_bf16 v[32:35], v[184:187], v[208:211], v[32:35]
	v_mfma_f32_16x16x32_bf16 v[20:23], v[148:151], v[220:223], v[20:23]
	v_mfma_f32_16x16x32_bf16 v[16:19], v[184:187], v[220:223], v[16:19]
	v_mfma_f32_16x16x32_bf16 v[4:7], v[148:151], v[228:231], v[4:7]
	v_mfma_f32_16x16x32_bf16 v[0:3], v[184:187], v[228:231], v[0:3]
	v_mfma_f32_16x16x32_bf16 v[52:55], v[180:183], v[204:207], v[52:55]
	v_mfma_f32_16x16x32_bf16 v[48:51], v[188:191], v[204:207], v[48:51]
	v_mfma_f32_16x16x32_bf16 v[36:39], v[180:183], v[216:219], v[36:39]
	v_mfma_f32_16x16x32_bf16 v[32:35], v[188:191], v[216:219], v[32:35]
	v_mfma_f32_16x16x32_bf16 v[20:23], v[180:183], v[224:227], v[20:23]
	v_mfma_f32_16x16x32_bf16 v[16:19], v[188:191], v[224:227], v[16:19]
	v_mfma_f32_16x16x32_bf16 v[4:7], v[180:183], v[232:235], v[4:7]
	v_mfma_f32_16x16x32_bf16 v[0:3], v[188:191], v[232:235], v[0:3]
	s_setprio 0
	s_barrier
	v_lshl_add_u64 v[128:129], v[128:129], 0, s[26:27]
	s_cmp_ge_i32 s12, s47
	v_lshl_add_u64 v[130:131], v[130:131], 0, s[26:27]
	s_cbranch_scc0 .LBB0_1695

; #define PG8_STAGE(bufoff, gbase, voff) do { _Pragma("unroll") for (int _i = 0; _i < 2; ++_i) \
;         __builtin_amdgcn_global_load_lds((const unsigned*)((const char*)(gbase) + (voff)[_i]), (PG8_LAS unsigned*)(lds + (bufoff) + ldsw + _i * 8192), 16, 0, 0); } while (0)
; #define PG8_LDA(dst, b, h) do { _Pragma("unroll") for (int m = 0; m < 4; ++m) _Pragma("unroll") for (int k = 0; k < 2; ++k) dst[m][k] = *(const PG8_LAS bf16x8*)(lds + PG8_SA(b, h) + aoff + m * 2048 + k * 1024); } while (0)
; #define PG8_LDB(dst, b, h) do { _Pragma("unroll") for (int n = 0; n < 2; ++n) _Pragma("unroll") for (int k = 0; k < 2; ++k) dst[n][k] = *(const PG8_LAS bf16x8*)(lds + PG8_SB(b, h) + boff + n * 2048 + k * 1024); } while (0)
; #define PG8_MMA(ai, bj, At, Bt) do { __builtin_amdgcn_s_setprio(1); _Pragma("unroll") for (int m = 0; m < 4; ++m) _Pragma("unroll") for (int n = 0; n < 2; ++n) _Pragma("unroll") for (int k = 0; k < 2; ++k) \
;         acc[ai][bj][m][n] = __builtin_amdgcn_mfma_f32_16x16x32_bf16(Bt[n][k], At[m][k], acc[ai][bj][m][n], 0, 0, 0); __builtin_amdgcn_s_setprio(0); } while (0)
; #define PG8_WAIT_V(n) asm volatile("s_waitcnt vmcnt(" #n ")" ::: "memory")
; #define PG8_BAR __builtin_amdgcn_s_barrier()
; template <class Epi, class Sched, bool ALIGN_EPI = false, bool SP2 = false>
; __device__ __forceinline__ void gemm_phase(PG8_LAS unsigned char* lds, const Gemm g, const Sched& S, const Epi& E) {
;     ...
;         for (int t = 0; t < nt; t += 2) {
;             const bool last = (t == nt - 2);
;             const char* a1 = cA + (size_t)(t + 1) * kstep;
;             const char* a2 = last ? nA : cA + (size_t)(t + 2) * kstep; const char* b2 = last ? nB : cB + (size_t)(t + 2) * kstep;
;             const char* a3 = a2 + kstep; const char* b3 = b2 + kstep;
;             if (last && has_next) S.a_ready(nxt);
;             if constexpr (SP2) {
;             PG8_LDB(B0, 0, 0); PG8_LDB(B1, 0, 1); PG8_SCHED; PG8_LDA(At, 0, 0); PG8_STAGE(PG8_SA(1, 1), a1 + hstep, voffA);
;             PG8_WAIT_V(8); PG8_WAIT_L(0); PG8_BAR; PG8_MMA(0, 0, At, B0); PG8_MMA(0, 1, At, B1); PG8_BAR; PG8_SCHED;
;             PG8_LDA(At, 0, 1); PG8_STAGE(PG8_SB(0, 0), b2, voffB); PG8_STAGE(PG8_SB(0, 1), b2 + hstep, voffB); PG8_STAGE(PG8_SA(0, 0), a2, voffA);
;             PG8_WAIT_V(8); PG8_WAIT_L(0); PG8_BAR; PG8_MMA(1, 0, At, B0); PG8_MMA(1, 1, At, B1); PG8_BAR; PG8_SCHED;
.LBB0_1776:
	v_add_u32_e32 v166, s54, v169
	v_add_u32_e32 v168, s55, v169
	ds_read_b128 v[162:165], v166
	ds_read_b128 v[182:185], v166 offset:1024
	ds_read_b128 v[186:189], v166 offset:2048
	ds_read_b128 v[190:193], v166 offset:3072
	ds_read_b128 v[194:197], v168
	ds_read_b128 v[198:201], v168 offset:1024
	ds_read_b128 v[202:205], v168 offset:2048
	ds_read_b128 v[206:209], v168 offset:3072
	s_cmp_eq_u32 s53, s10
	v_lshl_add_u64 v[172:173], v[160:161], 0, s[22:23]
	s_cselect_b64 vcc, -1, 0
	s_add_i32 s10, s10, 2
	v_cndmask_b32_e32 v173, v173, v153, vcc
	v_cndmask_b32_e32 v172, v172, v152, vcc
	v_cndmask_b32_e32 v215, v159, v155, vcc
	v_cndmask_b32_e32 v214, v158, v154, vcc
	s_mov_b32 m0, s56
	v_lshl_add_u64 v[244:245], v[160:161], 0, v[148:149]
	ds_read_b128 v[210:213], v179
	ds_read_b128 v[216:219], v179 offset:1024
	ds_read_b128 v[220:223], v179 offset:2048
	ds_read_b128 v[224:227], v179 offset:3072
	ds_read_b128 v[228:231], v179 offset:4096
	ds_read_b128 v[232:235], v179 offset:5120
	ds_read_b128 v[236:239], v179 offset:6144
	ds_read_b128 v[240:243], v179 offset:7168
	global_load_lds_dwordx4 v[244:245], off
	s_mov_b32 m0, s57
	v_lshl_add_u64 v[244:245], v[160:161], 0, v[146:147]
	global_load_lds_dwordx4 v[244:245], off
	s_waitcnt vmcnt(8) lgkmcnt(0)
	s_setprio 1
	s_barrier
	v_mfma_f32_16x16x32_bf16 v[124:127], v[162:165], v[210:213], v[124:127]
	v_mfma_f32_16x16x32_bf16 v[116:119], v[186:189], v[210:213], v[116:119]
	v_mfma_f32_16x16x32_bf16 v[108:111], v[162:165], v[220:223], v[108:111]
	v_mfma_f32_16x16x32_bf16 v[100:103], v[186:189], v[220:223], v[100:103]
	v_mfma_f32_16x16x32_bf16 v[92:95], v[162:165], v[228:231], v[92:95]
	v_mfma_f32_16x16x32_bf16 v[84:87], v[186:189], v[228:231], v[84:87]
	v_mfma_f32_16x16x32_bf16 v[76:79], v[162:165], v[236:239], v[76:79]
	v_mfma_f32_16x16x32_bf16 v[68:71], v[186:189], v[236:239], v[68:71]
	v_mfma_f32_16x16x32_bf16 v[124:127], v[182:185], v[216:219], v[124:127]
	v_mfma_f32_16x16x32_bf16 v[116:119], v[190:193], v[216:219], v[116:119]
	v_mfma_f32_16x16x32_bf16 v[108:111], v[182:185], v[224:227], v[108:111]
	v_mfma_f32_16x16x32_bf16 v[100:103], v[190:193], v[224:227], v[100:103]
	v_mfma_f32_16x16x32_bf16 v[92:95], v[182:185], v[232:235], v[92:95]
	v_mfma_f32_16x16x32_bf16 v[84:87], v[190:193], v[232:235], v[84:87]
	v_mfma_f32_16x16x32_bf16 v[76:79], v[182:185], v[240:243], v[76:79]
	v_mfma_f32_16x16x32_bf16 v[68:71], v[190:193], v[240:243], v[68:71]
	v_mfma_f32_16x16x32_bf16 v[120:123], v[194:197], v[210:213], v[120:123]
	v_mfma_f32_16x16x32_bf16 v[112:115], v[202:205], v[210:213], v[112:115]
	v_mfma_f32_16x16x32_bf16 v[104:107], v[194:197], v[220:223], v[104:107]
	v_mfma_f32_16x16x32_bf16 v[96:99], v[202:205], v[220:223], v[96:99]
	v_mfma_f32_16x16x32_bf16 v[88:91], v[194:197], v[228:231], v[88:91]
	v_mfma_f32_16x16x32_bf16 v[80:83], v[202:205], v[228:231], v[80:83]
	v_mfma_f32_16x16x32_bf16 v[72:75], v[194:197], v[236:239], v[72:75]
	v_mfma_f32_16x16x32_bf16 v[64:67], v[202:205], v[236:239], v[64:67]
	v_mfma_f32_16x16x32_bf16 v[120:123], v[198:201], v[216:219], v[120:123]
	v_mfma_f32_16x16x32_bf16 v[112:115], v[206:209], v[216:219], v[112:115]
	v_mfma_f32_16x16x32_bf16 v[104:107], v[198:201], v[224:227], v[104:107]
	v_mfma_f32_16x16x32_bf16 v[96:99], v[206:209], v[224:227], v[96:99]
	v_mfma_f32_16x16x32_bf16 v[88:91], v[198:201], v[232:235], v[88:91]
	v_mfma_f32_16x16x32_bf16 v[80:83], v[206:209], v[232:235], v[80:83]
	v_mfma_f32_16x16x32_bf16 v[72:75], v[198:201], v[240:243], v[72:75]
	v_mfma_f32_16x16x32_bf16 v[64:67], v[206:209], v[240:243], v[64:67]
	s_setprio 0
	s_barrier
	s_mov_b32 m0, s60
	v_lshl_add_u64 v[244:245], v[214:215], 0, v[138:139]
	ds_read_b128 v[210:213], v179 offset:16384
	ds_read_b128 v[216:219], v179 offset:17408
	ds_read_b128 v[220:223], v179 offset:18432
	ds_read_b128 v[224:227], v179 offset:19456
	ds_read_b128 v[228:231], v179 offset:20480
	ds_read_b128 v[232:235], v179 offset:21504
	ds_read_b128 v[236:239], v179 offset:22528
	global_load_lds_dwordx4 v[244:245], off
	v_lshl_add_u64 v[246:247], v[214:215], 0, v[134:135]
	s_mov_b32 m0, s61
	v_lshl_add_u64 v[214:215], v[214:215], 0, s[14:15]
	global_load_lds_dwordx4 v[246:247], off
	v_lshl_add_u64 v[248:249], v[214:215], 0, v[138:139]
	s_mov_b32 m0, s62
	v_lshl_add_u64 v[214:215], v[214:215], 0, v[134:135]
	global_load_lds_dwordx4 v[248:249], off
	s_add_i32 m0, s62, 0x2000
	ds_read_b128 v[240:243], v179 offset:23552
	global_load_lds_dwordx4 v[214:215], off
	s_waitcnt vmcnt(6) lgkmcnt(0)
	s_setprio 1
	s_barrier
; #define PG8_STAGE(bufoff, gbase, voff) do { _Pragma("unroll") for (int _i = 0; _i < 2; ++_i) \
;         __builtin_amdgcn_global_load_lds((const unsigned*)((const char*)(gbase) + (voff)[_i]), (PG8_LAS unsigned*)(lds + (bufoff) + ldsw + _i * 8192), 16, 0, 0); } while (0)
; #define PG8_LDA(dst, b, h) do { _Pragma("unroll") for (int m = 0; m < 4; ++m) _Pragma("unroll") for (int k = 0; k < 2; ++k) dst[m][k] = *(const PG8_LAS bf16x8*)(lds + PG8_SA(b, h) + aoff + m * 2048 + k * 1024); } while (0)
; #define PG8_LDB(dst, b, h) do { _Pragma("unroll") for (int n = 0; n < 2; ++n) _Pragma("unroll") for (int k = 0; k < 2; ++k) dst[n][k] = *(const PG8_LAS bf16x8*)(lds + PG8_SB(b, h) + boff + n * 2048 + k * 1024); } while (0)
; #define PG8_MMA(ai, bj, At, Bt) do { __builtin_amdgcn_s_setprio(1); _Pragma("unroll") for (int m = 0; m < 4; ++m) _Pragma("unroll") for (int n = 0; n < 2; ++n) _Pragma("unroll") for (int k = 0; k < 2; ++k) \
;         acc[ai][bj][m][n] = __builtin_amdgcn_mfma_f32_16x16x32_bf16(Bt[n][k], At[m][k], acc[ai][bj][m][n], 0, 0, 0); __builtin_amdgcn_s_setprio(0); } while (0)
; #define PG8_WAIT_V(n) asm volatile("s_waitcnt vmcnt(" #n ")" ::: "memory")
; #define PG8_WAIT_L(n) asm volatile("s_waitcnt lgkmcnt(" #n ")" ::: "memory")
; #define PG8_BAR __builtin_amdgcn_s_barrier()
; #define PG8_SCHED __builtin_amdgcn_sched_barrier(0)
; template <class Epi, class Sched, bool ALIGN_EPI = false, bool SP2 = false>
; __device__ __forceinline__ void gemm_phase(PG8_LAS unsigned char* lds, const Gemm g, const Sched& S, const Epi& E) {
;     ...
;             PG8_WAIT_V(8); PG8_WAIT_L(0); PG8_BAR; PG8_MMA(1, 0, At, B0); PG8_MMA(1, 1, At, B1); PG8_BAR; PG8_SCHED;
;             PG8_LDB(B0, 1, 0); PG8_LDB(B1, 1, 1); PG8_SCHED; PG8_LDA(At, 1, 0); PG8_STAGE(PG8_SA(0, 1), a2 + hstep, voffA);
;             PG8_WAIT_V(8); PG8_WAIT_L(0); PG8_BAR; PG8_MMA(0, 0, At, B0); PG8_MMA(0, 1, At, B1); PG8_BAR; PG8_SCHED;
	v_mfma_f32_16x16x32_bf16 v[60:63], v[162:165], v[210:213], v[60:63]
	v_mfma_f32_16x16x32_bf16 v[52:55], v[186:189], v[210:213], v[52:55]
	v_mfma_f32_16x16x32_bf16 v[44:47], v[162:165], v[220:223], v[44:47]
	v_mfma_f32_16x16x32_bf16 v[36:39], v[186:189], v[220:223], v[36:39]
	s_mov_b32 m0, s46
	v_lshl_add_u64 v[250:251], v[172:173], 0, v[140:141]
	v_mfma_f32_16x16x32_bf16 v[28:31], v[162:165], v[228:231], v[28:31]
	global_load_lds_dwordx4 v[250:251], off
	v_mfma_f32_16x16x32_bf16 v[20:23], v[186:189], v[228:231], v[20:23]
	v_mfma_f32_16x16x32_bf16 v[12:15], v[162:165], v[236:239], v[12:15]
	v_mfma_f32_16x16x32_bf16 v[4:7], v[186:189], v[236:239], v[4:7]
	v_mfma_f32_16x16x32_bf16 v[60:63], v[182:185], v[216:219], v[60:63]
	v_mfma_f32_16x16x32_bf16 v[52:55], v[190:193], v[216:219], v[52:55]
	s_mov_b32 m0, s47
	v_lshl_add_u64 v[252:253], v[172:173], 0, v[136:137]
	v_mfma_f32_16x16x32_bf16 v[44:47], v[182:185], v[224:227], v[44:47]
	global_load_lds_dwordx4 v[252:253], off
	v_mfma_f32_16x16x32_bf16 v[36:39], v[190:193], v[224:227], v[36:39]
	v_mfma_f32_16x16x32_bf16 v[28:31], v[182:185], v[232:235], v[28:31]
	v_mfma_f32_16x16x32_bf16 v[20:23], v[190:193], v[232:235], v[20:23]
	v_mfma_f32_16x16x32_bf16 v[12:15], v[182:185], v[240:243], v[12:15]
	v_mfma_f32_16x16x32_bf16 v[4:7], v[190:193], v[240:243], v[4:7]
	v_mfma_f32_16x16x32_bf16 v[56:59], v[194:197], v[210:213], v[56:59]
	v_mfma_f32_16x16x32_bf16 v[48:51], v[202:205], v[210:213], v[48:51]
	v_mfma_f32_16x16x32_bf16 v[40:43], v[194:197], v[220:223], v[40:43]
	v_mfma_f32_16x16x32_bf16 v[32:35], v[202:205], v[220:223], v[32:35]
	v_mfma_f32_16x16x32_bf16 v[24:27], v[194:197], v[228:231], v[24:27]
	v_mfma_f32_16x16x32_bf16 v[16:19], v[202:205], v[228:231], v[16:19]
	v_mfma_f32_16x16x32_bf16 v[8:11], v[194:197], v[236:239], v[8:11]
	v_mfma_f32_16x16x32_bf16 v[0:3], v[202:205], v[236:239], v[0:3]
	v_mfma_f32_16x16x32_bf16 v[56:59], v[198:201], v[216:219], v[56:59]
	v_mfma_f32_16x16x32_bf16 v[48:51], v[206:209], v[216:219], v[48:51]
	v_mfma_f32_16x16x32_bf16 v[40:43], v[198:201], v[224:227], v[40:43]
	v_mfma_f32_16x16x32_bf16 v[32:35], v[206:209], v[224:227], v[32:35]
	v_mfma_f32_16x16x32_bf16 v[24:27], v[198:201], v[232:235], v[24:27]
	v_mfma_f32_16x16x32_bf16 v[16:19], v[206:209], v[232:235], v[16:19]
	v_mfma_f32_16x16x32_bf16 v[8:11], v[198:201], v[240:243], v[8:11]
	v_mfma_f32_16x16x32_bf16 v[0:3], v[206:209], v[240:243], v[0:3]
	s_setprio 0
	s_barrier
	s_add_i32 s11, 0, 0x18000
	v_add_u32_e32 v166, s11, v169
	s_add_i32 s13, 0, 0x1c000
	ds_read_b128 v[162:165], v166
	ds_read_b128 v[182:185], v166 offset:1024
	ds_read_b128 v[186:189], v166 offset:2048
	ds_read_b128 v[190:193], v166 offset:3072
	v_add_u32_e32 v166, s13, v169
	ds_read_b128 v[194:197], v166
	ds_read_b128 v[198:201], v166 offset:1024
	ds_read_b128 v[202:205], v166 offset:2048
	ds_read_b128 v[206:209], v166 offset:3072
	v_lshl_add_u64 v[172:173], v[172:173], 0, s[14:15]
	s_mov_b32 m0, s48
	v_lshl_add_u64 v[170:171], v[172:173], 0, v[140:141]
	ds_read_b128 v[210:213], v179 offset:32768
	ds_read_b128 v[216:219], v179 offset:33792
	ds_read_b128 v[220:223], v179 offset:34816
	ds_read_b128 v[224:227], v179 offset:35840
	ds_read_b128 v[228:231], v179 offset:36864
	ds_read_b128 v[232:235], v179 offset:37888
	ds_read_b128 v[236:239], v179 offset:38912
	ds_read_b128 v[240:243], v179 offset:39936
	global_load_lds_dwordx4 v[170:171], off
	s_mov_b32 m0, s49
	v_lshl_add_u64 v[170:171], v[172:173], 0, v[136:137]
	global_load_lds_dwordx4 v[170:171], off
	s_waitcnt vmcnt(8) lgkmcnt(0)
	s_setprio 1
	s_barrier
; #define PG8_STAGE(bufoff, gbase, voff) do { _Pragma("unroll") for (int _i = 0; _i < 2; ++_i) \
;         __builtin_amdgcn_global_load_lds((const unsigned*)((const char*)(gbase) + (voff)[_i]), (PG8_LAS unsigned*)(lds + (bufoff) + ldsw + _i * 8192), 16, 0, 0); } while (0)
; #define PG8_LDA(dst, b, h) do { _Pragma("unroll") for (int m = 0; m < 4; ++m) _Pragma("unroll") for (int k = 0; k < 2; ++k) dst[m][k] = *(const PG8_LAS bf16x8*)(lds + PG8_SA(b, h) + aoff + m * 2048 + k * 1024); } while (0)
; #define PG8_MMA(ai, bj, At, Bt) do { __builtin_amdgcn_s_setprio(1); _Pragma("unroll") for (int m = 0; m < 4; ++m) _Pragma("unroll") for (int n = 0; n < 2; ++n) _Pragma("unroll") for (int k = 0; k < 2; ++k) \
;         acc[ai][bj][m][n] = __builtin_amdgcn_mfma_f32_16x16x32_bf16(Bt[n][k], At[m][k], acc[ai][bj][m][n], 0, 0, 0); __builtin_amdgcn_s_setprio(0); } while (0)
; #define PG8_WAIT_V(n) asm volatile("s_waitcnt vmcnt(" #n ")" ::: "memory")
; #define PG8_WAIT_L(n) asm volatile("s_waitcnt lgkmcnt(" #n ")" ::: "memory")
; #define PG8_BAR __builtin_amdgcn_s_barrier()
; #define PG8_SCHED __builtin_amdgcn_sched_barrier(0)
; template <class Epi, class Sched, bool ALIGN_EPI = false, bool SP2 = false>
; __device__ __forceinline__ void gemm_phase(PG8_LAS unsigned char* lds, const Gemm g, const Sched& S, const Epi& E) {
;     ...
;             PG8_WAIT_V(8); PG8_WAIT_L(0); PG8_BAR; PG8_MMA(0, 0, At, B0); PG8_MMA(0, 1, At, B1); PG8_BAR; PG8_SCHED;
;             PG8_LDA(At, 1, 1); PG8_STAGE(PG8_SB(1, 0), b3, voffB); PG8_STAGE(PG8_SB(1, 1), b3 + hstep, voffB); PG8_STAGE(PG8_SA(1, 0), a3, voffA);
;             PG8_WAIT_V(8); PG8_WAIT_L(0); PG8_BAR; PG8_MMA(1, 0, At, B0); PG8_MMA(1, 1, At, B1); PG8_BAR; PG8_SCHED;
	v_mfma_f32_16x16x32_bf16 v[124:127], v[162:165], v[210:213], v[124:127]
	v_mfma_f32_16x16x32_bf16 v[116:119], v[186:189], v[210:213], v[116:119]
	v_mfma_f32_16x16x32_bf16 v[108:111], v[162:165], v[220:223], v[108:111]
	v_mfma_f32_16x16x32_bf16 v[100:103], v[186:189], v[220:223], v[100:103]
	v_mfma_f32_16x16x32_bf16 v[92:95], v[162:165], v[228:231], v[92:95]
	v_mfma_f32_16x16x32_bf16 v[84:87], v[186:189], v[228:231], v[84:87]
	v_mfma_f32_16x16x32_bf16 v[76:79], v[162:165], v[236:239], v[76:79]
	v_mfma_f32_16x16x32_bf16 v[68:71], v[186:189], v[236:239], v[68:71]
	v_mfma_f32_16x16x32_bf16 v[124:127], v[182:185], v[216:219], v[124:127]
	v_mfma_f32_16x16x32_bf16 v[116:119], v[190:193], v[216:219], v[116:119]
	v_mfma_f32_16x16x32_bf16 v[108:111], v[182:185], v[224:227], v[108:111]
	v_mfma_f32_16x16x32_bf16 v[100:103], v[190:193], v[224:227], v[100:103]
	v_mfma_f32_16x16x32_bf16 v[92:95], v[182:185], v[232:235], v[92:95]
	v_mfma_f32_16x16x32_bf16 v[84:87], v[190:193], v[232:235], v[84:87]
	v_mfma_f32_16x16x32_bf16 v[76:79], v[182:185], v[240:243], v[76:79]
	v_mfma_f32_16x16x32_bf16 v[68:71], v[190:193], v[240:243], v[68:71]
	v_mfma_f32_16x16x32_bf16 v[120:123], v[194:197], v[210:213], v[120:123]
	v_mfma_f32_16x16x32_bf16 v[112:115], v[202:205], v[210:213], v[112:115]
	v_mfma_f32_16x16x32_bf16 v[104:107], v[194:197], v[220:223], v[104:107]
	v_mfma_f32_16x16x32_bf16 v[96:99], v[202:205], v[220:223], v[96:99]
	v_mfma_f32_16x16x32_bf16 v[88:91], v[194:197], v[228:231], v[88:91]
	v_mfma_f32_16x16x32_bf16 v[80:83], v[202:205], v[228:231], v[80:83]
	v_mfma_f32_16x16x32_bf16 v[72:75], v[194:197], v[236:239], v[72:75]
	v_mfma_f32_16x16x32_bf16 v[64:67], v[202:205], v[236:239], v[64:67]
	v_mfma_f32_16x16x32_bf16 v[120:123], v[198:201], v[216:219], v[120:123]
	v_mfma_f32_16x16x32_bf16 v[112:115], v[206:209], v[216:219], v[112:115]
	v_mfma_f32_16x16x32_bf16 v[104:107], v[198:201], v[224:227], v[104:107]
	v_mfma_f32_16x16x32_bf16 v[96:99], v[206:209], v[224:227], v[96:99]
	v_mfma_f32_16x16x32_bf16 v[88:91], v[198:201], v[232:235], v[88:91]
	v_mfma_f32_16x16x32_bf16 v[80:83], v[206:209], v[232:235], v[80:83]
	v_mfma_f32_16x16x32_bf16 v[72:75], v[198:201], v[240:243], v[72:75]
	v_mfma_f32_16x16x32_bf16 v[64:67], v[206:209], v[240:243], v[64:67]
	s_setprio 0
	s_barrier
	s_add_i32 s11, s11, s29
	s_add_i32 m0, s11, 0xffffff80
	ds_read_b128 v[210:213], v179 offset:49152
	ds_read_b128 v[216:219], v179 offset:50176
	ds_read_b128 v[220:223], v179 offset:51200
	ds_read_b128 v[224:227], v179 offset:52224
	ds_read_b128 v[228:231], v179 offset:53248
	ds_read_b128 v[232:235], v179 offset:54272
	global_load_lds_dwordx4 v[244:245], off offset:128
	s_add_i32 m0, s11, 0x1f80
	s_add_i32 s11, s13, s29
	global_load_lds_dwordx4 v[246:247], off offset:128
	s_add_i32 m0, s11, 0xffffff80
	ds_read_b128 v[240:243], v179 offset:56320
	global_load_lds_dwordx4 v[248:249], off offset:128
	s_add_i32 m0, s11, 0x1f80
	ds_read_b128 v[236:239], v179 offset:55296
	global_load_lds_dwordx4 v[214:215], off offset:128
	s_waitcnt vmcnt(6) lgkmcnt(0)
	s_setprio 1
	s_barrier
	v_mfma_f32_16x16x32_bf16 v[60:63], v[162:165], v[210:213], v[60:63]
	v_mfma_f32_16x16x32_bf16 v[52:55], v[186:189], v[210:213], v[52:55]
	v_mfma_f32_16x16x32_bf16 v[44:47], v[162:165], v[220:223], v[44:47]
	v_mfma_f32_16x16x32_bf16 v[36:39], v[186:189], v[220:223], v[36:39]
	s_add_i32 m0, s50, 0xffffff80
	v_mfma_f32_16x16x32_bf16 v[28:31], v[162:165], v[228:231], v[28:31]
	global_load_lds_dwordx4 v[250:251], off offset:128
	v_mfma_f32_16x16x32_bf16 v[20:23], v[186:189], v[228:231], v[20:23]
	v_mfma_f32_16x16x32_bf16 v[12:15], v[162:165], v[236:239], v[12:15]
	v_mfma_f32_16x16x32_bf16 v[4:7], v[186:189], v[236:239], v[4:7]
	v_mfma_f32_16x16x32_bf16 v[60:63], v[182:185], v[216:219], v[60:63]
	v_mfma_f32_16x16x32_bf16 v[52:55], v[190:193], v[216:219], v[52:55]
	s_add_i32 m0, s51, 0xffffff80
	v_mfma_f32_16x16x32_bf16 v[44:47], v[182:185], v[224:227], v[44:47]
	global_load_lds_dwordx4 v[252:253], off offset:128
	v_mfma_f32_16x16x32_bf16 v[36:39], v[190:193], v[224:227], v[36:39]
	v_mfma_f32_16x16x32_bf16 v[28:31], v[182:185], v[232:235], v[28:31]
	v_mfma_f32_16x16x32_bf16 v[20:23], v[190:193], v[232:235], v[20:23]
	v_mfma_f32_16x16x32_bf16 v[12:15], v[182:185], v[240:243], v[12:15]
	v_mfma_f32_16x16x32_bf16 v[4:7], v[190:193], v[240:243], v[4:7]
	v_mfma_f32_16x16x32_bf16 v[56:59], v[194:197], v[210:213], v[56:59]
	v_mfma_f32_16x16x32_bf16 v[48:51], v[202:205], v[210:213], v[48:51]
	v_mfma_f32_16x16x32_bf16 v[40:43], v[194:197], v[220:223], v[40:43]
	v_mfma_f32_16x16x32_bf16 v[32:35], v[202:205], v[220:223], v[32:35]
	v_mfma_f32_16x16x32_bf16 v[24:27], v[194:197], v[228:231], v[24:27]
	v_mfma_f32_16x16x32_bf16 v[16:19], v[202:205], v[228:231], v[16:19]
	v_mfma_f32_16x16x32_bf16 v[8:11], v[194:197], v[236:239], v[8:11]
	v_mfma_f32_16x16x32_bf16 v[0:3], v[202:205], v[236:239], v[0:3]
	v_mfma_f32_16x16x32_bf16 v[56:59], v[198:201], v[216:219], v[56:59]
	v_mfma_f32_16x16x32_bf16 v[48:51], v[206:209], v[216:219], v[48:51]
	v_mfma_f32_16x16x32_bf16 v[40:43], v[198:201], v[224:227], v[40:43]
	v_mfma_f32_16x16x32_bf16 v[32:35], v[206:209], v[224:227], v[32:35]
	v_mfma_f32_16x16x32_bf16 v[24:27], v[198:201], v[232:235], v[24:27]
	v_mfma_f32_16x16x32_bf16 v[16:19], v[206:209], v[232:235], v[16:19]
	v_mfma_f32_16x16x32_bf16 v[8:11], v[198:201], v[240:243], v[8:11]
	v_mfma_f32_16x16x32_bf16 v[0:3], v[206:209], v[240:243], v[0:3]
	s_setprio 0
	s_barrier
	v_lshl_add_u64 v[158:159], v[158:159], 0, s[26:27]
	s_cmp_ge_i32 s10, s52
	v_lshl_add_u64 v[160:161], v[160:161], 0, s[26:27]
	s_cbranch_scc0 .LBB0_1776

; #define PG8_STAGE(bufoff, gbase, voff) do { _Pragma("unroll") for (int _i = 0; _i < 2; ++_i) \
;         __builtin_amdgcn_global_load_lds((const unsigned*)((const char*)(gbase) + (voff)[_i]), (PG8_LAS unsigned*)(lds + (bufoff) + ldsw + _i * 8192), 16, 0, 0); } while (0)
; #define PG8_LDA(dst, b, h) do { _Pragma("unroll") for (int m = 0; m < 4; ++m) _Pragma("unroll") for (int k = 0; k < 2; ++k) dst[m][k] = *(const PG8_LAS bf16x8*)(lds + PG8_SA(b, h) + aoff + m * 2048 + k * 1024); } while (0)
; #define PG8_LDB(dst, b, h) do { _Pragma("unroll") for (int n = 0; n < 2; ++n) _Pragma("unroll") for (int k = 0; k < 2; ++k) dst[n][k] = *(const PG8_LAS bf16x8*)(lds + PG8_SB(b, h) + boff + n * 2048 + k * 1024); } while (0)
; #define PG8_MMA(ai, bj, At, Bt) do { __builtin_amdgcn_s_setprio(1); _Pragma("unroll") for (int m = 0; m < 4; ++m) _Pragma("unroll") for (int n = 0; n < 2; ++n) _Pragma("unroll") for (int k = 0; k < 2; ++k) \
;         acc[ai][bj][m][n] = __builtin_amdgcn_mfma_f32_16x16x32_bf16(Bt[n][k], At[m][k], acc[ai][bj][m][n], 0, 0, 0); __builtin_amdgcn_s_setprio(0); } while (0)
; #define PG8_WAIT_V(n) asm volatile("s_waitcnt vmcnt(" #n ")" ::: "memory")
; #define PG8_BAR __builtin_amdgcn_s_barrier()
; template <class Epi, class Sched, bool ALIGN_EPI = false, bool SP2 = false>
; __device__ __forceinline__ void gemm_phase(PG8_LAS unsigned char* lds, const Gemm g, const Sched& S, const Epi& E) {
;     ...
;         for (int t = 0; t < nt; t += 2) {
;             const bool last = (t == nt - 2);
;             const char* a1 = cA + (size_t)(t + 1) * kstep;
;             const char* a2 = last ? nA : cA + (size_t)(t + 2) * kstep; const char* b2 = last ? nB : cB + (size_t)(t + 2) * kstep;
;             const char* a3 = a2 + kstep; const char* b3 = b2 + kstep;
;             if (last && has_next) S.a_ready(nxt);
;             if constexpr (SP2) {
;             PG8_LDB(B0, 0, 0); PG8_LDB(B1, 0, 1); PG8_SCHED; PG8_LDA(At, 0, 0); PG8_STAGE(PG8_SA(1, 1), a1 + hstep, voffA);
;             PG8_WAIT_V(8); PG8_WAIT_L(0); PG8_BAR; PG8_MMA(0, 0, At, B0); PG8_MMA(0, 1, At, B1); PG8_BAR; PG8_SCHED;
;             PG8_LDA(At, 0, 1); PG8_STAGE(PG8_SB(0, 0), b2, voffB); PG8_STAGE(PG8_SB(0, 1), b2 + hstep, voffB); PG8_STAGE(PG8_SA(0, 0), a2, voffA);
;             PG8_WAIT_V(8); PG8_WAIT_L(0); PG8_BAR; PG8_MMA(1, 0, At, B0); PG8_MMA(1, 1, At, B1); PG8_BAR; PG8_SCHED;
.LBB0_1924:
	v_add_u32_e32 v192, s50, v161
	ds_read_b128 v[164:167], v162
	ds_read_b128 v[168:171], v162 offset:1024
	ds_read_b128 v[172:175], v162 offset:2048
	ds_read_b128 v[176:179], v162 offset:3072
	ds_read_b128 v[180:183], v192
	ds_read_b128 v[184:187], v192 offset:1024
	ds_read_b128 v[188:191], v192 offset:2048
	ds_read_b128 v[192:195], v192 offset:3072
	s_cmp_eq_u32 s49, s10
	v_lshl_add_u64 v[196:197], v[158:159], 0, s[24:25]
	s_cselect_b64 vcc, -1, 0
	s_add_i32 s10, s10, 2
	v_cndmask_b32_e32 v213, v197, v151, vcc
	v_cndmask_b32_e32 v212, v196, v150, vcc
	v_cndmask_b32_e32 v215, v155, v153, vcc
	v_cndmask_b32_e32 v214, v154, v152, vcc
	s_mov_b32 m0, s51
	v_lshl_add_u64 v[232:233], v[158:159], 0, v[146:147]
	ds_read_b128 v[196:199], v163
	ds_read_b128 v[200:203], v163 offset:1024
	ds_read_b128 v[204:207], v163 offset:2048
	ds_read_b128 v[208:211], v163 offset:3072
	ds_read_b128 v[216:219], v163 offset:4096
	ds_read_b128 v[220:223], v163 offset:5120
	ds_read_b128 v[224:227], v163 offset:6144
	ds_read_b128 v[228:231], v163 offset:7168
	global_load_lds_dwordx4 v[232:233], off
	s_mov_b32 m0, s52
	v_lshl_add_u64 v[232:233], v[158:159], 0, v[144:145]
	global_load_lds_dwordx4 v[232:233], off
	s_waitcnt vmcnt(8) lgkmcnt(0)
	s_setprio 1
	s_barrier
	v_mfma_f32_16x16x32_bf16 v[124:127], v[164:167], v[196:199], v[124:127]
	v_mfma_f32_16x16x32_bf16 v[120:123], v[172:175], v[196:199], v[120:123]
	v_mfma_f32_16x16x32_bf16 v[108:111], v[164:167], v[204:207], v[108:111]
	v_mfma_f32_16x16x32_bf16 v[104:107], v[172:175], v[204:207], v[104:107]
	v_mfma_f32_16x16x32_bf16 v[92:95], v[164:167], v[216:219], v[92:95]
	v_mfma_f32_16x16x32_bf16 v[88:91], v[172:175], v[216:219], v[88:91]
	v_mfma_f32_16x16x32_bf16 v[76:79], v[164:167], v[224:227], v[76:79]
	v_mfma_f32_16x16x32_bf16 v[72:75], v[172:175], v[224:227], v[72:75]
	v_mfma_f32_16x16x32_bf16 v[124:127], v[168:171], v[200:203], v[124:127]
	v_mfma_f32_16x16x32_bf16 v[120:123], v[176:179], v[200:203], v[120:123]
	v_mfma_f32_16x16x32_bf16 v[108:111], v[168:171], v[208:211], v[108:111]
	v_mfma_f32_16x16x32_bf16 v[104:107], v[176:179], v[208:211], v[104:107]
	v_mfma_f32_16x16x32_bf16 v[92:95], v[168:171], v[220:223], v[92:95]
	v_mfma_f32_16x16x32_bf16 v[88:91], v[176:179], v[220:223], v[88:91]
	v_mfma_f32_16x16x32_bf16 v[76:79], v[168:171], v[228:231], v[76:79]
	v_mfma_f32_16x16x32_bf16 v[72:75], v[176:179], v[228:231], v[72:75]
	v_mfma_f32_16x16x32_bf16 v[116:119], v[180:183], v[196:199], v[116:119]
	v_mfma_f32_16x16x32_bf16 v[112:115], v[188:191], v[196:199], v[112:115]
	v_mfma_f32_16x16x32_bf16 v[100:103], v[180:183], v[204:207], v[100:103]
	v_mfma_f32_16x16x32_bf16 v[96:99], v[188:191], v[204:207], v[96:99]
	v_mfma_f32_16x16x32_bf16 v[84:87], v[180:183], v[216:219], v[84:87]
	v_mfma_f32_16x16x32_bf16 v[80:83], v[188:191], v[216:219], v[80:83]
	v_mfma_f32_16x16x32_bf16 v[68:71], v[180:183], v[224:227], v[68:71]
	v_mfma_f32_16x16x32_bf16 v[64:67], v[188:191], v[224:227], v[64:67]
	v_mfma_f32_16x16x32_bf16 v[116:119], v[184:187], v[200:203], v[116:119]
	v_mfma_f32_16x16x32_bf16 v[112:115], v[192:195], v[200:203], v[112:115]
	v_mfma_f32_16x16x32_bf16 v[100:103], v[184:187], v[208:211], v[100:103]
	v_mfma_f32_16x16x32_bf16 v[96:99], v[192:195], v[208:211], v[96:99]
	v_mfma_f32_16x16x32_bf16 v[84:87], v[184:187], v[220:223], v[84:87]
	v_mfma_f32_16x16x32_bf16 v[80:83], v[192:195], v[220:223], v[80:83]
	v_mfma_f32_16x16x32_bf16 v[68:71], v[184:187], v[228:231], v[68:71]
	v_mfma_f32_16x16x32_bf16 v[64:67], v[192:195], v[228:231], v[64:67]
	s_setprio 0
	s_barrier
	s_mov_b32 m0, s53
	v_lshl_add_u64 v[232:233], v[214:215], 0, v[138:139]
	ds_read_b128 v[196:199], v163 offset:16384
	ds_read_b128 v[200:203], v163 offset:17408
	ds_read_b128 v[204:207], v163 offset:18432
	ds_read_b128 v[208:211], v163 offset:19456
	ds_read_b128 v[216:219], v163 offset:20480
	ds_read_b128 v[220:223], v163 offset:21504
	ds_read_b128 v[224:227], v163 offset:22528
	global_load_lds_dwordx4 v[232:233], off
	v_lshl_add_u64 v[234:235], v[214:215], 0, v[134:135]
	s_mov_b32 m0, s54
	v_lshl_add_u64 v[214:215], v[214:215], 0, s[14:15]
	global_load_lds_dwordx4 v[234:235], off
	v_lshl_add_u64 v[236:237], v[214:215], 0, v[138:139]
	s_mov_b32 m0, s55
	v_lshl_add_u64 v[214:215], v[214:215], 0, v[134:135]
	global_load_lds_dwordx4 v[236:237], off
	s_mov_b32 m0, s56
	ds_read_b128 v[228:231], v163 offset:23552
	global_load_lds_dwordx4 v[214:215], off
	s_waitcnt vmcnt(6) lgkmcnt(0)
	s_setprio 1
	s_barrier
; #define PG8_STAGE(bufoff, gbase, voff) do { _Pragma("unroll") for (int _i = 0; _i < 2; ++_i) \
;         __builtin_amdgcn_global_load_lds((const unsigned*)((const char*)(gbase) + (voff)[_i]), (PG8_LAS unsigned*)(lds + (bufoff) + ldsw + _i * 8192), 16, 0, 0); } while (0)
; #define PG8_LDA(dst, b, h) do { _Pragma("unroll") for (int m = 0; m < 4; ++m) _Pragma("unroll") for (int k = 0; k < 2; ++k) dst[m][k] = *(const PG8_LAS bf16x8*)(lds + PG8_SA(b, h) + aoff + m * 2048 + k * 1024); } while (0)
; #define PG8_LDB(dst, b, h) do { _Pragma("unroll") for (int n = 0; n < 2; ++n) _Pragma("unroll") for (int k = 0; k < 2; ++k) dst[n][k] = *(const PG8_LAS bf16x8*)(lds + PG8_SB(b, h) + boff + n * 2048 + k * 1024); } while (0)
; #define PG8_MMA(ai, bj, At, Bt) do { __builtin_amdgcn_s_setprio(1); _Pragma("unroll") for (int m = 0; m < 4; ++m) _Pragma("unroll") for (int n = 0; n < 2; ++n) _Pragma("unroll") for (int k = 0; k < 2; ++k) \
;         acc[ai][bj][m][n] = __builtin_amdgcn_mfma_f32_16x16x32_bf16(Bt[n][k], At[m][k], acc[ai][bj][m][n], 0, 0, 0); __builtin_amdgcn_s_setprio(0); } while (0)
; #define PG8_WAIT_V(n) asm volatile("s_waitcnt vmcnt(" #n ")" ::: "memory")
; #define PG8_WAIT_L(n) asm volatile("s_waitcnt lgkmcnt(" #n ")" ::: "memory")
; #define PG8_BAR __builtin_amdgcn_s_barrier()
; #define PG8_SCHED __builtin_amdgcn_sched_barrier(0)
; template <class Epi, class Sched, bool ALIGN_EPI = false, bool SP2 = false>
; __device__ __forceinline__ void gemm_phase(PG8_LAS unsigned char* lds, const Gemm g, const Sched& S, const Epi& E) {
;     ...
;             PG8_WAIT_V(8); PG8_WAIT_L(0); PG8_BAR; PG8_MMA(1, 0, At, B0); PG8_MMA(1, 1, At, B1); PG8_BAR; PG8_SCHED;
;             PG8_LDB(B0, 1, 0); PG8_LDB(B1, 1, 1); PG8_SCHED; PG8_LDA(At, 1, 0); PG8_STAGE(PG8_SA(0, 1), a2 + hstep, voffA);
;             PG8_WAIT_V(8); PG8_WAIT_L(0); PG8_BAR; PG8_MMA(0, 0, At, B0); PG8_MMA(0, 1, At, B1); PG8_BAR; PG8_SCHED;
	v_mfma_f32_16x16x32_bf16 v[60:63], v[164:167], v[196:199], v[60:63]
	v_mfma_f32_16x16x32_bf16 v[56:59], v[172:175], v[196:199], v[56:59]
	v_mfma_f32_16x16x32_bf16 v[44:47], v[164:167], v[204:207], v[44:47]
	v_mfma_f32_16x16x32_bf16 v[40:43], v[172:175], v[204:207], v[40:43]
	s_mov_b32 m0, s37
	v_lshl_add_u64 v[238:239], v[212:213], 0, v[140:141]
	v_mfma_f32_16x16x32_bf16 v[28:31], v[164:167], v[216:219], v[28:31]
	global_load_lds_dwordx4 v[238:239], off
	v_mfma_f32_16x16x32_bf16 v[24:27], v[172:175], v[216:219], v[24:27]
	v_mfma_f32_16x16x32_bf16 v[12:15], v[164:167], v[224:227], v[12:15]
	v_mfma_f32_16x16x32_bf16 v[8:11], v[172:175], v[224:227], v[8:11]
	v_mfma_f32_16x16x32_bf16 v[60:63], v[168:171], v[200:203], v[60:63]
	v_mfma_f32_16x16x32_bf16 v[56:59], v[176:179], v[200:203], v[56:59]
	s_mov_b32 m0, s41
	v_lshl_add_u64 v[240:241], v[212:213], 0, v[136:137]
	v_mfma_f32_16x16x32_bf16 v[44:47], v[168:171], v[208:211], v[44:47]
	global_load_lds_dwordx4 v[240:241], off
	v_mfma_f32_16x16x32_bf16 v[40:43], v[176:179], v[208:211], v[40:43]
	v_mfma_f32_16x16x32_bf16 v[28:31], v[168:171], v[220:223], v[28:31]
	v_mfma_f32_16x16x32_bf16 v[24:27], v[176:179], v[220:223], v[24:27]
	v_mfma_f32_16x16x32_bf16 v[12:15], v[168:171], v[228:231], v[12:15]
	v_mfma_f32_16x16x32_bf16 v[8:11], v[176:179], v[228:231], v[8:11]
	v_mfma_f32_16x16x32_bf16 v[52:55], v[180:183], v[196:199], v[52:55]
	v_mfma_f32_16x16x32_bf16 v[48:51], v[188:191], v[196:199], v[48:51]
	v_mfma_f32_16x16x32_bf16 v[36:39], v[180:183], v[204:207], v[36:39]
	v_mfma_f32_16x16x32_bf16 v[32:35], v[188:191], v[204:207], v[32:35]
	v_mfma_f32_16x16x32_bf16 v[20:23], v[180:183], v[216:219], v[20:23]
	v_mfma_f32_16x16x32_bf16 v[16:19], v[188:191], v[216:219], v[16:19]
	v_mfma_f32_16x16x32_bf16 v[4:7], v[180:183], v[224:227], v[4:7]
	v_mfma_f32_16x16x32_bf16 v[0:3], v[188:191], v[224:227], v[0:3]
	v_mfma_f32_16x16x32_bf16 v[52:55], v[184:187], v[200:203], v[52:55]
	v_mfma_f32_16x16x32_bf16 v[48:51], v[192:195], v[200:203], v[48:51]
	v_mfma_f32_16x16x32_bf16 v[36:39], v[184:187], v[208:211], v[36:39]
	v_mfma_f32_16x16x32_bf16 v[32:35], v[192:195], v[208:211], v[32:35]
	v_mfma_f32_16x16x32_bf16 v[20:23], v[184:187], v[220:223], v[20:23]
	v_mfma_f32_16x16x32_bf16 v[16:19], v[192:195], v[220:223], v[16:19]
	v_mfma_f32_16x16x32_bf16 v[4:7], v[184:187], v[228:231], v[4:7]
	v_mfma_f32_16x16x32_bf16 v[0:3], v[192:195], v[228:231], v[0:3]
	s_setprio 0
	s_barrier
	v_add_u32_e32 v176, s57, v161
	v_add_u32_e32 v192, s58, v161
	ds_read_b128 v[164:167], v176
	ds_read_b128 v[168:171], v176 offset:1024
	ds_read_b128 v[172:175], v176 offset:2048
	ds_read_b128 v[176:179], v176 offset:3072
	ds_read_b128 v[180:183], v192
	ds_read_b128 v[184:187], v192 offset:1024
	ds_read_b128 v[188:191], v192 offset:2048
	ds_read_b128 v[192:195], v192 offset:3072
	v_lshl_add_u64 v[212:213], v[212:213], 0, s[14:15]
	s_mov_b32 m0, s44
	v_lshl_add_u64 v[242:243], v[212:213], 0, v[140:141]
	ds_read_b128 v[196:199], v163 offset:32768
	ds_read_b128 v[200:203], v163 offset:33792
	ds_read_b128 v[204:207], v163 offset:34816
	ds_read_b128 v[208:211], v163 offset:35840
	ds_read_b128 v[216:219], v163 offset:36864
	ds_read_b128 v[220:223], v163 offset:37888
	ds_read_b128 v[224:227], v163 offset:38912
	ds_read_b128 v[228:231], v163 offset:39936
	global_load_lds_dwordx4 v[242:243], off
	s_mov_b32 m0, s45
	v_lshl_add_u64 v[212:213], v[212:213], 0, v[136:137]
	global_load_lds_dwordx4 v[212:213], off
	s_waitcnt vmcnt(8) lgkmcnt(0)
	s_setprio 1
	s_barrier
; #define PG8_STAGE(bufoff, gbase, voff) do { _Pragma("unroll") for (int _i = 0; _i < 2; ++_i) \
;         __builtin_amdgcn_global_load_lds((const unsigned*)((const char*)(gbase) + (voff)[_i]), (PG8_LAS unsigned*)(lds + (bufoff) + ldsw + _i * 8192), 16, 0, 0); } while (0)
; #define PG8_LDA(dst, b, h) do { _Pragma("unroll") for (int m = 0; m < 4; ++m) _Pragma("unroll") for (int k = 0; k < 2; ++k) dst[m][k] = *(const PG8_LAS bf16x8*)(lds + PG8_SA(b, h) + aoff + m * 2048 + k * 1024); } while (0)
; #define PG8_MMA(ai, bj, At, Bt) do { __builtin_amdgcn_s_setprio(1); _Pragma("unroll") for (int m = 0; m < 4; ++m) _Pragma("unroll") for (int n = 0; n < 2; ++n) _Pragma("unroll") for (int k = 0; k < 2; ++k) \
;         acc[ai][bj][m][n] = __builtin_amdgcn_mfma_f32_16x16x32_bf16(Bt[n][k], At[m][k], acc[ai][bj][m][n], 0, 0, 0); __builtin_amdgcn_s_setprio(0); } while (0)
; #define PG8_WAIT_V(n) asm volatile("s_waitcnt vmcnt(" #n ")" ::: "memory")
; #define PG8_WAIT_L(n) asm volatile("s_waitcnt lgkmcnt(" #n ")" ::: "memory")
; #define PG8_BAR __builtin_amdgcn_s_barrier()
; #define PG8_SCHED __builtin_amdgcn_sched_barrier(0)
; template <class Epi, class Sched, bool ALIGN_EPI = false, bool SP2 = false>
; __device__ __forceinline__ void gemm_phase(PG8_LAS unsigned char* lds, const Gemm g, const Sched& S, const Epi& E) {
;     ...
;             PG8_WAIT_V(8); PG8_WAIT_L(0); PG8_BAR; PG8_MMA(0, 0, At, B0); PG8_MMA(0, 1, At, B1); PG8_BAR; PG8_SCHED;
;             PG8_LDA(At, 1, 1); PG8_STAGE(PG8_SB(1, 0), b3, voffB); PG8_STAGE(PG8_SB(1, 1), b3 + hstep, voffB); PG8_STAGE(PG8_SA(1, 0), a3, voffA);
;             PG8_WAIT_V(8); PG8_WAIT_L(0); PG8_BAR; PG8_MMA(1, 0, At, B0); PG8_MMA(1, 1, At, B1); PG8_BAR; PG8_SCHED;
	v_mfma_f32_16x16x32_bf16 v[124:127], v[164:167], v[196:199], v[124:127]
	v_mfma_f32_16x16x32_bf16 v[120:123], v[172:175], v[196:199], v[120:123]
	v_mfma_f32_16x16x32_bf16 v[108:111], v[164:167], v[204:207], v[108:111]
	v_mfma_f32_16x16x32_bf16 v[104:107], v[172:175], v[204:207], v[104:107]
	v_mfma_f32_16x16x32_bf16 v[92:95], v[164:167], v[216:219], v[92:95]
	v_mfma_f32_16x16x32_bf16 v[88:91], v[172:175], v[216:219], v[88:91]
	v_mfma_f32_16x16x32_bf16 v[76:79], v[164:167], v[224:227], v[76:79]
	v_mfma_f32_16x16x32_bf16 v[72:75], v[172:175], v[224:227], v[72:75]
	v_mfma_f32_16x16x32_bf16 v[124:127], v[168:171], v[200:203], v[124:127]
	v_mfma_f32_16x16x32_bf16 v[120:123], v[176:179], v[200:203], v[120:123]
	v_mfma_f32_16x16x32_bf16 v[108:111], v[168:171], v[208:211], v[108:111]
	v_mfma_f32_16x16x32_bf16 v[104:107], v[176:179], v[208:211], v[104:107]
	v_mfma_f32_16x16x32_bf16 v[92:95], v[168:171], v[220:223], v[92:95]
	v_mfma_f32_16x16x32_bf16 v[88:91], v[176:179], v[220:223], v[88:91]
	v_mfma_f32_16x16x32_bf16 v[76:79], v[168:171], v[228:231], v[76:79]
	v_mfma_f32_16x16x32_bf16 v[72:75], v[176:179], v[228:231], v[72:75]
	v_mfma_f32_16x16x32_bf16 v[116:119], v[180:183], v[196:199], v[116:119]
	v_mfma_f32_16x16x32_bf16 v[112:115], v[188:191], v[196:199], v[112:115]
	v_mfma_f32_16x16x32_bf16 v[100:103], v[180:183], v[204:207], v[100:103]
	v_mfma_f32_16x16x32_bf16 v[96:99], v[188:191], v[204:207], v[96:99]
	v_mfma_f32_16x16x32_bf16 v[84:87], v[180:183], v[216:219], v[84:87]
	v_mfma_f32_16x16x32_bf16 v[80:83], v[188:191], v[216:219], v[80:83]
	v_mfma_f32_16x16x32_bf16 v[68:71], v[180:183], v[224:227], v[68:71]
	v_mfma_f32_16x16x32_bf16 v[64:67], v[188:191], v[224:227], v[64:67]
	v_mfma_f32_16x16x32_bf16 v[116:119], v[184:187], v[200:203], v[116:119]
	v_mfma_f32_16x16x32_bf16 v[112:115], v[192:195], v[200:203], v[112:115]
	v_mfma_f32_16x16x32_bf16 v[100:103], v[184:187], v[208:211], v[100:103]
	v_mfma_f32_16x16x32_bf16 v[96:99], v[192:195], v[208:211], v[96:99]
	v_mfma_f32_16x16x32_bf16 v[84:87], v[184:187], v[220:223], v[84:87]
	v_mfma_f32_16x16x32_bf16 v[80:83], v[192:195], v[220:223], v[80:83]
	v_mfma_f32_16x16x32_bf16 v[68:71], v[184:187], v[228:231], v[68:71]
	v_mfma_f32_16x16x32_bf16 v[64:67], v[192:195], v[228:231], v[64:67]
	s_setprio 0
	s_barrier
	s_add_i32 m0, s59, 0xffffff80
	ds_read_b128 v[196:199], v163 offset:49152
	ds_read_b128 v[200:203], v163 offset:50176
	ds_read_b128 v[204:207], v163 offset:51200
	ds_read_b128 v[208:211], v163 offset:52224
	ds_read_b128 v[216:219], v163 offset:53248
	global_load_lds_dwordx4 v[232:233], off offset:128
	s_add_i32 m0, s60, 0xffffff80
	ds_read_b128 v[228:231], v163 offset:56320
	global_load_lds_dwordx4 v[234:235], off offset:128
	s_add_i32 m0, s61, 0xffffff80
	ds_read_b128 v[224:227], v163 offset:55296
	global_load_lds_dwordx4 v[236:237], off offset:128
	s_add_i32 m0, s62, 0xffffff80
	ds_read_b128 v[220:223], v163 offset:54272
	global_load_lds_dwordx4 v[214:215], off offset:128
	s_waitcnt vmcnt(6) lgkmcnt(0)
	s_setprio 1
	s_barrier
	v_mfma_f32_16x16x32_bf16 v[60:63], v[164:167], v[196:199], v[60:63]
	v_mfma_f32_16x16x32_bf16 v[56:59], v[172:175], v[196:199], v[56:59]
	v_mfma_f32_16x16x32_bf16 v[44:47], v[164:167], v[204:207], v[44:47]
	v_mfma_f32_16x16x32_bf16 v[40:43], v[172:175], v[204:207], v[40:43]
	s_add_i32 m0, s46, 0xffffff80
	v_mfma_f32_16x16x32_bf16 v[28:31], v[164:167], v[216:219], v[28:31]
	global_load_lds_dwordx4 v[238:239], off offset:128
	v_mfma_f32_16x16x32_bf16 v[24:27], v[172:175], v[216:219], v[24:27]
	v_mfma_f32_16x16x32_bf16 v[12:15], v[164:167], v[224:227], v[12:15]
	v_mfma_f32_16x16x32_bf16 v[8:11], v[172:175], v[224:227], v[8:11]
	v_mfma_f32_16x16x32_bf16 v[60:63], v[168:171], v[200:203], v[60:63]
	v_mfma_f32_16x16x32_bf16 v[56:59], v[176:179], v[200:203], v[56:59]
	s_add_i32 m0, s47, 0xffffff80
	v_mfma_f32_16x16x32_bf16 v[44:47], v[168:171], v[208:211], v[44:47]
	global_load_lds_dwordx4 v[240:241], off offset:128
	v_mfma_f32_16x16x32_bf16 v[40:43], v[176:179], v[208:211], v[40:43]
	v_mfma_f32_16x16x32_bf16 v[28:31], v[168:171], v[220:223], v[28:31]
	v_mfma_f32_16x16x32_bf16 v[24:27], v[176:179], v[220:223], v[24:27]
	v_mfma_f32_16x16x32_bf16 v[12:15], v[168:171], v[228:231], v[12:15]
	v_mfma_f32_16x16x32_bf16 v[8:11], v[176:179], v[228:231], v[8:11]
	v_mfma_f32_16x16x32_bf16 v[52:55], v[180:183], v[196:199], v[52:55]
	v_mfma_f32_16x16x32_bf16 v[48:51], v[188:191], v[196:199], v[48:51]
	v_mfma_f32_16x16x32_bf16 v[36:39], v[180:183], v[204:207], v[36:39]
	v_mfma_f32_16x16x32_bf16 v[32:35], v[188:191], v[204:207], v[32:35]
	v_mfma_f32_16x16x32_bf16 v[20:23], v[180:183], v[216:219], v[20:23]
	v_mfma_f32_16x16x32_bf16 v[16:19], v[188:191], v[216:219], v[16:19]
	v_mfma_f32_16x16x32_bf16 v[4:7], v[180:183], v[224:227], v[4:7]
	v_mfma_f32_16x16x32_bf16 v[0:3], v[188:191], v[224:227], v[0:3]
	v_mfma_f32_16x16x32_bf16 v[52:55], v[184:187], v[200:203], v[52:55]
	v_mfma_f32_16x16x32_bf16 v[48:51], v[192:195], v[200:203], v[48:51]
	v_mfma_f32_16x16x32_bf16 v[36:39], v[184:187], v[208:211], v[36:39]
	v_mfma_f32_16x16x32_bf16 v[32:35], v[192:195], v[208:211], v[32:35]
	v_mfma_f32_16x16x32_bf16 v[20:23], v[184:187], v[220:223], v[20:23]
	v_mfma_f32_16x16x32_bf16 v[16:19], v[192:195], v[220:223], v[16:19]
	v_mfma_f32_16x16x32_bf16 v[4:7], v[184:187], v[228:231], v[4:7]
	v_mfma_f32_16x16x32_bf16 v[0:3], v[192:195], v[228:231], v[0:3]
	s_setprio 0
	s_barrier
	v_lshl_add_u64 v[154:155], v[154:155], 0, s[28:29]
	s_cmp_ge_i32 s10, s48
	v_lshl_add_u64 v[158:159], v[158:159], 0, s[28:29]
	s_cbranch_scc0 .LBB0_1924

; #define PG8_STAGE(bufoff, gbase, voff) do { _Pragma("unroll") for (int _i = 0; _i < 2; ++_i) \
;         __builtin_amdgcn_global_load_lds((const unsigned*)((const char*)(gbase) + (voff)[_i]), (PG8_LAS unsigned*)(lds + (bufoff) + ldsw + _i * 8192), 16, 0, 0); } while (0)
; #define PG8_LDA(dst, b, h) do { _Pragma("unroll") for (int m = 0; m < 4; ++m) _Pragma("unroll") for (int k = 0; k < 2; ++k) dst[m][k] = *(const PG8_LAS bf16x8*)(lds + PG8_SA(b, h) + aoff + m * 2048 + k * 1024); } while (0)
; #define PG8_LDB(dst, b, h) do { _Pragma("unroll") for (int n = 0; n < 2; ++n) _Pragma("unroll") for (int k = 0; k < 2; ++k) dst[n][k] = *(const PG8_LAS bf16x8*)(lds + PG8_SB(b, h) + boff + n * 2048 + k * 1024); } while (0)
; #define PG8_MMA(ai, bj, At, Bt) do { __builtin_amdgcn_s_setprio(1); _Pragma("unroll") for (int m = 0; m < 4; ++m) _Pragma("unroll") for (int n = 0; n < 2; ++n) _Pragma("unroll") for (int k = 0; k < 2; ++k) \
;         acc[ai][bj][m][n] = __builtin_amdgcn_mfma_f32_16x16x32_bf16(Bt[n][k], At[m][k], acc[ai][bj][m][n], 0, 0, 0); __builtin_amdgcn_s_setprio(0); } while (0)
; #define PG8_WAIT_V(n) asm volatile("s_waitcnt vmcnt(" #n ")" ::: "memory")
; #define PG8_BAR __builtin_amdgcn_s_barrier()
; template <class Epi, class Sched, bool ALIGN_EPI = false, bool SP2 = false>
; __device__ __forceinline__ void gemm_phase(PG8_LAS unsigned char* lds, const Gemm g, const Sched& S, const Epi& E) {
;     ...
;         for (int t = 0; t < nt; t += 2) {
;             const bool last = (t == nt - 2);
;             const char* a1 = cA + (size_t)(t + 1) * kstep;
;             const char* a2 = last ? nA : cA + (size_t)(t + 2) * kstep; const char* b2 = last ? nB : cB + (size_t)(t + 2) * kstep;
;             const char* a3 = a2 + kstep; const char* b3 = b2 + kstep;
;             if (last && has_next) S.a_ready(nxt);
;             if constexpr (SP2) {
;             PG8_LDB(B0, 0, 0); PG8_LDB(B1, 0, 1); PG8_SCHED; PG8_LDA(At, 0, 0); PG8_STAGE(PG8_SA(1, 1), a1 + hstep, voffA);
;             PG8_WAIT_V(8); PG8_WAIT_L(0); PG8_BAR; PG8_MMA(0, 0, At, B0); PG8_MMA(0, 1, At, B1); PG8_BAR; PG8_SCHED;
;             PG8_LDA(At, 0, 1); PG8_STAGE(PG8_SB(0, 0), b2, voffB); PG8_STAGE(PG8_SB(0, 1), b2 + hstep, voffB); PG8_STAGE(PG8_SA(0, 0), a2, voffA);
;             PG8_WAIT_V(8); PG8_WAIT_L(0); PG8_BAR; PG8_MMA(1, 0, At, B0); PG8_MMA(1, 1, At, B1); PG8_BAR; PG8_SCHED;
.LBB0_1947:
	v_add_u32_e32 v178, s53, v216
	v_add_u32_e32 v194, s54, v216
	ds_read_b128 v[138:141], v178
	ds_read_b128 v[142:145], v178 offset:1024
	ds_read_b128 v[146:149], v178 offset:2048
	ds_read_b128 v[178:181], v178 offset:3072
	ds_read_b128 v[182:185], v194
	ds_read_b128 v[186:189], v194 offset:1024
	ds_read_b128 v[190:193], v194 offset:2048
	ds_read_b128 v[194:197], v194 offset:3072
	s_cmp_eq_u32 s47, s10
	v_lshl_add_u64 v[198:199], v[136:137], 0, s[20:21]
	s_cselect_b64 vcc, -1, 0
	s_add_i32 s10, s10, 2
	v_cndmask_b32_e32 v215, v199, v175, vcc
	v_cndmask_b32_e32 v214, v198, v174, vcc
	v_cndmask_b32_e32 v237, v135, v177, vcc
	v_cndmask_b32_e32 v236, v134, v176, vcc
	v_lshl_add_u64 v[238:239], v[136:137], 0, v[168:169]
	s_add_i32 m0, s34, 0xc000
	ds_read_b128 v[198:201], v218
	ds_read_b128 v[202:205], v218 offset:1024
	ds_read_b128 v[206:209], v218 offset:2048
	ds_read_b128 v[210:213], v218 offset:3072
	ds_read_b128 v[220:223], v218 offset:4096
	ds_read_b128 v[224:227], v218 offset:5120
	ds_read_b128 v[228:231], v218 offset:6144
	ds_read_b128 v[232:235], v218 offset:7168
	global_load_lds_dwordx4 v[238:239], off
	s_add_i32 m0, s34, 0xe000
	v_lshl_add_u64 v[238:239], v[136:137], 0, v[166:167]
	global_load_lds_dwordx4 v[238:239], off
	s_waitcnt vmcnt(8) lgkmcnt(0)
	s_setprio 1
	s_barrier
	v_mfma_f32_16x16x32_bf16 v[130:133], v[138:141], v[198:201], v[130:133]
	v_mfma_f32_16x16x32_bf16 v[126:129], v[146:149], v[198:201], v[126:129]
	v_mfma_f32_16x16x32_bf16 v[114:117], v[138:141], v[206:209], v[114:117]
	v_mfma_f32_16x16x32_bf16 v[110:113], v[146:149], v[206:209], v[110:113]
	v_mfma_f32_16x16x32_bf16 v[98:101], v[138:141], v[220:223], v[98:101]
	v_mfma_f32_16x16x32_bf16 v[94:97], v[146:149], v[220:223], v[94:97]
	v_mfma_f32_16x16x32_bf16 v[82:85], v[138:141], v[228:231], v[82:85]
	v_mfma_f32_16x16x32_bf16 v[78:81], v[146:149], v[228:231], v[78:81]
	v_mfma_f32_16x16x32_bf16 v[130:133], v[142:145], v[202:205], v[130:133]
	v_mfma_f32_16x16x32_bf16 v[126:129], v[178:181], v[202:205], v[126:129]
	v_mfma_f32_16x16x32_bf16 v[114:117], v[142:145], v[210:213], v[114:117]
	v_mfma_f32_16x16x32_bf16 v[110:113], v[178:181], v[210:213], v[110:113]
	v_mfma_f32_16x16x32_bf16 v[98:101], v[142:145], v[224:227], v[98:101]
	v_mfma_f32_16x16x32_bf16 v[94:97], v[178:181], v[224:227], v[94:97]
	v_mfma_f32_16x16x32_bf16 v[82:85], v[142:145], v[232:235], v[82:85]
	v_mfma_f32_16x16x32_bf16 v[78:81], v[178:181], v[232:235], v[78:81]
	v_mfma_f32_16x16x32_bf16 v[122:125], v[182:185], v[198:201], v[122:125]
	v_mfma_f32_16x16x32_bf16 v[118:121], v[190:193], v[198:201], v[118:121]
	v_mfma_f32_16x16x32_bf16 v[106:109], v[182:185], v[206:209], v[106:109]
	v_mfma_f32_16x16x32_bf16 v[102:105], v[190:193], v[206:209], v[102:105]
	v_mfma_f32_16x16x32_bf16 v[90:93], v[182:185], v[220:223], v[90:93]
	v_mfma_f32_16x16x32_bf16 v[86:89], v[190:193], v[220:223], v[86:89]
	v_mfma_f32_16x16x32_bf16 v[74:77], v[182:185], v[228:231], v[74:77]
	v_mfma_f32_16x16x32_bf16 v[70:73], v[190:193], v[228:231], v[70:73]
	v_mfma_f32_16x16x32_bf16 v[122:125], v[186:189], v[202:205], v[122:125]
	v_mfma_f32_16x16x32_bf16 v[118:121], v[194:197], v[202:205], v[118:121]
	v_mfma_f32_16x16x32_bf16 v[106:109], v[186:189], v[210:213], v[106:109]
	v_mfma_f32_16x16x32_bf16 v[102:105], v[194:197], v[210:213], v[102:105]
	v_mfma_f32_16x16x32_bf16 v[90:93], v[186:189], v[224:227], v[90:93]
	v_mfma_f32_16x16x32_bf16 v[86:89], v[194:197], v[224:227], v[86:89]
	v_mfma_f32_16x16x32_bf16 v[74:77], v[186:189], v[232:235], v[74:77]
	v_mfma_f32_16x16x32_bf16 v[70:73], v[194:197], v[232:235], v[70:73]
	s_setprio 0
	s_barrier
	s_add_i32 s11, s53, s29
	v_lshl_add_u64 v[238:239], v[236:237], 0, v[158:159]
	s_mov_b32 m0, s11
	ds_read_b128 v[198:201], v218 offset:16384
	ds_read_b128 v[202:205], v218 offset:17408
	ds_read_b128 v[206:209], v218 offset:18432
	ds_read_b128 v[210:213], v218 offset:19456
	ds_read_b128 v[220:223], v218 offset:20480
	ds_read_b128 v[224:227], v218 offset:21504
	ds_read_b128 v[228:231], v218 offset:22528
	global_load_lds_dwordx4 v[238:239], off
	v_lshl_add_u64 v[240:241], v[236:237], 0, v[162:163]
	s_add_i32 m0, s11, 0x2000
	v_lshl_add_u64 v[236:237], v[236:237], 0, s[12:13]
	s_add_i32 s11, s54, s29
	global_load_lds_dwordx4 v[240:241], off
	v_lshl_add_u64 v[242:243], v[236:237], 0, v[158:159]
	s_mov_b32 m0, s11
	v_lshl_add_u64 v[236:237], v[236:237], 0, v[162:163]
	global_load_lds_dwordx4 v[242:243], off
	s_add_i32 m0, s11, 0x2000
	ds_read_b128 v[232:235], v218 offset:23552
	global_load_lds_dwordx4 v[236:237], off
	s_waitcnt vmcnt(6) lgkmcnt(0)
	s_setprio 1
	s_barrier
; #define PG8_STAGE(bufoff, gbase, voff) do { _Pragma("unroll") for (int _i = 0; _i < 2; ++_i) \
;         __builtin_amdgcn_global_load_lds((const unsigned*)((const char*)(gbase) + (voff)[_i]), (PG8_LAS unsigned*)(lds + (bufoff) + ldsw + _i * 8192), 16, 0, 0); } while (0)
; #define PG8_LDA(dst, b, h) do { _Pragma("unroll") for (int m = 0; m < 4; ++m) _Pragma("unroll") for (int k = 0; k < 2; ++k) dst[m][k] = *(const PG8_LAS bf16x8*)(lds + PG8_SA(b, h) + aoff + m * 2048 + k * 1024); } while (0)
; #define PG8_LDB(dst, b, h) do { _Pragma("unroll") for (int n = 0; n < 2; ++n) _Pragma("unroll") for (int k = 0; k < 2; ++k) dst[n][k] = *(const PG8_LAS bf16x8*)(lds + PG8_SB(b, h) + boff + n * 2048 + k * 1024); } while (0)
; #define PG8_MMA(ai, bj, At, Bt) do { __builtin_amdgcn_s_setprio(1); _Pragma("unroll") for (int m = 0; m < 4; ++m) _Pragma("unroll") for (int n = 0; n < 2; ++n) _Pragma("unroll") for (int k = 0; k < 2; ++k) \
;         acc[ai][bj][m][n] = __builtin_amdgcn_mfma_f32_16x16x32_bf16(Bt[n][k], At[m][k], acc[ai][bj][m][n], 0, 0, 0); __builtin_amdgcn_s_setprio(0); } while (0)
; #define PG8_WAIT_V(n) asm volatile("s_waitcnt vmcnt(" #n ")" ::: "memory")
; #define PG8_WAIT_L(n) asm volatile("s_waitcnt lgkmcnt(" #n ")" ::: "memory")
; #define PG8_BAR __builtin_amdgcn_s_barrier()
; #define PG8_SCHED __builtin_amdgcn_sched_barrier(0)
; template <class Epi, class Sched, bool ALIGN_EPI = false, bool SP2 = false>
; __device__ __forceinline__ void gemm_phase(PG8_LAS unsigned char* lds, const Gemm g, const Sched& S, const Epi& E) {
;     ...
;             PG8_WAIT_V(8); PG8_WAIT_L(0); PG8_BAR; PG8_MMA(1, 0, At, B0); PG8_MMA(1, 1, At, B1); PG8_BAR; PG8_SCHED;
;             PG8_LDB(B0, 1, 0); PG8_LDB(B1, 1, 1); PG8_SCHED; PG8_LDA(At, 1, 0); PG8_STAGE(PG8_SA(0, 1), a2 + hstep, voffA);
;             PG8_WAIT_V(8); PG8_WAIT_L(0); PG8_BAR; PG8_MMA(0, 0, At, B0); PG8_MMA(0, 1, At, B1); PG8_BAR; PG8_SCHED;
	v_mfma_f32_16x16x32_bf16 v[66:69], v[138:141], v[198:201], v[66:69]
	v_mfma_f32_16x16x32_bf16 v[62:65], v[146:149], v[198:201], v[62:65]
	v_mfma_f32_16x16x32_bf16 v[50:53], v[138:141], v[206:209], v[50:53]
	v_mfma_f32_16x16x32_bf16 v[46:49], v[146:149], v[206:209], v[46:49]
	s_mov_b32 m0, s34
	v_lshl_add_u64 v[244:245], v[214:215], 0, v[154:155]
	v_mfma_f32_16x16x32_bf16 v[34:37], v[138:141], v[220:223], v[34:37]
	global_load_lds_dwordx4 v[244:245], off
	v_mfma_f32_16x16x32_bf16 v[30:33], v[146:149], v[220:223], v[30:33]
	v_mfma_f32_16x16x32_bf16 v[18:21], v[138:141], v[228:231], v[18:21]
	v_mfma_f32_16x16x32_bf16 v[14:17], v[146:149], v[228:231], v[14:17]
	v_mfma_f32_16x16x32_bf16 v[66:69], v[142:145], v[202:205], v[66:69]
	v_mfma_f32_16x16x32_bf16 v[62:65], v[178:181], v[202:205], v[62:65]
	s_mov_b32 m0, s35
	v_lshl_add_u64 v[246:247], v[214:215], 0, v[160:161]
	v_mfma_f32_16x16x32_bf16 v[50:53], v[142:145], v[210:213], v[50:53]
	global_load_lds_dwordx4 v[246:247], off
	v_mfma_f32_16x16x32_bf16 v[46:49], v[178:181], v[210:213], v[46:49]
	v_mfma_f32_16x16x32_bf16 v[34:37], v[142:145], v[224:227], v[34:37]
	v_mfma_f32_16x16x32_bf16 v[30:33], v[178:181], v[224:227], v[30:33]
	v_mfma_f32_16x16x32_bf16 v[18:21], v[142:145], v[232:235], v[18:21]
	v_mfma_f32_16x16x32_bf16 v[14:17], v[178:181], v[232:235], v[14:17]
	v_mfma_f32_16x16x32_bf16 v[58:61], v[182:185], v[198:201], v[58:61]
	v_mfma_f32_16x16x32_bf16 v[54:57], v[190:193], v[198:201], v[54:57]
	v_mfma_f32_16x16x32_bf16 v[42:45], v[182:185], v[206:209], v[42:45]
	v_mfma_f32_16x16x32_bf16 v[38:41], v[190:193], v[206:209], v[38:41]
	v_mfma_f32_16x16x32_bf16 v[26:29], v[182:185], v[220:223], v[26:29]
	v_mfma_f32_16x16x32_bf16 v[22:25], v[190:193], v[220:223], v[22:25]
	v_mfma_f32_16x16x32_bf16 v[10:13], v[182:185], v[228:231], v[10:13]
	v_mfma_f32_16x16x32_bf16 v[6:9], v[190:193], v[228:231], v[6:9]
	v_mfma_f32_16x16x32_bf16 v[58:61], v[186:189], v[202:205], v[58:61]
	v_mfma_f32_16x16x32_bf16 v[54:57], v[194:197], v[202:205], v[54:57]
	v_mfma_f32_16x16x32_bf16 v[42:45], v[186:189], v[210:213], v[42:45]
	v_mfma_f32_16x16x32_bf16 v[38:41], v[194:197], v[210:213], v[38:41]
	v_mfma_f32_16x16x32_bf16 v[26:29], v[186:189], v[224:227], v[26:29]
	v_mfma_f32_16x16x32_bf16 v[22:25], v[194:197], v[224:227], v[22:25]
	v_mfma_f32_16x16x32_bf16 v[10:13], v[186:189], v[232:235], v[10:13]
	v_mfma_f32_16x16x32_bf16 v[6:9], v[194:197], v[232:235], v[6:9]
	s_setprio 0
	s_barrier
	s_add_i32 s11, 0, 0x18000
	s_add_i32 s31, 0, 0x1c000
	v_add_u32_e32 v178, s11, v216
	v_add_u32_e32 v194, s31, v216
	ds_read_b128 v[138:141], v178
	ds_read_b128 v[142:145], v178 offset:1024
	ds_read_b128 v[146:149], v178 offset:2048
	ds_read_b128 v[178:181], v178 offset:3072
	ds_read_b128 v[182:185], v194
	ds_read_b128 v[186:189], v194 offset:1024
	ds_read_b128 v[190:193], v194 offset:2048
	ds_read_b128 v[194:197], v194 offset:3072
	v_lshl_add_u64 v[214:215], v[214:215], 0, s[12:13]
	s_mov_b32 m0, s36
	v_lshl_add_u64 v[248:249], v[214:215], 0, v[154:155]
	ds_read_b128 v[198:201], v218 offset:32768
	ds_read_b128 v[202:205], v218 offset:33792
	ds_read_b128 v[206:209], v218 offset:34816
	ds_read_b128 v[210:213], v218 offset:35840
	ds_read_b128 v[220:223], v218 offset:36864
	ds_read_b128 v[224:227], v218 offset:37888
	ds_read_b128 v[228:231], v218 offset:38912
	ds_read_b128 v[232:235], v218 offset:39936
	global_load_lds_dwordx4 v[248:249], off
	s_mov_b32 m0, s37
	v_lshl_add_u64 v[214:215], v[214:215], 0, v[160:161]
	global_load_lds_dwordx4 v[214:215], off
	s_waitcnt vmcnt(8) lgkmcnt(0)
	s_setprio 1
	s_barrier
; #define PG8_STAGE(bufoff, gbase, voff) do { _Pragma("unroll") for (int _i = 0; _i < 2; ++_i) \
;         __builtin_amdgcn_global_load_lds((const unsigned*)((const char*)(gbase) + (voff)[_i]), (PG8_LAS unsigned*)(lds + (bufoff) + ldsw + _i * 8192), 16, 0, 0); } while (0)
; #define PG8_LDA(dst, b, h) do { _Pragma("unroll") for (int m = 0; m < 4; ++m) _Pragma("unroll") for (int k = 0; k < 2; ++k) dst[m][k] = *(const PG8_LAS bf16x8*)(lds + PG8_SA(b, h) + aoff + m * 2048 + k * 1024); } while (0)
; #define PG8_MMA(ai, bj, At, Bt) do { __builtin_amdgcn_s_setprio(1); _Pragma("unroll") for (int m = 0; m < 4; ++m) _Pragma("unroll") for (int n = 0; n < 2; ++n) _Pragma("unroll") for (int k = 0; k < 2; ++k) \
;         acc[ai][bj][m][n] = __builtin_amdgcn_mfma_f32_16x16x32_bf16(Bt[n][k], At[m][k], acc[ai][bj][m][n], 0, 0, 0); __builtin_amdgcn_s_setprio(0); } while (0)
; #define PG8_WAIT_V(n) asm volatile("s_waitcnt vmcnt(" #n ")" ::: "memory")
; #define PG8_WAIT_L(n) asm volatile("s_waitcnt lgkmcnt(" #n ")" ::: "memory")
; #define PG8_BAR __builtin_amdgcn_s_barrier()
; #define PG8_SCHED __builtin_amdgcn_sched_barrier(0)
; template <class Epi, class Sched, bool ALIGN_EPI = false, bool SP2 = false>
; __device__ __forceinline__ void gemm_phase(PG8_LAS unsigned char* lds, const Gemm g, const Sched& S, const Epi& E) {
;     ...
;             PG8_WAIT_V(8); PG8_WAIT_L(0); PG8_BAR; PG8_MMA(0, 0, At, B0); PG8_MMA(0, 1, At, B1); PG8_BAR; PG8_SCHED;
;             PG8_LDA(At, 1, 1); PG8_STAGE(PG8_SB(1, 0), b3, voffB); PG8_STAGE(PG8_SB(1, 1), b3 + hstep, voffB); PG8_STAGE(PG8_SA(1, 0), a3, voffA);
;             PG8_WAIT_V(8); PG8_WAIT_L(0); PG8_BAR; PG8_MMA(1, 0, At, B0); PG8_MMA(1, 1, At, B1); PG8_BAR; PG8_SCHED;
	v_mfma_f32_16x16x32_bf16 v[130:133], v[138:141], v[198:201], v[130:133]
	v_mfma_f32_16x16x32_bf16 v[126:129], v[146:149], v[198:201], v[126:129]
	v_mfma_f32_16x16x32_bf16 v[114:117], v[138:141], v[206:209], v[114:117]
	v_mfma_f32_16x16x32_bf16 v[110:113], v[146:149], v[206:209], v[110:113]
	v_mfma_f32_16x16x32_bf16 v[98:101], v[138:141], v[220:223], v[98:101]
	v_mfma_f32_16x16x32_bf16 v[94:97], v[146:149], v[220:223], v[94:97]
	v_mfma_f32_16x16x32_bf16 v[82:85], v[138:141], v[228:231], v[82:85]
	v_mfma_f32_16x16x32_bf16 v[78:81], v[146:149], v[228:231], v[78:81]
	v_mfma_f32_16x16x32_bf16 v[130:133], v[142:145], v[202:205], v[130:133]
	v_mfma_f32_16x16x32_bf16 v[126:129], v[178:181], v[202:205], v[126:129]
	v_mfma_f32_16x16x32_bf16 v[114:117], v[142:145], v[210:213], v[114:117]
	v_mfma_f32_16x16x32_bf16 v[110:113], v[178:181], v[210:213], v[110:113]
	v_mfma_f32_16x16x32_bf16 v[98:101], v[142:145], v[224:227], v[98:101]
	v_mfma_f32_16x16x32_bf16 v[94:97], v[178:181], v[224:227], v[94:97]
	v_mfma_f32_16x16x32_bf16 v[82:85], v[142:145], v[232:235], v[82:85]
	v_mfma_f32_16x16x32_bf16 v[78:81], v[178:181], v[232:235], v[78:81]
	v_mfma_f32_16x16x32_bf16 v[122:125], v[182:185], v[198:201], v[122:125]
	v_mfma_f32_16x16x32_bf16 v[118:121], v[190:193], v[198:201], v[118:121]
	v_mfma_f32_16x16x32_bf16 v[106:109], v[182:185], v[206:209], v[106:109]
	v_mfma_f32_16x16x32_bf16 v[102:105], v[190:193], v[206:209], v[102:105]
	v_mfma_f32_16x16x32_bf16 v[90:93], v[182:185], v[220:223], v[90:93]
	v_mfma_f32_16x16x32_bf16 v[86:89], v[190:193], v[220:223], v[86:89]
	v_mfma_f32_16x16x32_bf16 v[74:77], v[182:185], v[228:231], v[74:77]
	v_mfma_f32_16x16x32_bf16 v[70:73], v[190:193], v[228:231], v[70:73]
	v_mfma_f32_16x16x32_bf16 v[122:125], v[186:189], v[202:205], v[122:125]
	v_mfma_f32_16x16x32_bf16 v[118:121], v[194:197], v[202:205], v[118:121]
	v_mfma_f32_16x16x32_bf16 v[106:109], v[186:189], v[210:213], v[106:109]
	v_mfma_f32_16x16x32_bf16 v[102:105], v[194:197], v[210:213], v[102:105]
	v_mfma_f32_16x16x32_bf16 v[90:93], v[186:189], v[224:227], v[90:93]
	v_mfma_f32_16x16x32_bf16 v[86:89], v[194:197], v[224:227], v[86:89]
	v_mfma_f32_16x16x32_bf16 v[74:77], v[186:189], v[232:235], v[74:77]
	v_mfma_f32_16x16x32_bf16 v[70:73], v[194:197], v[232:235], v[70:73]
	s_setprio 0
	s_barrier
	s_add_i32 s11, s11, s29
	s_add_i32 m0, s11, 0xffffff80
	ds_read_b128 v[198:201], v218 offset:49152
	ds_read_b128 v[202:205], v218 offset:50176
	ds_read_b128 v[206:209], v218 offset:51200
	ds_read_b128 v[210:213], v218 offset:52224
	ds_read_b128 v[220:223], v218 offset:53248
	ds_read_b128 v[224:227], v218 offset:54272
	global_load_lds_dwordx4 v[238:239], off offset:128
	s_add_i32 m0, s11, 0x1f80
	s_add_i32 s11, s31, s29
	global_load_lds_dwordx4 v[240:241], off offset:128
	s_add_i32 m0, s11, 0xffffff80
	ds_read_b128 v[232:235], v218 offset:56320
	global_load_lds_dwordx4 v[242:243], off offset:128
	s_add_i32 m0, s11, 0x1f80
	ds_read_b128 v[228:231], v218 offset:55296
	global_load_lds_dwordx4 v[236:237], off offset:128
	s_waitcnt vmcnt(6) lgkmcnt(0)
	s_setprio 1
	s_barrier
	v_mfma_f32_16x16x32_bf16 v[66:69], v[138:141], v[198:201], v[66:69]
	v_mfma_f32_16x16x32_bf16 v[62:65], v[146:149], v[198:201], v[62:65]
	v_mfma_f32_16x16x32_bf16 v[50:53], v[138:141], v[206:209], v[50:53]
	v_mfma_f32_16x16x32_bf16 v[46:49], v[146:149], v[206:209], v[46:49]
	s_add_i32 m0, s41, 0xffffff80
	v_mfma_f32_16x16x32_bf16 v[34:37], v[138:141], v[220:223], v[34:37]
	global_load_lds_dwordx4 v[244:245], off offset:128
	v_mfma_f32_16x16x32_bf16 v[30:33], v[146:149], v[220:223], v[30:33]
	v_mfma_f32_16x16x32_bf16 v[18:21], v[138:141], v[228:231], v[18:21]
	v_mfma_f32_16x16x32_bf16 v[14:17], v[146:149], v[228:231], v[14:17]
	v_mfma_f32_16x16x32_bf16 v[66:69], v[142:145], v[202:205], v[66:69]
	v_mfma_f32_16x16x32_bf16 v[62:65], v[178:181], v[202:205], v[62:65]
	s_add_i32 m0, s44, 0xffffff80
	v_mfma_f32_16x16x32_bf16 v[50:53], v[142:145], v[210:213], v[50:53]
	global_load_lds_dwordx4 v[246:247], off offset:128
	v_mfma_f32_16x16x32_bf16 v[46:49], v[178:181], v[210:213], v[46:49]
	v_mfma_f32_16x16x32_bf16 v[34:37], v[142:145], v[224:227], v[34:37]
	v_mfma_f32_16x16x32_bf16 v[30:33], v[178:181], v[224:227], v[30:33]
	v_mfma_f32_16x16x32_bf16 v[18:21], v[142:145], v[232:235], v[18:21]
	v_mfma_f32_16x16x32_bf16 v[14:17], v[178:181], v[232:235], v[14:17]
	v_mfma_f32_16x16x32_bf16 v[58:61], v[182:185], v[198:201], v[58:61]
	v_mfma_f32_16x16x32_bf16 v[54:57], v[190:193], v[198:201], v[54:57]
	v_mfma_f32_16x16x32_bf16 v[42:45], v[182:185], v[206:209], v[42:45]
	v_mfma_f32_16x16x32_bf16 v[38:41], v[190:193], v[206:209], v[38:41]
	v_mfma_f32_16x16x32_bf16 v[26:29], v[182:185], v[220:223], v[26:29]
	v_mfma_f32_16x16x32_bf16 v[22:25], v[190:193], v[220:223], v[22:25]
	v_mfma_f32_16x16x32_bf16 v[10:13], v[182:185], v[228:231], v[10:13]
	v_mfma_f32_16x16x32_bf16 v[6:9], v[190:193], v[228:231], v[6:9]
	v_mfma_f32_16x16x32_bf16 v[58:61], v[186:189], v[202:205], v[58:61]
	v_mfma_f32_16x16x32_bf16 v[54:57], v[194:197], v[202:205], v[54:57]
	v_mfma_f32_16x16x32_bf16 v[42:45], v[186:189], v[210:213], v[42:45]
	v_mfma_f32_16x16x32_bf16 v[38:41], v[194:197], v[210:213], v[38:41]
	v_mfma_f32_16x16x32_bf16 v[26:29], v[186:189], v[224:227], v[26:29]
	v_mfma_f32_16x16x32_bf16 v[22:25], v[194:197], v[224:227], v[22:25]
	v_mfma_f32_16x16x32_bf16 v[10:13], v[186:189], v[232:235], v[10:13]
	v_mfma_f32_16x16x32_bf16 v[6:9], v[194:197], v[232:235], v[6:9]
	s_setprio 0
	s_barrier
	v_lshl_add_u64 v[134:135], v[134:135], 0, s[26:27]
	s_cmp_ge_i32 s10, s46
	v_lshl_add_u64 v[136:137], v[136:137], 0, s[26:27]
	s_cbranch_scc0 .LBB0_1947
